# K-loops counted LDS waits: load-closing wait covers only the reads the first MFMA consumes; remaining fragments waited (in-order lgkmcnt) in front of their first consuming MFMA
# speedup vs baseline: 1.0009x; 1.0009x over previous
; #define PG8_STAGE(bufoff, gbase, voff) do { _Pragma("unroll") for (int _i = 0; _i < 2; ++_i) \
;         __builtin_amdgcn_global_load_lds((const unsigned*)((const char*)(gbase) + (voff)[_i]), (PG8_LAS unsigned*)(lds + (bufoff) + ldsw + _i * 8192), 16, 0, 0); } while (0)
; #define PG8_LDA(dst, b, h) do { _Pragma("unroll") for (int m = 0; m < 4; ++m) _Pragma("unroll") for (int k = 0; k < 2; ++k) dst[m][k] = *(const PG8_LAS bf16x8*)(lds + PG8_SA(b, h) + aoff + m * 2048 + k * 1024); } while (0)
; #define PG8_LDB(dst, b, h) do { _Pragma("unroll") for (int n = 0; n < 2; ++n) _Pragma("unroll") for (int k = 0; k < 2; ++k) dst[n][k] = *(const PG8_LAS bf16x8*)(lds + PG8_SB(b, h) + boff + n * 2048 + k * 1024); } while (0)
; #define PG8_WAIT_V(n) asm volatile("s_waitcnt vmcnt(" #n ")" ::: "memory")
; #define PG8_WAIT_L(n) asm volatile("s_waitcnt lgkmcnt(" #n ")" ::: "memory")
; #define PG8_BAR __builtin_amdgcn_s_barrier()
; #define PG8_SCHED __builtin_amdgcn_sched_barrier(0)
; template <class Epi, class Sched, bool ALIGN_EPI = false, bool SP2 = false, bool I8 = false>
; __device__ __forceinline__ void gemm_phase(PG8_LAS unsigned char* lds, const Gemm g, const Sched& S, const Epi& E) {
;     ...
;         const char* nA = has_next ? (const char*)g.A + (size_t)nxt.pm * tstep : cA; const char* nB = has_next ? (const char*)g.Bt + (size_t)nxt.pn * tstep : cB;
;         for (int t = 0; t < nt; t += 2) {
;             const bool last = (t == nt - 2);
;             const char* a1 = cA + (size_t)(t + 1) * kstep;
;             const char* a2 = last ? nA : cA + (size_t)(t + 2) * kstep; const char* b2 = last ? nB : cB + (size_t)(t + 2) * kstep;
;             const char* a3 = a2 + kstep; const char* b3 = b2 + kstep;
;             if (last && has_next) S.a_ready(nxt);
;             if constexpr (SP2) {
;             PG8_LDB(B0, 0, 0); PG8_LDB(B1, 0, 1); PG8_SCHED; PG8_LDA(At, 0, 0); PG8_STAGE(PG8_SA(1, 1), a1 + hstep, voffA);
;             PG8_WAIT_V(8); PG8_WAIT_L(0); PG8_BAR; PG8_MMA(0, 0, At, B0); PG8_MMA(0, 1, At, B1); PG8_BAR; PG8_SCHED;
;             PG8_LDA(At, 0, 1); PG8_STAGE(PG8_SB(0, 0), b2, voffB); PG8_STAGE(PG8_SB(0, 1), b2 + hstep, voffB); PG8_STAGE(PG8_SA(0, 0), a2, voffA);
;             PG8_WAIT_V(8); PG8_WAIT_L(0); PG8_BAR; PG8_MMA(1, 0, At, B0); PG8_MMA(1, 1, At, B1); PG8_BAR; PG8_SCHED;
.LBB0_207:
	s_ashr_i32 s19, s18, 31
	s_lshl_b64 s[22:23], s[18:19], 20
	s_add_u32 s22, s28, s22
	s_addc_u32 s23, s34, s23
	s_and_b64 s[24:25], s[6:7], exec
	s_cselect_b32 s19, s23, s27
	s_cselect_b32 s64, s22, s26
	s_ashr_i32 s17, s16, 31
	s_lshl_b64 s[24:25], s[16:17], 20
	s_add_u32 s24, s35, s24
	s_addc_u32 s25, s42, s25
	s_and_b64 s[40:41], s[6:7], exec
	s_cselect_b32 s17, s25, s37
	s_cselect_b32 s65, s24, s36
	s_add_u32 s26, s26, 0x80080
	s_addc_u32 s27, s27, 0
	s_add_u32 s72, s36, 0x100
	s_addc_u32 s73, s37, 0
	s_mov_b32 s76, -2
	s_add_u32 s36, s26, 0xfff80080
	s_addc_u32 s37, s27, -1
	s_add_i32 s50, 0, 0x10000
	s_cmp_eq_u32 s76, 28
	s_cselect_b32 s41, s19, s37
	s_cselect_b32 s40, s64, s36
	s_cselect_b32 s37, s17, s73
	s_cselect_b32 s36, s65, s72
	s_add_i32 s56, 0, 0x14000
	v_add_u32_e32 v136, s50, v175
	v_add_u32_e32 v172, s56, v175
	ds_read_b128 v[116:119], v136
	ds_read_b128 v[124:127], v136 offset:1024
	ds_read_b128 v[132:135], v136 offset:2048
	ds_read_b128 v[136:139], v136 offset:3072
	ds_read_b128 v[160:163], v172
	ds_read_b128 v[164:167], v172 offset:1024
	ds_read_b128 v[168:171], v172 offset:2048
	ds_read_b128 v[178:181], v172 offset:3072
	s_add_i32 m0, s44, 0xc000
	ds_read_b128 v[182:185], v177
	ds_read_b128 v[186:189], v177 offset:1024
	ds_read_b128 v[204:207], v177 offset:2048
	ds_read_b128 v[208:211], v177 offset:3072
	ds_read_b128 v[212:215], v177 offset:4096
	ds_read_b128 v[216:219], v177 offset:5120
	ds_read_b128 v[220:223], v177 offset:6144
	ds_read_b128 v[224:227], v177 offset:7168
	global_load_lds_dwordx4 v156, s[26:27]
	s_add_i32 m0, s44, 0xe000
	s_nop 0
	global_load_lds_dwordx4 v158, s[26:27]
	s_waitcnt vmcnt(8)
	s_waitcnt lgkmcnt(7)
	s_setprio 1
	s_barrier
	v_mfma_i32_16x16x64_i8 v[144:147], v[116:119], v[182:185], 0
	s_waitcnt lgkmcnt(6)
	v_mfma_i32_16x16x64_i8 v[144:147], v[124:127], v[186:189], v[144:147]
	s_waitcnt lgkmcnt(4)
	v_mfma_i32_16x16x64_i8 v[112:115], v[124:127], v[208:211], 0
	v_mfma_i32_16x16x64_i8 v[112:115], v[116:119], v[204:207], v[112:115]
	s_waitcnt lgkmcnt(3)
	v_mfma_i32_16x16x64_i8 v[96:99], v[116:119], v[212:215], 0
	s_waitcnt lgkmcnt(2)
	v_mfma_i32_16x16x64_i8 v[96:99], v[124:127], v[216:219], v[96:99]
	s_waitcnt lgkmcnt(0)
	v_mfma_i32_16x16x64_i8 v[80:83], v[124:127], v[224:227], 0
	v_mfma_i32_16x16x64_i8 v[80:83], v[116:119], v[220:223], v[80:83]
	v_mfma_i32_16x16x64_i8 v[76:79], v[132:135], v[220:223], 0
	v_mfma_i32_16x16x64_i8 v[76:79], v[136:139], v[224:227], v[76:79]
	v_mfma_i32_16x16x64_i8 v[92:95], v[136:139], v[216:219], 0
	v_mfma_i32_16x16x64_i8 v[92:95], v[132:135], v[212:215], v[92:95]
	v_mfma_i32_16x16x64_i8 v[108:111], v[132:135], v[204:207], 0
	v_mfma_i32_16x16x64_i8 v[108:111], v[136:139], v[208:211], v[108:111]
	v_mfma_i32_16x16x64_i8 v[140:143], v[136:139], v[186:189], 0
	v_mfma_i32_16x16x64_i8 v[140:143], v[132:135], v[182:185], v[140:143]
	v_mfma_i32_16x16x64_i8 v[128:131], v[160:163], v[182:185], 0
	v_mfma_i32_16x16x64_i8 v[128:131], v[164:167], v[186:189], v[128:131]
	v_mfma_i32_16x16x64_i8 v[104:107], v[164:167], v[208:211], 0
	v_mfma_i32_16x16x64_i8 v[104:107], v[160:163], v[204:207], v[104:107]
	v_mfma_i32_16x16x64_i8 v[88:91], v[160:163], v[212:215], 0
	v_mfma_i32_16x16x64_i8 v[88:91], v[164:167], v[216:219], v[88:91]
	v_mfma_i32_16x16x64_i8 v[72:75], v[164:167], v[224:227], 0
	v_mfma_i32_16x16x64_i8 v[72:75], v[160:163], v[220:223], v[72:75]
	v_mfma_i32_16x16x64_i8 v[68:71], v[168:171], v[220:223], 0
	v_mfma_i32_16x16x64_i8 v[68:71], v[178:181], v[224:227], v[68:71]
	v_mfma_i32_16x16x64_i8 v[84:87], v[178:181], v[216:219], 0
	v_mfma_i32_16x16x64_i8 v[84:87], v[168:171], v[212:215], v[84:87]
	v_mfma_i32_16x16x64_i8 v[100:103], v[168:171], v[204:207], 0
	v_mfma_i32_16x16x64_i8 v[100:103], v[178:181], v[208:211], v[100:103]
	v_mfma_i32_16x16x64_i8 v[120:123], v[178:181], v[186:189], 0
	v_mfma_i32_16x16x64_i8 v[120:123], v[168:171], v[182:185], v[120:123]
	s_barrier
	s_setprio 0
	s_add_i32 s50, s50, s43
	v_lshl_add_u64 v[172:173], s[36:37], 0, v[2:3]
	s_mov_b32 m0, s50
	ds_read_b128 v[182:185], v177 offset:16384
	ds_read_b128 v[186:189], v177 offset:17408
	ds_read_b128 v[204:207], v177 offset:18432
	ds_read_b128 v[208:211], v177 offset:19456
	ds_read_b128 v[212:215], v177 offset:20480
	ds_read_b128 v[216:219], v177 offset:21504
	ds_read_b128 v[220:223], v177 offset:22528
	ds_read_b128 v[224:227], v177 offset:23552
	global_load_lds_dwordx4 v[172:173], off
	s_add_i32 m0, s50, 0x2000
	s_add_u32 s50, s36, 0x80000
	v_lshl_add_u64 v[190:191], s[36:37], 0, v[148:149]
	s_addc_u32 s51, s37, 0
	s_add_i32 s56, s56, s43
	global_load_lds_dwordx4 v[190:191], off
	s_mov_b32 m0, s56
	v_lshl_add_u64 v[240:241], s[40:41], 0, v[150:151]
	global_load_lds_dwordx4 v2, s[50:51]
	s_add_i32 m0, s56, 0x2000
	s_nop 0
	global_load_lds_dwordx4 v148, s[50:51]
	v_lshl_add_u64 v[228:229], s[40:41], 0, v[152:153]
	s_waitcnt vmcnt(6)
	s_waitcnt lgkmcnt(7)
	s_setprio 1
	s_barrier
; #define PG8_STAGE(bufoff, gbase, voff) do { _Pragma("unroll") for (int _i = 0; _i < 2; ++_i) \
;         __builtin_amdgcn_global_load_lds((const unsigned*)((const char*)(gbase) + (voff)[_i]), (PG8_LAS unsigned*)(lds + (bufoff) + ldsw + _i * 8192), 16, 0, 0); } while (0)
; #define PG8_LDA(dst, b, h) do { _Pragma("unroll") for (int m = 0; m < 4; ++m) _Pragma("unroll") for (int k = 0; k < 2; ++k) dst[m][k] = *(const PG8_LAS bf16x8*)(lds + PG8_SA(b, h) + aoff + m * 2048 + k * 1024); } while (0)
; #define PG8_LDB(dst, b, h) do { _Pragma("unroll") for (int n = 0; n < 2; ++n) _Pragma("unroll") for (int k = 0; k < 2; ++k) dst[n][k] = *(const PG8_LAS bf16x8*)(lds + PG8_SB(b, h) + boff + n * 2048 + k * 1024); } while (0)
; #define PG8_WAIT_V(n) asm volatile("s_waitcnt vmcnt(" #n ")" ::: "memory")
; #define PG8_WAIT_L(n) asm volatile("s_waitcnt lgkmcnt(" #n ")" ::: "memory")
; #define PG8_BAR __builtin_amdgcn_s_barrier()
; #define PG8_SCHED __builtin_amdgcn_sched_barrier(0)
; template <class Epi, class Sched, bool ALIGN_EPI = false, bool SP2 = false, bool I8 = false>
; __device__ __forceinline__ void gemm_phase(PG8_LAS unsigned char* lds, const Gemm g, const Sched& S, const Epi& E) {
;     ...
;             PG8_WAIT_V(8); PG8_WAIT_L(0); PG8_BAR; PG8_MMA(1, 0, At, B0); PG8_MMA(1, 1, At, B1); PG8_BAR; PG8_SCHED;
;             PG8_LDB(B0, 1, 0); PG8_LDB(B1, 1, 1); PG8_SCHED; PG8_LDA(At, 1, 0); PG8_STAGE(PG8_SA(0, 1), a2 + hstep, voffA);
;             PG8_WAIT_V(8); PG8_WAIT_L(0); PG8_BAR; PG8_MMA(0, 0, At, B0); PG8_MMA(0, 1, At, B1); PG8_BAR; PG8_SCHED;
;             PG8_LDA(At, 1, 1); PG8_STAGE(PG8_SB(1, 0), b3, voffB); PG8_STAGE(PG8_SB(1, 1), b3 + hstep, voffB); PG8_STAGE(PG8_SA(1, 0), a3, voffA);
	v_mfma_i32_16x16x64_i8 v[64:67], v[116:119], v[182:185], 0
	s_waitcnt lgkmcnt(6)
	v_mfma_i32_16x16x64_i8 v[64:67], v[124:127], v[186:189], v[64:67]
	s_waitcnt lgkmcnt(4)
	v_mfma_i32_16x16x64_i8 v[48:51], v[124:127], v[208:211], 0
	v_mfma_i32_16x16x64_i8 v[48:51], v[116:119], v[204:207], v[48:51]
	s_waitcnt lgkmcnt(3)
	v_mfma_i32_16x16x64_i8 v[32:35], v[116:119], v[212:215], 0
	s_waitcnt lgkmcnt(2)
	v_mfma_i32_16x16x64_i8 v[32:35], v[124:127], v[216:219], v[32:35]
	s_waitcnt lgkmcnt(0)
	v_mfma_i32_16x16x64_i8 v[16:19], v[124:127], v[224:227], 0
	v_mfma_i32_16x16x64_i8 v[16:19], v[116:119], v[220:223], v[16:19]
	v_mfma_i32_16x16x64_i8 v[12:15], v[132:135], v[220:223], 0
	v_mfma_i32_16x16x64_i8 v[12:15], v[136:139], v[224:227], v[12:15]
	v_mfma_i32_16x16x64_i8 v[28:31], v[136:139], v[216:219], 0
	v_mfma_i32_16x16x64_i8 v[28:31], v[132:135], v[212:215], v[28:31]
	v_mfma_i32_16x16x64_i8 v[44:47], v[132:135], v[204:207], 0
	v_mfma_i32_16x16x64_i8 v[44:47], v[136:139], v[208:211], v[44:47]
	v_mfma_i32_16x16x64_i8 v[60:63], v[136:139], v[186:189], 0
	v_mfma_i32_16x16x64_i8 v[60:63], v[132:135], v[182:185], v[60:63]
	v_mfma_i32_16x16x64_i8 v[56:59], v[160:163], v[182:185], 0
	v_mfma_i32_16x16x64_i8 v[56:59], v[164:167], v[186:189], v[56:59]
	v_mfma_i32_16x16x64_i8 v[40:43], v[164:167], v[208:211], 0
	v_mfma_i32_16x16x64_i8 v[40:43], v[160:163], v[204:207], v[40:43]
	v_mfma_i32_16x16x64_i8 v[24:27], v[160:163], v[212:215], 0
	v_mfma_i32_16x16x64_i8 v[24:27], v[164:167], v[216:219], v[24:27]
	v_mfma_i32_16x16x64_i8 v[8:11], v[164:167], v[224:227], 0
	v_mfma_i32_16x16x64_i8 v[8:11], v[160:163], v[220:223], v[8:11]
	v_mfma_i32_16x16x64_i8 v[4:7], v[168:171], v[220:223], 0
	v_mfma_i32_16x16x64_i8 v[4:7], v[178:181], v[224:227], v[4:7]
	v_mfma_i32_16x16x64_i8 v[20:23], v[178:181], v[216:219], 0
	v_mfma_i32_16x16x64_i8 v[20:23], v[168:171], v[212:215], v[20:23]
	v_mfma_i32_16x16x64_i8 v[36:39], v[168:171], v[204:207], 0
	v_mfma_i32_16x16x64_i8 v[36:39], v[178:181], v[208:211], v[36:39]
	v_mfma_i32_16x16x64_i8 v[52:55], v[178:181], v[186:189], 0
	v_mfma_i32_16x16x64_i8 v[52:55], v[168:171], v[182:185], v[52:55]
	s_barrier
	s_setprio 0
	s_mov_b32 m0, s44
	s_nop 0
	global_load_lds_dwordx4 v[228:229], off
	s_mov_b32 m0, s45
	s_nop 0
	global_load_lds_dwordx4 v[240:241], off
	s_add_i32 s50, 0, 0x18000
	s_add_i32 s51, 0, 0x1c000
	v_add_u32_e32 v136, s50, v175
	v_add_u32_e32 v178, s51, v175
	ds_read_b128 v[116:119], v136
	ds_read_b128 v[124:127], v136 offset:1024
	ds_read_b128 v[132:135], v136 offset:2048
	ds_read_b128 v[136:139], v136 offset:3072
	ds_read_b128 v[160:163], v178
	ds_read_b128 v[164:167], v178 offset:1024
	ds_read_b128 v[168:171], v178 offset:2048
	ds_read_b128 v[178:181], v178 offset:3072
	s_add_u32 s40, s40, 0x80000
	s_addc_u32 s41, s41, 0
	s_mov_b32 m0, s46
	ds_read_b128 v[182:185], v177 offset:32768
	ds_read_b128 v[186:189], v177 offset:33792
	ds_read_b128 v[204:207], v177 offset:34816
	ds_read_b128 v[208:211], v177 offset:35840
	ds_read_b128 v[212:215], v177 offset:36864
	ds_read_b128 v[216:219], v177 offset:37888
	ds_read_b128 v[220:223], v177 offset:38912
	ds_read_b128 v[224:227], v177 offset:39936
	global_load_lds_dwordx4 v152, s[40:41]
	s_mov_b32 m0, s47
	s_nop 0
	global_load_lds_dwordx4 v150, s[40:41]
	s_waitcnt vmcnt(8)
	s_waitcnt lgkmcnt(7)
	s_setprio 1
	s_barrier
	v_mfma_i32_16x16x64_i8 v[144:147], v[116:119], v[182:185], v[144:147]
	s_waitcnt lgkmcnt(6)
	v_mfma_i32_16x16x64_i8 v[144:147], v[124:127], v[186:189], v[144:147]
	s_waitcnt lgkmcnt(4)
	v_mfma_i32_16x16x64_i8 v[112:115], v[124:127], v[208:211], v[112:115]
	v_mfma_i32_16x16x64_i8 v[112:115], v[116:119], v[204:207], v[112:115]
	s_waitcnt lgkmcnt(3)
	v_mfma_i32_16x16x64_i8 v[96:99], v[116:119], v[212:215], v[96:99]
	s_waitcnt lgkmcnt(2)
	v_mfma_i32_16x16x64_i8 v[96:99], v[124:127], v[216:219], v[96:99]
	s_waitcnt lgkmcnt(0)
	v_mfma_i32_16x16x64_i8 v[80:83], v[124:127], v[224:227], v[80:83]
	v_mfma_i32_16x16x64_i8 v[80:83], v[116:119], v[220:223], v[80:83]
	v_mfma_i32_16x16x64_i8 v[76:79], v[132:135], v[220:223], v[76:79]
	v_mfma_i32_16x16x64_i8 v[76:79], v[136:139], v[224:227], v[76:79]
	v_mfma_i32_16x16x64_i8 v[92:95], v[136:139], v[216:219], v[92:95]
	v_mfma_i32_16x16x64_i8 v[92:95], v[132:135], v[212:215], v[92:95]
	v_mfma_i32_16x16x64_i8 v[108:111], v[132:135], v[204:207], v[108:111]
	v_mfma_i32_16x16x64_i8 v[108:111], v[136:139], v[208:211], v[108:111]
	v_mfma_i32_16x16x64_i8 v[140:143], v[136:139], v[186:189], v[140:143]
	v_mfma_i32_16x16x64_i8 v[140:143], v[132:135], v[182:185], v[140:143]
	v_mfma_i32_16x16x64_i8 v[128:131], v[160:163], v[182:185], v[128:131]
	v_mfma_i32_16x16x64_i8 v[128:131], v[164:167], v[186:189], v[128:131]
	v_mfma_i32_16x16x64_i8 v[104:107], v[164:167], v[208:211], v[104:107]
	v_mfma_i32_16x16x64_i8 v[104:107], v[160:163], v[204:207], v[104:107]
	v_mfma_i32_16x16x64_i8 v[88:91], v[160:163], v[212:215], v[88:91]
	v_mfma_i32_16x16x64_i8 v[88:91], v[164:167], v[216:219], v[88:91]
	v_mfma_i32_16x16x64_i8 v[72:75], v[164:167], v[224:227], v[72:75]
	v_mfma_i32_16x16x64_i8 v[72:75], v[160:163], v[220:223], v[72:75]
	v_mfma_i32_16x16x64_i8 v[68:71], v[168:171], v[220:223], v[68:71]
	v_mfma_i32_16x16x64_i8 v[68:71], v[178:181], v[224:227], v[68:71]
	v_mfma_i32_16x16x64_i8 v[84:87], v[178:181], v[216:219], v[84:87]
	v_mfma_i32_16x16x64_i8 v[84:87], v[168:171], v[212:215], v[84:87]
	v_mfma_i32_16x16x64_i8 v[100:103], v[168:171], v[204:207], v[100:103]
	v_mfma_i32_16x16x64_i8 v[100:103], v[178:181], v[208:211], v[100:103]
	v_mfma_i32_16x16x64_i8 v[120:123], v[178:181], v[186:189], v[120:123]
	v_mfma_i32_16x16x64_i8 v[120:123], v[168:171], v[182:185], v[120:123]
	s_barrier
	s_setprio 0
	s_add_i32 s40, s50, s43
	v_lshl_add_u64 v[172:173], v[172:173], 0, s[84:85]
	s_mov_b32 m0, s40
	ds_read_b128 v[182:185], v177 offset:49152
	ds_read_b128 v[186:189], v177 offset:50176
	ds_read_b128 v[204:207], v177 offset:51200
	ds_read_b128 v[208:211], v177 offset:52224
	ds_read_b128 v[212:215], v177 offset:53248
	ds_read_b128 v[216:219], v177 offset:54272
	ds_read_b128 v[220:223], v177 offset:55296
	ds_read_b128 v[224:227], v177 offset:56320
	global_load_lds_dwordx4 v[172:173], off
	s_add_i32 m0, s40, 0x2000
	s_add_u32 s36, s36, 0x80080
	v_lshl_add_u64 v[172:173], v[190:191], 0, s[84:85]
	s_addc_u32 s37, s37, 0
	s_add_i32 s40, s51, s43
	global_load_lds_dwordx4 v[172:173], off
	s_mov_b32 m0, s40
	s_nop 0
	global_load_lds_dwordx4 v2, s[36:37]
	s_add_i32 m0, s40, 0x2000
	s_nop 0
	global_load_lds_dwordx4 v148, s[36:37]
	s_cmp_eq_u32 s76, 28
	s_cbranch_scc0 .Ldefer_208_peel
	v_lshl_add_u64 v[172:173], v[228:229], 0, s[84:85]
	s_mov_b32 m0, s52
	s_nop 0
	global_load_lds_dwordx4 v[172:173], off
	v_lshl_add_u64 v[172:173], v[240:241], 0, s[84:85]
	s_mov_b32 m0, s53
	s_nop 0
	global_load_lds_dwordx4 v[172:173], off
; #define PG8_STAGE(bufoff, gbase, voff) do { _Pragma("unroll") for (int _i = 0; _i < 2; ++_i) \
;         __builtin_amdgcn_global_load_lds((const unsigned*)((const char*)(gbase) + (voff)[_i]), (PG8_LAS unsigned*)(lds + (bufoff) + ldsw + _i * 8192), 16, 0, 0); } while (0)
; #define PG8_LDA(dst, b, h) do { _Pragma("unroll") for (int m = 0; m < 4; ++m) _Pragma("unroll") for (int k = 0; k < 2; ++k) dst[m][k] = *(const PG8_LAS bf16x8*)(lds + PG8_SA(b, h) + aoff + m * 2048 + k * 1024); } while (0)
; #define PG8_LDB(dst, b, h) do { _Pragma("unroll") for (int n = 0; n < 2; ++n) _Pragma("unroll") for (int k = 0; k < 2; ++k) dst[n][k] = *(const PG8_LAS bf16x8*)(lds + PG8_SB(b, h) + boff + n * 2048 + k * 1024); } while (0)
; #define PG8_WAIT_V(n) asm volatile("s_waitcnt vmcnt(" #n ")" ::: "memory")
; #define PG8_WAIT_L(n) asm volatile("s_waitcnt lgkmcnt(" #n ")" ::: "memory")
; #define PG8_BAR __builtin_amdgcn_s_barrier()
; #define PG8_SCHED __builtin_amdgcn_sched_barrier(0)
; template <class Epi, class Sched, bool ALIGN_EPI = false, bool SP2 = false, bool I8 = false>
; __device__ __forceinline__ void gemm_phase(PG8_LAS unsigned char* lds, const Gemm g, const Sched& S, const Epi& E) {
;     ...
;         for (int t = 0; t < nt; t += 2) {
;             const bool last = (t == nt - 2);
;             const char* a1 = cA + (size_t)(t + 1) * kstep;
;             const char* a2 = last ? nA : cA + (size_t)(t + 2) * kstep; const char* b2 = last ? nB : cB + (size_t)(t + 2) * kstep;
;             const char* a3 = a2 + kstep; const char* b3 = b2 + kstep;
;             if (last && has_next) S.a_ready(nxt);
;             if constexpr (SP2) {
;             PG8_LDB(B0, 0, 0); PG8_LDB(B1, 0, 1); PG8_SCHED; PG8_LDA(At, 0, 0); PG8_STAGE(PG8_SA(1, 1), a1 + hstep, voffA);
;             PG8_WAIT_V(8); PG8_WAIT_L(0); PG8_BAR; PG8_MMA(0, 0, At, B0); PG8_MMA(0, 1, At, B1); PG8_BAR; PG8_SCHED;
;     ...
;             PG8_WAIT_V(8); PG8_WAIT_L(0); PG8_BAR; PG8_MMA(0, 0, At, B0); PG8_MMA(0, 1, At, B1); PG8_BAR; PG8_SCHED;
;             PG8_LDA(At, 1, 1); PG8_STAGE(PG8_SB(1, 0), b3, voffB); PG8_STAGE(PG8_SB(1, 1), b3 + hstep, voffB); PG8_STAGE(PG8_SA(1, 0), a3, voffA);
;             PG8_WAIT_V(8); PG8_WAIT_L(0); PG8_BAR; PG8_MMA(1, 0, At, B0); PG8_MMA(1, 1, At, B1); PG8_BAR; PG8_SCHED;
.Ldefer_208_peel:
	s_waitcnt vmcnt(6)
	s_waitcnt lgkmcnt(7)
	s_setprio 1
	s_barrier
	v_mfma_i32_16x16x64_i8 v[64:67], v[116:119], v[182:185], v[64:67]
	s_waitcnt lgkmcnt(6)
	v_mfma_i32_16x16x64_i8 v[64:67], v[124:127], v[186:189], v[64:67]
	s_waitcnt lgkmcnt(4)
	v_mfma_i32_16x16x64_i8 v[48:51], v[124:127], v[208:211], v[48:51]
	v_mfma_i32_16x16x64_i8 v[48:51], v[116:119], v[204:207], v[48:51]
	s_waitcnt lgkmcnt(3)
	v_mfma_i32_16x16x64_i8 v[32:35], v[116:119], v[212:215], v[32:35]
	s_waitcnt lgkmcnt(2)
	v_mfma_i32_16x16x64_i8 v[32:35], v[124:127], v[216:219], v[32:35]
	s_waitcnt lgkmcnt(0)
	v_mfma_i32_16x16x64_i8 v[16:19], v[124:127], v[224:227], v[16:19]
	v_mfma_i32_16x16x64_i8 v[16:19], v[116:119], v[220:223], v[16:19]
	v_mfma_i32_16x16x64_i8 v[12:15], v[132:135], v[220:223], v[12:15]
	v_mfma_i32_16x16x64_i8 v[12:15], v[136:139], v[224:227], v[12:15]
	v_mfma_i32_16x16x64_i8 v[28:31], v[136:139], v[216:219], v[28:31]
	v_mfma_i32_16x16x64_i8 v[28:31], v[132:135], v[212:215], v[28:31]
	v_mfma_i32_16x16x64_i8 v[44:47], v[132:135], v[204:207], v[44:47]
	v_mfma_i32_16x16x64_i8 v[44:47], v[136:139], v[208:211], v[44:47]
	v_mfma_i32_16x16x64_i8 v[60:63], v[136:139], v[186:189], v[60:63]
	v_mfma_i32_16x16x64_i8 v[60:63], v[132:135], v[182:185], v[60:63]
	v_mfma_i32_16x16x64_i8 v[56:59], v[160:163], v[182:185], v[56:59]
	v_mfma_i32_16x16x64_i8 v[56:59], v[164:167], v[186:189], v[56:59]
	v_mfma_i32_16x16x64_i8 v[40:43], v[164:167], v[208:211], v[40:43]
	v_mfma_i32_16x16x64_i8 v[40:43], v[160:163], v[204:207], v[40:43]
	v_mfma_i32_16x16x64_i8 v[24:27], v[160:163], v[212:215], v[24:27]
	v_mfma_i32_16x16x64_i8 v[24:27], v[164:167], v[216:219], v[24:27]
	v_mfma_i32_16x16x64_i8 v[8:11], v[164:167], v[224:227], v[8:11]
	v_mfma_i32_16x16x64_i8 v[8:11], v[160:163], v[220:223], v[8:11]
	v_mfma_i32_16x16x64_i8 v[4:7], v[168:171], v[220:223], v[4:7]
	v_mfma_i32_16x16x64_i8 v[4:7], v[178:181], v[224:227], v[4:7]
	v_mfma_i32_16x16x64_i8 v[20:23], v[178:181], v[216:219], v[20:23]
	v_mfma_i32_16x16x64_i8 v[20:23], v[168:171], v[212:215], v[20:23]
	v_mfma_i32_16x16x64_i8 v[36:39], v[168:171], v[204:207], v[36:39]
	v_mfma_i32_16x16x64_i8 v[36:39], v[178:181], v[208:211], v[36:39]
	v_mfma_i32_16x16x64_i8 v[52:55], v[178:181], v[186:189], v[52:55]
	v_mfma_i32_16x16x64_i8 v[52:55], v[168:171], v[182:185], v[52:55]
	s_barrier
	s_setprio 0
	s_add_i32 s76, s76, 2
	s_add_u32 s26, s26, 0x100
	s_addc_u32 s27, s27, 0
	s_add_u32 s72, s72, 0x100
	s_addc_u32 s73, s73, 0
	s_cmp_gt_u32 s76, 29
	s_cbranch_scc1 .Lkloop_exit_0
.LBB0_208:
	s_add_u32 s36, s26, 0xfff80080
	s_addc_u32 s37, s27, -1
	s_add_i32 s50, 0, 0x10000
	s_cmp_eq_u32 s76, 28
	s_cselect_b32 s41, s19, s37
	s_cselect_b32 s40, s64, s36
	s_cselect_b32 s37, s17, s73
	s_cselect_b32 s36, s65, s72
	s_add_i32 s56, 0, 0x14000
	v_add_u32_e32 v136, s50, v175
	v_add_u32_e32 v172, s56, v175
	ds_read_b128 v[116:119], v136
	ds_read_b128 v[124:127], v136 offset:1024
	ds_read_b128 v[132:135], v136 offset:2048
	ds_read_b128 v[136:139], v136 offset:3072
	ds_read_b128 v[160:163], v172
	ds_read_b128 v[164:167], v172 offset:1024
	ds_read_b128 v[168:171], v172 offset:2048
	ds_read_b128 v[178:181], v172 offset:3072
	v_lshl_add_u64 v[172:173], v[228:229], 0, s[84:85]
	s_mov_b32 m0, s52
	s_nop 0
	global_load_lds_dwordx4 v[172:173], off
	v_lshl_add_u64 v[172:173], v[240:241], 0, s[84:85]
	s_mov_b32 m0, s53
	s_nop 0
	global_load_lds_dwordx4 v[172:173], off
	s_add_i32 m0, s44, 0xc000
	ds_read_b128 v[182:185], v177
	ds_read_b128 v[186:189], v177 offset:1024
	ds_read_b128 v[204:207], v177 offset:2048
	ds_read_b128 v[208:211], v177 offset:3072
	ds_read_b128 v[212:215], v177 offset:4096
	ds_read_b128 v[216:219], v177 offset:5120
	ds_read_b128 v[220:223], v177 offset:6144
	ds_read_b128 v[224:227], v177 offset:7168
	global_load_lds_dwordx4 v156, s[26:27]
	s_add_i32 m0, s44, 0xe000
	s_nop 0
	global_load_lds_dwordx4 v158, s[26:27]
	s_waitcnt vmcnt(8)
	s_waitcnt lgkmcnt(7)
	s_setprio 1
	s_barrier
	v_mfma_i32_16x16x64_i8 v[144:147], v[116:119], v[182:185], v[144:147]
	s_waitcnt lgkmcnt(6)
	v_mfma_i32_16x16x64_i8 v[144:147], v[124:127], v[186:189], v[144:147]
	s_waitcnt lgkmcnt(4)
	v_mfma_i32_16x16x64_i8 v[112:115], v[124:127], v[208:211], v[112:115]
	v_mfma_i32_16x16x64_i8 v[112:115], v[116:119], v[204:207], v[112:115]
	s_waitcnt lgkmcnt(3)
	v_mfma_i32_16x16x64_i8 v[96:99], v[116:119], v[212:215], v[96:99]
	s_waitcnt lgkmcnt(2)
	v_mfma_i32_16x16x64_i8 v[96:99], v[124:127], v[216:219], v[96:99]
	s_waitcnt lgkmcnt(0)
	v_mfma_i32_16x16x64_i8 v[80:83], v[124:127], v[224:227], v[80:83]
	v_mfma_i32_16x16x64_i8 v[80:83], v[116:119], v[220:223], v[80:83]
	v_mfma_i32_16x16x64_i8 v[76:79], v[132:135], v[220:223], v[76:79]
	v_mfma_i32_16x16x64_i8 v[76:79], v[136:139], v[224:227], v[76:79]
	v_mfma_i32_16x16x64_i8 v[92:95], v[136:139], v[216:219], v[92:95]
	v_mfma_i32_16x16x64_i8 v[92:95], v[132:135], v[212:215], v[92:95]
	v_mfma_i32_16x16x64_i8 v[108:111], v[132:135], v[204:207], v[108:111]
	v_mfma_i32_16x16x64_i8 v[108:111], v[136:139], v[208:211], v[108:111]
	v_mfma_i32_16x16x64_i8 v[140:143], v[136:139], v[186:189], v[140:143]
	v_mfma_i32_16x16x64_i8 v[140:143], v[132:135], v[182:185], v[140:143]
	v_mfma_i32_16x16x64_i8 v[128:131], v[160:163], v[182:185], v[128:131]
	v_mfma_i32_16x16x64_i8 v[128:131], v[164:167], v[186:189], v[128:131]
	v_mfma_i32_16x16x64_i8 v[104:107], v[164:167], v[208:211], v[104:107]
	v_mfma_i32_16x16x64_i8 v[104:107], v[160:163], v[204:207], v[104:107]
	v_mfma_i32_16x16x64_i8 v[88:91], v[160:163], v[212:215], v[88:91]
	v_mfma_i32_16x16x64_i8 v[88:91], v[164:167], v[216:219], v[88:91]
	v_mfma_i32_16x16x64_i8 v[72:75], v[164:167], v[224:227], v[72:75]
	v_mfma_i32_16x16x64_i8 v[72:75], v[160:163], v[220:223], v[72:75]
	v_mfma_i32_16x16x64_i8 v[68:71], v[168:171], v[220:223], v[68:71]
	v_mfma_i32_16x16x64_i8 v[68:71], v[178:181], v[224:227], v[68:71]
	v_mfma_i32_16x16x64_i8 v[84:87], v[178:181], v[216:219], v[84:87]
	v_mfma_i32_16x16x64_i8 v[84:87], v[168:171], v[212:215], v[84:87]
	v_mfma_i32_16x16x64_i8 v[100:103], v[168:171], v[204:207], v[100:103]
	v_mfma_i32_16x16x64_i8 v[100:103], v[178:181], v[208:211], v[100:103]
	v_mfma_i32_16x16x64_i8 v[120:123], v[178:181], v[186:189], v[120:123]
	v_mfma_i32_16x16x64_i8 v[120:123], v[168:171], v[182:185], v[120:123]
	s_barrier
; #define PG8_STAGE(bufoff, gbase, voff) do { _Pragma("unroll") for (int _i = 0; _i < 2; ++_i) \
;         __builtin_amdgcn_global_load_lds((const unsigned*)((const char*)(gbase) + (voff)[_i]), (PG8_LAS unsigned*)(lds + (bufoff) + ldsw + _i * 8192), 16, 0, 0); } while (0)
; #define PG8_LDA(dst, b, h) do { _Pragma("unroll") for (int m = 0; m < 4; ++m) _Pragma("unroll") for (int k = 0; k < 2; ++k) dst[m][k] = *(const PG8_LAS bf16x8*)(lds + PG8_SA(b, h) + aoff + m * 2048 + k * 1024); } while (0)
; #define PG8_LDB(dst, b, h) do { _Pragma("unroll") for (int n = 0; n < 2; ++n) _Pragma("unroll") for (int k = 0; k < 2; ++k) dst[n][k] = *(const PG8_LAS bf16x8*)(lds + PG8_SB(b, h) + boff + n * 2048 + k * 1024); } while (0)
; #define PG8_WAIT_V(n) asm volatile("s_waitcnt vmcnt(" #n ")" ::: "memory")
; #define PG8_WAIT_L(n) asm volatile("s_waitcnt lgkmcnt(" #n ")" ::: "memory")
; #define PG8_BAR __builtin_amdgcn_s_barrier()
; #define PG8_SCHED __builtin_amdgcn_sched_barrier(0)
; template <class Epi, class Sched, bool ALIGN_EPI = false, bool SP2 = false, bool I8 = false>
; __device__ __forceinline__ void gemm_phase(PG8_LAS unsigned char* lds, const Gemm g, const Sched& S, const Epi& E) {
;     ...
;             PG8_LDA(At, 0, 1); PG8_STAGE(PG8_SB(0, 0), b2, voffB); PG8_STAGE(PG8_SB(0, 1), b2 + hstep, voffB); PG8_STAGE(PG8_SA(0, 0), a2, voffA);
;             PG8_WAIT_V(8); PG8_WAIT_L(0); PG8_BAR; PG8_MMA(1, 0, At, B0); PG8_MMA(1, 1, At, B1); PG8_BAR; PG8_SCHED;
;             PG8_LDB(B0, 1, 0); PG8_LDB(B1, 1, 1); PG8_SCHED; PG8_LDA(At, 1, 0); PG8_STAGE(PG8_SA(0, 1), a2 + hstep, voffA);
;             PG8_WAIT_V(8); PG8_WAIT_L(0); PG8_BAR; PG8_MMA(0, 0, At, B0); PG8_MMA(0, 1, At, B1); PG8_BAR; PG8_SCHED;
	s_setprio 0
	s_add_i32 s50, s50, s43
	v_lshl_add_u64 v[172:173], s[36:37], 0, v[2:3]
	s_mov_b32 m0, s50
	ds_read_b128 v[182:185], v177 offset:16384
	ds_read_b128 v[186:189], v177 offset:17408
	ds_read_b128 v[204:207], v177 offset:18432
	ds_read_b128 v[208:211], v177 offset:19456
	ds_read_b128 v[212:215], v177 offset:20480
	ds_read_b128 v[216:219], v177 offset:21504
	ds_read_b128 v[220:223], v177 offset:22528
	ds_read_b128 v[224:227], v177 offset:23552
	global_load_lds_dwordx4 v[172:173], off
	s_add_i32 m0, s50, 0x2000
	s_add_u32 s50, s36, 0x80000
	v_lshl_add_u64 v[190:191], s[36:37], 0, v[148:149]
	s_addc_u32 s51, s37, 0
	s_add_i32 s56, s56, s43
	global_load_lds_dwordx4 v[190:191], off
	s_mov_b32 m0, s56
	v_lshl_add_u64 v[240:241], s[40:41], 0, v[150:151]
	global_load_lds_dwordx4 v2, s[50:51]
	s_add_i32 m0, s56, 0x2000
	s_nop 0
	global_load_lds_dwordx4 v148, s[50:51]
	v_lshl_add_u64 v[228:229], s[40:41], 0, v[152:153]
	s_waitcnt vmcnt(6)
	s_waitcnt lgkmcnt(7)
	s_setprio 1
	s_barrier
	v_mfma_i32_16x16x64_i8 v[64:67], v[116:119], v[182:185], v[64:67]
	s_waitcnt lgkmcnt(6)
	v_mfma_i32_16x16x64_i8 v[64:67], v[124:127], v[186:189], v[64:67]
	s_waitcnt lgkmcnt(4)
	v_mfma_i32_16x16x64_i8 v[48:51], v[124:127], v[208:211], v[48:51]
	v_mfma_i32_16x16x64_i8 v[48:51], v[116:119], v[204:207], v[48:51]
	s_waitcnt lgkmcnt(3)
	v_mfma_i32_16x16x64_i8 v[32:35], v[116:119], v[212:215], v[32:35]
	s_waitcnt lgkmcnt(2)
	v_mfma_i32_16x16x64_i8 v[32:35], v[124:127], v[216:219], v[32:35]
	s_waitcnt lgkmcnt(0)
	v_mfma_i32_16x16x64_i8 v[16:19], v[124:127], v[224:227], v[16:19]
	v_mfma_i32_16x16x64_i8 v[16:19], v[116:119], v[220:223], v[16:19]
	v_mfma_i32_16x16x64_i8 v[12:15], v[132:135], v[220:223], v[12:15]
	v_mfma_i32_16x16x64_i8 v[12:15], v[136:139], v[224:227], v[12:15]
	v_mfma_i32_16x16x64_i8 v[28:31], v[136:139], v[216:219], v[28:31]
	v_mfma_i32_16x16x64_i8 v[28:31], v[132:135], v[212:215], v[28:31]
	v_mfma_i32_16x16x64_i8 v[44:47], v[132:135], v[204:207], v[44:47]
	v_mfma_i32_16x16x64_i8 v[44:47], v[136:139], v[208:211], v[44:47]
	v_mfma_i32_16x16x64_i8 v[60:63], v[136:139], v[186:189], v[60:63]
	v_mfma_i32_16x16x64_i8 v[60:63], v[132:135], v[182:185], v[60:63]
	v_mfma_i32_16x16x64_i8 v[56:59], v[160:163], v[182:185], v[56:59]
	v_mfma_i32_16x16x64_i8 v[56:59], v[164:167], v[186:189], v[56:59]
	v_mfma_i32_16x16x64_i8 v[40:43], v[164:167], v[208:211], v[40:43]
	v_mfma_i32_16x16x64_i8 v[40:43], v[160:163], v[204:207], v[40:43]
	v_mfma_i32_16x16x64_i8 v[24:27], v[160:163], v[212:215], v[24:27]
	v_mfma_i32_16x16x64_i8 v[24:27], v[164:167], v[216:219], v[24:27]
	v_mfma_i32_16x16x64_i8 v[8:11], v[164:167], v[224:227], v[8:11]
	v_mfma_i32_16x16x64_i8 v[8:11], v[160:163], v[220:223], v[8:11]
	v_mfma_i32_16x16x64_i8 v[4:7], v[168:171], v[220:223], v[4:7]
	v_mfma_i32_16x16x64_i8 v[4:7], v[178:181], v[224:227], v[4:7]
	v_mfma_i32_16x16x64_i8 v[20:23], v[178:181], v[216:219], v[20:23]
	v_mfma_i32_16x16x64_i8 v[20:23], v[168:171], v[212:215], v[20:23]
	v_mfma_i32_16x16x64_i8 v[36:39], v[168:171], v[204:207], v[36:39]
	v_mfma_i32_16x16x64_i8 v[36:39], v[178:181], v[208:211], v[36:39]
	v_mfma_i32_16x16x64_i8 v[52:55], v[178:181], v[186:189], v[52:55]
	v_mfma_i32_16x16x64_i8 v[52:55], v[168:171], v[182:185], v[52:55]
	s_barrier
	s_setprio 0
	s_mov_b32 m0, s44
	s_nop 0
	global_load_lds_dwordx4 v[228:229], off
	s_mov_b32 m0, s45
	s_nop 0
	global_load_lds_dwordx4 v[240:241], off
	s_add_i32 s50, 0, 0x18000
	s_add_i32 s51, 0, 0x1c000
	v_add_u32_e32 v136, s50, v175
	v_add_u32_e32 v178, s51, v175
	ds_read_b128 v[116:119], v136
	ds_read_b128 v[124:127], v136 offset:1024
	ds_read_b128 v[132:135], v136 offset:2048
	ds_read_b128 v[136:139], v136 offset:3072
	ds_read_b128 v[160:163], v178
	ds_read_b128 v[164:167], v178 offset:1024
	ds_read_b128 v[168:171], v178 offset:2048
	ds_read_b128 v[178:181], v178 offset:3072
	s_add_u32 s40, s40, 0x80000
	s_addc_u32 s41, s41, 0
	s_mov_b32 m0, s46
	ds_read_b128 v[182:185], v177 offset:32768
	ds_read_b128 v[186:189], v177 offset:33792
	ds_read_b128 v[204:207], v177 offset:34816
	ds_read_b128 v[208:211], v177 offset:35840
	ds_read_b128 v[212:215], v177 offset:36864
	ds_read_b128 v[216:219], v177 offset:37888
	ds_read_b128 v[220:223], v177 offset:38912
	ds_read_b128 v[224:227], v177 offset:39936
	global_load_lds_dwordx4 v152, s[40:41]
	s_mov_b32 m0, s47
	s_nop 0
	global_load_lds_dwordx4 v150, s[40:41]
	s_waitcnt vmcnt(8)
	s_waitcnt lgkmcnt(7)
	s_setprio 1
	s_barrier
; #define PG8_STAGE(bufoff, gbase, voff) do { _Pragma("unroll") for (int _i = 0; _i < 2; ++_i) \
;         __builtin_amdgcn_global_load_lds((const unsigned*)((const char*)(gbase) + (voff)[_i]), (PG8_LAS unsigned*)(lds + (bufoff) + ldsw + _i * 8192), 16, 0, 0); } while (0)
; #define PG8_LDA(dst, b, h) do { _Pragma("unroll") for (int m = 0; m < 4; ++m) _Pragma("unroll") for (int k = 0; k < 2; ++k) dst[m][k] = *(const PG8_LAS bf16x8*)(lds + PG8_SA(b, h) + aoff + m * 2048 + k * 1024); } while (0)
; #define PG8_WAIT_V(n) asm volatile("s_waitcnt vmcnt(" #n ")" ::: "memory")
; #define PG8_WAIT_L(n) asm volatile("s_waitcnt lgkmcnt(" #n ")" ::: "memory")
; #define PG8_BAR __builtin_amdgcn_s_barrier()
; #define PG8_SCHED __builtin_amdgcn_sched_barrier(0)
; template <class Epi, class Sched, bool ALIGN_EPI = false, bool SP2 = false, bool I8 = false>
; __device__ __forceinline__ void gemm_phase(PG8_LAS unsigned char* lds, const Gemm g, const Sched& S, const Epi& E) {
;     ...
;             PG8_WAIT_V(8); PG8_WAIT_L(0); PG8_BAR; PG8_MMA(0, 0, At, B0); PG8_MMA(0, 1, At, B1); PG8_BAR; PG8_SCHED;
;             PG8_LDA(At, 1, 1); PG8_STAGE(PG8_SB(1, 0), b3, voffB); PG8_STAGE(PG8_SB(1, 1), b3 + hstep, voffB); PG8_STAGE(PG8_SA(1, 0), a3, voffA);
;             PG8_WAIT_V(8); PG8_WAIT_L(0); PG8_BAR; PG8_MMA(1, 0, At, B0); PG8_MMA(1, 1, At, B1); PG8_BAR; PG8_SCHED;
	v_mfma_i32_16x16x64_i8 v[144:147], v[116:119], v[182:185], v[144:147]
	s_waitcnt lgkmcnt(6)
	v_mfma_i32_16x16x64_i8 v[144:147], v[124:127], v[186:189], v[144:147]
	s_waitcnt lgkmcnt(4)
	v_mfma_i32_16x16x64_i8 v[112:115], v[124:127], v[208:211], v[112:115]
	v_mfma_i32_16x16x64_i8 v[112:115], v[116:119], v[204:207], v[112:115]
	s_waitcnt lgkmcnt(3)
	v_mfma_i32_16x16x64_i8 v[96:99], v[116:119], v[212:215], v[96:99]
	s_waitcnt lgkmcnt(2)
	v_mfma_i32_16x16x64_i8 v[96:99], v[124:127], v[216:219], v[96:99]
	s_waitcnt lgkmcnt(0)
	v_mfma_i32_16x16x64_i8 v[80:83], v[124:127], v[224:227], v[80:83]
	v_mfma_i32_16x16x64_i8 v[80:83], v[116:119], v[220:223], v[80:83]
	v_mfma_i32_16x16x64_i8 v[76:79], v[132:135], v[220:223], v[76:79]
	v_mfma_i32_16x16x64_i8 v[76:79], v[136:139], v[224:227], v[76:79]
	v_mfma_i32_16x16x64_i8 v[92:95], v[136:139], v[216:219], v[92:95]
	v_mfma_i32_16x16x64_i8 v[92:95], v[132:135], v[212:215], v[92:95]
	v_mfma_i32_16x16x64_i8 v[108:111], v[132:135], v[204:207], v[108:111]
	v_mfma_i32_16x16x64_i8 v[108:111], v[136:139], v[208:211], v[108:111]
	v_mfma_i32_16x16x64_i8 v[140:143], v[136:139], v[186:189], v[140:143]
	v_mfma_i32_16x16x64_i8 v[140:143], v[132:135], v[182:185], v[140:143]
	v_mfma_i32_16x16x64_i8 v[128:131], v[160:163], v[182:185], v[128:131]
	v_mfma_i32_16x16x64_i8 v[128:131], v[164:167], v[186:189], v[128:131]
	v_mfma_i32_16x16x64_i8 v[104:107], v[164:167], v[208:211], v[104:107]
	v_mfma_i32_16x16x64_i8 v[104:107], v[160:163], v[204:207], v[104:107]
	v_mfma_i32_16x16x64_i8 v[88:91], v[160:163], v[212:215], v[88:91]
	v_mfma_i32_16x16x64_i8 v[88:91], v[164:167], v[216:219], v[88:91]
	v_mfma_i32_16x16x64_i8 v[72:75], v[164:167], v[224:227], v[72:75]
	v_mfma_i32_16x16x64_i8 v[72:75], v[160:163], v[220:223], v[72:75]
	v_mfma_i32_16x16x64_i8 v[68:71], v[168:171], v[220:223], v[68:71]
	v_mfma_i32_16x16x64_i8 v[68:71], v[178:181], v[224:227], v[68:71]
	v_mfma_i32_16x16x64_i8 v[84:87], v[178:181], v[216:219], v[84:87]
	v_mfma_i32_16x16x64_i8 v[84:87], v[168:171], v[212:215], v[84:87]
	v_mfma_i32_16x16x64_i8 v[100:103], v[168:171], v[204:207], v[100:103]
	v_mfma_i32_16x16x64_i8 v[100:103], v[178:181], v[208:211], v[100:103]
	v_mfma_i32_16x16x64_i8 v[120:123], v[178:181], v[186:189], v[120:123]
	v_mfma_i32_16x16x64_i8 v[120:123], v[168:171], v[182:185], v[120:123]
	s_barrier
	s_setprio 0
	s_add_i32 s40, s50, s43
	v_lshl_add_u64 v[172:173], v[172:173], 0, s[84:85]
	s_mov_b32 m0, s40
	ds_read_b128 v[182:185], v177 offset:49152
	ds_read_b128 v[186:189], v177 offset:50176
	ds_read_b128 v[204:207], v177 offset:51200
	ds_read_b128 v[208:211], v177 offset:52224
	ds_read_b128 v[212:215], v177 offset:53248
	ds_read_b128 v[216:219], v177 offset:54272
	ds_read_b128 v[220:223], v177 offset:55296
	ds_read_b128 v[224:227], v177 offset:56320
	global_load_lds_dwordx4 v[172:173], off
	s_add_i32 m0, s40, 0x2000
	s_add_u32 s36, s36, 0x80080
	v_lshl_add_u64 v[172:173], v[190:191], 0, s[84:85]
	s_addc_u32 s37, s37, 0
	s_add_i32 s40, s51, s43
	global_load_lds_dwordx4 v[172:173], off
	s_mov_b32 m0, s40
	s_nop 0
	global_load_lds_dwordx4 v2, s[36:37]
	s_add_i32 m0, s40, 0x2000
	s_nop 0
	global_load_lds_dwordx4 v148, s[36:37]
	s_cmp_eq_u32 s76, 28
	s_cbranch_scc0 .Ldefer_208_body
	v_lshl_add_u64 v[172:173], v[228:229], 0, s[84:85]
	s_mov_b32 m0, s52
	s_nop 0
	global_load_lds_dwordx4 v[172:173], off
	v_lshl_add_u64 v[172:173], v[240:241], 0, s[84:85]
	s_mov_b32 m0, s53
	s_nop 0
	global_load_lds_dwordx4 v[172:173], off
.Ldefer_208_body:
	s_waitcnt vmcnt(6)
	s_waitcnt lgkmcnt(7)
	s_setprio 1
	s_barrier
	v_mfma_i32_16x16x64_i8 v[64:67], v[116:119], v[182:185], v[64:67]
	s_waitcnt lgkmcnt(6)
	v_mfma_i32_16x16x64_i8 v[64:67], v[124:127], v[186:189], v[64:67]
	s_waitcnt lgkmcnt(4)
	v_mfma_i32_16x16x64_i8 v[48:51], v[124:127], v[208:211], v[48:51]
	v_mfma_i32_16x16x64_i8 v[48:51], v[116:119], v[204:207], v[48:51]
	s_waitcnt lgkmcnt(3)
	v_mfma_i32_16x16x64_i8 v[32:35], v[116:119], v[212:215], v[32:35]
	s_waitcnt lgkmcnt(2)
	v_mfma_i32_16x16x64_i8 v[32:35], v[124:127], v[216:219], v[32:35]
	s_waitcnt lgkmcnt(0)
	v_mfma_i32_16x16x64_i8 v[16:19], v[124:127], v[224:227], v[16:19]
	v_mfma_i32_16x16x64_i8 v[16:19], v[116:119], v[220:223], v[16:19]
	v_mfma_i32_16x16x64_i8 v[12:15], v[132:135], v[220:223], v[12:15]
	v_mfma_i32_16x16x64_i8 v[12:15], v[136:139], v[224:227], v[12:15]
	v_mfma_i32_16x16x64_i8 v[28:31], v[136:139], v[216:219], v[28:31]
	v_mfma_i32_16x16x64_i8 v[28:31], v[132:135], v[212:215], v[28:31]
	v_mfma_i32_16x16x64_i8 v[44:47], v[132:135], v[204:207], v[44:47]
	v_mfma_i32_16x16x64_i8 v[44:47], v[136:139], v[208:211], v[44:47]
	v_mfma_i32_16x16x64_i8 v[60:63], v[136:139], v[186:189], v[60:63]
	v_mfma_i32_16x16x64_i8 v[60:63], v[132:135], v[182:185], v[60:63]
	v_mfma_i32_16x16x64_i8 v[56:59], v[160:163], v[182:185], v[56:59]
	v_mfma_i32_16x16x64_i8 v[56:59], v[164:167], v[186:189], v[56:59]
	v_mfma_i32_16x16x64_i8 v[40:43], v[164:167], v[208:211], v[40:43]
	v_mfma_i32_16x16x64_i8 v[40:43], v[160:163], v[204:207], v[40:43]
	v_mfma_i32_16x16x64_i8 v[24:27], v[160:163], v[212:215], v[24:27]
	v_mfma_i32_16x16x64_i8 v[24:27], v[164:167], v[216:219], v[24:27]
	v_mfma_i32_16x16x64_i8 v[8:11], v[164:167], v[224:227], v[8:11]
	v_mfma_i32_16x16x64_i8 v[8:11], v[160:163], v[220:223], v[8:11]
	v_mfma_i32_16x16x64_i8 v[4:7], v[168:171], v[220:223], v[4:7]
	v_mfma_i32_16x16x64_i8 v[4:7], v[178:181], v[224:227], v[4:7]
	v_mfma_i32_16x16x64_i8 v[20:23], v[178:181], v[216:219], v[20:23]
	v_mfma_i32_16x16x64_i8 v[20:23], v[168:171], v[212:215], v[20:23]
	v_mfma_i32_16x16x64_i8 v[36:39], v[168:171], v[204:207], v[36:39]
	v_mfma_i32_16x16x64_i8 v[36:39], v[178:181], v[208:211], v[36:39]
	v_mfma_i32_16x16x64_i8 v[52:55], v[178:181], v[186:189], v[52:55]
	v_mfma_i32_16x16x64_i8 v[52:55], v[168:171], v[182:185], v[52:55]
	s_barrier
	s_setprio 0
	s_add_i32 s76, s76, 2
	s_add_u32 s26, s26, 0x100
	s_addc_u32 s27, s27, 0
	s_add_u32 s72, s72, 0x100
	s_addc_u32 s73, s73, 0
	s_cmp_gt_u32 s76, 29
	s_cbranch_scc0 .LBB0_208

; #define PG8_STAGE(bufoff, gbase, voff) do { _Pragma("unroll") for (int _i = 0; _i < 2; ++_i) \
;         __builtin_amdgcn_global_load_lds((const unsigned*)((const char*)(gbase) + (voff)[_i]), (PG8_LAS unsigned*)(lds + (bufoff) + ldsw + _i * 8192), 16, 0, 0); } while (0)
; #define PG8_LDA(dst, b, h) do { _Pragma("unroll") for (int m = 0; m < 4; ++m) _Pragma("unroll") for (int k = 0; k < 2; ++k) dst[m][k] = *(const PG8_LAS bf16x8*)(lds + PG8_SA(b, h) + aoff + m * 2048 + k * 1024); } while (0)
; #define PG8_LDB(dst, b, h) do { _Pragma("unroll") for (int n = 0; n < 2; ++n) _Pragma("unroll") for (int k = 0; k < 2; ++k) dst[n][k] = *(const PG8_LAS bf16x8*)(lds + PG8_SB(b, h) + boff + n * 2048 + k * 1024); } while (0)
; #define PG8_WAIT_V(n) asm volatile("s_waitcnt vmcnt(" #n ")" ::: "memory")
; #define PG8_WAIT_L(n) asm volatile("s_waitcnt lgkmcnt(" #n ")" ::: "memory")
; #define PG8_BAR __builtin_amdgcn_s_barrier()
; #define PG8_SCHED __builtin_amdgcn_sched_barrier(0)
; template <class Epi, class Sched, bool ALIGN_EPI = false, bool SP2 = false, bool I8 = false>
; __device__ __forceinline__ void gemm_phase(PG8_LAS unsigned char* lds, const Gemm g, const Sched& S, const Epi& E) {
;     ...
;         const char* nA = has_next ? (const char*)g.A + (size_t)nxt.pm * tstep : cA; const char* nB = has_next ? (const char*)g.Bt + (size_t)nxt.pn * tstep : cB;
;         for (int t = 0; t < nt; t += 2) {
;             const bool last = (t == nt - 2);
;             const char* a1 = cA + (size_t)(t + 1) * kstep;
;             const char* a2 = last ? nA : cA + (size_t)(t + 2) * kstep; const char* b2 = last ? nB : cB + (size_t)(t + 2) * kstep;
;             const char* a3 = a2 + kstep; const char* b3 = b2 + kstep;
;             if (last && has_next) S.a_ready(nxt);
;             if constexpr (SP2) {
;             PG8_LDB(B0, 0, 0); PG8_LDB(B1, 0, 1); PG8_SCHED; PG8_LDA(At, 0, 0); PG8_STAGE(PG8_SA(1, 1), a1 + hstep, voffA);
;             PG8_WAIT_V(8); PG8_WAIT_L(0); PG8_BAR; PG8_MMA(0, 0, At, B0); PG8_MMA(0, 1, At, B1); PG8_BAR; PG8_SCHED;
;             PG8_LDA(At, 0, 1); PG8_STAGE(PG8_SB(0, 0), b2, voffB); PG8_STAGE(PG8_SB(0, 1), b2 + hstep, voffB); PG8_STAGE(PG8_SA(0, 0), a2, voffA);
;             PG8_WAIT_V(8); PG8_WAIT_L(0); PG8_BAR; PG8_MMA(1, 0, At, B0); PG8_MMA(1, 1, At, B1); PG8_BAR; PG8_SCHED;
.LBB0_229:
	s_ashr_i32 s37, s36, 31
	s_lshl_b64 s[34:35], s[36:37], 21
	s_add_u32 s40, s42, s34
	s_addc_u32 s41, s43, s35
	s_and_b64 s[34:35], s[8:9], exec
	s_cselect_b32 s11, s41, s13
	s_cselect_b32 s34, s40, s12
	s_ashr_i32 s27, s26, 31
	s_lshl_b64 s[50:51], s[26:27], 21
	s_add_u32 s54, s44, s50
	s_addc_u32 s55, s45, s51
	s_and_b64 s[50:51], s[8:9], exec
	s_cselect_b32 s27, s55, s73
	s_cselect_b32 s35, s54, s72
	s_add_u32 s12, s12, 0x100080
	s_addc_u32 s13, s13, 0
	s_add_u32 s37, s72, 0x100
	s_addc_u32 s61, s73, 0
	s_mov_b32 s97, -2
	s_add_u32 s50, s12, 0xfff00080
	s_addc_u32 s51, s13, -1
	s_add_i32 s56, 0, 0x10000
	s_cmp_eq_u32 s97, 60
	s_cselect_b32 s77, s11, s51
	s_cselect_b32 s76, s34, s50
	s_cselect_b32 s73, s27, s61
	s_cselect_b32 s72, s35, s37
	s_add_i32 s57, 0, 0x14000
	v_add_u32_e32 v156, s56, v171
	v_add_u32_e32 v168, s57, v171
	s_waitcnt vmcnt(0)
	ds_read_b128 v[112:115], v156
	ds_read_b128 v[120:123], v156 offset:1024
	ds_read_b128 v[152:155], v156 offset:2048
	ds_read_b128 v[156:159], v156 offset:3072
	ds_read_b128 v[160:163], v168
	ds_read_b128 v[164:167], v168 offset:1024
	s_waitcnt lgkmcnt(0)
	ds_read_b128 v[176:179], v168 offset:2048
	ds_read_b128 v[180:183], v168 offset:3072
	s_add_i32 m0, s47, 0xc000
	ds_read_b128 v[184:187], v173
	ds_read_b128 v[188:191], v173 offset:1024
	ds_read_b128 v[204:207], v173 offset:2048
	ds_read_b128 v[208:211], v173 offset:3072
	ds_read_b128 v[212:215], v173 offset:4096
	ds_read_b128 v[216:219], v173 offset:5120
	ds_read_b128 v[220:223], v173 offset:6144
	ds_read_b128 v[224:227], v173 offset:7168
	global_load_lds_dwordx4 v148, s[12:13]
	s_add_i32 m0, s47, 0xe000
	s_nop 0
	global_load_lds_dwordx4 v150, s[12:13]
	s_waitcnt vmcnt(8)
	s_waitcnt lgkmcnt(7)
	s_setprio 1
	s_barrier
	v_mfma_f32_16x16x32_bf16 v[136:139], v[112:115], v[184:187], 0
	s_waitcnt lgkmcnt(6)
	v_mfma_f32_16x16x32_bf16 v[136:139], v[120:123], v[188:191], v[136:139]
	s_waitcnt lgkmcnt(4)
	v_mfma_f32_16x16x32_bf16 v[116:119], v[120:123], v[208:211], 0
	v_mfma_f32_16x16x32_bf16 v[116:119], v[112:115], v[204:207], v[116:119]
	s_waitcnt lgkmcnt(3)
	v_mfma_f32_16x16x32_bf16 v[96:99], v[112:115], v[212:215], 0
	s_waitcnt lgkmcnt(2)
	v_mfma_f32_16x16x32_bf16 v[96:99], v[120:123], v[216:219], v[96:99]
	s_waitcnt lgkmcnt(0)
	v_mfma_f32_16x16x32_bf16 v[80:83], v[120:123], v[224:227], 0
	v_mfma_f32_16x16x32_bf16 v[80:83], v[112:115], v[220:223], v[80:83]
	v_mfma_f32_16x16x32_bf16 v[76:79], v[152:155], v[220:223], 0
	v_mfma_f32_16x16x32_bf16 v[76:79], v[156:159], v[224:227], v[76:79]
	v_mfma_f32_16x16x32_bf16 v[92:95], v[156:159], v[216:219], 0
	v_mfma_f32_16x16x32_bf16 v[92:95], v[152:155], v[212:215], v[92:95]
	v_mfma_f32_16x16x32_bf16 v[108:111], v[152:155], v[204:207], 0
	v_mfma_f32_16x16x32_bf16 v[108:111], v[156:159], v[208:211], v[108:111]
	v_mfma_f32_16x16x32_bf16 v[132:135], v[156:159], v[188:191], 0
	v_mfma_f32_16x16x32_bf16 v[132:135], v[152:155], v[184:187], v[132:135]
	v_mfma_f32_16x16x32_bf16 v[128:131], v[160:163], v[184:187], 0
	v_mfma_f32_16x16x32_bf16 v[128:131], v[164:167], v[188:191], v[128:131]
	v_mfma_f32_16x16x32_bf16 v[104:107], v[164:167], v[208:211], 0
	v_mfma_f32_16x16x32_bf16 v[104:107], v[160:163], v[204:207], v[104:107]
	v_mfma_f32_16x16x32_bf16 v[88:91], v[160:163], v[212:215], 0
	v_mfma_f32_16x16x32_bf16 v[88:91], v[164:167], v[216:219], v[88:91]
	v_mfma_f32_16x16x32_bf16 v[72:75], v[164:167], v[224:227], 0
	v_mfma_f32_16x16x32_bf16 v[72:75], v[160:163], v[220:223], v[72:75]
	v_mfma_f32_16x16x32_bf16 v[68:71], v[176:179], v[220:223], 0
	v_mfma_f32_16x16x32_bf16 v[68:71], v[180:183], v[224:227], v[68:71]
	v_mfma_f32_16x16x32_bf16 v[84:87], v[180:183], v[216:219], 0
	v_mfma_f32_16x16x32_bf16 v[84:87], v[176:179], v[212:215], v[84:87]
	v_mfma_f32_16x16x32_bf16 v[100:103], v[176:179], v[204:207], 0
	v_mfma_f32_16x16x32_bf16 v[100:103], v[180:183], v[208:211], v[100:103]
	v_mfma_f32_16x16x32_bf16 v[124:127], v[180:183], v[188:191], 0
	v_mfma_f32_16x16x32_bf16 v[124:127], v[176:179], v[184:187], v[124:127]
	s_barrier
	s_setprio 0
	s_add_i32 s50, s56, s46
	v_lshl_add_u64 v[168:169], s[72:73], 0, v[2:3]
	s_mov_b32 m0, s50
	ds_read_b128 v[184:187], v173 offset:16384
	ds_read_b128 v[188:191], v173 offset:17408
	ds_read_b128 v[204:207], v173 offset:18432
	ds_read_b128 v[208:211], v173 offset:19456
	ds_read_b128 v[212:215], v173 offset:20480
	ds_read_b128 v[216:219], v173 offset:21504
	ds_read_b128 v[220:223], v173 offset:22528
	ds_read_b128 v[224:227], v173 offset:23552
	global_load_lds_dwordx4 v[168:169], off
	s_add_i32 m0, s50, 0x2000
	s_add_u32 s50, s72, 0x100000
	v_lshl_add_u64 v[228:229], s[72:73], 0, v[144:145]
	s_addc_u32 s51, s73, 0
	s_add_i32 s56, s57, s46
	global_load_lds_dwordx4 v[228:229], off
	s_mov_b32 m0, s56
	v_lshl_add_u64 v[242:243], s[76:77], 0, v[142:143]
	global_load_lds_dwordx4 v2, s[50:51]
	s_add_i32 m0, s56, 0x2000
	s_nop 0
	global_load_lds_dwordx4 v144, s[50:51]
	v_lshl_add_u64 v[240:241], s[76:77], 0, v[140:141]
	s_waitcnt vmcnt(6)
	s_waitcnt lgkmcnt(7)
	s_setprio 1
	s_barrier
; #define PG8_STAGE(bufoff, gbase, voff) do { _Pragma("unroll") for (int _i = 0; _i < 2; ++_i) \
;         __builtin_amdgcn_global_load_lds((const unsigned*)((const char*)(gbase) + (voff)[_i]), (PG8_LAS unsigned*)(lds + (bufoff) + ldsw + _i * 8192), 16, 0, 0); } while (0)
; #define PG8_LDA(dst, b, h) do { _Pragma("unroll") for (int m = 0; m < 4; ++m) _Pragma("unroll") for (int k = 0; k < 2; ++k) dst[m][k] = *(const PG8_LAS bf16x8*)(lds + PG8_SA(b, h) + aoff + m * 2048 + k * 1024); } while (0)
; #define PG8_LDB(dst, b, h) do { _Pragma("unroll") for (int n = 0; n < 2; ++n) _Pragma("unroll") for (int k = 0; k < 2; ++k) dst[n][k] = *(const PG8_LAS bf16x8*)(lds + PG8_SB(b, h) + boff + n * 2048 + k * 1024); } while (0)
; #define PG8_WAIT_V(n) asm volatile("s_waitcnt vmcnt(" #n ")" ::: "memory")
; #define PG8_WAIT_L(n) asm volatile("s_waitcnt lgkmcnt(" #n ")" ::: "memory")
; #define PG8_BAR __builtin_amdgcn_s_barrier()
; #define PG8_SCHED __builtin_amdgcn_sched_barrier(0)
; template <class Epi, class Sched, bool ALIGN_EPI = false, bool SP2 = false, bool I8 = false>
; __device__ __forceinline__ void gemm_phase(PG8_LAS unsigned char* lds, const Gemm g, const Sched& S, const Epi& E) {
;     ...
;             PG8_LDA(At, 0, 1); PG8_STAGE(PG8_SB(0, 0), b2, voffB); PG8_STAGE(PG8_SB(0, 1), b2 + hstep, voffB); PG8_STAGE(PG8_SA(0, 0), a2, voffA);
;             PG8_WAIT_V(8); PG8_WAIT_L(0); PG8_BAR; PG8_MMA(1, 0, At, B0); PG8_MMA(1, 1, At, B1); PG8_BAR; PG8_SCHED;
;             PG8_LDB(B0, 1, 0); PG8_LDB(B1, 1, 1); PG8_SCHED; PG8_LDA(At, 1, 0); PG8_STAGE(PG8_SA(0, 1), a2 + hstep, voffA);
;             PG8_WAIT_V(8); PG8_WAIT_L(0); PG8_BAR; PG8_MMA(0, 0, At, B0); PG8_MMA(0, 1, At, B1); PG8_BAR; PG8_SCHED;
;             PG8_LDA(At, 1, 1); PG8_STAGE(PG8_SB(1, 0), b3, voffB); PG8_STAGE(PG8_SB(1, 1), b3 + hstep, voffB); PG8_STAGE(PG8_SA(1, 0), a3, voffA);
;             PG8_WAIT_V(8); PG8_WAIT_L(0); PG8_BAR; PG8_MMA(1, 0, At, B0); PG8_MMA(1, 1, At, B1); PG8_BAR; PG8_SCHED;
	v_mfma_f32_16x16x32_bf16 v[64:67], v[112:115], v[184:187], 0
	s_waitcnt lgkmcnt(6)
	v_mfma_f32_16x16x32_bf16 v[64:67], v[120:123], v[188:191], v[64:67]
	s_waitcnt lgkmcnt(4)
	v_mfma_f32_16x16x32_bf16 v[48:51], v[120:123], v[208:211], 0
	v_mfma_f32_16x16x32_bf16 v[48:51], v[112:115], v[204:207], v[48:51]
	s_waitcnt lgkmcnt(3)
	v_mfma_f32_16x16x32_bf16 v[32:35], v[112:115], v[212:215], 0
	s_waitcnt lgkmcnt(2)
	v_mfma_f32_16x16x32_bf16 v[32:35], v[120:123], v[216:219], v[32:35]
	s_waitcnt lgkmcnt(0)
	v_mfma_f32_16x16x32_bf16 v[16:19], v[120:123], v[224:227], 0
	v_mfma_f32_16x16x32_bf16 v[16:19], v[112:115], v[220:223], v[16:19]
	v_mfma_f32_16x16x32_bf16 v[12:15], v[152:155], v[220:223], 0
	v_mfma_f32_16x16x32_bf16 v[12:15], v[156:159], v[224:227], v[12:15]
	v_mfma_f32_16x16x32_bf16 v[28:31], v[156:159], v[216:219], 0
	v_mfma_f32_16x16x32_bf16 v[28:31], v[152:155], v[212:215], v[28:31]
	v_mfma_f32_16x16x32_bf16 v[44:47], v[152:155], v[204:207], 0
	v_mfma_f32_16x16x32_bf16 v[44:47], v[156:159], v[208:211], v[44:47]
	v_mfma_f32_16x16x32_bf16 v[60:63], v[156:159], v[188:191], 0
	v_mfma_f32_16x16x32_bf16 v[60:63], v[152:155], v[184:187], v[60:63]
	v_mfma_f32_16x16x32_bf16 v[56:59], v[160:163], v[184:187], 0
	v_mfma_f32_16x16x32_bf16 v[56:59], v[164:167], v[188:191], v[56:59]
	v_mfma_f32_16x16x32_bf16 v[40:43], v[164:167], v[208:211], 0
	v_mfma_f32_16x16x32_bf16 v[40:43], v[160:163], v[204:207], v[40:43]
	v_mfma_f32_16x16x32_bf16 v[24:27], v[160:163], v[212:215], 0
	v_mfma_f32_16x16x32_bf16 v[24:27], v[164:167], v[216:219], v[24:27]
	v_mfma_f32_16x16x32_bf16 v[8:11], v[164:167], v[224:227], 0
	v_mfma_f32_16x16x32_bf16 v[8:11], v[160:163], v[220:223], v[8:11]
	v_mfma_f32_16x16x32_bf16 v[4:7], v[176:179], v[220:223], 0
	v_mfma_f32_16x16x32_bf16 v[4:7], v[180:183], v[224:227], v[4:7]
	v_mfma_f32_16x16x32_bf16 v[20:23], v[180:183], v[216:219], 0
	v_mfma_f32_16x16x32_bf16 v[20:23], v[176:179], v[212:215], v[20:23]
	v_mfma_f32_16x16x32_bf16 v[36:39], v[176:179], v[204:207], 0
	v_mfma_f32_16x16x32_bf16 v[36:39], v[180:183], v[208:211], v[36:39]
	v_mfma_f32_16x16x32_bf16 v[52:55], v[180:183], v[188:191], 0
	v_mfma_f32_16x16x32_bf16 v[52:55], v[176:179], v[184:187], v[52:55]
	s_barrier
	s_setprio 0
	s_mov_b32 m0, s47
	s_nop 0
	global_load_lds_dwordx4 v[240:241], off
	s_mov_b32 m0, s52
	s_nop 0
	global_load_lds_dwordx4 v[242:243], off
	s_add_i32 s56, 0, 0x18000
	s_add_i32 s57, 0, 0x1c000
	v_add_u32_e32 v156, s56, v171
	v_add_u32_e32 v175, s57, v171
	ds_read_b128 v[112:115], v156
	ds_read_b128 v[120:123], v156 offset:1024
	ds_read_b128 v[152:155], v156 offset:2048
	ds_read_b128 v[156:159], v156 offset:3072
	ds_read_b128 v[160:163], v175
	ds_read_b128 v[164:167], v175 offset:1024
	ds_read_b128 v[176:179], v175 offset:2048
	ds_read_b128 v[180:183], v175 offset:3072
	s_add_u32 s50, s76, 0x100000
	s_addc_u32 s51, s77, 0
	s_mov_b32 m0, s53
	ds_read_b128 v[184:187], v173 offset:32768
	ds_read_b128 v[188:191], v173 offset:33792
	ds_read_b128 v[204:207], v173 offset:34816
	ds_read_b128 v[208:211], v173 offset:35840
	ds_read_b128 v[212:215], v173 offset:36864
	ds_read_b128 v[216:219], v173 offset:37888
	ds_read_b128 v[220:223], v173 offset:38912
	ds_read_b128 v[224:227], v173 offset:39936
	global_load_lds_dwordx4 v140, s[50:51]
	s_mov_b32 m0, s64
	s_nop 0
	global_load_lds_dwordx4 v142, s[50:51]
	s_waitcnt vmcnt(8)
	s_waitcnt lgkmcnt(7)
	s_setprio 1
	s_barrier
	v_mfma_f32_16x16x32_bf16 v[136:139], v[112:115], v[184:187], v[136:139]
	s_waitcnt lgkmcnt(6)
	v_mfma_f32_16x16x32_bf16 v[136:139], v[120:123], v[188:191], v[136:139]
	s_waitcnt lgkmcnt(4)
	v_mfma_f32_16x16x32_bf16 v[116:119], v[120:123], v[208:211], v[116:119]
	v_mfma_f32_16x16x32_bf16 v[116:119], v[112:115], v[204:207], v[116:119]
	s_waitcnt lgkmcnt(3)
	v_mfma_f32_16x16x32_bf16 v[96:99], v[112:115], v[212:215], v[96:99]
	s_waitcnt lgkmcnt(2)
	v_mfma_f32_16x16x32_bf16 v[96:99], v[120:123], v[216:219], v[96:99]
	s_waitcnt lgkmcnt(0)
	v_mfma_f32_16x16x32_bf16 v[80:83], v[120:123], v[224:227], v[80:83]
	v_mfma_f32_16x16x32_bf16 v[80:83], v[112:115], v[220:223], v[80:83]
	v_mfma_f32_16x16x32_bf16 v[76:79], v[152:155], v[220:223], v[76:79]
	v_mfma_f32_16x16x32_bf16 v[76:79], v[156:159], v[224:227], v[76:79]
	v_mfma_f32_16x16x32_bf16 v[92:95], v[156:159], v[216:219], v[92:95]
	v_mfma_f32_16x16x32_bf16 v[92:95], v[152:155], v[212:215], v[92:95]
	v_mfma_f32_16x16x32_bf16 v[108:111], v[152:155], v[204:207], v[108:111]
	v_mfma_f32_16x16x32_bf16 v[108:111], v[156:159], v[208:211], v[108:111]
	v_mfma_f32_16x16x32_bf16 v[132:135], v[156:159], v[188:191], v[132:135]
	v_mfma_f32_16x16x32_bf16 v[132:135], v[152:155], v[184:187], v[132:135]
	v_mfma_f32_16x16x32_bf16 v[128:131], v[160:163], v[184:187], v[128:131]
	v_mfma_f32_16x16x32_bf16 v[128:131], v[164:167], v[188:191], v[128:131]
	v_mfma_f32_16x16x32_bf16 v[104:107], v[164:167], v[208:211], v[104:107]
	v_mfma_f32_16x16x32_bf16 v[104:107], v[160:163], v[204:207], v[104:107]
	v_mfma_f32_16x16x32_bf16 v[88:91], v[160:163], v[212:215], v[88:91]
	v_mfma_f32_16x16x32_bf16 v[88:91], v[164:167], v[216:219], v[88:91]
	v_mfma_f32_16x16x32_bf16 v[72:75], v[164:167], v[224:227], v[72:75]
	v_mfma_f32_16x16x32_bf16 v[72:75], v[160:163], v[220:223], v[72:75]
	v_mfma_f32_16x16x32_bf16 v[68:71], v[176:179], v[220:223], v[68:71]
	v_mfma_f32_16x16x32_bf16 v[68:71], v[180:183], v[224:227], v[68:71]
	v_mfma_f32_16x16x32_bf16 v[84:87], v[180:183], v[216:219], v[84:87]
	v_mfma_f32_16x16x32_bf16 v[84:87], v[176:179], v[212:215], v[84:87]
	v_mfma_f32_16x16x32_bf16 v[100:103], v[176:179], v[204:207], v[100:103]
	v_mfma_f32_16x16x32_bf16 v[100:103], v[180:183], v[208:211], v[100:103]
	v_mfma_f32_16x16x32_bf16 v[124:127], v[180:183], v[188:191], v[124:127]
	v_mfma_f32_16x16x32_bf16 v[124:127], v[176:179], v[184:187], v[124:127]
	s_barrier
	s_setprio 0
	s_add_i32 s50, s56, s46
	v_lshl_add_u64 v[168:169], v[168:169], 0, s[84:85]
	s_mov_b32 m0, s50
	ds_read_b128 v[184:187], v173 offset:49152
	ds_read_b128 v[188:191], v173 offset:50176
	ds_read_b128 v[204:207], v173 offset:51200
	ds_read_b128 v[208:211], v173 offset:52224
	ds_read_b128 v[212:215], v173 offset:53248
	ds_read_b128 v[216:219], v173 offset:54272
	ds_read_b128 v[220:223], v173 offset:55296
	ds_read_b128 v[224:227], v173 offset:56320
	global_load_lds_dwordx4 v[168:169], off
	s_add_i32 m0, s50, 0x2000
	s_add_u32 s50, s72, 0x100080
	v_lshl_add_u64 v[168:169], v[228:229], 0, s[84:85]
	s_addc_u32 s51, s73, 0
	s_add_i32 s56, s57, s46
	global_load_lds_dwordx4 v[168:169], off
	s_mov_b32 m0, s56
	s_nop 0
	global_load_lds_dwordx4 v2, s[50:51]
	s_add_i32 m0, s56, 0x2000
	s_nop 0
	global_load_lds_dwordx4 v144, s[50:51]
	s_cmp_eq_u32 s97, 60
	s_cbranch_scc0 .Ldefer_230_peel
	v_lshl_add_u64 v[168:169], v[240:241], 0, s[84:85]
	s_mov_b32 m0, s28
	s_nop 0
	global_load_lds_dwordx4 v[168:169], off
	v_lshl_add_u64 v[168:169], v[242:243], 0, s[84:85]
	s_mov_b32 m0, s65
	s_nop 0
	global_load_lds_dwordx4 v[168:169], off
; #define PG8_STAGE(bufoff, gbase, voff) do { _Pragma("unroll") for (int _i = 0; _i < 2; ++_i) \
;         __builtin_amdgcn_global_load_lds((const unsigned*)((const char*)(gbase) + (voff)[_i]), (PG8_LAS unsigned*)(lds + (bufoff) + ldsw + _i * 8192), 16, 0, 0); } while (0)
; #define PG8_LDA(dst, b, h) do { _Pragma("unroll") for (int m = 0; m < 4; ++m) _Pragma("unroll") for (int k = 0; k < 2; ++k) dst[m][k] = *(const PG8_LAS bf16x8*)(lds + PG8_SA(b, h) + aoff + m * 2048 + k * 1024); } while (0)
; #define PG8_LDB(dst, b, h) do { _Pragma("unroll") for (int n = 0; n < 2; ++n) _Pragma("unroll") for (int k = 0; k < 2; ++k) dst[n][k] = *(const PG8_LAS bf16x8*)(lds + PG8_SB(b, h) + boff + n * 2048 + k * 1024); } while (0)
; #define PG8_WAIT_V(n) asm volatile("s_waitcnt vmcnt(" #n ")" ::: "memory")
; #define PG8_WAIT_L(n) asm volatile("s_waitcnt lgkmcnt(" #n ")" ::: "memory")
; #define PG8_BAR __builtin_amdgcn_s_barrier()
; #define PG8_SCHED __builtin_amdgcn_sched_barrier(0)
; template <class Epi, class Sched, bool ALIGN_EPI = false, bool SP2 = false, bool I8 = false>
; __device__ __forceinline__ void gemm_phase(PG8_LAS unsigned char* lds, const Gemm g, const Sched& S, const Epi& E) {
;     ...
;             PG8_LDB(B0, 0, 0); PG8_LDB(B1, 0, 1); PG8_SCHED; PG8_LDA(At, 0, 0); PG8_STAGE(PG8_SA(1, 1), a1 + hstep, voffA);
;             PG8_WAIT_V(8); PG8_WAIT_L(0); PG8_BAR; PG8_MMA(0, 0, At, B0); PG8_MMA(0, 1, At, B1); PG8_BAR; PG8_SCHED;
;             PG8_LDA(At, 0, 1); PG8_STAGE(PG8_SB(0, 0), b2, voffB); PG8_STAGE(PG8_SB(0, 1), b2 + hstep, voffB); PG8_STAGE(PG8_SA(0, 0), a2, voffA);
;             PG8_WAIT_V(8); PG8_WAIT_L(0); PG8_BAR; PG8_MMA(1, 0, At, B0); PG8_MMA(1, 1, At, B1); PG8_BAR; PG8_SCHED;
;             PG8_LDB(B0, 1, 0); PG8_LDB(B1, 1, 1); PG8_SCHED; PG8_LDA(At, 1, 0); PG8_STAGE(PG8_SA(0, 1), a2 + hstep, voffA);
;             PG8_WAIT_V(8); PG8_WAIT_L(0); PG8_BAR; PG8_MMA(0, 0, At, B0); PG8_MMA(0, 1, At, B1); PG8_BAR; PG8_SCHED;
;             PG8_LDA(At, 1, 1); PG8_STAGE(PG8_SB(1, 0), b3, voffB); PG8_STAGE(PG8_SB(1, 1), b3 + hstep, voffB); PG8_STAGE(PG8_SA(1, 0), a3, voffA);
;             PG8_WAIT_V(8); PG8_WAIT_L(0); PG8_BAR; PG8_MMA(1, 0, At, B0); PG8_MMA(1, 1, At, B1); PG8_BAR; PG8_SCHED;
.Ldefer_230_peel:
	s_waitcnt vmcnt(6)
	s_waitcnt lgkmcnt(7)
	s_setprio 1
	s_barrier
	v_mfma_f32_16x16x32_bf16 v[64:67], v[112:115], v[184:187], v[64:67]
	s_waitcnt lgkmcnt(6)
	v_mfma_f32_16x16x32_bf16 v[64:67], v[120:123], v[188:191], v[64:67]
	s_waitcnt lgkmcnt(4)
	v_mfma_f32_16x16x32_bf16 v[48:51], v[120:123], v[208:211], v[48:51]
	v_mfma_f32_16x16x32_bf16 v[48:51], v[112:115], v[204:207], v[48:51]
	s_waitcnt lgkmcnt(3)
	v_mfma_f32_16x16x32_bf16 v[32:35], v[112:115], v[212:215], v[32:35]
	s_waitcnt lgkmcnt(2)
	v_mfma_f32_16x16x32_bf16 v[32:35], v[120:123], v[216:219], v[32:35]
	s_waitcnt lgkmcnt(0)
	v_mfma_f32_16x16x32_bf16 v[16:19], v[120:123], v[224:227], v[16:19]
	v_mfma_f32_16x16x32_bf16 v[16:19], v[112:115], v[220:223], v[16:19]
	v_mfma_f32_16x16x32_bf16 v[12:15], v[152:155], v[220:223], v[12:15]
	v_mfma_f32_16x16x32_bf16 v[12:15], v[156:159], v[224:227], v[12:15]
	v_mfma_f32_16x16x32_bf16 v[28:31], v[156:159], v[216:219], v[28:31]
	v_mfma_f32_16x16x32_bf16 v[28:31], v[152:155], v[212:215], v[28:31]
	v_mfma_f32_16x16x32_bf16 v[44:47], v[152:155], v[204:207], v[44:47]
	v_mfma_f32_16x16x32_bf16 v[44:47], v[156:159], v[208:211], v[44:47]
	v_mfma_f32_16x16x32_bf16 v[60:63], v[156:159], v[188:191], v[60:63]
	v_mfma_f32_16x16x32_bf16 v[60:63], v[152:155], v[184:187], v[60:63]
	v_mfma_f32_16x16x32_bf16 v[56:59], v[160:163], v[184:187], v[56:59]
	v_mfma_f32_16x16x32_bf16 v[56:59], v[164:167], v[188:191], v[56:59]
	v_mfma_f32_16x16x32_bf16 v[40:43], v[164:167], v[208:211], v[40:43]
	v_mfma_f32_16x16x32_bf16 v[40:43], v[160:163], v[204:207], v[40:43]
	v_mfma_f32_16x16x32_bf16 v[24:27], v[160:163], v[212:215], v[24:27]
	v_mfma_f32_16x16x32_bf16 v[24:27], v[164:167], v[216:219], v[24:27]
	v_mfma_f32_16x16x32_bf16 v[8:11], v[164:167], v[224:227], v[8:11]
	v_mfma_f32_16x16x32_bf16 v[8:11], v[160:163], v[220:223], v[8:11]
	v_mfma_f32_16x16x32_bf16 v[4:7], v[176:179], v[220:223], v[4:7]
	v_mfma_f32_16x16x32_bf16 v[4:7], v[180:183], v[224:227], v[4:7]
	v_mfma_f32_16x16x32_bf16 v[20:23], v[180:183], v[216:219], v[20:23]
	v_mfma_f32_16x16x32_bf16 v[20:23], v[176:179], v[212:215], v[20:23]
	v_mfma_f32_16x16x32_bf16 v[36:39], v[176:179], v[204:207], v[36:39]
	v_mfma_f32_16x16x32_bf16 v[36:39], v[180:183], v[208:211], v[36:39]
	v_mfma_f32_16x16x32_bf16 v[52:55], v[180:183], v[188:191], v[52:55]
	v_mfma_f32_16x16x32_bf16 v[52:55], v[176:179], v[184:187], v[52:55]
	s_barrier
	s_setprio 0
	s_add_i32 s97, s97, 2
	s_add_u32 s12, s12, 0x100
	s_addc_u32 s13, s13, 0
	s_add_u32 s37, s37, 0x100
	s_addc_u32 s61, s61, 0
	s_cmp_gt_u32 s97, 61
	s_cbranch_scc1 .Lkloop_exit_1
.LBB0_230:
	s_add_u32 s50, s12, 0xfff00080
	s_addc_u32 s51, s13, -1
	s_add_i32 s56, 0, 0x10000
	s_cmp_eq_u32 s97, 60
	s_cselect_b32 s77, s11, s51
	s_cselect_b32 s76, s34, s50
	s_cselect_b32 s73, s27, s61
	s_cselect_b32 s72, s35, s37
	s_add_i32 s57, 0, 0x14000
	v_add_u32_e32 v156, s56, v171
	v_add_u32_e32 v168, s57, v171
	ds_read_b128 v[112:115], v156
	ds_read_b128 v[120:123], v156 offset:1024
	ds_read_b128 v[152:155], v156 offset:2048
	ds_read_b128 v[156:159], v156 offset:3072
	ds_read_b128 v[160:163], v168
	ds_read_b128 v[164:167], v168 offset:1024
	ds_read_b128 v[176:179], v168 offset:2048
	ds_read_b128 v[180:183], v168 offset:3072
	v_lshl_add_u64 v[168:169], v[240:241], 0, s[84:85]
	s_mov_b32 m0, s28
	s_nop 0
	global_load_lds_dwordx4 v[168:169], off
	v_lshl_add_u64 v[168:169], v[242:243], 0, s[84:85]
	s_mov_b32 m0, s65
	s_nop 0
	global_load_lds_dwordx4 v[168:169], off
	s_add_i32 m0, s47, 0xc000
	ds_read_b128 v[184:187], v173
	ds_read_b128 v[188:191], v173 offset:1024
	ds_read_b128 v[204:207], v173 offset:2048
	ds_read_b128 v[208:211], v173 offset:3072
	ds_read_b128 v[212:215], v173 offset:4096
	ds_read_b128 v[216:219], v173 offset:5120
	ds_read_b128 v[220:223], v173 offset:6144
	ds_read_b128 v[224:227], v173 offset:7168
	global_load_lds_dwordx4 v148, s[12:13]
	s_add_i32 m0, s47, 0xe000
	s_nop 0
	global_load_lds_dwordx4 v150, s[12:13]
	s_waitcnt vmcnt(8)
	s_waitcnt lgkmcnt(7)
	s_setprio 1
	s_barrier
	v_mfma_f32_16x16x32_bf16 v[136:139], v[112:115], v[184:187], v[136:139]
	s_waitcnt lgkmcnt(6)
	v_mfma_f32_16x16x32_bf16 v[136:139], v[120:123], v[188:191], v[136:139]
	s_waitcnt lgkmcnt(4)
	v_mfma_f32_16x16x32_bf16 v[116:119], v[120:123], v[208:211], v[116:119]
	v_mfma_f32_16x16x32_bf16 v[116:119], v[112:115], v[204:207], v[116:119]
	s_waitcnt lgkmcnt(3)
	v_mfma_f32_16x16x32_bf16 v[96:99], v[112:115], v[212:215], v[96:99]
	s_waitcnt lgkmcnt(2)
	v_mfma_f32_16x16x32_bf16 v[96:99], v[120:123], v[216:219], v[96:99]
	s_waitcnt lgkmcnt(0)
	v_mfma_f32_16x16x32_bf16 v[80:83], v[120:123], v[224:227], v[80:83]
	v_mfma_f32_16x16x32_bf16 v[80:83], v[112:115], v[220:223], v[80:83]
	v_mfma_f32_16x16x32_bf16 v[76:79], v[152:155], v[220:223], v[76:79]
	v_mfma_f32_16x16x32_bf16 v[76:79], v[156:159], v[224:227], v[76:79]
	v_mfma_f32_16x16x32_bf16 v[92:95], v[156:159], v[216:219], v[92:95]
	v_mfma_f32_16x16x32_bf16 v[92:95], v[152:155], v[212:215], v[92:95]
	v_mfma_f32_16x16x32_bf16 v[108:111], v[152:155], v[204:207], v[108:111]
	v_mfma_f32_16x16x32_bf16 v[108:111], v[156:159], v[208:211], v[108:111]
	v_mfma_f32_16x16x32_bf16 v[132:135], v[156:159], v[188:191], v[132:135]
	v_mfma_f32_16x16x32_bf16 v[132:135], v[152:155], v[184:187], v[132:135]
	v_mfma_f32_16x16x32_bf16 v[128:131], v[160:163], v[184:187], v[128:131]
	v_mfma_f32_16x16x32_bf16 v[128:131], v[164:167], v[188:191], v[128:131]
	v_mfma_f32_16x16x32_bf16 v[104:107], v[164:167], v[208:211], v[104:107]
	v_mfma_f32_16x16x32_bf16 v[104:107], v[160:163], v[204:207], v[104:107]
	v_mfma_f32_16x16x32_bf16 v[88:91], v[160:163], v[212:215], v[88:91]
	v_mfma_f32_16x16x32_bf16 v[88:91], v[164:167], v[216:219], v[88:91]
	v_mfma_f32_16x16x32_bf16 v[72:75], v[164:167], v[224:227], v[72:75]
	v_mfma_f32_16x16x32_bf16 v[72:75], v[160:163], v[220:223], v[72:75]
	v_mfma_f32_16x16x32_bf16 v[68:71], v[176:179], v[220:223], v[68:71]
	v_mfma_f32_16x16x32_bf16 v[68:71], v[180:183], v[224:227], v[68:71]
	v_mfma_f32_16x16x32_bf16 v[84:87], v[180:183], v[216:219], v[84:87]
	v_mfma_f32_16x16x32_bf16 v[84:87], v[176:179], v[212:215], v[84:87]
	v_mfma_f32_16x16x32_bf16 v[100:103], v[176:179], v[204:207], v[100:103]
	v_mfma_f32_16x16x32_bf16 v[100:103], v[180:183], v[208:211], v[100:103]
	v_mfma_f32_16x16x32_bf16 v[124:127], v[180:183], v[188:191], v[124:127]
	v_mfma_f32_16x16x32_bf16 v[124:127], v[176:179], v[184:187], v[124:127]
	s_barrier
; #define PG8_STAGE(bufoff, gbase, voff) do { _Pragma("unroll") for (int _i = 0; _i < 2; ++_i) \
;         __builtin_amdgcn_global_load_lds((const unsigned*)((const char*)(gbase) + (voff)[_i]), (PG8_LAS unsigned*)(lds + (bufoff) + ldsw + _i * 8192), 16, 0, 0); } while (0)
; #define PG8_LDA(dst, b, h) do { _Pragma("unroll") for (int m = 0; m < 4; ++m) _Pragma("unroll") for (int k = 0; k < 2; ++k) dst[m][k] = *(const PG8_LAS bf16x8*)(lds + PG8_SA(b, h) + aoff + m * 2048 + k * 1024); } while (0)
; #define PG8_LDB(dst, b, h) do { _Pragma("unroll") for (int n = 0; n < 2; ++n) _Pragma("unroll") for (int k = 0; k < 2; ++k) dst[n][k] = *(const PG8_LAS bf16x8*)(lds + PG8_SB(b, h) + boff + n * 2048 + k * 1024); } while (0)
; #define PG8_WAIT_V(n) asm volatile("s_waitcnt vmcnt(" #n ")" ::: "memory")
; #define PG8_WAIT_L(n) asm volatile("s_waitcnt lgkmcnt(" #n ")" ::: "memory")
; #define PG8_BAR __builtin_amdgcn_s_barrier()
; #define PG8_SCHED __builtin_amdgcn_sched_barrier(0)
; template <class Epi, class Sched, bool ALIGN_EPI = false, bool SP2 = false, bool I8 = false>
; __device__ __forceinline__ void gemm_phase(PG8_LAS unsigned char* lds, const Gemm g, const Sched& S, const Epi& E) {
;     ...
;             PG8_LDA(At, 0, 1); PG8_STAGE(PG8_SB(0, 0), b2, voffB); PG8_STAGE(PG8_SB(0, 1), b2 + hstep, voffB); PG8_STAGE(PG8_SA(0, 0), a2, voffA);
;             PG8_WAIT_V(8); PG8_WAIT_L(0); PG8_BAR; PG8_MMA(1, 0, At, B0); PG8_MMA(1, 1, At, B1); PG8_BAR; PG8_SCHED;
;             PG8_LDB(B0, 1, 0); PG8_LDB(B1, 1, 1); PG8_SCHED; PG8_LDA(At, 1, 0); PG8_STAGE(PG8_SA(0, 1), a2 + hstep, voffA);
;             PG8_WAIT_V(8); PG8_WAIT_L(0); PG8_BAR; PG8_MMA(0, 0, At, B0); PG8_MMA(0, 1, At, B1); PG8_BAR; PG8_SCHED;
;             PG8_LDA(At, 1, 1); PG8_STAGE(PG8_SB(1, 0), b3, voffB); PG8_STAGE(PG8_SB(1, 1), b3 + hstep, voffB); PG8_STAGE(PG8_SA(1, 0), a3, voffA);
	s_setprio 0
	s_add_i32 s50, s56, s46
	v_lshl_add_u64 v[168:169], s[72:73], 0, v[2:3]
	s_mov_b32 m0, s50
	ds_read_b128 v[184:187], v173 offset:16384
	ds_read_b128 v[188:191], v173 offset:17408
	ds_read_b128 v[204:207], v173 offset:18432
	ds_read_b128 v[208:211], v173 offset:19456
	ds_read_b128 v[212:215], v173 offset:20480
	ds_read_b128 v[216:219], v173 offset:21504
	ds_read_b128 v[220:223], v173 offset:22528
	ds_read_b128 v[224:227], v173 offset:23552
	global_load_lds_dwordx4 v[168:169], off
	s_add_i32 m0, s50, 0x2000
	s_add_u32 s50, s72, 0x100000
	v_lshl_add_u64 v[228:229], s[72:73], 0, v[144:145]
	s_addc_u32 s51, s73, 0
	s_add_i32 s56, s57, s46
	global_load_lds_dwordx4 v[228:229], off
	s_mov_b32 m0, s56
	v_lshl_add_u64 v[242:243], s[76:77], 0, v[142:143]
	global_load_lds_dwordx4 v2, s[50:51]
	s_add_i32 m0, s56, 0x2000
	s_nop 0
	global_load_lds_dwordx4 v144, s[50:51]
	v_lshl_add_u64 v[240:241], s[76:77], 0, v[140:141]
	s_waitcnt vmcnt(6)
	s_waitcnt lgkmcnt(7)
	s_setprio 1
	s_barrier
	v_mfma_f32_16x16x32_bf16 v[64:67], v[112:115], v[184:187], v[64:67]
	s_waitcnt lgkmcnt(6)
	v_mfma_f32_16x16x32_bf16 v[64:67], v[120:123], v[188:191], v[64:67]
	s_waitcnt lgkmcnt(4)
	v_mfma_f32_16x16x32_bf16 v[48:51], v[120:123], v[208:211], v[48:51]
	v_mfma_f32_16x16x32_bf16 v[48:51], v[112:115], v[204:207], v[48:51]
	s_waitcnt lgkmcnt(3)
	v_mfma_f32_16x16x32_bf16 v[32:35], v[112:115], v[212:215], v[32:35]
	s_waitcnt lgkmcnt(2)
	v_mfma_f32_16x16x32_bf16 v[32:35], v[120:123], v[216:219], v[32:35]
	s_waitcnt lgkmcnt(0)
	v_mfma_f32_16x16x32_bf16 v[16:19], v[120:123], v[224:227], v[16:19]
	v_mfma_f32_16x16x32_bf16 v[16:19], v[112:115], v[220:223], v[16:19]
	v_mfma_f32_16x16x32_bf16 v[12:15], v[152:155], v[220:223], v[12:15]
	v_mfma_f32_16x16x32_bf16 v[12:15], v[156:159], v[224:227], v[12:15]
	v_mfma_f32_16x16x32_bf16 v[28:31], v[156:159], v[216:219], v[28:31]
	v_mfma_f32_16x16x32_bf16 v[28:31], v[152:155], v[212:215], v[28:31]
	v_mfma_f32_16x16x32_bf16 v[44:47], v[152:155], v[204:207], v[44:47]
	v_mfma_f32_16x16x32_bf16 v[44:47], v[156:159], v[208:211], v[44:47]
	v_mfma_f32_16x16x32_bf16 v[60:63], v[156:159], v[188:191], v[60:63]
	v_mfma_f32_16x16x32_bf16 v[60:63], v[152:155], v[184:187], v[60:63]
	v_mfma_f32_16x16x32_bf16 v[56:59], v[160:163], v[184:187], v[56:59]
	v_mfma_f32_16x16x32_bf16 v[56:59], v[164:167], v[188:191], v[56:59]
	v_mfma_f32_16x16x32_bf16 v[40:43], v[164:167], v[208:211], v[40:43]
	v_mfma_f32_16x16x32_bf16 v[40:43], v[160:163], v[204:207], v[40:43]
	v_mfma_f32_16x16x32_bf16 v[24:27], v[160:163], v[212:215], v[24:27]
	v_mfma_f32_16x16x32_bf16 v[24:27], v[164:167], v[216:219], v[24:27]
	v_mfma_f32_16x16x32_bf16 v[8:11], v[164:167], v[224:227], v[8:11]
	v_mfma_f32_16x16x32_bf16 v[8:11], v[160:163], v[220:223], v[8:11]
	v_mfma_f32_16x16x32_bf16 v[4:7], v[176:179], v[220:223], v[4:7]
	v_mfma_f32_16x16x32_bf16 v[4:7], v[180:183], v[224:227], v[4:7]
	v_mfma_f32_16x16x32_bf16 v[20:23], v[180:183], v[216:219], v[20:23]
	v_mfma_f32_16x16x32_bf16 v[20:23], v[176:179], v[212:215], v[20:23]
	v_mfma_f32_16x16x32_bf16 v[36:39], v[176:179], v[204:207], v[36:39]
	v_mfma_f32_16x16x32_bf16 v[36:39], v[180:183], v[208:211], v[36:39]
	v_mfma_f32_16x16x32_bf16 v[52:55], v[180:183], v[188:191], v[52:55]
	v_mfma_f32_16x16x32_bf16 v[52:55], v[176:179], v[184:187], v[52:55]
	s_barrier
	s_setprio 0
	s_mov_b32 m0, s47
	s_nop 0
	global_load_lds_dwordx4 v[240:241], off
	s_mov_b32 m0, s52
	s_nop 0
	global_load_lds_dwordx4 v[242:243], off
	s_add_i32 s56, 0, 0x18000
	s_add_i32 s57, 0, 0x1c000
	v_add_u32_e32 v156, s56, v171
	v_add_u32_e32 v175, s57, v171
	ds_read_b128 v[112:115], v156
	ds_read_b128 v[120:123], v156 offset:1024
	ds_read_b128 v[152:155], v156 offset:2048
	ds_read_b128 v[156:159], v156 offset:3072
	ds_read_b128 v[160:163], v175
	ds_read_b128 v[164:167], v175 offset:1024
	ds_read_b128 v[176:179], v175 offset:2048
	ds_read_b128 v[180:183], v175 offset:3072
	s_add_u32 s50, s76, 0x100000
	s_addc_u32 s51, s77, 0
	s_mov_b32 m0, s53
	ds_read_b128 v[184:187], v173 offset:32768
	ds_read_b128 v[188:191], v173 offset:33792
	ds_read_b128 v[204:207], v173 offset:34816
	ds_read_b128 v[208:211], v173 offset:35840
	ds_read_b128 v[212:215], v173 offset:36864
	ds_read_b128 v[216:219], v173 offset:37888
	ds_read_b128 v[220:223], v173 offset:38912
	ds_read_b128 v[224:227], v173 offset:39936
	global_load_lds_dwordx4 v140, s[50:51]
	s_mov_b32 m0, s64
	s_nop 0
	global_load_lds_dwordx4 v142, s[50:51]
	s_waitcnt vmcnt(8)
	s_waitcnt lgkmcnt(7)
	s_setprio 1
	s_barrier
; #define PG8_STAGE(bufoff, gbase, voff) do { _Pragma("unroll") for (int _i = 0; _i < 2; ++_i) \
;         __builtin_amdgcn_global_load_lds((const unsigned*)((const char*)(gbase) + (voff)[_i]), (PG8_LAS unsigned*)(lds + (bufoff) + ldsw + _i * 8192), 16, 0, 0); } while (0)
; #define PG8_LDA(dst, b, h) do { _Pragma("unroll") for (int m = 0; m < 4; ++m) _Pragma("unroll") for (int k = 0; k < 2; ++k) dst[m][k] = *(const PG8_LAS bf16x8*)(lds + PG8_SA(b, h) + aoff + m * 2048 + k * 1024); } while (0)
; #define PG8_LDB(dst, b, h) do { _Pragma("unroll") for (int n = 0; n < 2; ++n) _Pragma("unroll") for (int k = 0; k < 2; ++k) dst[n][k] = *(const PG8_LAS bf16x8*)(lds + PG8_SB(b, h) + boff + n * 2048 + k * 1024); } while (0)
; #define PG8_WAIT_V(n) asm volatile("s_waitcnt vmcnt(" #n ")" ::: "memory")
; #define PG8_WAIT_L(n) asm volatile("s_waitcnt lgkmcnt(" #n ")" ::: "memory")
; #define PG8_BAR __builtin_amdgcn_s_barrier()
; #define PG8_SCHED __builtin_amdgcn_sched_barrier(0)
; template <class Epi, class Sched, bool ALIGN_EPI = false, bool SP2 = false, bool I8 = false>
; __device__ __forceinline__ void gemm_phase(PG8_LAS unsigned char* lds, const Gemm g, const Sched& S, const Epi& E) {
;     ...
;             PG8_LDB(B0, 1, 0); PG8_LDB(B1, 1, 1); PG8_SCHED; PG8_LDA(At, 1, 0); PG8_STAGE(PG8_SA(0, 1), a2 + hstep, voffA);
;             PG8_WAIT_V(8); PG8_WAIT_L(0); PG8_BAR; PG8_MMA(0, 0, At, B0); PG8_MMA(0, 1, At, B1); PG8_BAR; PG8_SCHED;
;             PG8_LDA(At, 1, 1); PG8_STAGE(PG8_SB(1, 0), b3, voffB); PG8_STAGE(PG8_SB(1, 1), b3 + hstep, voffB); PG8_STAGE(PG8_SA(1, 0), a3, voffA);
;             PG8_WAIT_V(8); PG8_WAIT_L(0); PG8_BAR; PG8_MMA(1, 0, At, B0); PG8_MMA(1, 1, At, B1); PG8_BAR; PG8_SCHED;
	v_mfma_f32_16x16x32_bf16 v[136:139], v[112:115], v[184:187], v[136:139]
	s_waitcnt lgkmcnt(6)
	v_mfma_f32_16x16x32_bf16 v[136:139], v[120:123], v[188:191], v[136:139]
	s_waitcnt lgkmcnt(4)
	v_mfma_f32_16x16x32_bf16 v[116:119], v[120:123], v[208:211], v[116:119]
	v_mfma_f32_16x16x32_bf16 v[116:119], v[112:115], v[204:207], v[116:119]
	s_waitcnt lgkmcnt(3)
	v_mfma_f32_16x16x32_bf16 v[96:99], v[112:115], v[212:215], v[96:99]
	s_waitcnt lgkmcnt(2)
	v_mfma_f32_16x16x32_bf16 v[96:99], v[120:123], v[216:219], v[96:99]
	s_waitcnt lgkmcnt(0)
	v_mfma_f32_16x16x32_bf16 v[80:83], v[120:123], v[224:227], v[80:83]
	v_mfma_f32_16x16x32_bf16 v[80:83], v[112:115], v[220:223], v[80:83]
	v_mfma_f32_16x16x32_bf16 v[76:79], v[152:155], v[220:223], v[76:79]
	v_mfma_f32_16x16x32_bf16 v[76:79], v[156:159], v[224:227], v[76:79]
	v_mfma_f32_16x16x32_bf16 v[92:95], v[156:159], v[216:219], v[92:95]
	v_mfma_f32_16x16x32_bf16 v[92:95], v[152:155], v[212:215], v[92:95]
	v_mfma_f32_16x16x32_bf16 v[108:111], v[152:155], v[204:207], v[108:111]
	v_mfma_f32_16x16x32_bf16 v[108:111], v[156:159], v[208:211], v[108:111]
	v_mfma_f32_16x16x32_bf16 v[132:135], v[156:159], v[188:191], v[132:135]
	v_mfma_f32_16x16x32_bf16 v[132:135], v[152:155], v[184:187], v[132:135]
	v_mfma_f32_16x16x32_bf16 v[128:131], v[160:163], v[184:187], v[128:131]
	v_mfma_f32_16x16x32_bf16 v[128:131], v[164:167], v[188:191], v[128:131]
	v_mfma_f32_16x16x32_bf16 v[104:107], v[164:167], v[208:211], v[104:107]
	v_mfma_f32_16x16x32_bf16 v[104:107], v[160:163], v[204:207], v[104:107]
	v_mfma_f32_16x16x32_bf16 v[88:91], v[160:163], v[212:215], v[88:91]
	v_mfma_f32_16x16x32_bf16 v[88:91], v[164:167], v[216:219], v[88:91]
	v_mfma_f32_16x16x32_bf16 v[72:75], v[164:167], v[224:227], v[72:75]
	v_mfma_f32_16x16x32_bf16 v[72:75], v[160:163], v[220:223], v[72:75]
	v_mfma_f32_16x16x32_bf16 v[68:71], v[176:179], v[220:223], v[68:71]
	v_mfma_f32_16x16x32_bf16 v[68:71], v[180:183], v[224:227], v[68:71]
	v_mfma_f32_16x16x32_bf16 v[84:87], v[180:183], v[216:219], v[84:87]
	v_mfma_f32_16x16x32_bf16 v[84:87], v[176:179], v[212:215], v[84:87]
	v_mfma_f32_16x16x32_bf16 v[100:103], v[176:179], v[204:207], v[100:103]
	v_mfma_f32_16x16x32_bf16 v[100:103], v[180:183], v[208:211], v[100:103]
	v_mfma_f32_16x16x32_bf16 v[124:127], v[180:183], v[188:191], v[124:127]
	v_mfma_f32_16x16x32_bf16 v[124:127], v[176:179], v[184:187], v[124:127]
	s_barrier
	s_setprio 0
	s_add_i32 s50, s56, s46
	v_lshl_add_u64 v[168:169], v[168:169], 0, s[84:85]
	s_mov_b32 m0, s50
	ds_read_b128 v[184:187], v173 offset:49152
	ds_read_b128 v[188:191], v173 offset:50176
	ds_read_b128 v[204:207], v173 offset:51200
	ds_read_b128 v[208:211], v173 offset:52224
	ds_read_b128 v[212:215], v173 offset:53248
	ds_read_b128 v[216:219], v173 offset:54272
	ds_read_b128 v[220:223], v173 offset:55296
	ds_read_b128 v[224:227], v173 offset:56320
	global_load_lds_dwordx4 v[168:169], off
	s_add_i32 m0, s50, 0x2000
	s_add_u32 s50, s72, 0x100080
	v_lshl_add_u64 v[168:169], v[228:229], 0, s[84:85]
	s_addc_u32 s51, s73, 0
	s_add_i32 s56, s57, s46
	global_load_lds_dwordx4 v[168:169], off
	s_mov_b32 m0, s56
	s_nop 0
	global_load_lds_dwordx4 v2, s[50:51]
	s_add_i32 m0, s56, 0x2000
	s_nop 0
	global_load_lds_dwordx4 v144, s[50:51]
	s_cmp_eq_u32 s97, 60
	s_cbranch_scc0 .Ldefer_230_body
	v_lshl_add_u64 v[168:169], v[240:241], 0, s[84:85]
	s_mov_b32 m0, s28
	s_nop 0
	global_load_lds_dwordx4 v[168:169], off
	v_lshl_add_u64 v[168:169], v[242:243], 0, s[84:85]
	s_mov_b32 m0, s65
	s_nop 0
	global_load_lds_dwordx4 v[168:169], off
.Ldefer_230_body:
	s_waitcnt vmcnt(6)
	s_waitcnt lgkmcnt(7)
	s_setprio 1
	s_barrier
	v_mfma_f32_16x16x32_bf16 v[64:67], v[112:115], v[184:187], v[64:67]
	s_waitcnt lgkmcnt(6)
	v_mfma_f32_16x16x32_bf16 v[64:67], v[120:123], v[188:191], v[64:67]
	s_waitcnt lgkmcnt(4)
	v_mfma_f32_16x16x32_bf16 v[48:51], v[120:123], v[208:211], v[48:51]
	v_mfma_f32_16x16x32_bf16 v[48:51], v[112:115], v[204:207], v[48:51]
	s_waitcnt lgkmcnt(3)
	v_mfma_f32_16x16x32_bf16 v[32:35], v[112:115], v[212:215], v[32:35]
	s_waitcnt lgkmcnt(2)
	v_mfma_f32_16x16x32_bf16 v[32:35], v[120:123], v[216:219], v[32:35]
	s_waitcnt lgkmcnt(0)
	v_mfma_f32_16x16x32_bf16 v[16:19], v[120:123], v[224:227], v[16:19]
	v_mfma_f32_16x16x32_bf16 v[16:19], v[112:115], v[220:223], v[16:19]
	v_mfma_f32_16x16x32_bf16 v[12:15], v[152:155], v[220:223], v[12:15]
	v_mfma_f32_16x16x32_bf16 v[12:15], v[156:159], v[224:227], v[12:15]
	v_mfma_f32_16x16x32_bf16 v[28:31], v[156:159], v[216:219], v[28:31]
	v_mfma_f32_16x16x32_bf16 v[28:31], v[152:155], v[212:215], v[28:31]
	v_mfma_f32_16x16x32_bf16 v[44:47], v[152:155], v[204:207], v[44:47]
	v_mfma_f32_16x16x32_bf16 v[44:47], v[156:159], v[208:211], v[44:47]
	v_mfma_f32_16x16x32_bf16 v[60:63], v[156:159], v[188:191], v[60:63]
	v_mfma_f32_16x16x32_bf16 v[60:63], v[152:155], v[184:187], v[60:63]
	v_mfma_f32_16x16x32_bf16 v[56:59], v[160:163], v[184:187], v[56:59]
	v_mfma_f32_16x16x32_bf16 v[56:59], v[164:167], v[188:191], v[56:59]
	v_mfma_f32_16x16x32_bf16 v[40:43], v[164:167], v[208:211], v[40:43]
	v_mfma_f32_16x16x32_bf16 v[40:43], v[160:163], v[204:207], v[40:43]
	v_mfma_f32_16x16x32_bf16 v[24:27], v[160:163], v[212:215], v[24:27]
	v_mfma_f32_16x16x32_bf16 v[24:27], v[164:167], v[216:219], v[24:27]
	v_mfma_f32_16x16x32_bf16 v[8:11], v[164:167], v[224:227], v[8:11]
	v_mfma_f32_16x16x32_bf16 v[8:11], v[160:163], v[220:223], v[8:11]
	v_mfma_f32_16x16x32_bf16 v[4:7], v[176:179], v[220:223], v[4:7]
	v_mfma_f32_16x16x32_bf16 v[4:7], v[180:183], v[224:227], v[4:7]
	v_mfma_f32_16x16x32_bf16 v[20:23], v[180:183], v[216:219], v[20:23]
	v_mfma_f32_16x16x32_bf16 v[20:23], v[176:179], v[212:215], v[20:23]
	v_mfma_f32_16x16x32_bf16 v[36:39], v[176:179], v[204:207], v[36:39]
	v_mfma_f32_16x16x32_bf16 v[36:39], v[180:183], v[208:211], v[36:39]
	v_mfma_f32_16x16x32_bf16 v[52:55], v[180:183], v[188:191], v[52:55]
	v_mfma_f32_16x16x32_bf16 v[52:55], v[176:179], v[184:187], v[52:55]
	s_barrier
	s_setprio 0
	s_add_i32 s97, s97, 2
	s_add_u32 s12, s12, 0x100
	s_addc_u32 s13, s13, 0
	s_add_u32 s37, s37, 0x100
	s_addc_u32 s61, s61, 0
	s_cmp_gt_u32 s97, 61
	s_cbranch_scc0 .LBB0_230

; #define PG8_STAGE(bufoff, gbase, voff) do { _Pragma("unroll") for (int _i = 0; _i < 2; ++_i) \
;         __builtin_amdgcn_global_load_lds((const unsigned*)((const char*)(gbase) + (voff)[_i]), (PG8_LAS unsigned*)(lds + (bufoff) + ldsw + _i * 8192), 16, 0, 0); } while (0)
; #define PG8_LDA(dst, b, h) do { _Pragma("unroll") for (int m = 0; m < 4; ++m) _Pragma("unroll") for (int k = 0; k < 2; ++k) dst[m][k] = *(const PG8_LAS bf16x8*)(lds + PG8_SA(b, h) + aoff + m * 2048 + k * 1024); } while (0)
; #define PG8_LDB(dst, b, h) do { _Pragma("unroll") for (int n = 0; n < 2; ++n) _Pragma("unroll") for (int k = 0; k < 2; ++k) dst[n][k] = *(const PG8_LAS bf16x8*)(lds + PG8_SB(b, h) + boff + n * 2048 + k * 1024); } while (0)
; #define PG8_WAIT_V(n) asm volatile("s_waitcnt vmcnt(" #n ")" ::: "memory")
; #define PG8_WAIT_L(n) asm volatile("s_waitcnt lgkmcnt(" #n ")" ::: "memory")
; #define PG8_BAR __builtin_amdgcn_s_barrier()
; #define PG8_SCHED __builtin_amdgcn_sched_barrier(0)
; template <class Epi, class Sched, bool ALIGN_EPI = false, bool SP2 = false, bool I8 = false>
; __device__ __forceinline__ void gemm_phase(PG8_LAS unsigned char* lds, const Gemm g, const Sched& S, const Epi& E) {
;     ...
;         const char* nA = has_next ? (const char*)g.A + (size_t)nxt.pm * tstep : cA; const char* nB = has_next ? (const char*)g.Bt + (size_t)nxt.pn * tstep : cB;
;         for (int t = 0; t < nt; t += 2) {
;             const bool last = (t == nt - 2);
;             const char* a1 = cA + (size_t)(t + 1) * kstep;
;             const char* a2 = last ? nA : cA + (size_t)(t + 2) * kstep; const char* b2 = last ? nB : cB + (size_t)(t + 2) * kstep;
;             const char* a3 = a2 + kstep; const char* b3 = b2 + kstep;
;             if (last && has_next) S.a_ready(nxt);
;             if constexpr (SP2) {
;             PG8_LDB(B0, 0, 0); PG8_LDB(B1, 0, 1); PG8_SCHED; PG8_LDA(At, 0, 0); PG8_STAGE(PG8_SA(1, 1), a1 + hstep, voffA);
;             PG8_WAIT_V(8); PG8_WAIT_L(0); PG8_BAR; PG8_MMA(0, 0, At, B0); PG8_MMA(0, 1, At, B1); PG8_BAR; PG8_SCHED;
;             PG8_LDA(At, 0, 1); PG8_STAGE(PG8_SB(0, 0), b2, voffB); PG8_STAGE(PG8_SB(0, 1), b2 + hstep, voffB); PG8_STAGE(PG8_SA(0, 0), a2, voffA);
;             PG8_WAIT_V(8); PG8_WAIT_L(0); PG8_BAR; PG8_MMA(1, 0, At, B0); PG8_MMA(1, 1, At, B1); PG8_BAR; PG8_SCHED;
.LBB0_1455:
	s_ashr_i32 s17, s16, 31
	s_lshl_b64 s[20:21], s[16:17], 21
	s_add_u32 s20, s28, s20
	s_addc_u32 s21, s34, s21
	s_and_b64 s[22:23], s[8:9], exec
	s_cselect_b32 s17, s21, s25
	s_cselect_b32 s51, s20, s24
	s_ashr_i32 s19, s18, 31
	s_lshl_b64 s[22:23], s[18:19], 21
	s_add_u32 s22, s35, s22
	s_addc_u32 s23, s39, s23
	s_and_b64 s[36:37], s[8:9], exec
	s_cselect_b32 s19, s23, s27
	s_cselect_b32 s52, s22, s26
	s_add_u32 s24, s24, 0x100080
	s_addc_u32 s25, s25, 0
	s_add_u32 s53, s26, 0x100
	s_addc_u32 s54, s27, 0
	s_mov_b32 s55, -2
	s_waitcnt vmcnt(0)
	s_add_u32 s26, s24, 0xfff00080
	s_addc_u32 s27, s25, -1
	s_add_i32 s56, 0, 0x10000
	s_cmp_eq_u32 s55, 60
	s_cselect_b32 s37, s17, s27
	s_cselect_b32 s36, s51, s26
	s_cselect_b32 s27, s19, s54
	s_cselect_b32 s26, s52, s53
	s_add_i32 s58, 0, 0x14000
	v_add_u32_e32 v144, s56, v240
	v_add_u32_e32 v160, s58, v240
	ds_read_b128 v[124:127], v144
	ds_read_b128 v[128:131], v144 offset:1024
	ds_read_b128 v[132:135], v144 offset:2048
	ds_read_b128 v[144:147], v144 offset:3072
	ds_read_b128 v[148:151], v160
	ds_read_b128 v[152:155], v160 offset:1024
	ds_read_b128 v[156:159], v160 offset:2048
	ds_read_b128 v[160:163], v160 offset:3072
	s_add_i32 m0, s41, 0xc000
	ds_read_b128 v[164:167], v242
	ds_read_b128 v[168:171], v242 offset:1024
	ds_read_b128 v[172:175], v242 offset:2048
	ds_read_b128 v[176:179], v242 offset:3072
	ds_read_b128 v[180:183], v242 offset:4096
	ds_read_b128 v[184:187], v242 offset:5120
	ds_read_b128 v[188:191], v242 offset:6144
	ds_read_b128 v[214:217], v242 offset:7168
	global_load_lds_dwordx4 v210, s[24:25]
	s_add_i32 m0, s41, 0xe000
	s_nop 0
	global_load_lds_dwordx4 v212, s[24:25]
	s_waitcnt vmcnt(8)
	s_waitcnt lgkmcnt(7)
	s_setprio 1
	s_barrier
	v_mfma_f32_16x16x32_bf16 v[140:143], v[124:127], v[164:167], 0
	s_waitcnt lgkmcnt(6)
	v_mfma_f32_16x16x32_bf16 v[140:143], v[128:131], v[168:171], v[140:143]
	s_waitcnt lgkmcnt(4)
	v_mfma_f32_16x16x32_bf16 v[112:115], v[128:131], v[176:179], 0
	v_mfma_f32_16x16x32_bf16 v[112:115], v[124:127], v[172:175], v[112:115]
	s_waitcnt lgkmcnt(3)
	v_mfma_f32_16x16x32_bf16 v[96:99], v[124:127], v[180:183], 0
	s_waitcnt lgkmcnt(2)
	v_mfma_f32_16x16x32_bf16 v[96:99], v[128:131], v[184:187], v[96:99]
	s_waitcnt lgkmcnt(0)
	v_mfma_f32_16x16x32_bf16 v[80:83], v[128:131], v[214:217], 0
	v_mfma_f32_16x16x32_bf16 v[80:83], v[124:127], v[188:191], v[80:83]
	v_mfma_f32_16x16x32_bf16 v[76:79], v[132:135], v[188:191], 0
	v_mfma_f32_16x16x32_bf16 v[76:79], v[144:147], v[214:217], v[76:79]
	v_mfma_f32_16x16x32_bf16 v[92:95], v[144:147], v[184:187], 0
	v_mfma_f32_16x16x32_bf16 v[92:95], v[132:135], v[180:183], v[92:95]
	v_mfma_f32_16x16x32_bf16 v[108:111], v[132:135], v[172:175], 0
	v_mfma_f32_16x16x32_bf16 v[108:111], v[144:147], v[176:179], v[108:111]
	v_mfma_f32_16x16x32_bf16 v[136:139], v[144:147], v[168:171], 0
	v_mfma_f32_16x16x32_bf16 v[136:139], v[132:135], v[164:167], v[136:139]
	v_mfma_f32_16x16x32_bf16 v[120:123], v[148:151], v[164:167], 0
	v_mfma_f32_16x16x32_bf16 v[120:123], v[152:155], v[168:171], v[120:123]
	v_mfma_f32_16x16x32_bf16 v[104:107], v[152:155], v[176:179], 0
	v_mfma_f32_16x16x32_bf16 v[104:107], v[148:151], v[172:175], v[104:107]
	v_mfma_f32_16x16x32_bf16 v[88:91], v[148:151], v[180:183], 0
	v_mfma_f32_16x16x32_bf16 v[88:91], v[152:155], v[184:187], v[88:91]
	v_mfma_f32_16x16x32_bf16 v[72:75], v[152:155], v[214:217], 0
	v_mfma_f32_16x16x32_bf16 v[72:75], v[148:151], v[188:191], v[72:75]
	v_mfma_f32_16x16x32_bf16 v[68:71], v[156:159], v[188:191], 0
	v_mfma_f32_16x16x32_bf16 v[68:71], v[160:163], v[214:217], v[68:71]
	v_mfma_f32_16x16x32_bf16 v[84:87], v[160:163], v[184:187], 0
	v_mfma_f32_16x16x32_bf16 v[84:87], v[156:159], v[180:183], v[84:87]
	v_mfma_f32_16x16x32_bf16 v[100:103], v[156:159], v[172:175], 0
	v_mfma_f32_16x16x32_bf16 v[100:103], v[160:163], v[176:179], v[100:103]
	v_mfma_f32_16x16x32_bf16 v[116:119], v[160:163], v[168:171], 0
	v_mfma_f32_16x16x32_bf16 v[116:119], v[156:159], v[164:167], v[116:119]
	s_barrier
	s_setprio 0
	s_add_i32 s56, s56, s40
	v_lshl_add_u64 v[218:219], s[26:27], 0, v[2:3]
	s_mov_b32 m0, s56
	ds_read_b128 v[164:167], v242 offset:16384
	ds_read_b128 v[168:171], v242 offset:17408
	ds_read_b128 v[172:175], v242 offset:18432
	ds_read_b128 v[176:179], v242 offset:19456
	ds_read_b128 v[180:183], v242 offset:20480
	ds_read_b128 v[184:187], v242 offset:21504
	ds_read_b128 v[188:191], v242 offset:22528
	ds_read_b128 v[214:217], v242 offset:23552
	global_load_lds_dwordx4 v[218:219], off
	s_add_i32 m0, s56, 0x2000
	s_add_u32 s56, s26, 0x100000
	v_lshl_add_u64 v[220:221], s[26:27], 0, v[204:205]
	s_addc_u32 s57, s27, 0
	s_add_i32 s58, s58, s40
	global_load_lds_dwordx4 v[220:221], off
	s_mov_b32 m0, s58
	v_lshl_add_u64 v[224:225], s[36:37], 0, v[206:207]
	global_load_lds_dwordx4 v2, s[56:57]
	s_add_i32 m0, s58, 0x2000
	s_nop 0
	global_load_lds_dwordx4 v204, s[56:57]
	v_lshl_add_u64 v[222:223], s[36:37], 0, v[208:209]
	s_waitcnt vmcnt(6)
	s_waitcnt lgkmcnt(7)
	s_setprio 1
	s_barrier
; #define PG8_STAGE(bufoff, gbase, voff) do { _Pragma("unroll") for (int _i = 0; _i < 2; ++_i) \
;         __builtin_amdgcn_global_load_lds((const unsigned*)((const char*)(gbase) + (voff)[_i]), (PG8_LAS unsigned*)(lds + (bufoff) + ldsw + _i * 8192), 16, 0, 0); } while (0)
; #define PG8_LDA(dst, b, h) do { _Pragma("unroll") for (int m = 0; m < 4; ++m) _Pragma("unroll") for (int k = 0; k < 2; ++k) dst[m][k] = *(const PG8_LAS bf16x8*)(lds + PG8_SA(b, h) + aoff + m * 2048 + k * 1024); } while (0)
; #define PG8_LDB(dst, b, h) do { _Pragma("unroll") for (int n = 0; n < 2; ++n) _Pragma("unroll") for (int k = 0; k < 2; ++k) dst[n][k] = *(const PG8_LAS bf16x8*)(lds + PG8_SB(b, h) + boff + n * 2048 + k * 1024); } while (0)
; #define PG8_WAIT_V(n) asm volatile("s_waitcnt vmcnt(" #n ")" ::: "memory")
; #define PG8_WAIT_L(n) asm volatile("s_waitcnt lgkmcnt(" #n ")" ::: "memory")
; #define PG8_BAR __builtin_amdgcn_s_barrier()
; #define PG8_SCHED __builtin_amdgcn_sched_barrier(0)
; template <class Epi, class Sched, bool ALIGN_EPI = false, bool SP2 = false, bool I8 = false>
; __device__ __forceinline__ void gemm_phase(PG8_LAS unsigned char* lds, const Gemm g, const Sched& S, const Epi& E) {
;     ...
;             PG8_LDA(At, 0, 1); PG8_STAGE(PG8_SB(0, 0), b2, voffB); PG8_STAGE(PG8_SB(0, 1), b2 + hstep, voffB); PG8_STAGE(PG8_SA(0, 0), a2, voffA);
;             PG8_WAIT_V(8); PG8_WAIT_L(0); PG8_BAR; PG8_MMA(1, 0, At, B0); PG8_MMA(1, 1, At, B1); PG8_BAR; PG8_SCHED;
;             PG8_LDB(B0, 1, 0); PG8_LDB(B1, 1, 1); PG8_SCHED; PG8_LDA(At, 1, 0); PG8_STAGE(PG8_SA(0, 1), a2 + hstep, voffA);
;             PG8_WAIT_V(8); PG8_WAIT_L(0); PG8_BAR; PG8_MMA(0, 0, At, B0); PG8_MMA(0, 1, At, B1); PG8_BAR; PG8_SCHED;
;             PG8_LDA(At, 1, 1); PG8_STAGE(PG8_SB(1, 0), b3, voffB); PG8_STAGE(PG8_SB(1, 1), b3 + hstep, voffB); PG8_STAGE(PG8_SA(1, 0), a3, voffA);
;             PG8_WAIT_V(8); PG8_WAIT_L(0); PG8_BAR; PG8_MMA(1, 0, At, B0); PG8_MMA(1, 1, At, B1); PG8_BAR; PG8_SCHED;
	v_mfma_f32_16x16x32_bf16 v[64:67], v[124:127], v[164:167], 0
	s_waitcnt lgkmcnt(6)
	v_mfma_f32_16x16x32_bf16 v[64:67], v[128:131], v[168:171], v[64:67]
	s_waitcnt lgkmcnt(4)
	v_mfma_f32_16x16x32_bf16 v[48:51], v[128:131], v[176:179], 0
	v_mfma_f32_16x16x32_bf16 v[48:51], v[124:127], v[172:175], v[48:51]
	s_waitcnt lgkmcnt(3)
	v_mfma_f32_16x16x32_bf16 v[32:35], v[124:127], v[180:183], 0
	s_waitcnt lgkmcnt(2)
	v_mfma_f32_16x16x32_bf16 v[32:35], v[128:131], v[184:187], v[32:35]
	s_waitcnt lgkmcnt(0)
	v_mfma_f32_16x16x32_bf16 v[16:19], v[128:131], v[214:217], 0
	v_mfma_f32_16x16x32_bf16 v[16:19], v[124:127], v[188:191], v[16:19]
	v_mfma_f32_16x16x32_bf16 v[12:15], v[132:135], v[188:191], 0
	v_mfma_f32_16x16x32_bf16 v[12:15], v[144:147], v[214:217], v[12:15]
	v_mfma_f32_16x16x32_bf16 v[28:31], v[144:147], v[184:187], 0
	v_mfma_f32_16x16x32_bf16 v[28:31], v[132:135], v[180:183], v[28:31]
	v_mfma_f32_16x16x32_bf16 v[44:47], v[132:135], v[172:175], 0
	v_mfma_f32_16x16x32_bf16 v[44:47], v[144:147], v[176:179], v[44:47]
	v_mfma_f32_16x16x32_bf16 v[60:63], v[144:147], v[168:171], 0
	v_mfma_f32_16x16x32_bf16 v[60:63], v[132:135], v[164:167], v[60:63]
	v_mfma_f32_16x16x32_bf16 v[56:59], v[148:151], v[164:167], 0
	v_mfma_f32_16x16x32_bf16 v[56:59], v[152:155], v[168:171], v[56:59]
	v_mfma_f32_16x16x32_bf16 v[40:43], v[152:155], v[176:179], 0
	v_mfma_f32_16x16x32_bf16 v[40:43], v[148:151], v[172:175], v[40:43]
	v_mfma_f32_16x16x32_bf16 v[24:27], v[148:151], v[180:183], 0
	v_mfma_f32_16x16x32_bf16 v[24:27], v[152:155], v[184:187], v[24:27]
	v_mfma_f32_16x16x32_bf16 v[8:11], v[152:155], v[214:217], 0
	v_mfma_f32_16x16x32_bf16 v[8:11], v[148:151], v[188:191], v[8:11]
	v_mfma_f32_16x16x32_bf16 v[4:7], v[156:159], v[188:191], 0
	v_mfma_f32_16x16x32_bf16 v[4:7], v[160:163], v[214:217], v[4:7]
	v_mfma_f32_16x16x32_bf16 v[20:23], v[160:163], v[184:187], 0
	v_mfma_f32_16x16x32_bf16 v[20:23], v[156:159], v[180:183], v[20:23]
	v_mfma_f32_16x16x32_bf16 v[36:39], v[156:159], v[172:175], 0
	v_mfma_f32_16x16x32_bf16 v[36:39], v[160:163], v[176:179], v[36:39]
	v_mfma_f32_16x16x32_bf16 v[52:55], v[160:163], v[168:171], 0
	v_mfma_f32_16x16x32_bf16 v[52:55], v[156:159], v[164:167], v[52:55]
	s_barrier
	s_setprio 0
	s_mov_b32 m0, s41
	s_nop 0
	global_load_lds_dwordx4 v[222:223], off
	s_mov_b32 m0, s42
	s_nop 0
	global_load_lds_dwordx4 v[224:225], off
	s_add_i32 s56, 0, 0x18000
	s_add_i32 s57, 0, 0x1c000
	v_add_u32_e32 v144, s56, v240
	v_add_u32_e32 v160, s57, v240
	ds_read_b128 v[124:127], v144
	ds_read_b128 v[128:131], v144 offset:1024
	ds_read_b128 v[132:135], v144 offset:2048
	ds_read_b128 v[144:147], v144 offset:3072
	ds_read_b128 v[148:151], v160
	ds_read_b128 v[152:155], v160 offset:1024
	ds_read_b128 v[156:159], v160 offset:2048
	ds_read_b128 v[160:163], v160 offset:3072
	s_add_u32 s36, s36, 0x100000
	s_addc_u32 s37, s37, 0
	s_mov_b32 m0, s43
	ds_read_b128 v[164:167], v242 offset:32768
	ds_read_b128 v[168:171], v242 offset:33792
	ds_read_b128 v[172:175], v242 offset:34816
	ds_read_b128 v[176:179], v242 offset:35840
	ds_read_b128 v[180:183], v242 offset:36864
	ds_read_b128 v[184:187], v242 offset:37888
	ds_read_b128 v[188:191], v242 offset:38912
	ds_read_b128 v[214:217], v242 offset:39936
	global_load_lds_dwordx4 v208, s[36:37]
	s_mov_b32 m0, s44
	s_nop 0
	global_load_lds_dwordx4 v206, s[36:37]
	s_waitcnt vmcnt(8)
	s_waitcnt lgkmcnt(7)
	s_setprio 1
	s_barrier
	v_mfma_f32_16x16x32_bf16 v[140:143], v[124:127], v[164:167], v[140:143]
	s_waitcnt lgkmcnt(6)
	v_mfma_f32_16x16x32_bf16 v[140:143], v[128:131], v[168:171], v[140:143]
	s_waitcnt lgkmcnt(4)
	v_mfma_f32_16x16x32_bf16 v[112:115], v[128:131], v[176:179], v[112:115]
	v_mfma_f32_16x16x32_bf16 v[112:115], v[124:127], v[172:175], v[112:115]
	s_waitcnt lgkmcnt(3)
	v_mfma_f32_16x16x32_bf16 v[96:99], v[124:127], v[180:183], v[96:99]
	s_waitcnt lgkmcnt(2)
	v_mfma_f32_16x16x32_bf16 v[96:99], v[128:131], v[184:187], v[96:99]
	s_waitcnt lgkmcnt(0)
	v_mfma_f32_16x16x32_bf16 v[80:83], v[128:131], v[214:217], v[80:83]
	v_mfma_f32_16x16x32_bf16 v[80:83], v[124:127], v[188:191], v[80:83]
	v_mfma_f32_16x16x32_bf16 v[76:79], v[132:135], v[188:191], v[76:79]
	v_mfma_f32_16x16x32_bf16 v[76:79], v[144:147], v[214:217], v[76:79]
	v_mfma_f32_16x16x32_bf16 v[92:95], v[144:147], v[184:187], v[92:95]
	v_mfma_f32_16x16x32_bf16 v[92:95], v[132:135], v[180:183], v[92:95]
	v_mfma_f32_16x16x32_bf16 v[108:111], v[132:135], v[172:175], v[108:111]
	v_mfma_f32_16x16x32_bf16 v[108:111], v[144:147], v[176:179], v[108:111]
	v_mfma_f32_16x16x32_bf16 v[136:139], v[144:147], v[168:171], v[136:139]
	v_mfma_f32_16x16x32_bf16 v[136:139], v[132:135], v[164:167], v[136:139]
	v_mfma_f32_16x16x32_bf16 v[120:123], v[148:151], v[164:167], v[120:123]
	v_mfma_f32_16x16x32_bf16 v[120:123], v[152:155], v[168:171], v[120:123]
	v_mfma_f32_16x16x32_bf16 v[104:107], v[152:155], v[176:179], v[104:107]
	v_mfma_f32_16x16x32_bf16 v[104:107], v[148:151], v[172:175], v[104:107]
	v_mfma_f32_16x16x32_bf16 v[88:91], v[148:151], v[180:183], v[88:91]
	v_mfma_f32_16x16x32_bf16 v[88:91], v[152:155], v[184:187], v[88:91]
	v_mfma_f32_16x16x32_bf16 v[72:75], v[152:155], v[214:217], v[72:75]
	v_mfma_f32_16x16x32_bf16 v[72:75], v[148:151], v[188:191], v[72:75]
	v_mfma_f32_16x16x32_bf16 v[68:71], v[156:159], v[188:191], v[68:71]
	v_mfma_f32_16x16x32_bf16 v[68:71], v[160:163], v[214:217], v[68:71]
	v_mfma_f32_16x16x32_bf16 v[84:87], v[160:163], v[184:187], v[84:87]
	v_mfma_f32_16x16x32_bf16 v[84:87], v[156:159], v[180:183], v[84:87]
	v_mfma_f32_16x16x32_bf16 v[100:103], v[156:159], v[172:175], v[100:103]
	v_mfma_f32_16x16x32_bf16 v[100:103], v[160:163], v[176:179], v[100:103]
	v_mfma_f32_16x16x32_bf16 v[116:119], v[160:163], v[168:171], v[116:119]
	v_mfma_f32_16x16x32_bf16 v[116:119], v[156:159], v[164:167], v[116:119]
	s_barrier
	s_setprio 0
	s_add_i32 s36, s56, s40
	v_lshl_add_u64 v[218:219], v[218:219], 0, s[84:85]
	s_mov_b32 m0, s36
	ds_read_b128 v[164:167], v242 offset:49152
	ds_read_b128 v[168:171], v242 offset:50176
	ds_read_b128 v[172:175], v242 offset:51200
	ds_read_b128 v[176:179], v242 offset:52224
	ds_read_b128 v[180:183], v242 offset:53248
	ds_read_b128 v[184:187], v242 offset:54272
	ds_read_b128 v[188:191], v242 offset:55296
	ds_read_b128 v[214:217], v242 offset:56320
	global_load_lds_dwordx4 v[218:219], off
	s_add_i32 m0, s36, 0x2000
	s_add_u32 s26, s26, 0x100080
	v_lshl_add_u64 v[218:219], v[220:221], 0, s[84:85]
	s_addc_u32 s27, s27, 0
	s_add_i32 s36, s57, s40
	global_load_lds_dwordx4 v[218:219], off
	s_mov_b32 m0, s36
	s_nop 0
	global_load_lds_dwordx4 v2, s[26:27]
	s_add_i32 m0, s36, 0x2000
	s_nop 0
	global_load_lds_dwordx4 v204, s[26:27]
	s_cmp_eq_u32 s55, 60
	s_cbranch_scc0 .Ldefer_1456_peel
	v_lshl_add_u64 v[218:219], v[222:223], 0, s[84:85]
	s_mov_b32 m0, s45
	s_nop 0
	global_load_lds_dwordx4 v[218:219], off
	v_lshl_add_u64 v[218:219], v[224:225], 0, s[84:85]
	s_mov_b32 m0, s46
	s_nop 0
	global_load_lds_dwordx4 v[218:219], off
; #define PG8_STAGE(bufoff, gbase, voff) do { _Pragma("unroll") for (int _i = 0; _i < 2; ++_i) \
;         __builtin_amdgcn_global_load_lds((const unsigned*)((const char*)(gbase) + (voff)[_i]), (PG8_LAS unsigned*)(lds + (bufoff) + ldsw + _i * 8192), 16, 0, 0); } while (0)
; #define PG8_LDA(dst, b, h) do { _Pragma("unroll") for (int m = 0; m < 4; ++m) _Pragma("unroll") for (int k = 0; k < 2; ++k) dst[m][k] = *(const PG8_LAS bf16x8*)(lds + PG8_SA(b, h) + aoff + m * 2048 + k * 1024); } while (0)
; #define PG8_LDB(dst, b, h) do { _Pragma("unroll") for (int n = 0; n < 2; ++n) _Pragma("unroll") for (int k = 0; k < 2; ++k) dst[n][k] = *(const PG8_LAS bf16x8*)(lds + PG8_SB(b, h) + boff + n * 2048 + k * 1024); } while (0)
; #define PG8_WAIT_V(n) asm volatile("s_waitcnt vmcnt(" #n ")" ::: "memory")
; #define PG8_WAIT_L(n) asm volatile("s_waitcnt lgkmcnt(" #n ")" ::: "memory")
; #define PG8_BAR __builtin_amdgcn_s_barrier()
; #define PG8_SCHED __builtin_amdgcn_sched_barrier(0)
; template <class Epi, class Sched, bool ALIGN_EPI = false, bool SP2 = false, bool I8 = false>
; __device__ __forceinline__ void gemm_phase(PG8_LAS unsigned char* lds, const Gemm g, const Sched& S, const Epi& E) {
;     ...
;             PG8_LDB(B0, 0, 0); PG8_LDB(B1, 0, 1); PG8_SCHED; PG8_LDA(At, 0, 0); PG8_STAGE(PG8_SA(1, 1), a1 + hstep, voffA);
;             PG8_WAIT_V(8); PG8_WAIT_L(0); PG8_BAR; PG8_MMA(0, 0, At, B0); PG8_MMA(0, 1, At, B1); PG8_BAR; PG8_SCHED;
;             PG8_LDA(At, 0, 1); PG8_STAGE(PG8_SB(0, 0), b2, voffB); PG8_STAGE(PG8_SB(0, 1), b2 + hstep, voffB); PG8_STAGE(PG8_SA(0, 0), a2, voffA);
;             PG8_WAIT_V(8); PG8_WAIT_L(0); PG8_BAR; PG8_MMA(1, 0, At, B0); PG8_MMA(1, 1, At, B1); PG8_BAR; PG8_SCHED;
;             PG8_LDB(B0, 1, 0); PG8_LDB(B1, 1, 1); PG8_SCHED; PG8_LDA(At, 1, 0); PG8_STAGE(PG8_SA(0, 1), a2 + hstep, voffA);
;             PG8_WAIT_V(8); PG8_WAIT_L(0); PG8_BAR; PG8_MMA(0, 0, At, B0); PG8_MMA(0, 1, At, B1); PG8_BAR; PG8_SCHED;
;             PG8_LDA(At, 1, 1); PG8_STAGE(PG8_SB(1, 0), b3, voffB); PG8_STAGE(PG8_SB(1, 1), b3 + hstep, voffB); PG8_STAGE(PG8_SA(1, 0), a3, voffA);
;             PG8_WAIT_V(8); PG8_WAIT_L(0); PG8_BAR; PG8_MMA(1, 0, At, B0); PG8_MMA(1, 1, At, B1); PG8_BAR; PG8_SCHED;
.Ldefer_1456_peel:
	s_waitcnt vmcnt(6)
	s_waitcnt lgkmcnt(7)
	s_setprio 1
	s_barrier
	v_mfma_f32_16x16x32_bf16 v[64:67], v[124:127], v[164:167], v[64:67]
	s_waitcnt lgkmcnt(6)
	v_mfma_f32_16x16x32_bf16 v[64:67], v[128:131], v[168:171], v[64:67]
	s_waitcnt lgkmcnt(4)
	v_mfma_f32_16x16x32_bf16 v[48:51], v[128:131], v[176:179], v[48:51]
	v_mfma_f32_16x16x32_bf16 v[48:51], v[124:127], v[172:175], v[48:51]
	s_waitcnt lgkmcnt(3)
	v_mfma_f32_16x16x32_bf16 v[32:35], v[124:127], v[180:183], v[32:35]
	s_waitcnt lgkmcnt(2)
	v_mfma_f32_16x16x32_bf16 v[32:35], v[128:131], v[184:187], v[32:35]
	s_waitcnt lgkmcnt(0)
	v_mfma_f32_16x16x32_bf16 v[16:19], v[128:131], v[214:217], v[16:19]
	v_mfma_f32_16x16x32_bf16 v[16:19], v[124:127], v[188:191], v[16:19]
	v_mfma_f32_16x16x32_bf16 v[12:15], v[132:135], v[188:191], v[12:15]
	v_mfma_f32_16x16x32_bf16 v[12:15], v[144:147], v[214:217], v[12:15]
	v_mfma_f32_16x16x32_bf16 v[28:31], v[144:147], v[184:187], v[28:31]
	v_mfma_f32_16x16x32_bf16 v[28:31], v[132:135], v[180:183], v[28:31]
	v_mfma_f32_16x16x32_bf16 v[44:47], v[132:135], v[172:175], v[44:47]
	v_mfma_f32_16x16x32_bf16 v[44:47], v[144:147], v[176:179], v[44:47]
	v_mfma_f32_16x16x32_bf16 v[60:63], v[144:147], v[168:171], v[60:63]
	v_mfma_f32_16x16x32_bf16 v[60:63], v[132:135], v[164:167], v[60:63]
	v_mfma_f32_16x16x32_bf16 v[56:59], v[148:151], v[164:167], v[56:59]
	v_mfma_f32_16x16x32_bf16 v[56:59], v[152:155], v[168:171], v[56:59]
	v_mfma_f32_16x16x32_bf16 v[40:43], v[152:155], v[176:179], v[40:43]
	v_mfma_f32_16x16x32_bf16 v[40:43], v[148:151], v[172:175], v[40:43]
	v_mfma_f32_16x16x32_bf16 v[24:27], v[148:151], v[180:183], v[24:27]
	v_mfma_f32_16x16x32_bf16 v[24:27], v[152:155], v[184:187], v[24:27]
	v_mfma_f32_16x16x32_bf16 v[8:11], v[152:155], v[214:217], v[8:11]
	v_mfma_f32_16x16x32_bf16 v[8:11], v[148:151], v[188:191], v[8:11]
	v_mfma_f32_16x16x32_bf16 v[4:7], v[156:159], v[188:191], v[4:7]
	v_mfma_f32_16x16x32_bf16 v[4:7], v[160:163], v[214:217], v[4:7]
	v_mfma_f32_16x16x32_bf16 v[20:23], v[160:163], v[184:187], v[20:23]
	v_mfma_f32_16x16x32_bf16 v[20:23], v[156:159], v[180:183], v[20:23]
	v_mfma_f32_16x16x32_bf16 v[36:39], v[156:159], v[172:175], v[36:39]
	v_mfma_f32_16x16x32_bf16 v[36:39], v[160:163], v[176:179], v[36:39]
	v_mfma_f32_16x16x32_bf16 v[52:55], v[160:163], v[168:171], v[52:55]
	v_mfma_f32_16x16x32_bf16 v[52:55], v[156:159], v[164:167], v[52:55]
	s_barrier
	s_setprio 0
	s_add_i32 s55, s55, 2
	s_add_u32 s24, s24, 0x100
	s_addc_u32 s25, s25, 0
	s_add_u32 s53, s53, 0x100
	s_addc_u32 s54, s54, 0
	s_cmp_gt_u32 s55, 61
	s_cbranch_scc1 .Lkloop_exit_2
.LBB0_1456:
	s_add_u32 s26, s24, 0xfff00080
	s_addc_u32 s27, s25, -1
	s_add_i32 s56, 0, 0x10000
	s_cmp_eq_u32 s55, 60
	s_cselect_b32 s37, s17, s27
	s_cselect_b32 s36, s51, s26
	s_cselect_b32 s27, s19, s54
	s_cselect_b32 s26, s52, s53
	s_add_i32 s58, 0, 0x14000
	v_add_u32_e32 v144, s56, v240
	v_add_u32_e32 v160, s58, v240
	ds_read_b128 v[124:127], v144
	ds_read_b128 v[128:131], v144 offset:1024
	ds_read_b128 v[132:135], v144 offset:2048
	ds_read_b128 v[144:147], v144 offset:3072
	ds_read_b128 v[148:151], v160
	ds_read_b128 v[152:155], v160 offset:1024
	ds_read_b128 v[156:159], v160 offset:2048
	ds_read_b128 v[160:163], v160 offset:3072
	v_lshl_add_u64 v[218:219], v[222:223], 0, s[84:85]
	s_mov_b32 m0, s45
	s_nop 0
	global_load_lds_dwordx4 v[218:219], off
	v_lshl_add_u64 v[218:219], v[224:225], 0, s[84:85]
	s_mov_b32 m0, s46
	s_nop 0
	global_load_lds_dwordx4 v[218:219], off
	s_add_i32 m0, s41, 0xc000
	ds_read_b128 v[164:167], v242
	ds_read_b128 v[168:171], v242 offset:1024
	ds_read_b128 v[172:175], v242 offset:2048
	ds_read_b128 v[176:179], v242 offset:3072
	ds_read_b128 v[180:183], v242 offset:4096
	ds_read_b128 v[184:187], v242 offset:5120
	ds_read_b128 v[188:191], v242 offset:6144
	ds_read_b128 v[214:217], v242 offset:7168
	global_load_lds_dwordx4 v210, s[24:25]
	s_add_i32 m0, s41, 0xe000
	s_nop 0
	global_load_lds_dwordx4 v212, s[24:25]
	s_waitcnt vmcnt(8)
	s_waitcnt lgkmcnt(7)
	s_setprio 1
	s_barrier
	v_mfma_f32_16x16x32_bf16 v[140:143], v[124:127], v[164:167], v[140:143]
	s_waitcnt lgkmcnt(6)
	v_mfma_f32_16x16x32_bf16 v[140:143], v[128:131], v[168:171], v[140:143]
	s_waitcnt lgkmcnt(4)
	v_mfma_f32_16x16x32_bf16 v[112:115], v[128:131], v[176:179], v[112:115]
	v_mfma_f32_16x16x32_bf16 v[112:115], v[124:127], v[172:175], v[112:115]
	s_waitcnt lgkmcnt(3)
	v_mfma_f32_16x16x32_bf16 v[96:99], v[124:127], v[180:183], v[96:99]
	s_waitcnt lgkmcnt(2)
	v_mfma_f32_16x16x32_bf16 v[96:99], v[128:131], v[184:187], v[96:99]
	s_waitcnt lgkmcnt(0)
	v_mfma_f32_16x16x32_bf16 v[80:83], v[128:131], v[214:217], v[80:83]
	v_mfma_f32_16x16x32_bf16 v[80:83], v[124:127], v[188:191], v[80:83]
	v_mfma_f32_16x16x32_bf16 v[76:79], v[132:135], v[188:191], v[76:79]
	v_mfma_f32_16x16x32_bf16 v[76:79], v[144:147], v[214:217], v[76:79]
	v_mfma_f32_16x16x32_bf16 v[92:95], v[144:147], v[184:187], v[92:95]
	v_mfma_f32_16x16x32_bf16 v[92:95], v[132:135], v[180:183], v[92:95]
	v_mfma_f32_16x16x32_bf16 v[108:111], v[132:135], v[172:175], v[108:111]
	v_mfma_f32_16x16x32_bf16 v[108:111], v[144:147], v[176:179], v[108:111]
	v_mfma_f32_16x16x32_bf16 v[136:139], v[144:147], v[168:171], v[136:139]
	v_mfma_f32_16x16x32_bf16 v[136:139], v[132:135], v[164:167], v[136:139]
	v_mfma_f32_16x16x32_bf16 v[120:123], v[148:151], v[164:167], v[120:123]
	v_mfma_f32_16x16x32_bf16 v[120:123], v[152:155], v[168:171], v[120:123]
	v_mfma_f32_16x16x32_bf16 v[104:107], v[152:155], v[176:179], v[104:107]
	v_mfma_f32_16x16x32_bf16 v[104:107], v[148:151], v[172:175], v[104:107]
	v_mfma_f32_16x16x32_bf16 v[88:91], v[148:151], v[180:183], v[88:91]
	v_mfma_f32_16x16x32_bf16 v[88:91], v[152:155], v[184:187], v[88:91]
	v_mfma_f32_16x16x32_bf16 v[72:75], v[152:155], v[214:217], v[72:75]
	v_mfma_f32_16x16x32_bf16 v[72:75], v[148:151], v[188:191], v[72:75]
	v_mfma_f32_16x16x32_bf16 v[68:71], v[156:159], v[188:191], v[68:71]
	v_mfma_f32_16x16x32_bf16 v[68:71], v[160:163], v[214:217], v[68:71]
	v_mfma_f32_16x16x32_bf16 v[84:87], v[160:163], v[184:187], v[84:87]
	v_mfma_f32_16x16x32_bf16 v[84:87], v[156:159], v[180:183], v[84:87]
	v_mfma_f32_16x16x32_bf16 v[100:103], v[156:159], v[172:175], v[100:103]
	v_mfma_f32_16x16x32_bf16 v[100:103], v[160:163], v[176:179], v[100:103]
	v_mfma_f32_16x16x32_bf16 v[116:119], v[160:163], v[168:171], v[116:119]
	v_mfma_f32_16x16x32_bf16 v[116:119], v[156:159], v[164:167], v[116:119]
	s_barrier
; #define PG8_STAGE(bufoff, gbase, voff) do { _Pragma("unroll") for (int _i = 0; _i < 2; ++_i) \
;         __builtin_amdgcn_global_load_lds((const unsigned*)((const char*)(gbase) + (voff)[_i]), (PG8_LAS unsigned*)(lds + (bufoff) + ldsw + _i * 8192), 16, 0, 0); } while (0)
; #define PG8_LDA(dst, b, h) do { _Pragma("unroll") for (int m = 0; m < 4; ++m) _Pragma("unroll") for (int k = 0; k < 2; ++k) dst[m][k] = *(const PG8_LAS bf16x8*)(lds + PG8_SA(b, h) + aoff + m * 2048 + k * 1024); } while (0)
; #define PG8_LDB(dst, b, h) do { _Pragma("unroll") for (int n = 0; n < 2; ++n) _Pragma("unroll") for (int k = 0; k < 2; ++k) dst[n][k] = *(const PG8_LAS bf16x8*)(lds + PG8_SB(b, h) + boff + n * 2048 + k * 1024); } while (0)
; #define PG8_WAIT_V(n) asm volatile("s_waitcnt vmcnt(" #n ")" ::: "memory")
; #define PG8_WAIT_L(n) asm volatile("s_waitcnt lgkmcnt(" #n ")" ::: "memory")
; #define PG8_BAR __builtin_amdgcn_s_barrier()
; #define PG8_SCHED __builtin_amdgcn_sched_barrier(0)
; template <class Epi, class Sched, bool ALIGN_EPI = false, bool SP2 = false, bool I8 = false>
; __device__ __forceinline__ void gemm_phase(PG8_LAS unsigned char* lds, const Gemm g, const Sched& S, const Epi& E) {
;     ...
;             PG8_LDA(At, 0, 1); PG8_STAGE(PG8_SB(0, 0), b2, voffB); PG8_STAGE(PG8_SB(0, 1), b2 + hstep, voffB); PG8_STAGE(PG8_SA(0, 0), a2, voffA);
;             PG8_WAIT_V(8); PG8_WAIT_L(0); PG8_BAR; PG8_MMA(1, 0, At, B0); PG8_MMA(1, 1, At, B1); PG8_BAR; PG8_SCHED;
;             PG8_LDB(B0, 1, 0); PG8_LDB(B1, 1, 1); PG8_SCHED; PG8_LDA(At, 1, 0); PG8_STAGE(PG8_SA(0, 1), a2 + hstep, voffA);
;             PG8_WAIT_V(8); PG8_WAIT_L(0); PG8_BAR; PG8_MMA(0, 0, At, B0); PG8_MMA(0, 1, At, B1); PG8_BAR; PG8_SCHED;
;             PG8_LDA(At, 1, 1); PG8_STAGE(PG8_SB(1, 0), b3, voffB); PG8_STAGE(PG8_SB(1, 1), b3 + hstep, voffB); PG8_STAGE(PG8_SA(1, 0), a3, voffA);
	s_setprio 0
	s_add_i32 s56, s56, s40
	v_lshl_add_u64 v[218:219], s[26:27], 0, v[2:3]
	s_mov_b32 m0, s56
	ds_read_b128 v[164:167], v242 offset:16384
	ds_read_b128 v[168:171], v242 offset:17408
	ds_read_b128 v[172:175], v242 offset:18432
	ds_read_b128 v[176:179], v242 offset:19456
	ds_read_b128 v[180:183], v242 offset:20480
	ds_read_b128 v[184:187], v242 offset:21504
	ds_read_b128 v[188:191], v242 offset:22528
	ds_read_b128 v[214:217], v242 offset:23552
	global_load_lds_dwordx4 v[218:219], off
	s_add_i32 m0, s56, 0x2000
	s_add_u32 s56, s26, 0x100000
	v_lshl_add_u64 v[220:221], s[26:27], 0, v[204:205]
	s_addc_u32 s57, s27, 0
	s_add_i32 s58, s58, s40
	global_load_lds_dwordx4 v[220:221], off
	s_mov_b32 m0, s58
	v_lshl_add_u64 v[224:225], s[36:37], 0, v[206:207]
	global_load_lds_dwordx4 v2, s[56:57]
	s_add_i32 m0, s58, 0x2000
	s_nop 0
	global_load_lds_dwordx4 v204, s[56:57]
	v_lshl_add_u64 v[222:223], s[36:37], 0, v[208:209]
	s_waitcnt vmcnt(6)
	s_waitcnt lgkmcnt(7)
	s_setprio 1
	s_barrier
	v_mfma_f32_16x16x32_bf16 v[64:67], v[124:127], v[164:167], v[64:67]
	s_waitcnt lgkmcnt(6)
	v_mfma_f32_16x16x32_bf16 v[64:67], v[128:131], v[168:171], v[64:67]
	s_waitcnt lgkmcnt(4)
	v_mfma_f32_16x16x32_bf16 v[48:51], v[128:131], v[176:179], v[48:51]
	v_mfma_f32_16x16x32_bf16 v[48:51], v[124:127], v[172:175], v[48:51]
	s_waitcnt lgkmcnt(3)
	v_mfma_f32_16x16x32_bf16 v[32:35], v[124:127], v[180:183], v[32:35]
	s_waitcnt lgkmcnt(2)
	v_mfma_f32_16x16x32_bf16 v[32:35], v[128:131], v[184:187], v[32:35]
	s_waitcnt lgkmcnt(0)
	v_mfma_f32_16x16x32_bf16 v[16:19], v[128:131], v[214:217], v[16:19]
	v_mfma_f32_16x16x32_bf16 v[16:19], v[124:127], v[188:191], v[16:19]
	v_mfma_f32_16x16x32_bf16 v[12:15], v[132:135], v[188:191], v[12:15]
	v_mfma_f32_16x16x32_bf16 v[12:15], v[144:147], v[214:217], v[12:15]
	v_mfma_f32_16x16x32_bf16 v[28:31], v[144:147], v[184:187], v[28:31]
	v_mfma_f32_16x16x32_bf16 v[28:31], v[132:135], v[180:183], v[28:31]
	v_mfma_f32_16x16x32_bf16 v[44:47], v[132:135], v[172:175], v[44:47]
	v_mfma_f32_16x16x32_bf16 v[44:47], v[144:147], v[176:179], v[44:47]
	v_mfma_f32_16x16x32_bf16 v[60:63], v[144:147], v[168:171], v[60:63]
	v_mfma_f32_16x16x32_bf16 v[60:63], v[132:135], v[164:167], v[60:63]
	v_mfma_f32_16x16x32_bf16 v[56:59], v[148:151], v[164:167], v[56:59]
	v_mfma_f32_16x16x32_bf16 v[56:59], v[152:155], v[168:171], v[56:59]
	v_mfma_f32_16x16x32_bf16 v[40:43], v[152:155], v[176:179], v[40:43]
	v_mfma_f32_16x16x32_bf16 v[40:43], v[148:151], v[172:175], v[40:43]
	v_mfma_f32_16x16x32_bf16 v[24:27], v[148:151], v[180:183], v[24:27]
	v_mfma_f32_16x16x32_bf16 v[24:27], v[152:155], v[184:187], v[24:27]
	v_mfma_f32_16x16x32_bf16 v[8:11], v[152:155], v[214:217], v[8:11]
	v_mfma_f32_16x16x32_bf16 v[8:11], v[148:151], v[188:191], v[8:11]
	v_mfma_f32_16x16x32_bf16 v[4:7], v[156:159], v[188:191], v[4:7]
	v_mfma_f32_16x16x32_bf16 v[4:7], v[160:163], v[214:217], v[4:7]
	v_mfma_f32_16x16x32_bf16 v[20:23], v[160:163], v[184:187], v[20:23]
	v_mfma_f32_16x16x32_bf16 v[20:23], v[156:159], v[180:183], v[20:23]
	v_mfma_f32_16x16x32_bf16 v[36:39], v[156:159], v[172:175], v[36:39]
	v_mfma_f32_16x16x32_bf16 v[36:39], v[160:163], v[176:179], v[36:39]
	v_mfma_f32_16x16x32_bf16 v[52:55], v[160:163], v[168:171], v[52:55]
	v_mfma_f32_16x16x32_bf16 v[52:55], v[156:159], v[164:167], v[52:55]
	s_barrier
	s_setprio 0
	s_mov_b32 m0, s41
	s_nop 0
	global_load_lds_dwordx4 v[222:223], off
	s_mov_b32 m0, s42
	s_nop 0
	global_load_lds_dwordx4 v[224:225], off
	s_add_i32 s56, 0, 0x18000
	s_add_i32 s57, 0, 0x1c000
	v_add_u32_e32 v144, s56, v240
	v_add_u32_e32 v160, s57, v240
	ds_read_b128 v[124:127], v144
	ds_read_b128 v[128:131], v144 offset:1024
	ds_read_b128 v[132:135], v144 offset:2048
	ds_read_b128 v[144:147], v144 offset:3072
	ds_read_b128 v[148:151], v160
	ds_read_b128 v[152:155], v160 offset:1024
	ds_read_b128 v[156:159], v160 offset:2048
	ds_read_b128 v[160:163], v160 offset:3072
	s_add_u32 s36, s36, 0x100000
	s_addc_u32 s37, s37, 0
	s_mov_b32 m0, s43
	ds_read_b128 v[164:167], v242 offset:32768
	ds_read_b128 v[168:171], v242 offset:33792
	ds_read_b128 v[172:175], v242 offset:34816
	ds_read_b128 v[176:179], v242 offset:35840
	ds_read_b128 v[180:183], v242 offset:36864
	ds_read_b128 v[184:187], v242 offset:37888
	ds_read_b128 v[188:191], v242 offset:38912
	ds_read_b128 v[214:217], v242 offset:39936
	global_load_lds_dwordx4 v208, s[36:37]
	s_mov_b32 m0, s44
	s_nop 0
	global_load_lds_dwordx4 v206, s[36:37]
	s_waitcnt vmcnt(8)
	s_waitcnt lgkmcnt(7)
	s_setprio 1
	s_barrier
; #define PG8_STAGE(bufoff, gbase, voff) do { _Pragma("unroll") for (int _i = 0; _i < 2; ++_i) \
;         __builtin_amdgcn_global_load_lds((const unsigned*)((const char*)(gbase) + (voff)[_i]), (PG8_LAS unsigned*)(lds + (bufoff) + ldsw + _i * 8192), 16, 0, 0); } while (0)
; #define PG8_LDA(dst, b, h) do { _Pragma("unroll") for (int m = 0; m < 4; ++m) _Pragma("unroll") for (int k = 0; k < 2; ++k) dst[m][k] = *(const PG8_LAS bf16x8*)(lds + PG8_SA(b, h) + aoff + m * 2048 + k * 1024); } while (0)
; #define PG8_LDB(dst, b, h) do { _Pragma("unroll") for (int n = 0; n < 2; ++n) _Pragma("unroll") for (int k = 0; k < 2; ++k) dst[n][k] = *(const PG8_LAS bf16x8*)(lds + PG8_SB(b, h) + boff + n * 2048 + k * 1024); } while (0)
; #define PG8_WAIT_V(n) asm volatile("s_waitcnt vmcnt(" #n ")" ::: "memory")
; #define PG8_WAIT_L(n) asm volatile("s_waitcnt lgkmcnt(" #n ")" ::: "memory")
; #define PG8_BAR __builtin_amdgcn_s_barrier()
; #define PG8_SCHED __builtin_amdgcn_sched_barrier(0)
; template <class Epi, class Sched, bool ALIGN_EPI = false, bool SP2 = false, bool I8 = false>
; __device__ __forceinline__ void gemm_phase(PG8_LAS unsigned char* lds, const Gemm g, const Sched& S, const Epi& E) {
;     ...
;             PG8_LDB(B0, 1, 0); PG8_LDB(B1, 1, 1); PG8_SCHED; PG8_LDA(At, 1, 0); PG8_STAGE(PG8_SA(0, 1), a2 + hstep, voffA);
;             PG8_WAIT_V(8); PG8_WAIT_L(0); PG8_BAR; PG8_MMA(0, 0, At, B0); PG8_MMA(0, 1, At, B1); PG8_BAR; PG8_SCHED;
;             PG8_LDA(At, 1, 1); PG8_STAGE(PG8_SB(1, 0), b3, voffB); PG8_STAGE(PG8_SB(1, 1), b3 + hstep, voffB); PG8_STAGE(PG8_SA(1, 0), a3, voffA);
;             PG8_WAIT_V(8); PG8_WAIT_L(0); PG8_BAR; PG8_MMA(1, 0, At, B0); PG8_MMA(1, 1, At, B1); PG8_BAR; PG8_SCHED;
	v_mfma_f32_16x16x32_bf16 v[140:143], v[124:127], v[164:167], v[140:143]
	s_waitcnt lgkmcnt(6)
	v_mfma_f32_16x16x32_bf16 v[140:143], v[128:131], v[168:171], v[140:143]
	s_waitcnt lgkmcnt(4)
	v_mfma_f32_16x16x32_bf16 v[112:115], v[128:131], v[176:179], v[112:115]
	v_mfma_f32_16x16x32_bf16 v[112:115], v[124:127], v[172:175], v[112:115]
	s_waitcnt lgkmcnt(3)
	v_mfma_f32_16x16x32_bf16 v[96:99], v[124:127], v[180:183], v[96:99]
	s_waitcnt lgkmcnt(2)
	v_mfma_f32_16x16x32_bf16 v[96:99], v[128:131], v[184:187], v[96:99]
	s_waitcnt lgkmcnt(0)
	v_mfma_f32_16x16x32_bf16 v[80:83], v[128:131], v[214:217], v[80:83]
	v_mfma_f32_16x16x32_bf16 v[80:83], v[124:127], v[188:191], v[80:83]
	v_mfma_f32_16x16x32_bf16 v[76:79], v[132:135], v[188:191], v[76:79]
	v_mfma_f32_16x16x32_bf16 v[76:79], v[144:147], v[214:217], v[76:79]
	v_mfma_f32_16x16x32_bf16 v[92:95], v[144:147], v[184:187], v[92:95]
	v_mfma_f32_16x16x32_bf16 v[92:95], v[132:135], v[180:183], v[92:95]
	v_mfma_f32_16x16x32_bf16 v[108:111], v[132:135], v[172:175], v[108:111]
	v_mfma_f32_16x16x32_bf16 v[108:111], v[144:147], v[176:179], v[108:111]
	v_mfma_f32_16x16x32_bf16 v[136:139], v[144:147], v[168:171], v[136:139]
	v_mfma_f32_16x16x32_bf16 v[136:139], v[132:135], v[164:167], v[136:139]
	v_mfma_f32_16x16x32_bf16 v[120:123], v[148:151], v[164:167], v[120:123]
	v_mfma_f32_16x16x32_bf16 v[120:123], v[152:155], v[168:171], v[120:123]
	v_mfma_f32_16x16x32_bf16 v[104:107], v[152:155], v[176:179], v[104:107]
	v_mfma_f32_16x16x32_bf16 v[104:107], v[148:151], v[172:175], v[104:107]
	v_mfma_f32_16x16x32_bf16 v[88:91], v[148:151], v[180:183], v[88:91]
	v_mfma_f32_16x16x32_bf16 v[88:91], v[152:155], v[184:187], v[88:91]
	v_mfma_f32_16x16x32_bf16 v[72:75], v[152:155], v[214:217], v[72:75]
	v_mfma_f32_16x16x32_bf16 v[72:75], v[148:151], v[188:191], v[72:75]
	v_mfma_f32_16x16x32_bf16 v[68:71], v[156:159], v[188:191], v[68:71]
	v_mfma_f32_16x16x32_bf16 v[68:71], v[160:163], v[214:217], v[68:71]
	v_mfma_f32_16x16x32_bf16 v[84:87], v[160:163], v[184:187], v[84:87]
	v_mfma_f32_16x16x32_bf16 v[84:87], v[156:159], v[180:183], v[84:87]
	v_mfma_f32_16x16x32_bf16 v[100:103], v[156:159], v[172:175], v[100:103]
	v_mfma_f32_16x16x32_bf16 v[100:103], v[160:163], v[176:179], v[100:103]
	v_mfma_f32_16x16x32_bf16 v[116:119], v[160:163], v[168:171], v[116:119]
	v_mfma_f32_16x16x32_bf16 v[116:119], v[156:159], v[164:167], v[116:119]
	s_barrier
	s_setprio 0
	s_add_i32 s36, s56, s40
	v_lshl_add_u64 v[218:219], v[218:219], 0, s[84:85]
	s_mov_b32 m0, s36
	ds_read_b128 v[164:167], v242 offset:49152
	ds_read_b128 v[168:171], v242 offset:50176
	ds_read_b128 v[172:175], v242 offset:51200
	ds_read_b128 v[176:179], v242 offset:52224
	ds_read_b128 v[180:183], v242 offset:53248
	ds_read_b128 v[184:187], v242 offset:54272
	ds_read_b128 v[188:191], v242 offset:55296
	ds_read_b128 v[214:217], v242 offset:56320
	global_load_lds_dwordx4 v[218:219], off
	s_add_i32 m0, s36, 0x2000
	s_add_u32 s26, s26, 0x100080
	v_lshl_add_u64 v[218:219], v[220:221], 0, s[84:85]
	s_addc_u32 s27, s27, 0
	s_add_i32 s36, s57, s40
	global_load_lds_dwordx4 v[218:219], off
	s_mov_b32 m0, s36
	s_nop 0
	global_load_lds_dwordx4 v2, s[26:27]
	s_add_i32 m0, s36, 0x2000
	s_nop 0
	global_load_lds_dwordx4 v204, s[26:27]
	s_cmp_eq_u32 s55, 60
	s_cbranch_scc0 .Ldefer_1456_body
	v_lshl_add_u64 v[218:219], v[222:223], 0, s[84:85]
	s_mov_b32 m0, s45
	s_nop 0
	global_load_lds_dwordx4 v[218:219], off
	v_lshl_add_u64 v[218:219], v[224:225], 0, s[84:85]
	s_mov_b32 m0, s46
	s_nop 0
	global_load_lds_dwordx4 v[218:219], off
.Ldefer_1456_body:
	s_waitcnt vmcnt(6)
	s_waitcnt lgkmcnt(7)
	s_setprio 1
	s_barrier
	v_mfma_f32_16x16x32_bf16 v[64:67], v[124:127], v[164:167], v[64:67]
	s_waitcnt lgkmcnt(6)
	v_mfma_f32_16x16x32_bf16 v[64:67], v[128:131], v[168:171], v[64:67]
	s_waitcnt lgkmcnt(4)
	v_mfma_f32_16x16x32_bf16 v[48:51], v[128:131], v[176:179], v[48:51]
	v_mfma_f32_16x16x32_bf16 v[48:51], v[124:127], v[172:175], v[48:51]
	s_waitcnt lgkmcnt(3)
	v_mfma_f32_16x16x32_bf16 v[32:35], v[124:127], v[180:183], v[32:35]
	s_waitcnt lgkmcnt(2)
	v_mfma_f32_16x16x32_bf16 v[32:35], v[128:131], v[184:187], v[32:35]
	s_waitcnt lgkmcnt(0)
	v_mfma_f32_16x16x32_bf16 v[16:19], v[128:131], v[214:217], v[16:19]
	v_mfma_f32_16x16x32_bf16 v[16:19], v[124:127], v[188:191], v[16:19]
	v_mfma_f32_16x16x32_bf16 v[12:15], v[132:135], v[188:191], v[12:15]
	v_mfma_f32_16x16x32_bf16 v[12:15], v[144:147], v[214:217], v[12:15]
	v_mfma_f32_16x16x32_bf16 v[28:31], v[144:147], v[184:187], v[28:31]
	v_mfma_f32_16x16x32_bf16 v[28:31], v[132:135], v[180:183], v[28:31]
	v_mfma_f32_16x16x32_bf16 v[44:47], v[132:135], v[172:175], v[44:47]
	v_mfma_f32_16x16x32_bf16 v[44:47], v[144:147], v[176:179], v[44:47]
	v_mfma_f32_16x16x32_bf16 v[60:63], v[144:147], v[168:171], v[60:63]
	v_mfma_f32_16x16x32_bf16 v[60:63], v[132:135], v[164:167], v[60:63]
	v_mfma_f32_16x16x32_bf16 v[56:59], v[148:151], v[164:167], v[56:59]
	v_mfma_f32_16x16x32_bf16 v[56:59], v[152:155], v[168:171], v[56:59]
	v_mfma_f32_16x16x32_bf16 v[40:43], v[152:155], v[176:179], v[40:43]
	v_mfma_f32_16x16x32_bf16 v[40:43], v[148:151], v[172:175], v[40:43]
	v_mfma_f32_16x16x32_bf16 v[24:27], v[148:151], v[180:183], v[24:27]
	v_mfma_f32_16x16x32_bf16 v[24:27], v[152:155], v[184:187], v[24:27]
	v_mfma_f32_16x16x32_bf16 v[8:11], v[152:155], v[214:217], v[8:11]
	v_mfma_f32_16x16x32_bf16 v[8:11], v[148:151], v[188:191], v[8:11]
	v_mfma_f32_16x16x32_bf16 v[4:7], v[156:159], v[188:191], v[4:7]
	v_mfma_f32_16x16x32_bf16 v[4:7], v[160:163], v[214:217], v[4:7]
	v_mfma_f32_16x16x32_bf16 v[20:23], v[160:163], v[184:187], v[20:23]
	v_mfma_f32_16x16x32_bf16 v[20:23], v[156:159], v[180:183], v[20:23]
	v_mfma_f32_16x16x32_bf16 v[36:39], v[156:159], v[172:175], v[36:39]
	v_mfma_f32_16x16x32_bf16 v[36:39], v[160:163], v[176:179], v[36:39]
	v_mfma_f32_16x16x32_bf16 v[52:55], v[160:163], v[168:171], v[52:55]
	v_mfma_f32_16x16x32_bf16 v[52:55], v[156:159], v[164:167], v[52:55]
	s_barrier
	s_setprio 0
	s_add_i32 s55, s55, 2
	s_add_u32 s24, s24, 0x100
	s_addc_u32 s25, s25, 0
	s_add_u32 s53, s53, 0x100
	s_addc_u32 s54, s54, 0
	s_cmp_gt_u32 s55, 61
	s_cbranch_scc0 .LBB0_1456

; #define PG8_STAGE(bufoff, gbase, voff) do { _Pragma("unroll") for (int _i = 0; _i < 2; ++_i) \
;         __builtin_amdgcn_global_load_lds((const unsigned*)((const char*)(gbase) + (voff)[_i]), (PG8_LAS unsigned*)(lds + (bufoff) + ldsw + _i * 8192), 16, 0, 0); } while (0)
; #define PG8_LDA(dst, b, h) do { _Pragma("unroll") for (int m = 0; m < 4; ++m) _Pragma("unroll") for (int k = 0; k < 2; ++k) dst[m][k] = *(const PG8_LAS bf16x8*)(lds + PG8_SA(b, h) + aoff + m * 2048 + k * 1024); } while (0)
; #define PG8_LDB(dst, b, h) do { _Pragma("unroll") for (int n = 0; n < 2; ++n) _Pragma("unroll") for (int k = 0; k < 2; ++k) dst[n][k] = *(const PG8_LAS bf16x8*)(lds + PG8_SB(b, h) + boff + n * 2048 + k * 1024); } while (0)
; #define PG8_WAIT_V(n) asm volatile("s_waitcnt vmcnt(" #n ")" ::: "memory")
; #define PG8_WAIT_L(n) asm volatile("s_waitcnt lgkmcnt(" #n ")" ::: "memory")
; #define PG8_BAR __builtin_amdgcn_s_barrier()
; #define PG8_SCHED __builtin_amdgcn_sched_barrier(0)
; template <class Epi, class Sched, bool ALIGN_EPI = false, bool SP2 = false, bool I8 = false>
; __device__ __forceinline__ void gemm_phase(PG8_LAS unsigned char* lds, const Gemm g, const Sched& S, const Epi& E) {
;     ...
;         const char* nA = has_next ? (const char*)g.A + (size_t)nxt.pm * tstep : cA; const char* nB = has_next ? (const char*)g.Bt + (size_t)nxt.pn * tstep : cB;
;         for (int t = 0; t < nt; t += 2) {
;             const bool last = (t == nt - 2);
;             const char* a1 = cA + (size_t)(t + 1) * kstep;
;             const char* a2 = last ? nA : cA + (size_t)(t + 2) * kstep; const char* b2 = last ? nB : cB + (size_t)(t + 2) * kstep;
;             const char* a3 = a2 + kstep; const char* b3 = b2 + kstep;
;             if (last && has_next) S.a_ready(nxt);
;             if constexpr (SP2) {
;             PG8_LDB(B0, 0, 0); PG8_LDB(B1, 0, 1); PG8_SCHED; PG8_LDA(At, 0, 0); PG8_STAGE(PG8_SA(1, 1), a1 + hstep, voffA);
;             PG8_WAIT_V(8); PG8_WAIT_L(0); PG8_BAR; PG8_MMA(0, 0, At, B0); PG8_MMA(0, 1, At, B1); PG8_BAR; PG8_SCHED;
;             PG8_LDA(At, 0, 1); PG8_STAGE(PG8_SB(0, 0), b2, voffB); PG8_STAGE(PG8_SB(0, 1), b2 + hstep, voffB); PG8_STAGE(PG8_SA(0, 0), a2, voffA);
;             PG8_WAIT_V(8); PG8_WAIT_L(0); PG8_BAR; PG8_MMA(1, 0, At, B0); PG8_MMA(1, 1, At, B1); PG8_BAR; PG8_SCHED;
.LBB0_1590:
	s_ashr_i32 s25, s24, 31
	s_lshl_b64 s[26:27], s[24:25], 20
	s_add_u32 s26, s28, s26
	s_addc_u32 s27, s42, s27
	s_and_b64 s[36:37], s[10:11], exec
	s_cselect_b32 s25, s27, s41
	s_cselect_b32 s57, s26, s40
	s_ashr_i32 s23, s22, 31
	s_lshl_b64 s[36:37], s[22:23], 20
	s_add_u32 s36, s43, s36
	s_addc_u32 s37, s46, s37
	s_and_b64 s[48:49], s[10:11], exec
	s_cselect_b32 s23, s37, s45
	s_cselect_b32 s58, s36, s44
	s_add_u32 s40, s40, 0x80080
	s_addc_u32 s41, s41, 0
	s_add_u32 s59, s44, 0x100
	s_addc_u32 s60, s45, 0
	s_mov_b32 s61, -2
	s_add_u32 s44, s40, 0xfff80080
	s_addc_u32 s45, s41, -1
	s_add_i32 s64, 0, 0x10000
	s_cmp_eq_u32 s61, 28
	s_cselect_b32 s49, s25, s45
	s_cselect_b32 s48, s57, s44
	s_cselect_b32 s45, s23, s60
	s_cselect_b32 s44, s58, s59
	s_add_i32 s67, 0, 0x14000
	v_add_u32_e32 v144, s64, v167
	v_add_u32_e32 v158, s67, v167
	ds_read_b128 v[36:39], v144
	ds_read_b128 v[44:47], v144 offset:1024
	ds_read_b128 v[140:143], v144 offset:2048
	ds_read_b128 v[144:147], v144 offset:3072
	ds_read_b128 v[160:163], v158
	ds_read_b128 v[172:175], v158 offset:1024
	ds_read_b128 v[176:179], v158 offset:2048
	ds_read_b128 v[180:183], v158 offset:3072
	s_add_i32 m0, s50, 0xc000
	ds_read_b128 v[184:187], v171
	ds_read_b128 v[188:191], v171 offset:1024
	ds_read_b128 v[204:207], v171 offset:2048
	ds_read_b128 v[208:211], v171 offset:3072
	ds_read_b128 v[212:215], v171 offset:4096
	ds_read_b128 v[216:219], v171 offset:5120
	ds_read_b128 v[220:223], v171 offset:6144
	ds_read_b128 v[224:227], v171 offset:7168
	global_load_lds_dwordx4 v154, s[40:41]
	s_add_i32 m0, s50, 0xe000
	s_nop 0
	global_load_lds_dwordx4 v156, s[40:41]
	s_waitcnt vmcnt(8)
	s_waitcnt lgkmcnt(7)
	s_setprio 1
	s_barrier
	v_mfma_i32_16x16x64_i8 v[136:139], v[36:39], v[184:187], 0
	s_waitcnt lgkmcnt(6)
	v_mfma_i32_16x16x64_i8 v[136:139], v[44:47], v[188:191], v[136:139]
	s_waitcnt lgkmcnt(4)
	v_mfma_i32_16x16x64_i8 v[120:123], v[44:47], v[208:211], 0
	v_mfma_i32_16x16x64_i8 v[120:123], v[36:39], v[204:207], v[120:123]
	s_waitcnt lgkmcnt(3)
	v_mfma_i32_16x16x64_i8 v[104:107], v[36:39], v[212:215], 0
	s_waitcnt lgkmcnt(2)
	v_mfma_i32_16x16x64_i8 v[104:107], v[44:47], v[216:219], v[104:107]
	s_waitcnt lgkmcnt(0)
	v_mfma_i32_16x16x64_i8 v[88:91], v[44:47], v[224:227], 0
	v_mfma_i32_16x16x64_i8 v[88:91], v[36:39], v[220:223], v[88:91]
	v_mfma_i32_16x16x64_i8 v[80:83], v[140:143], v[220:223], 0
	v_mfma_i32_16x16x64_i8 v[80:83], v[144:147], v[224:227], v[80:83]
	v_mfma_i32_16x16x64_i8 v[96:99], v[144:147], v[216:219], 0
	v_mfma_i32_16x16x64_i8 v[96:99], v[140:143], v[212:215], v[96:99]
	v_mfma_i32_16x16x64_i8 v[112:115], v[140:143], v[204:207], 0
	v_mfma_i32_16x16x64_i8 v[112:115], v[144:147], v[208:211], v[112:115]
	v_mfma_i32_16x16x64_i8 v[128:131], v[144:147], v[188:191], 0
	v_mfma_i32_16x16x64_i8 v[128:131], v[140:143], v[184:187], v[128:131]
	v_mfma_i32_16x16x64_i8 v[132:135], v[160:163], v[184:187], 0
	v_mfma_i32_16x16x64_i8 v[132:135], v[172:175], v[188:191], v[132:135]
	v_mfma_i32_16x16x64_i8 v[116:119], v[172:175], v[208:211], 0
	v_mfma_i32_16x16x64_i8 v[116:119], v[160:163], v[204:207], v[116:119]
	v_mfma_i32_16x16x64_i8 v[100:103], v[160:163], v[212:215], 0
	v_mfma_i32_16x16x64_i8 v[100:103], v[172:175], v[216:219], v[100:103]
	v_mfma_i32_16x16x64_i8 v[84:87], v[172:175], v[224:227], 0
	v_mfma_i32_16x16x64_i8 v[84:87], v[160:163], v[220:223], v[84:87]
	v_mfma_i32_16x16x64_i8 v[76:79], v[176:179], v[220:223], 0
	v_mfma_i32_16x16x64_i8 v[76:79], v[180:183], v[224:227], v[76:79]
	v_mfma_i32_16x16x64_i8 v[92:95], v[180:183], v[216:219], 0
	v_mfma_i32_16x16x64_i8 v[92:95], v[176:179], v[212:215], v[92:95]
	v_mfma_i32_16x16x64_i8 v[108:111], v[176:179], v[204:207], 0
	v_mfma_i32_16x16x64_i8 v[108:111], v[180:183], v[208:211], v[108:111]
	v_mfma_i32_16x16x64_i8 v[124:127], v[180:183], v[188:191], 0
	v_mfma_i32_16x16x64_i8 v[124:127], v[176:179], v[184:187], v[124:127]
	s_barrier
	s_setprio 0
	s_add_i32 s64, s64, s47
	v_lshl_add_u64 v[164:165], s[44:45], 0, v[2:3]
	s_mov_b32 m0, s64
	ds_read_b128 v[184:187], v171 offset:16384
	ds_read_b128 v[188:191], v171 offset:17408
	ds_read_b128 v[204:207], v171 offset:18432
	ds_read_b128 v[208:211], v171 offset:19456
	ds_read_b128 v[212:215], v171 offset:20480
	ds_read_b128 v[216:219], v171 offset:21504
	ds_read_b128 v[220:223], v171 offset:22528
	ds_read_b128 v[224:227], v171 offset:23552
	global_load_lds_dwordx4 v[164:165], off
	s_add_i32 m0, s64, 0x2000
	s_add_u32 s64, s44, 0x80000
	v_lshl_add_u64 v[228:229], s[44:45], 0, v[148:149]
	s_addc_u32 s65, s45, 0
	s_add_i32 s67, s67, s47
	global_load_lds_dwordx4 v[228:229], off
	s_mov_b32 m0, s67
	v_lshl_add_u64 v[242:243], s[48:49], 0, v[150:151]
	global_load_lds_dwordx4 v2, s[64:65]
	s_add_i32 m0, s67, 0x2000
	s_nop 0
	global_load_lds_dwordx4 v148, s[64:65]
	v_lshl_add_u64 v[240:241], s[48:49], 0, v[152:153]
	s_waitcnt vmcnt(6)
	s_waitcnt lgkmcnt(7)
	s_setprio 1
	s_barrier
; #define PG8_STAGE(bufoff, gbase, voff) do { _Pragma("unroll") for (int _i = 0; _i < 2; ++_i) \
;         __builtin_amdgcn_global_load_lds((const unsigned*)((const char*)(gbase) + (voff)[_i]), (PG8_LAS unsigned*)(lds + (bufoff) + ldsw + _i * 8192), 16, 0, 0); } while (0)
; #define PG8_LDA(dst, b, h) do { _Pragma("unroll") for (int m = 0; m < 4; ++m) _Pragma("unroll") for (int k = 0; k < 2; ++k) dst[m][k] = *(const PG8_LAS bf16x8*)(lds + PG8_SA(b, h) + aoff + m * 2048 + k * 1024); } while (0)
; #define PG8_LDB(dst, b, h) do { _Pragma("unroll") for (int n = 0; n < 2; ++n) _Pragma("unroll") for (int k = 0; k < 2; ++k) dst[n][k] = *(const PG8_LAS bf16x8*)(lds + PG8_SB(b, h) + boff + n * 2048 + k * 1024); } while (0)
; #define PG8_WAIT_V(n) asm volatile("s_waitcnt vmcnt(" #n ")" ::: "memory")
; #define PG8_WAIT_L(n) asm volatile("s_waitcnt lgkmcnt(" #n ")" ::: "memory")
; #define PG8_BAR __builtin_amdgcn_s_barrier()
; #define PG8_SCHED __builtin_amdgcn_sched_barrier(0)
; template <class Epi, class Sched, bool ALIGN_EPI = false, bool SP2 = false, bool I8 = false>
; __device__ __forceinline__ void gemm_phase(PG8_LAS unsigned char* lds, const Gemm g, const Sched& S, const Epi& E) {
;     ...
;             PG8_LDA(At, 0, 1); PG8_STAGE(PG8_SB(0, 0), b2, voffB); PG8_STAGE(PG8_SB(0, 1), b2 + hstep, voffB); PG8_STAGE(PG8_SA(0, 0), a2, voffA);
;             PG8_WAIT_V(8); PG8_WAIT_L(0); PG8_BAR; PG8_MMA(1, 0, At, B0); PG8_MMA(1, 1, At, B1); PG8_BAR; PG8_SCHED;
;             PG8_LDB(B0, 1, 0); PG8_LDB(B1, 1, 1); PG8_SCHED; PG8_LDA(At, 1, 0); PG8_STAGE(PG8_SA(0, 1), a2 + hstep, voffA);
;             PG8_WAIT_V(8); PG8_WAIT_L(0); PG8_BAR; PG8_MMA(0, 0, At, B0); PG8_MMA(0, 1, At, B1); PG8_BAR; PG8_SCHED;
;             PG8_LDA(At, 1, 1); PG8_STAGE(PG8_SB(1, 0), b3, voffB); PG8_STAGE(PG8_SB(1, 1), b3 + hstep, voffB); PG8_STAGE(PG8_SA(1, 0), a3, voffA);
;             PG8_WAIT_V(8); PG8_WAIT_L(0); PG8_BAR; PG8_MMA(1, 0, At, B0); PG8_MMA(1, 1, At, B1); PG8_BAR; PG8_SCHED;
	v_mfma_i32_16x16x64_i8 v[72:75], v[36:39], v[184:187], 0
	s_waitcnt lgkmcnt(6)
	v_mfma_i32_16x16x64_i8 v[72:75], v[44:47], v[188:191], v[72:75]
	s_waitcnt lgkmcnt(4)
	v_mfma_i32_16x16x64_i8 v[56:59], v[44:47], v[208:211], 0
	v_mfma_i32_16x16x64_i8 v[56:59], v[36:39], v[204:207], v[56:59]
	s_waitcnt lgkmcnt(3)
	v_mfma_i32_16x16x64_i8 v[32:35], v[36:39], v[212:215], 0
	s_waitcnt lgkmcnt(2)
	v_mfma_i32_16x16x64_i8 v[32:35], v[44:47], v[216:219], v[32:35]
	s_waitcnt lgkmcnt(0)
	v_mfma_i32_16x16x64_i8 v[16:19], v[44:47], v[224:227], 0
	v_mfma_i32_16x16x64_i8 v[16:19], v[36:39], v[220:223], v[16:19]
	v_mfma_i32_16x16x64_i8 v[8:11], v[140:143], v[220:223], 0
	v_mfma_i32_16x16x64_i8 v[8:11], v[144:147], v[224:227], v[8:11]
	v_mfma_i32_16x16x64_i8 v[24:27], v[144:147], v[216:219], 0
	v_mfma_i32_16x16x64_i8 v[24:27], v[140:143], v[212:215], v[24:27]
	v_mfma_i32_16x16x64_i8 v[48:51], v[140:143], v[204:207], 0
	v_mfma_i32_16x16x64_i8 v[48:51], v[144:147], v[208:211], v[48:51]
	v_mfma_i32_16x16x64_i8 v[64:67], v[144:147], v[188:191], 0
	v_mfma_i32_16x16x64_i8 v[64:67], v[140:143], v[184:187], v[64:67]
	v_mfma_i32_16x16x64_i8 v[36:39], v[160:163], v[184:187], 0
	v_mfma_i32_16x16x64_i8 v[36:39], v[172:175], v[188:191], v[36:39]
	v_mfma_i32_16x16x64_i8 v[52:55], v[172:175], v[208:211], 0
	v_mfma_i32_16x16x64_i8 v[52:55], v[160:163], v[204:207], v[52:55]
	v_mfma_i32_16x16x64_i8 v[28:31], v[160:163], v[212:215], 0
	v_mfma_i32_16x16x64_i8 v[28:31], v[172:175], v[216:219], v[28:31]
	v_mfma_i32_16x16x64_i8 v[12:15], v[172:175], v[224:227], 0
	v_mfma_i32_16x16x64_i8 v[12:15], v[160:163], v[220:223], v[12:15]
	v_mfma_i32_16x16x64_i8 v[4:7], v[176:179], v[220:223], 0
	v_mfma_i32_16x16x64_i8 v[4:7], v[180:183], v[224:227], v[4:7]
	v_mfma_i32_16x16x64_i8 v[20:23], v[180:183], v[216:219], 0
	v_mfma_i32_16x16x64_i8 v[20:23], v[176:179], v[212:215], v[20:23]
	v_mfma_i32_16x16x64_i8 v[40:43], v[176:179], v[204:207], 0
	v_mfma_i32_16x16x64_i8 v[40:43], v[180:183], v[208:211], v[40:43]
	v_mfma_i32_16x16x64_i8 v[44:47], v[180:183], v[188:191], 0
	v_mfma_i32_16x16x64_i8 v[44:47], v[176:179], v[184:187], v[44:47]
	s_barrier
	s_setprio 0
	s_mov_b32 m0, s50
	s_nop 0
	global_load_lds_dwordx4 v[240:241], off
	s_mov_b32 m0, s51
	s_nop 0
	global_load_lds_dwordx4 v[242:243], off
	s_add_i32 s64, 0, 0x18000
	s_add_i32 s65, 0, 0x1c000
	v_add_u32_e32 v144, s64, v167
	v_add_u32_e32 v158, s65, v167
	ds_read_b128 v[60:63], v144
	ds_read_b128 v[68:71], v144 offset:1024
	ds_read_b128 v[140:143], v144 offset:2048
	ds_read_b128 v[144:147], v144 offset:3072
	ds_read_b128 v[160:163], v158
	ds_read_b128 v[172:175], v158 offset:1024
	ds_read_b128 v[176:179], v158 offset:2048
	ds_read_b128 v[180:183], v158 offset:3072
	s_add_u32 s48, s48, 0x80000
	s_addc_u32 s49, s49, 0
	s_mov_b32 m0, s52
	ds_read_b128 v[184:187], v171 offset:32768
	ds_read_b128 v[188:191], v171 offset:33792
	ds_read_b128 v[204:207], v171 offset:34816
	ds_read_b128 v[208:211], v171 offset:35840
	ds_read_b128 v[212:215], v171 offset:36864
	ds_read_b128 v[216:219], v171 offset:37888
	ds_read_b128 v[220:223], v171 offset:38912
	ds_read_b128 v[224:227], v171 offset:39936
	global_load_lds_dwordx4 v152, s[48:49]
	s_mov_b32 m0, s53
	s_nop 0
	global_load_lds_dwordx4 v150, s[48:49]
	s_waitcnt vmcnt(8)
	s_waitcnt lgkmcnt(7)
	s_setprio 1
	s_barrier
	v_mfma_i32_16x16x64_i8 v[136:139], v[60:63], v[184:187], v[136:139]
	s_waitcnt lgkmcnt(6)
	v_mfma_i32_16x16x64_i8 v[136:139], v[68:71], v[188:191], v[136:139]
	s_waitcnt lgkmcnt(4)
	v_mfma_i32_16x16x64_i8 v[120:123], v[68:71], v[208:211], v[120:123]
	v_mfma_i32_16x16x64_i8 v[120:123], v[60:63], v[204:207], v[120:123]
	s_waitcnt lgkmcnt(3)
	v_mfma_i32_16x16x64_i8 v[104:107], v[60:63], v[212:215], v[104:107]
	s_waitcnt lgkmcnt(2)
	v_mfma_i32_16x16x64_i8 v[104:107], v[68:71], v[216:219], v[104:107]
	s_waitcnt lgkmcnt(0)
	v_mfma_i32_16x16x64_i8 v[88:91], v[68:71], v[224:227], v[88:91]
	v_mfma_i32_16x16x64_i8 v[88:91], v[60:63], v[220:223], v[88:91]
	v_mfma_i32_16x16x64_i8 v[80:83], v[140:143], v[220:223], v[80:83]
	v_mfma_i32_16x16x64_i8 v[80:83], v[144:147], v[224:227], v[80:83]
	v_mfma_i32_16x16x64_i8 v[96:99], v[144:147], v[216:219], v[96:99]
	v_mfma_i32_16x16x64_i8 v[96:99], v[140:143], v[212:215], v[96:99]
	v_mfma_i32_16x16x64_i8 v[112:115], v[140:143], v[204:207], v[112:115]
	v_mfma_i32_16x16x64_i8 v[112:115], v[144:147], v[208:211], v[112:115]
	v_mfma_i32_16x16x64_i8 v[128:131], v[144:147], v[188:191], v[128:131]
	v_mfma_i32_16x16x64_i8 v[128:131], v[140:143], v[184:187], v[128:131]
	v_mfma_i32_16x16x64_i8 v[132:135], v[160:163], v[184:187], v[132:135]
	v_mfma_i32_16x16x64_i8 v[132:135], v[172:175], v[188:191], v[132:135]
	v_mfma_i32_16x16x64_i8 v[116:119], v[172:175], v[208:211], v[116:119]
	v_mfma_i32_16x16x64_i8 v[116:119], v[160:163], v[204:207], v[116:119]
	v_mfma_i32_16x16x64_i8 v[100:103], v[160:163], v[212:215], v[100:103]
	v_mfma_i32_16x16x64_i8 v[100:103], v[172:175], v[216:219], v[100:103]
	v_mfma_i32_16x16x64_i8 v[84:87], v[172:175], v[224:227], v[84:87]
	v_mfma_i32_16x16x64_i8 v[84:87], v[160:163], v[220:223], v[84:87]
	v_mfma_i32_16x16x64_i8 v[76:79], v[176:179], v[220:223], v[76:79]
	v_mfma_i32_16x16x64_i8 v[76:79], v[180:183], v[224:227], v[76:79]
	v_mfma_i32_16x16x64_i8 v[92:95], v[180:183], v[216:219], v[92:95]
	v_mfma_i32_16x16x64_i8 v[92:95], v[176:179], v[212:215], v[92:95]
	v_mfma_i32_16x16x64_i8 v[108:111], v[176:179], v[204:207], v[108:111]
	v_mfma_i32_16x16x64_i8 v[108:111], v[180:183], v[208:211], v[108:111]
	v_mfma_i32_16x16x64_i8 v[124:127], v[180:183], v[188:191], v[124:127]
	v_mfma_i32_16x16x64_i8 v[124:127], v[176:179], v[184:187], v[124:127]
	s_barrier
	s_setprio 0
	s_add_i32 s48, s64, s47
	v_lshl_add_u64 v[164:165], v[164:165], 0, s[84:85]
	s_mov_b32 m0, s48
	ds_read_b128 v[184:187], v171 offset:49152
	ds_read_b128 v[188:191], v171 offset:50176
	ds_read_b128 v[204:207], v171 offset:51200
	ds_read_b128 v[208:211], v171 offset:52224
	ds_read_b128 v[212:215], v171 offset:53248
	ds_read_b128 v[216:219], v171 offset:54272
	ds_read_b128 v[220:223], v171 offset:55296
	ds_read_b128 v[224:227], v171 offset:56320
	global_load_lds_dwordx4 v[164:165], off
	s_add_i32 m0, s48, 0x2000
	s_add_u32 s44, s44, 0x80080
	v_lshl_add_u64 v[164:165], v[228:229], 0, s[84:85]
	s_addc_u32 s45, s45, 0
	s_add_i32 s48, s65, s47
	global_load_lds_dwordx4 v[164:165], off
	s_mov_b32 m0, s48
	s_nop 0
	global_load_lds_dwordx4 v2, s[44:45]
	s_add_i32 m0, s48, 0x2000
	s_nop 0
	global_load_lds_dwordx4 v148, s[44:45]
	s_cmp_eq_u32 s61, 28
	s_cbranch_scc0 .Ldefer_1591_peel
	v_lshl_add_u64 v[164:165], v[240:241], 0, s[84:85]
	s_mov_b32 m0, s54
	s_nop 0
	global_load_lds_dwordx4 v[164:165], off
	v_lshl_add_u64 v[164:165], v[242:243], 0, s[84:85]
	s_mov_b32 m0, s55
	s_nop 0
	global_load_lds_dwordx4 v[164:165], off
; #define PG8_STAGE(bufoff, gbase, voff) do { _Pragma("unroll") for (int _i = 0; _i < 2; ++_i) \
;         __builtin_amdgcn_global_load_lds((const unsigned*)((const char*)(gbase) + (voff)[_i]), (PG8_LAS unsigned*)(lds + (bufoff) + ldsw + _i * 8192), 16, 0, 0); } while (0)
; #define PG8_LDA(dst, b, h) do { _Pragma("unroll") for (int m = 0; m < 4; ++m) _Pragma("unroll") for (int k = 0; k < 2; ++k) dst[m][k] = *(const PG8_LAS bf16x8*)(lds + PG8_SA(b, h) + aoff + m * 2048 + k * 1024); } while (0)
; #define PG8_LDB(dst, b, h) do { _Pragma("unroll") for (int n = 0; n < 2; ++n) _Pragma("unroll") for (int k = 0; k < 2; ++k) dst[n][k] = *(const PG8_LAS bf16x8*)(lds + PG8_SB(b, h) + boff + n * 2048 + k * 1024); } while (0)
; #define PG8_WAIT_V(n) asm volatile("s_waitcnt vmcnt(" #n ")" ::: "memory")
; #define PG8_WAIT_L(n) asm volatile("s_waitcnt lgkmcnt(" #n ")" ::: "memory")
; #define PG8_BAR __builtin_amdgcn_s_barrier()
; #define PG8_SCHED __builtin_amdgcn_sched_barrier(0)
; template <class Epi, class Sched, bool ALIGN_EPI = false, bool SP2 = false, bool I8 = false>
; __device__ __forceinline__ void gemm_phase(PG8_LAS unsigned char* lds, const Gemm g, const Sched& S, const Epi& E) {
;     ...
;             PG8_LDB(B0, 0, 0); PG8_LDB(B1, 0, 1); PG8_SCHED; PG8_LDA(At, 0, 0); PG8_STAGE(PG8_SA(1, 1), a1 + hstep, voffA);
;             PG8_WAIT_V(8); PG8_WAIT_L(0); PG8_BAR; PG8_MMA(0, 0, At, B0); PG8_MMA(0, 1, At, B1); PG8_BAR; PG8_SCHED;
;             PG8_LDA(At, 0, 1); PG8_STAGE(PG8_SB(0, 0), b2, voffB); PG8_STAGE(PG8_SB(0, 1), b2 + hstep, voffB); PG8_STAGE(PG8_SA(0, 0), a2, voffA);
;             PG8_WAIT_V(8); PG8_WAIT_L(0); PG8_BAR; PG8_MMA(1, 0, At, B0); PG8_MMA(1, 1, At, B1); PG8_BAR; PG8_SCHED;
;             PG8_LDB(B0, 1, 0); PG8_LDB(B1, 1, 1); PG8_SCHED; PG8_LDA(At, 1, 0); PG8_STAGE(PG8_SA(0, 1), a2 + hstep, voffA);
;             PG8_WAIT_V(8); PG8_WAIT_L(0); PG8_BAR; PG8_MMA(0, 0, At, B0); PG8_MMA(0, 1, At, B1); PG8_BAR; PG8_SCHED;
;             PG8_LDA(At, 1, 1); PG8_STAGE(PG8_SB(1, 0), b3, voffB); PG8_STAGE(PG8_SB(1, 1), b3 + hstep, voffB); PG8_STAGE(PG8_SA(1, 0), a3, voffA);
;             PG8_WAIT_V(8); PG8_WAIT_L(0); PG8_BAR; PG8_MMA(1, 0, At, B0); PG8_MMA(1, 1, At, B1); PG8_BAR; PG8_SCHED;
.Ldefer_1591_peel:
	s_waitcnt vmcnt(6)
	s_waitcnt lgkmcnt(7)
	s_setprio 1
	s_barrier
	v_mfma_i32_16x16x64_i8 v[72:75], v[60:63], v[184:187], v[72:75]
	s_waitcnt lgkmcnt(6)
	v_mfma_i32_16x16x64_i8 v[72:75], v[68:71], v[188:191], v[72:75]
	s_waitcnt lgkmcnt(4)
	v_mfma_i32_16x16x64_i8 v[56:59], v[68:71], v[208:211], v[56:59]
	v_mfma_i32_16x16x64_i8 v[56:59], v[60:63], v[204:207], v[56:59]
	s_waitcnt lgkmcnt(3)
	v_mfma_i32_16x16x64_i8 v[32:35], v[60:63], v[212:215], v[32:35]
	s_waitcnt lgkmcnt(2)
	v_mfma_i32_16x16x64_i8 v[32:35], v[68:71], v[216:219], v[32:35]
	s_waitcnt lgkmcnt(0)
	v_mfma_i32_16x16x64_i8 v[16:19], v[68:71], v[224:227], v[16:19]
	v_mfma_i32_16x16x64_i8 v[16:19], v[60:63], v[220:223], v[16:19]
	v_mfma_i32_16x16x64_i8 v[8:11], v[140:143], v[220:223], v[8:11]
	v_mfma_i32_16x16x64_i8 v[8:11], v[144:147], v[224:227], v[8:11]
	v_mfma_i32_16x16x64_i8 v[24:27], v[144:147], v[216:219], v[24:27]
	v_mfma_i32_16x16x64_i8 v[24:27], v[140:143], v[212:215], v[24:27]
	v_mfma_i32_16x16x64_i8 v[48:51], v[140:143], v[204:207], v[48:51]
	v_mfma_i32_16x16x64_i8 v[48:51], v[144:147], v[208:211], v[48:51]
	v_mfma_i32_16x16x64_i8 v[64:67], v[144:147], v[188:191], v[64:67]
	v_mfma_i32_16x16x64_i8 v[64:67], v[140:143], v[184:187], v[64:67]
	v_mfma_i32_16x16x64_i8 v[36:39], v[160:163], v[184:187], v[36:39]
	v_mfma_i32_16x16x64_i8 v[68:71], v[172:175], v[188:191], v[36:39]
	v_mfma_i32_16x16x64_i8 v[36:39], v[172:175], v[208:211], v[52:55]
	v_mfma_i32_16x16x64_i8 v[52:55], v[160:163], v[204:207], v[36:39]
	v_mfma_i32_16x16x64_i8 v[28:31], v[160:163], v[212:215], v[28:31]
	v_mfma_i32_16x16x64_i8 v[28:31], v[172:175], v[216:219], v[28:31]
	v_mfma_i32_16x16x64_i8 v[12:15], v[172:175], v[224:227], v[12:15]
	v_mfma_i32_16x16x64_i8 v[12:15], v[160:163], v[220:223], v[12:15]
	v_mfma_i32_16x16x64_i8 v[4:7], v[176:179], v[220:223], v[4:7]
	v_mfma_i32_16x16x64_i8 v[4:7], v[180:183], v[224:227], v[4:7]
	v_mfma_i32_16x16x64_i8 v[20:23], v[180:183], v[216:219], v[20:23]
	v_mfma_i32_16x16x64_i8 v[20:23], v[176:179], v[212:215], v[20:23]
	v_mfma_i32_16x16x64_i8 v[36:39], v[176:179], v[204:207], v[40:43]
	v_mfma_i32_16x16x64_i8 v[40:43], v[180:183], v[208:211], v[36:39]
	v_mfma_i32_16x16x64_i8 v[36:39], v[180:183], v[188:191], v[44:47]
	v_mfma_i32_16x16x64_i8 v[60:63], v[176:179], v[184:187], v[36:39]
	s_barrier
	s_setprio 0
	s_add_i32 s61, s61, 2
	s_add_u32 s40, s40, 0x100
	s_addc_u32 s41, s41, 0
	s_add_u32 s59, s59, 0x100
	s_addc_u32 s60, s60, 0
	s_cmp_gt_u32 s61, 29
	s_cbranch_scc1 .Lkloop_exit_3
.LBB0_1591:
	s_add_u32 s44, s40, 0xfff80080
	s_addc_u32 s45, s41, -1
	s_add_i32 s64, 0, 0x10000
	s_cmp_eq_u32 s61, 28
	s_cselect_b32 s49, s25, s45
	s_cselect_b32 s48, s57, s44
	s_cselect_b32 s45, s23, s60
	s_cselect_b32 s44, s58, s59
	s_add_i32 s67, 0, 0x14000
	v_add_u32_e32 v144, s64, v167
	v_add_u32_e32 v158, s67, v167
	ds_read_b128 v[36:39], v144
	ds_read_b128 v[44:47], v144 offset:1024
	ds_read_b128 v[140:143], v144 offset:2048
	ds_read_b128 v[144:147], v144 offset:3072
	ds_read_b128 v[160:163], v158
	ds_read_b128 v[172:175], v158 offset:1024
	ds_read_b128 v[176:179], v158 offset:2048
	ds_read_b128 v[180:183], v158 offset:3072
	v_lshl_add_u64 v[164:165], v[240:241], 0, s[84:85]
	s_mov_b32 m0, s54
	s_nop 0
	global_load_lds_dwordx4 v[164:165], off
	v_lshl_add_u64 v[164:165], v[242:243], 0, s[84:85]
	s_mov_b32 m0, s55
	s_nop 0
	global_load_lds_dwordx4 v[164:165], off
	s_add_i32 m0, s50, 0xc000
	ds_read_b128 v[184:187], v171
	ds_read_b128 v[188:191], v171 offset:1024
	ds_read_b128 v[204:207], v171 offset:2048
	ds_read_b128 v[208:211], v171 offset:3072
	ds_read_b128 v[212:215], v171 offset:4096
	ds_read_b128 v[216:219], v171 offset:5120
	ds_read_b128 v[220:223], v171 offset:6144
	ds_read_b128 v[224:227], v171 offset:7168
	global_load_lds_dwordx4 v154, s[40:41]
	s_add_i32 m0, s50, 0xe000
	s_nop 0
	global_load_lds_dwordx4 v156, s[40:41]
	s_waitcnt vmcnt(8)
	s_waitcnt lgkmcnt(7)
	s_setprio 1
	s_barrier
	v_mfma_i32_16x16x64_i8 v[136:139], v[36:39], v[184:187], v[136:139]
	s_waitcnt lgkmcnt(6)
	v_mfma_i32_16x16x64_i8 v[136:139], v[44:47], v[188:191], v[136:139]
	s_waitcnt lgkmcnt(4)
	v_mfma_i32_16x16x64_i8 v[120:123], v[44:47], v[208:211], v[120:123]
	v_mfma_i32_16x16x64_i8 v[120:123], v[36:39], v[204:207], v[120:123]
	s_waitcnt lgkmcnt(3)
	v_mfma_i32_16x16x64_i8 v[104:107], v[36:39], v[212:215], v[104:107]
	s_waitcnt lgkmcnt(2)
	v_mfma_i32_16x16x64_i8 v[104:107], v[44:47], v[216:219], v[104:107]
	s_waitcnt lgkmcnt(0)
	v_mfma_i32_16x16x64_i8 v[88:91], v[44:47], v[224:227], v[88:91]
	v_mfma_i32_16x16x64_i8 v[88:91], v[36:39], v[220:223], v[88:91]
	v_mfma_i32_16x16x64_i8 v[80:83], v[140:143], v[220:223], v[80:83]
	v_mfma_i32_16x16x64_i8 v[80:83], v[144:147], v[224:227], v[80:83]
	v_mfma_i32_16x16x64_i8 v[96:99], v[144:147], v[216:219], v[96:99]
	v_mfma_i32_16x16x64_i8 v[96:99], v[140:143], v[212:215], v[96:99]
	v_mfma_i32_16x16x64_i8 v[112:115], v[140:143], v[204:207], v[112:115]
	v_mfma_i32_16x16x64_i8 v[112:115], v[144:147], v[208:211], v[112:115]
	v_mfma_i32_16x16x64_i8 v[128:131], v[144:147], v[188:191], v[128:131]
	v_mfma_i32_16x16x64_i8 v[128:131], v[140:143], v[184:187], v[128:131]
	v_mfma_i32_16x16x64_i8 v[132:135], v[160:163], v[184:187], v[132:135]
	v_mfma_i32_16x16x64_i8 v[132:135], v[172:175], v[188:191], v[132:135]
	v_mfma_i32_16x16x64_i8 v[116:119], v[172:175], v[208:211], v[116:119]
	v_mfma_i32_16x16x64_i8 v[116:119], v[160:163], v[204:207], v[116:119]
	v_mfma_i32_16x16x64_i8 v[100:103], v[160:163], v[212:215], v[100:103]
	v_mfma_i32_16x16x64_i8 v[100:103], v[172:175], v[216:219], v[100:103]
	v_mfma_i32_16x16x64_i8 v[84:87], v[172:175], v[224:227], v[84:87]
	v_mfma_i32_16x16x64_i8 v[84:87], v[160:163], v[220:223], v[84:87]
	v_mfma_i32_16x16x64_i8 v[76:79], v[176:179], v[220:223], v[76:79]
	v_mfma_i32_16x16x64_i8 v[76:79], v[180:183], v[224:227], v[76:79]
	v_mfma_i32_16x16x64_i8 v[92:95], v[180:183], v[216:219], v[92:95]
	v_mfma_i32_16x16x64_i8 v[92:95], v[176:179], v[212:215], v[92:95]
	v_mfma_i32_16x16x64_i8 v[108:111], v[176:179], v[204:207], v[108:111]
	v_mfma_i32_16x16x64_i8 v[108:111], v[180:183], v[208:211], v[108:111]
	v_mfma_i32_16x16x64_i8 v[124:127], v[180:183], v[188:191], v[124:127]
	v_mfma_i32_16x16x64_i8 v[124:127], v[176:179], v[184:187], v[124:127]
	s_barrier
; #define PG8_STAGE(bufoff, gbase, voff) do { _Pragma("unroll") for (int _i = 0; _i < 2; ++_i) \
;         __builtin_amdgcn_global_load_lds((const unsigned*)((const char*)(gbase) + (voff)[_i]), (PG8_LAS unsigned*)(lds + (bufoff) + ldsw + _i * 8192), 16, 0, 0); } while (0)
; #define PG8_LDA(dst, b, h) do { _Pragma("unroll") for (int m = 0; m < 4; ++m) _Pragma("unroll") for (int k = 0; k < 2; ++k) dst[m][k] = *(const PG8_LAS bf16x8*)(lds + PG8_SA(b, h) + aoff + m * 2048 + k * 1024); } while (0)
; #define PG8_LDB(dst, b, h) do { _Pragma("unroll") for (int n = 0; n < 2; ++n) _Pragma("unroll") for (int k = 0; k < 2; ++k) dst[n][k] = *(const PG8_LAS bf16x8*)(lds + PG8_SB(b, h) + boff + n * 2048 + k * 1024); } while (0)
; #define PG8_WAIT_V(n) asm volatile("s_waitcnt vmcnt(" #n ")" ::: "memory")
; #define PG8_WAIT_L(n) asm volatile("s_waitcnt lgkmcnt(" #n ")" ::: "memory")
; #define PG8_BAR __builtin_amdgcn_s_barrier()
; #define PG8_SCHED __builtin_amdgcn_sched_barrier(0)
; template <class Epi, class Sched, bool ALIGN_EPI = false, bool SP2 = false, bool I8 = false>
; __device__ __forceinline__ void gemm_phase(PG8_LAS unsigned char* lds, const Gemm g, const Sched& S, const Epi& E) {
;     ...
;             PG8_LDA(At, 0, 1); PG8_STAGE(PG8_SB(0, 0), b2, voffB); PG8_STAGE(PG8_SB(0, 1), b2 + hstep, voffB); PG8_STAGE(PG8_SA(0, 0), a2, voffA);
;             PG8_WAIT_V(8); PG8_WAIT_L(0); PG8_BAR; PG8_MMA(1, 0, At, B0); PG8_MMA(1, 1, At, B1); PG8_BAR; PG8_SCHED;
;             PG8_LDB(B0, 1, 0); PG8_LDB(B1, 1, 1); PG8_SCHED; PG8_LDA(At, 1, 0); PG8_STAGE(PG8_SA(0, 1), a2 + hstep, voffA);
;             PG8_WAIT_V(8); PG8_WAIT_L(0); PG8_BAR; PG8_MMA(0, 0, At, B0); PG8_MMA(0, 1, At, B1); PG8_BAR; PG8_SCHED;
;             PG8_LDA(At, 1, 1); PG8_STAGE(PG8_SB(1, 0), b3, voffB); PG8_STAGE(PG8_SB(1, 1), b3 + hstep, voffB); PG8_STAGE(PG8_SA(1, 0), a3, voffA);
	s_setprio 0
	s_add_i32 s64, s64, s47
	v_lshl_add_u64 v[164:165], s[44:45], 0, v[2:3]
	s_mov_b32 m0, s64
	ds_read_b128 v[184:187], v171 offset:16384
	ds_read_b128 v[188:191], v171 offset:17408
	ds_read_b128 v[204:207], v171 offset:18432
	ds_read_b128 v[208:211], v171 offset:19456
	ds_read_b128 v[212:215], v171 offset:20480
	ds_read_b128 v[216:219], v171 offset:21504
	ds_read_b128 v[220:223], v171 offset:22528
	ds_read_b128 v[224:227], v171 offset:23552
	global_load_lds_dwordx4 v[164:165], off
	s_add_i32 m0, s64, 0x2000
	s_add_u32 s64, s44, 0x80000
	v_lshl_add_u64 v[228:229], s[44:45], 0, v[148:149]
	s_addc_u32 s65, s45, 0
	s_add_i32 s67, s67, s47
	global_load_lds_dwordx4 v[228:229], off
	s_mov_b32 m0, s67
	v_lshl_add_u64 v[242:243], s[48:49], 0, v[150:151]
	global_load_lds_dwordx4 v2, s[64:65]
	s_add_i32 m0, s67, 0x2000
	s_nop 0
	global_load_lds_dwordx4 v148, s[64:65]
	v_lshl_add_u64 v[240:241], s[48:49], 0, v[152:153]
	s_waitcnt vmcnt(6)
	s_waitcnt lgkmcnt(7)
	s_setprio 1
	s_barrier
	v_mfma_i32_16x16x64_i8 v[72:75], v[36:39], v[184:187], v[72:75]
	s_waitcnt lgkmcnt(6)
	v_mfma_i32_16x16x64_i8 v[72:75], v[44:47], v[188:191], v[72:75]
	s_waitcnt lgkmcnt(4)
	v_mfma_i32_16x16x64_i8 v[56:59], v[44:47], v[208:211], v[56:59]
	v_mfma_i32_16x16x64_i8 v[56:59], v[36:39], v[204:207], v[56:59]
	s_waitcnt lgkmcnt(3)
	v_mfma_i32_16x16x64_i8 v[32:35], v[36:39], v[212:215], v[32:35]
	s_waitcnt lgkmcnt(2)
	v_mfma_i32_16x16x64_i8 v[32:35], v[44:47], v[216:219], v[32:35]
	s_waitcnt lgkmcnt(0)
	v_mfma_i32_16x16x64_i8 v[16:19], v[44:47], v[224:227], v[16:19]
	v_mfma_i32_16x16x64_i8 v[16:19], v[36:39], v[220:223], v[16:19]
	v_mfma_i32_16x16x64_i8 v[8:11], v[140:143], v[220:223], v[8:11]
	v_mfma_i32_16x16x64_i8 v[8:11], v[144:147], v[224:227], v[8:11]
	v_mfma_i32_16x16x64_i8 v[24:27], v[144:147], v[216:219], v[24:27]
	v_mfma_i32_16x16x64_i8 v[24:27], v[140:143], v[212:215], v[24:27]
	v_mfma_i32_16x16x64_i8 v[48:51], v[140:143], v[204:207], v[48:51]
	v_mfma_i32_16x16x64_i8 v[48:51], v[144:147], v[208:211], v[48:51]
	v_mfma_i32_16x16x64_i8 v[64:67], v[144:147], v[188:191], v[64:67]
	v_mfma_i32_16x16x64_i8 v[64:67], v[140:143], v[184:187], v[64:67]
	v_mfma_i32_16x16x64_i8 v[36:39], v[160:163], v[184:187], v[68:71]
	v_mfma_i32_16x16x64_i8 v[36:39], v[172:175], v[188:191], v[36:39]
	v_mfma_i32_16x16x64_i8 v[52:55], v[172:175], v[208:211], v[52:55]
	v_mfma_i32_16x16x64_i8 v[52:55], v[160:163], v[204:207], v[52:55]
	v_mfma_i32_16x16x64_i8 v[28:31], v[160:163], v[212:215], v[28:31]
	v_mfma_i32_16x16x64_i8 v[28:31], v[172:175], v[216:219], v[28:31]
	v_mfma_i32_16x16x64_i8 v[12:15], v[172:175], v[224:227], v[12:15]
	v_mfma_i32_16x16x64_i8 v[12:15], v[160:163], v[220:223], v[12:15]
	v_mfma_i32_16x16x64_i8 v[4:7], v[176:179], v[220:223], v[4:7]
	v_mfma_i32_16x16x64_i8 v[4:7], v[180:183], v[224:227], v[4:7]
	v_mfma_i32_16x16x64_i8 v[20:23], v[180:183], v[216:219], v[20:23]
	v_mfma_i32_16x16x64_i8 v[20:23], v[176:179], v[212:215], v[20:23]
	v_mfma_i32_16x16x64_i8 v[40:43], v[176:179], v[204:207], v[40:43]
	v_mfma_i32_16x16x64_i8 v[40:43], v[180:183], v[208:211], v[40:43]
	v_mfma_i32_16x16x64_i8 v[44:47], v[180:183], v[188:191], v[60:63]
	v_mfma_i32_16x16x64_i8 v[44:47], v[176:179], v[184:187], v[44:47]
	s_barrier
	s_setprio 0
	s_mov_b32 m0, s50
	s_nop 0
	global_load_lds_dwordx4 v[240:241], off
	s_mov_b32 m0, s51
	s_nop 0
	global_load_lds_dwordx4 v[242:243], off
	s_add_i32 s64, 0, 0x18000
	s_add_i32 s65, 0, 0x1c000
	v_add_u32_e32 v144, s64, v167
	v_add_u32_e32 v158, s65, v167
	ds_read_b128 v[60:63], v144
	ds_read_b128 v[68:71], v144 offset:1024
	ds_read_b128 v[140:143], v144 offset:2048
	ds_read_b128 v[144:147], v144 offset:3072
	ds_read_b128 v[160:163], v158
	ds_read_b128 v[172:175], v158 offset:1024
	ds_read_b128 v[176:179], v158 offset:2048
	ds_read_b128 v[180:183], v158 offset:3072
	s_add_u32 s48, s48, 0x80000
	s_addc_u32 s49, s49, 0
	s_mov_b32 m0, s52
	ds_read_b128 v[184:187], v171 offset:32768
	ds_read_b128 v[188:191], v171 offset:33792
	ds_read_b128 v[204:207], v171 offset:34816
	ds_read_b128 v[208:211], v171 offset:35840
	ds_read_b128 v[212:215], v171 offset:36864
	ds_read_b128 v[216:219], v171 offset:37888
	ds_read_b128 v[220:223], v171 offset:38912
	ds_read_b128 v[224:227], v171 offset:39936
	global_load_lds_dwordx4 v152, s[48:49]
	s_mov_b32 m0, s53
	s_nop 0
	global_load_lds_dwordx4 v150, s[48:49]
	s_waitcnt vmcnt(8)
	s_waitcnt lgkmcnt(7)
	s_setprio 1
	s_barrier
; #define PG8_STAGE(bufoff, gbase, voff) do { _Pragma("unroll") for (int _i = 0; _i < 2; ++_i) \
;         __builtin_amdgcn_global_load_lds((const unsigned*)((const char*)(gbase) + (voff)[_i]), (PG8_LAS unsigned*)(lds + (bufoff) + ldsw + _i * 8192), 16, 0, 0); } while (0)
; #define PG8_LDA(dst, b, h) do { _Pragma("unroll") for (int m = 0; m < 4; ++m) _Pragma("unroll") for (int k = 0; k < 2; ++k) dst[m][k] = *(const PG8_LAS bf16x8*)(lds + PG8_SA(b, h) + aoff + m * 2048 + k * 1024); } while (0)
; #define PG8_LDB(dst, b, h) do { _Pragma("unroll") for (int n = 0; n < 2; ++n) _Pragma("unroll") for (int k = 0; k < 2; ++k) dst[n][k] = *(const PG8_LAS bf16x8*)(lds + PG8_SB(b, h) + boff + n * 2048 + k * 1024); } while (0)
; #define PG8_WAIT_V(n) asm volatile("s_waitcnt vmcnt(" #n ")" ::: "memory")
; #define PG8_WAIT_L(n) asm volatile("s_waitcnt lgkmcnt(" #n ")" ::: "memory")
; #define PG8_BAR __builtin_amdgcn_s_barrier()
; #define PG8_SCHED __builtin_amdgcn_sched_barrier(0)
; template <class Epi, class Sched, bool ALIGN_EPI = false, bool SP2 = false, bool I8 = false>
; __device__ __forceinline__ void gemm_phase(PG8_LAS unsigned char* lds, const Gemm g, const Sched& S, const Epi& E) {
;     ...
;             PG8_LDB(B0, 1, 0); PG8_LDB(B1, 1, 1); PG8_SCHED; PG8_LDA(At, 1, 0); PG8_STAGE(PG8_SA(0, 1), a2 + hstep, voffA);
;             PG8_WAIT_V(8); PG8_WAIT_L(0); PG8_BAR; PG8_MMA(0, 0, At, B0); PG8_MMA(0, 1, At, B1); PG8_BAR; PG8_SCHED;
;             PG8_LDA(At, 1, 1); PG8_STAGE(PG8_SB(1, 0), b3, voffB); PG8_STAGE(PG8_SB(1, 1), b3 + hstep, voffB); PG8_STAGE(PG8_SA(1, 0), a3, voffA);
;             PG8_WAIT_V(8); PG8_WAIT_L(0); PG8_BAR; PG8_MMA(1, 0, At, B0); PG8_MMA(1, 1, At, B1); PG8_BAR; PG8_SCHED;
	v_mfma_i32_16x16x64_i8 v[136:139], v[60:63], v[184:187], v[136:139]
	s_waitcnt lgkmcnt(6)
	v_mfma_i32_16x16x64_i8 v[136:139], v[68:71], v[188:191], v[136:139]
	s_waitcnt lgkmcnt(4)
	v_mfma_i32_16x16x64_i8 v[120:123], v[68:71], v[208:211], v[120:123]
	v_mfma_i32_16x16x64_i8 v[120:123], v[60:63], v[204:207], v[120:123]
	s_waitcnt lgkmcnt(3)
	v_mfma_i32_16x16x64_i8 v[104:107], v[60:63], v[212:215], v[104:107]
	s_waitcnt lgkmcnt(2)
	v_mfma_i32_16x16x64_i8 v[104:107], v[68:71], v[216:219], v[104:107]
	s_waitcnt lgkmcnt(0)
	v_mfma_i32_16x16x64_i8 v[88:91], v[68:71], v[224:227], v[88:91]
	v_mfma_i32_16x16x64_i8 v[88:91], v[60:63], v[220:223], v[88:91]
	v_mfma_i32_16x16x64_i8 v[80:83], v[140:143], v[220:223], v[80:83]
	v_mfma_i32_16x16x64_i8 v[80:83], v[144:147], v[224:227], v[80:83]
	v_mfma_i32_16x16x64_i8 v[96:99], v[144:147], v[216:219], v[96:99]
	v_mfma_i32_16x16x64_i8 v[96:99], v[140:143], v[212:215], v[96:99]
	v_mfma_i32_16x16x64_i8 v[112:115], v[140:143], v[204:207], v[112:115]
	v_mfma_i32_16x16x64_i8 v[112:115], v[144:147], v[208:211], v[112:115]
	v_mfma_i32_16x16x64_i8 v[128:131], v[144:147], v[188:191], v[128:131]
	v_mfma_i32_16x16x64_i8 v[128:131], v[140:143], v[184:187], v[128:131]
	v_mfma_i32_16x16x64_i8 v[132:135], v[160:163], v[184:187], v[132:135]
	v_mfma_i32_16x16x64_i8 v[132:135], v[172:175], v[188:191], v[132:135]
	v_mfma_i32_16x16x64_i8 v[116:119], v[172:175], v[208:211], v[116:119]
	v_mfma_i32_16x16x64_i8 v[116:119], v[160:163], v[204:207], v[116:119]
	v_mfma_i32_16x16x64_i8 v[100:103], v[160:163], v[212:215], v[100:103]
	v_mfma_i32_16x16x64_i8 v[100:103], v[172:175], v[216:219], v[100:103]
	v_mfma_i32_16x16x64_i8 v[84:87], v[172:175], v[224:227], v[84:87]
	v_mfma_i32_16x16x64_i8 v[84:87], v[160:163], v[220:223], v[84:87]
	v_mfma_i32_16x16x64_i8 v[76:79], v[176:179], v[220:223], v[76:79]
	v_mfma_i32_16x16x64_i8 v[76:79], v[180:183], v[224:227], v[76:79]
	v_mfma_i32_16x16x64_i8 v[92:95], v[180:183], v[216:219], v[92:95]
	v_mfma_i32_16x16x64_i8 v[92:95], v[176:179], v[212:215], v[92:95]
	v_mfma_i32_16x16x64_i8 v[108:111], v[176:179], v[204:207], v[108:111]
	v_mfma_i32_16x16x64_i8 v[108:111], v[180:183], v[208:211], v[108:111]
	v_mfma_i32_16x16x64_i8 v[124:127], v[180:183], v[188:191], v[124:127]
	v_mfma_i32_16x16x64_i8 v[124:127], v[176:179], v[184:187], v[124:127]
	s_barrier
	s_setprio 0
	s_add_i32 s48, s64, s47
	v_lshl_add_u64 v[164:165], v[164:165], 0, s[84:85]
	s_mov_b32 m0, s48
	ds_read_b128 v[184:187], v171 offset:49152
	ds_read_b128 v[188:191], v171 offset:50176
	ds_read_b128 v[204:207], v171 offset:51200
	ds_read_b128 v[208:211], v171 offset:52224
	ds_read_b128 v[212:215], v171 offset:53248
	ds_read_b128 v[216:219], v171 offset:54272
	ds_read_b128 v[220:223], v171 offset:55296
	ds_read_b128 v[224:227], v171 offset:56320
	global_load_lds_dwordx4 v[164:165], off
	s_add_i32 m0, s48, 0x2000
	s_add_u32 s44, s44, 0x80080
	v_lshl_add_u64 v[164:165], v[228:229], 0, s[84:85]
	s_addc_u32 s45, s45, 0
	s_add_i32 s48, s65, s47
	global_load_lds_dwordx4 v[164:165], off
	s_mov_b32 m0, s48
	s_nop 0
	global_load_lds_dwordx4 v2, s[44:45]
	s_add_i32 m0, s48, 0x2000
	s_nop 0
	global_load_lds_dwordx4 v148, s[44:45]
	s_cmp_eq_u32 s61, 28
	s_cbranch_scc0 .Ldefer_1591_body
	v_lshl_add_u64 v[164:165], v[240:241], 0, s[84:85]
	s_mov_b32 m0, s54
	s_nop 0
	global_load_lds_dwordx4 v[164:165], off
	v_lshl_add_u64 v[164:165], v[242:243], 0, s[84:85]
	s_mov_b32 m0, s55
	s_nop 0
	global_load_lds_dwordx4 v[164:165], off
.Ldefer_1591_body:
	s_waitcnt vmcnt(6)
	s_waitcnt lgkmcnt(7)
	s_setprio 1
	s_barrier
	v_mfma_i32_16x16x64_i8 v[72:75], v[60:63], v[184:187], v[72:75]
	s_waitcnt lgkmcnt(6)
	v_mfma_i32_16x16x64_i8 v[72:75], v[68:71], v[188:191], v[72:75]
	s_waitcnt lgkmcnt(4)
	v_mfma_i32_16x16x64_i8 v[56:59], v[68:71], v[208:211], v[56:59]
	v_mfma_i32_16x16x64_i8 v[56:59], v[60:63], v[204:207], v[56:59]
	s_waitcnt lgkmcnt(3)
	v_mfma_i32_16x16x64_i8 v[32:35], v[60:63], v[212:215], v[32:35]
	s_waitcnt lgkmcnt(2)
	v_mfma_i32_16x16x64_i8 v[32:35], v[68:71], v[216:219], v[32:35]
	s_waitcnt lgkmcnt(0)
	v_mfma_i32_16x16x64_i8 v[16:19], v[68:71], v[224:227], v[16:19]
	v_mfma_i32_16x16x64_i8 v[16:19], v[60:63], v[220:223], v[16:19]
	v_mfma_i32_16x16x64_i8 v[8:11], v[140:143], v[220:223], v[8:11]
	v_mfma_i32_16x16x64_i8 v[8:11], v[144:147], v[224:227], v[8:11]
	v_mfma_i32_16x16x64_i8 v[24:27], v[144:147], v[216:219], v[24:27]
	v_mfma_i32_16x16x64_i8 v[24:27], v[140:143], v[212:215], v[24:27]
	v_mfma_i32_16x16x64_i8 v[48:51], v[140:143], v[204:207], v[48:51]
	v_mfma_i32_16x16x64_i8 v[48:51], v[144:147], v[208:211], v[48:51]
	v_mfma_i32_16x16x64_i8 v[64:67], v[144:147], v[188:191], v[64:67]
	v_mfma_i32_16x16x64_i8 v[64:67], v[140:143], v[184:187], v[64:67]
	v_mfma_i32_16x16x64_i8 v[36:39], v[160:163], v[184:187], v[36:39]
	v_mfma_i32_16x16x64_i8 v[68:71], v[172:175], v[188:191], v[36:39]
	v_mfma_i32_16x16x64_i8 v[36:39], v[172:175], v[208:211], v[52:55]
	v_mfma_i32_16x16x64_i8 v[52:55], v[160:163], v[204:207], v[36:39]
	v_mfma_i32_16x16x64_i8 v[28:31], v[160:163], v[212:215], v[28:31]
	v_mfma_i32_16x16x64_i8 v[28:31], v[172:175], v[216:219], v[28:31]
	v_mfma_i32_16x16x64_i8 v[12:15], v[172:175], v[224:227], v[12:15]
	v_mfma_i32_16x16x64_i8 v[12:15], v[160:163], v[220:223], v[12:15]
	v_mfma_i32_16x16x64_i8 v[4:7], v[176:179], v[220:223], v[4:7]
	v_mfma_i32_16x16x64_i8 v[4:7], v[180:183], v[224:227], v[4:7]
	v_mfma_i32_16x16x64_i8 v[20:23], v[180:183], v[216:219], v[20:23]
	v_mfma_i32_16x16x64_i8 v[20:23], v[176:179], v[212:215], v[20:23]
	v_mfma_i32_16x16x64_i8 v[36:39], v[176:179], v[204:207], v[40:43]
	v_mfma_i32_16x16x64_i8 v[40:43], v[180:183], v[208:211], v[36:39]
	v_mfma_i32_16x16x64_i8 v[36:39], v[180:183], v[188:191], v[44:47]
	v_mfma_i32_16x16x64_i8 v[60:63], v[176:179], v[184:187], v[36:39]
	s_barrier
	s_setprio 0
	s_add_i32 s61, s61, 2
	s_add_u32 s40, s40, 0x100
	s_addc_u32 s41, s41, 0
	s_add_u32 s59, s59, 0x100
	s_addc_u32 s60, s60, 0
	s_cmp_gt_u32 s61, 29
	s_cbranch_scc0 .LBB0_1591

; #define PG8_STAGE(bufoff, gbase, voff) do { _Pragma("unroll") for (int _i = 0; _i < 2; ++_i) \
;         __builtin_amdgcn_global_load_lds((const unsigned*)((const char*)(gbase) + (voff)[_i]), (PG8_LAS unsigned*)(lds + (bufoff) + ldsw + _i * 8192), 16, 0, 0); } while (0)
; #define PG8_LDA(dst, b, h) do { _Pragma("unroll") for (int m = 0; m < 4; ++m) _Pragma("unroll") for (int k = 0; k < 2; ++k) dst[m][k] = *(const PG8_LAS bf16x8*)(lds + PG8_SA(b, h) + aoff + m * 2048 + k * 1024); } while (0)
; #define PG8_LDB(dst, b, h) do { _Pragma("unroll") for (int n = 0; n < 2; ++n) _Pragma("unroll") for (int k = 0; k < 2; ++k) dst[n][k] = *(const PG8_LAS bf16x8*)(lds + PG8_SB(b, h) + boff + n * 2048 + k * 1024); } while (0)
; #define PG8_WAIT_V(n) asm volatile("s_waitcnt vmcnt(" #n ")" ::: "memory")
; #define PG8_WAIT_L(n) asm volatile("s_waitcnt lgkmcnt(" #n ")" ::: "memory")
; #define PG8_BAR __builtin_amdgcn_s_barrier()
; #define PG8_SCHED __builtin_amdgcn_sched_barrier(0)
; template <class Epi, class Sched, bool ALIGN_EPI = false, bool SP2 = false, bool I8 = false>
; __device__ __forceinline__ void gemm_phase(PG8_LAS unsigned char* lds, const Gemm g, const Sched& S, const Epi& E) {
;     ...
;             const char* a1 = cA + (size_t)(t + 1) * kstep;
;             const char* a2 = last ? nA : cA + (size_t)(t + 2) * kstep; const char* b2 = last ? nB : cB + (size_t)(t + 2) * kstep;
;             const char* a3 = a2 + kstep; const char* b3 = b2 + kstep;
;             if (last && has_next) S.a_ready(nxt);
;             if constexpr (SP2) {
;             PG8_LDB(B0, 0, 0); PG8_LDB(B1, 0, 1); PG8_SCHED; PG8_LDA(At, 0, 0); PG8_STAGE(PG8_SA(1, 1), a1 + hstep, voffA);
;             PG8_WAIT_V(8); PG8_WAIT_L(0); PG8_BAR; PG8_MMA(0, 0, At, B0); PG8_MMA(0, 1, At, B1); PG8_BAR; PG8_SCHED;
;     ...
;         for (int a = 0; a < 2; ++a)
; #pragma unroll
;             for (int b = 0; b < 2; ++b)
; #pragma unroll
;                 for (int m = 0; m < 4; ++m)
; #pragma unroll
;                     for (int n = 0; n < 2; ++n) acc[a][b][m][n] = (acc_t){0, 0, 0, 0};
.LBB0_1621:
	v_mov_b32_e32 v127, 0
	s_andn2_b64 vcc, exec, s[26:27]
	v_mov_b32_e32 v126, v127
	v_mov_b32_e32 v125, v127
	v_mov_b32_e32 v124, v127
	v_mov_b32_e32 v131, v127
	v_mov_b32_e32 v130, v127
	v_mov_b32_e32 v129, v127
	v_mov_b32_e32 v128, v127
	v_mov_b32_e32 v115, v127
	v_mov_b32_e32 v114, v127
	v_mov_b32_e32 v113, v127
	v_mov_b32_e32 v112, v127
	v_mov_b32_e32 v111, v127
	v_mov_b32_e32 v110, v127
	v_mov_b32_e32 v109, v127
	v_mov_b32_e32 v108, v127
	v_mov_b32_e32 v99, v127
	v_mov_b32_e32 v98, v127
	v_mov_b32_e32 v97, v127
	v_mov_b32_e32 v96, v127
	v_mov_b32_e32 v95, v127
	v_mov_b32_e32 v94, v127
	v_mov_b32_e32 v93, v127
	v_mov_b32_e32 v92, v127
	v_mov_b32_e32 v83, v127
	v_mov_b32_e32 v82, v127
	v_mov_b32_e32 v81, v127
	v_mov_b32_e32 v80, v127
	v_mov_b32_e32 v79, v127
	v_mov_b32_e32 v78, v127
	v_mov_b32_e32 v77, v127
	v_mov_b32_e32 v76, v127
	v_mov_b32_e32 v123, v127
	v_mov_b32_e32 v122, v127
	v_mov_b32_e32 v121, v127
	v_mov_b32_e32 v120, v127
	v_mov_b32_e32 v119, v127
	v_mov_b32_e32 v118, v127
	v_mov_b32_e32 v117, v127
	v_mov_b32_e32 v116, v127
	v_mov_b32_e32 v107, v127
	v_mov_b32_e32 v106, v127
	v_mov_b32_e32 v105, v127
	v_mov_b32_e32 v104, v127
	v_mov_b32_e32 v103, v127
	v_mov_b32_e32 v102, v127
	v_mov_b32_e32 v101, v127
	v_mov_b32_e32 v100, v127
	v_mov_b32_e32 v91, v127
	v_mov_b32_e32 v90, v127
	v_mov_b32_e32 v89, v127
	v_mov_b32_e32 v88, v127
	v_mov_b32_e32 v87, v127
	v_mov_b32_e32 v86, v127
	v_mov_b32_e32 v85, v127
	v_mov_b32_e32 v84, v127
	v_mov_b32_e32 v75, v127
	v_mov_b32_e32 v74, v127
	v_mov_b32_e32 v73, v127
	v_mov_b32_e32 v72, v127
	v_mov_b32_e32 v71, v127
	v_mov_b32_e32 v70, v127
	v_mov_b32_e32 v69, v127
	v_mov_b32_e32 v68, v127
	v_mov_b32_e32 v67, v127
	v_mov_b32_e32 v66, v127
	v_mov_b32_e32 v65, v127
	v_mov_b32_e32 v64, v127
	v_mov_b32_e32 v63, v127
	v_mov_b32_e32 v62, v127
	v_mov_b32_e32 v61, v127
	v_mov_b32_e32 v60, v127
	v_mov_b32_e32 v51, v127
	v_mov_b32_e32 v50, v127
	v_mov_b32_e32 v49, v127
	v_mov_b32_e32 v48, v127
	v_mov_b32_e32 v47, v127
	v_mov_b32_e32 v46, v127
	v_mov_b32_e32 v45, v127
	v_mov_b32_e32 v44, v127
	v_mov_b32_e32 v35, v127
	v_mov_b32_e32 v34, v127
	v_mov_b32_e32 v33, v127
	v_mov_b32_e32 v32, v127
	v_mov_b32_e32 v31, v127
	v_mov_b32_e32 v30, v127
	v_mov_b32_e32 v29, v127
	v_mov_b32_e32 v28, v127
	v_mov_b32_e32 v19, v127
	v_mov_b32_e32 v18, v127
	v_mov_b32_e32 v17, v127
	v_mov_b32_e32 v16, v127
	v_mov_b32_e32 v15, v127
	v_mov_b32_e32 v14, v127
	v_mov_b32_e32 v13, v127
	v_mov_b32_e32 v12, v127
	v_mov_b32_e32 v59, v127
	v_mov_b32_e32 v58, v127
	v_mov_b32_e32 v57, v127
	v_mov_b32_e32 v56, v127
	v_mov_b32_e32 v55, v127
	v_mov_b32_e32 v54, v127
	v_mov_b32_e32 v53, v127
	v_mov_b32_e32 v52, v127
	v_mov_b32_e32 v43, v127
	v_mov_b32_e32 v42, v127
	v_mov_b32_e32 v41, v127
	v_mov_b32_e32 v40, v127
	v_mov_b32_e32 v39, v127
	v_mov_b32_e32 v38, v127
	v_mov_b32_e32 v37, v127
	v_mov_b32_e32 v36, v127
	v_mov_b32_e32 v27, v127
	v_mov_b32_e32 v26, v127
	v_mov_b32_e32 v25, v127
	v_mov_b32_e32 v24, v127
	v_mov_b32_e32 v23, v127
	v_mov_b32_e32 v22, v127
	v_mov_b32_e32 v21, v127
	v_mov_b32_e32 v20, v127
	v_mov_b32_e32 v11, v127
	v_mov_b32_e32 v10, v127
	v_mov_b32_e32 v9, v127
	v_mov_b32_e32 v8, v127
	v_mov_b32_e32 v7, v127
	v_mov_b32_e32 v6, v127
	v_mov_b32_e32 v5, v127
	v_mov_b32_e32 v4, v127
	s_cbranch_vccnz .LBB0_1625
	s_add_u32 s44, s44, 0x80
	s_addc_u32 s45, s45, 0
	s_add_u32 s65, s48, 0x100
	s_addc_u32 s67, s49, 0
	s_mov_b32 s48, 0
	s_add_i32 s72, s48, 2
	s_add_u32 s73, s44, 0x80
	s_addc_u32 s49, s45, 0
	s_add_i32 s86, 0, 0x10000
	s_cmp_eq_u32 s57, s48
	s_cselect_b32 s49, s13, s49
	s_cselect_b32 s48, s12, s73
	s_cselect_b32 s77, s41, s67
	s_cselect_b32 s76, s40, s65
	s_add_i32 s73, 0, 0x14000
	v_add_u32_e32 v158, s86, v143
	v_add_u32_e32 v174, s73, v143
	ds_read_b128 v[146:149], v158
	ds_read_b128 v[150:153], v158 offset:1024
	ds_read_b128 v[154:157], v158 offset:2048
	ds_read_b128 v[158:161], v158 offset:3072
	ds_read_b128 v[162:165], v174
	ds_read_b128 v[166:169], v174 offset:1024
	ds_read_b128 v[170:173], v174 offset:2048
	ds_read_b128 v[174:177], v174 offset:3072
	v_lshl_add_u64 v[190:191], s[44:45], 0, v[138:139]
	s_add_i32 m0, s47, 0xc000
	ds_read_b128 v[178:181], v145
	ds_read_b128 v[182:185], v145 offset:1024
	ds_read_b128 v[186:189], v145 offset:2048
	ds_read_b128 v[204:207], v145 offset:3072
	ds_read_b128 v[208:211], v145 offset:4096
	ds_read_b128 v[212:215], v145 offset:5120
	ds_read_b128 v[216:219], v145 offset:6144
	ds_read_b128 v[220:223], v145 offset:7168
	global_load_lds_dwordx4 v[190:191], off
	v_lshl_add_u64 v[190:191], s[44:45], 0, v[140:141]
	s_add_i32 m0, s47, 0xe000
	s_nop 0
	global_load_lds_dwordx4 v[190:191], off
	s_waitcnt vmcnt(8)
	s_waitcnt lgkmcnt(7)
	s_setprio 1
	s_barrier
; #define PG8_STAGE(bufoff, gbase, voff) do { _Pragma("unroll") for (int _i = 0; _i < 2; ++_i) \
;         __builtin_amdgcn_global_load_lds((const unsigned*)((const char*)(gbase) + (voff)[_i]), (PG8_LAS unsigned*)(lds + (bufoff) + ldsw + _i * 8192), 16, 0, 0); } while (0)
; #define PG8_LDA(dst, b, h) do { _Pragma("unroll") for (int m = 0; m < 4; ++m) _Pragma("unroll") for (int k = 0; k < 2; ++k) dst[m][k] = *(const PG8_LAS bf16x8*)(lds + PG8_SA(b, h) + aoff + m * 2048 + k * 1024); } while (0)
; #define PG8_WAIT_V(n) asm volatile("s_waitcnt vmcnt(" #n ")" ::: "memory")
; #define PG8_WAIT_L(n) asm volatile("s_waitcnt lgkmcnt(" #n ")" ::: "memory")
; #define PG8_BAR __builtin_amdgcn_s_barrier()
; #define PG8_SCHED __builtin_amdgcn_sched_barrier(0)
; template <class Epi, class Sched, bool ALIGN_EPI = false, bool SP2 = false, bool I8 = false>
; __device__ __forceinline__ void gemm_phase(PG8_LAS unsigned char* lds, const Gemm g, const Sched& S, const Epi& E) {
;     ...
;             PG8_WAIT_V(8); PG8_WAIT_L(0); PG8_BAR; PG8_MMA(0, 0, At, B0); PG8_MMA(0, 1, At, B1); PG8_BAR; PG8_SCHED;
;             PG8_LDA(At, 0, 1); PG8_STAGE(PG8_SB(0, 0), b2, voffB); PG8_STAGE(PG8_SB(0, 1), b2 + hstep, voffB); PG8_STAGE(PG8_SA(0, 0), a2, voffA);
;             PG8_WAIT_V(8); PG8_WAIT_L(0); PG8_BAR; PG8_MMA(1, 0, At, B0); PG8_MMA(1, 1, At, B1); PG8_BAR; PG8_SCHED;
	v_mfma_f32_16x16x32_bf16 v[124:127], v[146:149], v[178:181], 0
	s_waitcnt lgkmcnt(6)
	v_mfma_f32_16x16x32_bf16 v[124:127], v[150:153], v[182:185], v[124:127]
	s_waitcnt lgkmcnt(4)
	v_mfma_f32_16x16x32_bf16 v[112:115], v[150:153], v[204:207], 0
	v_mfma_f32_16x16x32_bf16 v[112:115], v[146:149], v[186:189], v[112:115]
	s_waitcnt lgkmcnt(3)
	v_mfma_f32_16x16x32_bf16 v[96:99], v[146:149], v[208:211], 0
	s_waitcnt lgkmcnt(2)
	v_mfma_f32_16x16x32_bf16 v[96:99], v[150:153], v[212:215], v[96:99]
	s_waitcnt lgkmcnt(0)
	v_mfma_f32_16x16x32_bf16 v[80:83], v[150:153], v[220:223], 0
	v_mfma_f32_16x16x32_bf16 v[80:83], v[146:149], v[216:219], v[80:83]
	v_mfma_f32_16x16x32_bf16 v[76:79], v[154:157], v[216:219], 0
	v_mfma_f32_16x16x32_bf16 v[76:79], v[158:161], v[220:223], v[76:79]
	v_mfma_f32_16x16x32_bf16 v[92:95], v[158:161], v[212:215], 0
	v_mfma_f32_16x16x32_bf16 v[92:95], v[154:157], v[208:211], v[92:95]
	v_mfma_f32_16x16x32_bf16 v[108:111], v[154:157], v[186:189], 0
	v_mfma_f32_16x16x32_bf16 v[108:111], v[158:161], v[204:207], v[108:111]
	v_mfma_f32_16x16x32_bf16 v[128:131], v[158:161], v[182:185], 0
	v_mfma_f32_16x16x32_bf16 v[128:131], v[154:157], v[178:181], v[128:131]
	v_mfma_f32_16x16x32_bf16 v[120:123], v[162:165], v[178:181], 0
	v_mfma_f32_16x16x32_bf16 v[120:123], v[166:169], v[182:185], v[120:123]
	v_mfma_f32_16x16x32_bf16 v[104:107], v[166:169], v[204:207], 0
	v_mfma_f32_16x16x32_bf16 v[104:107], v[162:165], v[186:189], v[104:107]
	v_mfma_f32_16x16x32_bf16 v[88:91], v[162:165], v[208:211], 0
	v_mfma_f32_16x16x32_bf16 v[88:91], v[166:169], v[212:215], v[88:91]
	v_mfma_f32_16x16x32_bf16 v[72:75], v[166:169], v[220:223], 0
	v_mfma_f32_16x16x32_bf16 v[72:75], v[162:165], v[216:219], v[72:75]
	v_mfma_f32_16x16x32_bf16 v[68:71], v[170:173], v[216:219], 0
	v_mfma_f32_16x16x32_bf16 v[68:71], v[174:177], v[220:223], v[68:71]
	v_mfma_f32_16x16x32_bf16 v[84:87], v[174:177], v[212:215], 0
	v_mfma_f32_16x16x32_bf16 v[84:87], v[170:173], v[208:211], v[84:87]
	v_mfma_f32_16x16x32_bf16 v[100:103], v[170:173], v[186:189], 0
	v_mfma_f32_16x16x32_bf16 v[100:103], v[174:177], v[204:207], v[100:103]
	v_mfma_f32_16x16x32_bf16 v[116:119], v[174:177], v[182:185], 0
	v_mfma_f32_16x16x32_bf16 v[116:119], v[170:173], v[178:181], v[116:119]
	s_barrier
	s_setprio 0
	s_add_i32 s86, s86, s28
	v_lshl_add_u64 v[190:191], s[76:77], 0, v[2:3]
	s_mov_b32 m0, s86
	ds_read_b128 v[178:181], v145 offset:16384
	ds_read_b128 v[182:185], v145 offset:17408
	ds_read_b128 v[186:189], v145 offset:18432
	ds_read_b128 v[204:207], v145 offset:19456
	ds_read_b128 v[208:211], v145 offset:20480
	ds_read_b128 v[212:215], v145 offset:21504
	ds_read_b128 v[216:219], v145 offset:22528
	ds_read_b128 v[220:223], v145 offset:23552
	global_load_lds_dwordx4 v[190:191], off
	s_add_i32 m0, s86, 0x2000
	v_lshl_add_u64 v[224:225], s[76:77], 0, v[136:137]
	s_add_u32 s76, s76, s18
	s_addc_u32 s77, s77, s19
	s_add_i32 s73, s73, s28
	global_load_lds_dwordx4 v[224:225], off
	v_lshl_add_u64 v[226:227], s[76:77], 0, v[2:3]
	s_mov_b32 m0, s73
	v_lshl_add_u64 v[228:229], s[76:77], 0, v[136:137]
	global_load_lds_dwordx4 v[226:227], off
	s_add_i32 m0, s73, 0x2000
	v_lshl_add_u64 v[240:241], s[48:49], 0, v[132:133]
	global_load_lds_dwordx4 v[228:229], off
	v_lshl_add_u64 v[242:243], s[48:49], 0, v[134:135]
	s_waitcnt vmcnt(6)
	s_waitcnt lgkmcnt(7)
	s_setprio 1
	s_barrier
	v_mfma_f32_16x16x32_bf16 v[64:67], v[146:149], v[178:181], 0
	s_waitcnt lgkmcnt(6)
	v_mfma_f32_16x16x32_bf16 v[64:67], v[150:153], v[182:185], v[64:67]
	s_waitcnt lgkmcnt(4)
	v_mfma_f32_16x16x32_bf16 v[48:51], v[150:153], v[204:207], 0
	v_mfma_f32_16x16x32_bf16 v[48:51], v[146:149], v[186:189], v[48:51]
	s_waitcnt lgkmcnt(3)
	v_mfma_f32_16x16x32_bf16 v[32:35], v[146:149], v[208:211], 0
	s_waitcnt lgkmcnt(2)
	v_mfma_f32_16x16x32_bf16 v[32:35], v[150:153], v[212:215], v[32:35]
	s_waitcnt lgkmcnt(0)
	v_mfma_f32_16x16x32_bf16 v[16:19], v[150:153], v[220:223], 0
	v_mfma_f32_16x16x32_bf16 v[16:19], v[146:149], v[216:219], v[16:19]
	v_mfma_f32_16x16x32_bf16 v[12:15], v[154:157], v[216:219], 0
	v_mfma_f32_16x16x32_bf16 v[12:15], v[158:161], v[220:223], v[12:15]
	v_mfma_f32_16x16x32_bf16 v[28:31], v[158:161], v[212:215], 0
	v_mfma_f32_16x16x32_bf16 v[28:31], v[154:157], v[208:211], v[28:31]
	v_mfma_f32_16x16x32_bf16 v[44:47], v[154:157], v[186:189], 0
	v_mfma_f32_16x16x32_bf16 v[44:47], v[158:161], v[204:207], v[44:47]
	v_mfma_f32_16x16x32_bf16 v[60:63], v[158:161], v[182:185], 0
	v_mfma_f32_16x16x32_bf16 v[60:63], v[154:157], v[178:181], v[60:63]
	v_mfma_f32_16x16x32_bf16 v[56:59], v[162:165], v[178:181], 0
	v_mfma_f32_16x16x32_bf16 v[56:59], v[166:169], v[182:185], v[56:59]
	v_mfma_f32_16x16x32_bf16 v[40:43], v[166:169], v[204:207], 0
	v_mfma_f32_16x16x32_bf16 v[40:43], v[162:165], v[186:189], v[40:43]
	v_mfma_f32_16x16x32_bf16 v[24:27], v[162:165], v[208:211], 0
	v_mfma_f32_16x16x32_bf16 v[24:27], v[166:169], v[212:215], v[24:27]
	v_mfma_f32_16x16x32_bf16 v[8:11], v[166:169], v[220:223], 0
	v_mfma_f32_16x16x32_bf16 v[8:11], v[162:165], v[216:219], v[8:11]
	v_mfma_f32_16x16x32_bf16 v[4:7], v[170:173], v[216:219], 0
	v_mfma_f32_16x16x32_bf16 v[4:7], v[174:177], v[220:223], v[4:7]
	v_mfma_f32_16x16x32_bf16 v[20:23], v[174:177], v[212:215], 0
	v_mfma_f32_16x16x32_bf16 v[20:23], v[170:173], v[208:211], v[20:23]
	v_mfma_f32_16x16x32_bf16 v[36:39], v[170:173], v[186:189], 0
	v_mfma_f32_16x16x32_bf16 v[36:39], v[174:177], v[204:207], v[36:39]
	v_mfma_f32_16x16x32_bf16 v[52:55], v[174:177], v[182:185], 0
	v_mfma_f32_16x16x32_bf16 v[52:55], v[170:173], v[178:181], v[52:55]
	s_barrier
; #define PG8_STAGE(bufoff, gbase, voff) do { _Pragma("unroll") for (int _i = 0; _i < 2; ++_i) \
;         __builtin_amdgcn_global_load_lds((const unsigned*)((const char*)(gbase) + (voff)[_i]), (PG8_LAS unsigned*)(lds + (bufoff) + ldsw + _i * 8192), 16, 0, 0); } while (0)
; #define PG8_LDA(dst, b, h) do { _Pragma("unroll") for (int m = 0; m < 4; ++m) _Pragma("unroll") for (int k = 0; k < 2; ++k) dst[m][k] = *(const PG8_LAS bf16x8*)(lds + PG8_SA(b, h) + aoff + m * 2048 + k * 1024); } while (0)
; #define PG8_LDB(dst, b, h) do { _Pragma("unroll") for (int n = 0; n < 2; ++n) _Pragma("unroll") for (int k = 0; k < 2; ++k) dst[n][k] = *(const PG8_LAS bf16x8*)(lds + PG8_SB(b, h) + boff + n * 2048 + k * 1024); } while (0)
; #define PG8_WAIT_V(n) asm volatile("s_waitcnt vmcnt(" #n ")" ::: "memory")
; #define PG8_WAIT_L(n) asm volatile("s_waitcnt lgkmcnt(" #n ")" ::: "memory")
; #define PG8_BAR __builtin_amdgcn_s_barrier()
; #define PG8_SCHED __builtin_amdgcn_sched_barrier(0)
; template <class Epi, class Sched, bool ALIGN_EPI = false, bool SP2 = false, bool I8 = false>
; __device__ __forceinline__ void gemm_phase(PG8_LAS unsigned char* lds, const Gemm g, const Sched& S, const Epi& E) {
;     ...
;             PG8_LDB(B0, 1, 0); PG8_LDB(B1, 1, 1); PG8_SCHED; PG8_LDA(At, 1, 0); PG8_STAGE(PG8_SA(0, 1), a2 + hstep, voffA);
;             PG8_WAIT_V(8); PG8_WAIT_L(0); PG8_BAR; PG8_MMA(0, 0, At, B0); PG8_MMA(0, 1, At, B1); PG8_BAR; PG8_SCHED;
;             PG8_LDA(At, 1, 1); PG8_STAGE(PG8_SB(1, 0), b3, voffB); PG8_STAGE(PG8_SB(1, 1), b3 + hstep, voffB); PG8_STAGE(PG8_SA(1, 0), a3, voffA);
;             PG8_WAIT_V(8); PG8_WAIT_L(0); PG8_BAR; PG8_MMA(1, 0, At, B0); PG8_MMA(1, 1, At, B1); PG8_BAR; PG8_SCHED;
	s_setprio 0
	s_mov_b32 m0, s47
	s_nop 0
	global_load_lds_dwordx4 v[240:241], off
	s_mov_b32 m0, s50
	s_nop 0
	global_load_lds_dwordx4 v[242:243], off
	s_add_i32 s73, 0, 0x18000
	s_add_i32 s76, 0, 0x1c000
	v_add_u32_e32 v158, s73, v143
	v_add_u32_e32 v174, s76, v143
	ds_read_b128 v[146:149], v158
	ds_read_b128 v[150:153], v158 offset:1024
	ds_read_b128 v[154:157], v158 offset:2048
	ds_read_b128 v[158:161], v158 offset:3072
	ds_read_b128 v[162:165], v174
	ds_read_b128 v[166:169], v174 offset:1024
	ds_read_b128 v[170:173], v174 offset:2048
	ds_read_b128 v[174:177], v174 offset:3072
	s_add_u32 s48, s48, s18
	s_addc_u32 s49, s49, s19
	s_mov_b32 m0, s51
	ds_read_b128 v[178:181], v145 offset:32768
	ds_read_b128 v[182:185], v145 offset:33792
	ds_read_b128 v[186:189], v145 offset:34816
	ds_read_b128 v[204:207], v145 offset:35840
	ds_read_b128 v[208:211], v145 offset:36864
	ds_read_b128 v[212:215], v145 offset:37888
	ds_read_b128 v[216:219], v145 offset:38912
	ds_read_b128 v[220:223], v145 offset:39936
	global_load_lds_dwordx4 v132, s[48:49]
	s_mov_b32 m0, s52
	s_nop 0
	global_load_lds_dwordx4 v134, s[48:49]
	s_waitcnt vmcnt(8)
	s_waitcnt lgkmcnt(7)
	s_setprio 1
	s_barrier
	v_mfma_f32_16x16x32_bf16 v[124:127], v[146:149], v[178:181], v[124:127]
	s_waitcnt lgkmcnt(6)
	v_mfma_f32_16x16x32_bf16 v[124:127], v[150:153], v[182:185], v[124:127]
	s_waitcnt lgkmcnt(4)
	v_mfma_f32_16x16x32_bf16 v[112:115], v[150:153], v[204:207], v[112:115]
	v_mfma_f32_16x16x32_bf16 v[112:115], v[146:149], v[186:189], v[112:115]
	s_waitcnt lgkmcnt(3)
	v_mfma_f32_16x16x32_bf16 v[96:99], v[146:149], v[208:211], v[96:99]
	s_waitcnt lgkmcnt(2)
	v_mfma_f32_16x16x32_bf16 v[96:99], v[150:153], v[212:215], v[96:99]
	s_waitcnt lgkmcnt(0)
	v_mfma_f32_16x16x32_bf16 v[80:83], v[150:153], v[220:223], v[80:83]
	v_mfma_f32_16x16x32_bf16 v[80:83], v[146:149], v[216:219], v[80:83]
	v_mfma_f32_16x16x32_bf16 v[76:79], v[154:157], v[216:219], v[76:79]
	v_mfma_f32_16x16x32_bf16 v[76:79], v[158:161], v[220:223], v[76:79]
	v_mfma_f32_16x16x32_bf16 v[92:95], v[158:161], v[212:215], v[92:95]
	v_mfma_f32_16x16x32_bf16 v[92:95], v[154:157], v[208:211], v[92:95]
	v_mfma_f32_16x16x32_bf16 v[108:111], v[154:157], v[186:189], v[108:111]
	v_mfma_f32_16x16x32_bf16 v[108:111], v[158:161], v[204:207], v[108:111]
	v_mfma_f32_16x16x32_bf16 v[128:131], v[158:161], v[182:185], v[128:131]
	v_mfma_f32_16x16x32_bf16 v[128:131], v[154:157], v[178:181], v[128:131]
	v_mfma_f32_16x16x32_bf16 v[120:123], v[162:165], v[178:181], v[120:123]
	v_mfma_f32_16x16x32_bf16 v[120:123], v[166:169], v[182:185], v[120:123]
	v_mfma_f32_16x16x32_bf16 v[104:107], v[166:169], v[204:207], v[104:107]
	v_mfma_f32_16x16x32_bf16 v[104:107], v[162:165], v[186:189], v[104:107]
	v_mfma_f32_16x16x32_bf16 v[88:91], v[162:165], v[208:211], v[88:91]
	v_mfma_f32_16x16x32_bf16 v[88:91], v[166:169], v[212:215], v[88:91]
	v_mfma_f32_16x16x32_bf16 v[72:75], v[166:169], v[220:223], v[72:75]
	v_mfma_f32_16x16x32_bf16 v[72:75], v[162:165], v[216:219], v[72:75]
	v_mfma_f32_16x16x32_bf16 v[68:71], v[170:173], v[216:219], v[68:71]
	v_mfma_f32_16x16x32_bf16 v[68:71], v[174:177], v[220:223], v[68:71]
	v_mfma_f32_16x16x32_bf16 v[84:87], v[174:177], v[212:215], v[84:87]
	v_mfma_f32_16x16x32_bf16 v[84:87], v[170:173], v[208:211], v[84:87]
	v_mfma_f32_16x16x32_bf16 v[100:103], v[170:173], v[186:189], v[100:103]
	v_mfma_f32_16x16x32_bf16 v[100:103], v[174:177], v[204:207], v[100:103]
	v_mfma_f32_16x16x32_bf16 v[116:119], v[174:177], v[182:185], v[116:119]
	v_mfma_f32_16x16x32_bf16 v[116:119], v[170:173], v[178:181], v[116:119]
	s_barrier
	s_setprio 0
	s_add_i32 s48, s73, s28
	v_lshl_add_u64 v[190:191], v[190:191], 0, s[84:85]
	s_mov_b32 m0, s48
	ds_read_b128 v[178:181], v145 offset:49152
	ds_read_b128 v[182:185], v145 offset:50176
	ds_read_b128 v[186:189], v145 offset:51200
	ds_read_b128 v[204:207], v145 offset:52224
	ds_read_b128 v[208:211], v145 offset:53248
	ds_read_b128 v[212:215], v145 offset:54272
	ds_read_b128 v[216:219], v145 offset:55296
	ds_read_b128 v[220:223], v145 offset:56320
	global_load_lds_dwordx4 v[190:191], off
	v_lshl_add_u64 v[190:191], v[224:225], 0, s[84:85]
	s_add_i32 m0, s48, 0x2000
	s_add_i32 s48, s76, s28
	global_load_lds_dwordx4 v[190:191], off
	v_lshl_add_u64 v[190:191], v[226:227], 0, s[84:85]
	s_mov_b32 m0, s48
	s_nop 0
	global_load_lds_dwordx4 v[190:191], off
	v_lshl_add_u64 v[190:191], v[228:229], 0, s[84:85]
	s_add_i32 m0, s48, 0x2000
	s_nop 0
	global_load_lds_dwordx4 v[190:191], off
	v_lshl_add_u64 v[190:191], v[240:241], 0, s[84:85]
	s_mov_b32 m0, s55
	s_nop 0
	global_load_lds_dwordx4 v[190:191], off
	v_lshl_add_u64 v[190:191], v[242:243], 0, s[84:85]
	s_mov_b32 m0, s56
	s_nop 0
	global_load_lds_dwordx4 v[190:191], off
	s_waitcnt vmcnt(8)
	s_waitcnt lgkmcnt(7)
	s_setprio 1
	s_barrier
; #define PG8_STAGE(bufoff, gbase, voff) do { _Pragma("unroll") for (int _i = 0; _i < 2; ++_i) \
;         __builtin_amdgcn_global_load_lds((const unsigned*)((const char*)(gbase) + (voff)[_i]), (PG8_LAS unsigned*)(lds + (bufoff) + ldsw + _i * 8192), 16, 0, 0); } while (0)
; #define PG8_LDA(dst, b, h) do { _Pragma("unroll") for (int m = 0; m < 4; ++m) _Pragma("unroll") for (int k = 0; k < 2; ++k) dst[m][k] = *(const PG8_LAS bf16x8*)(lds + PG8_SA(b, h) + aoff + m * 2048 + k * 1024); } while (0)
; #define PG8_LDB(dst, b, h) do { _Pragma("unroll") for (int n = 0; n < 2; ++n) _Pragma("unroll") for (int k = 0; k < 2; ++k) dst[n][k] = *(const PG8_LAS bf16x8*)(lds + PG8_SB(b, h) + boff + n * 2048 + k * 1024); } while (0)
; #define PG8_WAIT_V(n) asm volatile("s_waitcnt vmcnt(" #n ")" ::: "memory")
; #define PG8_WAIT_L(n) asm volatile("s_waitcnt lgkmcnt(" #n ")" ::: "memory")
; #define PG8_BAR __builtin_amdgcn_s_barrier()
; #define PG8_SCHED __builtin_amdgcn_sched_barrier(0)
; template <class Epi, class Sched, bool ALIGN_EPI = false, bool SP2 = false, bool I8 = false>
; __device__ __forceinline__ void gemm_phase(PG8_LAS unsigned char* lds, const Gemm g, const Sched& S, const Epi& E) {
;     ...
;             PG8_LDB(B0, 0, 0); PG8_LDB(B1, 0, 1); PG8_SCHED; PG8_LDA(At, 0, 0); PG8_STAGE(PG8_SA(1, 1), a1 + hstep, voffA);
;             PG8_WAIT_V(8); PG8_WAIT_L(0); PG8_BAR; PG8_MMA(0, 0, At, B0); PG8_MMA(0, 1, At, B1); PG8_BAR; PG8_SCHED;
;             PG8_LDA(At, 0, 1); PG8_STAGE(PG8_SB(0, 0), b2, voffB); PG8_STAGE(PG8_SB(0, 1), b2 + hstep, voffB); PG8_STAGE(PG8_SA(0, 0), a2, voffA);
;             PG8_WAIT_V(8); PG8_WAIT_L(0); PG8_BAR; PG8_MMA(1, 0, At, B0); PG8_MMA(1, 1, At, B1); PG8_BAR; PG8_SCHED;
;             PG8_LDB(B0, 1, 0); PG8_LDB(B1, 1, 1); PG8_SCHED; PG8_LDA(At, 1, 0); PG8_STAGE(PG8_SA(0, 1), a2 + hstep, voffA);
;             PG8_WAIT_V(8); PG8_WAIT_L(0); PG8_BAR; PG8_MMA(0, 0, At, B0); PG8_MMA(0, 1, At, B1); PG8_BAR; PG8_SCHED;
;             PG8_LDA(At, 1, 1); PG8_STAGE(PG8_SB(1, 0), b3, voffB); PG8_STAGE(PG8_SB(1, 1), b3 + hstep, voffB); PG8_STAGE(PG8_SA(1, 0), a3, voffA);
;             PG8_WAIT_V(8); PG8_WAIT_L(0); PG8_BAR; PG8_MMA(1, 0, At, B0); PG8_MMA(1, 1, At, B1); PG8_BAR; PG8_SCHED;
	v_mfma_f32_16x16x32_bf16 v[64:67], v[146:149], v[178:181], v[64:67]
	s_waitcnt lgkmcnt(6)
	v_mfma_f32_16x16x32_bf16 v[64:67], v[150:153], v[182:185], v[64:67]
	s_waitcnt lgkmcnt(4)
	v_mfma_f32_16x16x32_bf16 v[48:51], v[150:153], v[204:207], v[48:51]
	v_mfma_f32_16x16x32_bf16 v[48:51], v[146:149], v[186:189], v[48:51]
	s_waitcnt lgkmcnt(3)
	v_mfma_f32_16x16x32_bf16 v[32:35], v[146:149], v[208:211], v[32:35]
	s_waitcnt lgkmcnt(2)
	v_mfma_f32_16x16x32_bf16 v[32:35], v[150:153], v[212:215], v[32:35]
	s_waitcnt lgkmcnt(0)
	v_mfma_f32_16x16x32_bf16 v[16:19], v[150:153], v[220:223], v[16:19]
	v_mfma_f32_16x16x32_bf16 v[16:19], v[146:149], v[216:219], v[16:19]
	v_mfma_f32_16x16x32_bf16 v[12:15], v[154:157], v[216:219], v[12:15]
	v_mfma_f32_16x16x32_bf16 v[12:15], v[158:161], v[220:223], v[12:15]
	v_mfma_f32_16x16x32_bf16 v[28:31], v[158:161], v[212:215], v[28:31]
	v_mfma_f32_16x16x32_bf16 v[28:31], v[154:157], v[208:211], v[28:31]
	v_mfma_f32_16x16x32_bf16 v[44:47], v[154:157], v[186:189], v[44:47]
	v_mfma_f32_16x16x32_bf16 v[44:47], v[158:161], v[204:207], v[44:47]
	v_mfma_f32_16x16x32_bf16 v[60:63], v[158:161], v[182:185], v[60:63]
	v_mfma_f32_16x16x32_bf16 v[60:63], v[154:157], v[178:181], v[60:63]
	v_mfma_f32_16x16x32_bf16 v[56:59], v[162:165], v[178:181], v[56:59]
	v_mfma_f32_16x16x32_bf16 v[56:59], v[166:169], v[182:185], v[56:59]
	v_mfma_f32_16x16x32_bf16 v[40:43], v[166:169], v[204:207], v[40:43]
	v_mfma_f32_16x16x32_bf16 v[40:43], v[162:165], v[186:189], v[40:43]
	v_mfma_f32_16x16x32_bf16 v[24:27], v[162:165], v[208:211], v[24:27]
	v_mfma_f32_16x16x32_bf16 v[24:27], v[166:169], v[212:215], v[24:27]
	v_mfma_f32_16x16x32_bf16 v[8:11], v[166:169], v[220:223], v[8:11]
	v_mfma_f32_16x16x32_bf16 v[8:11], v[162:165], v[216:219], v[8:11]
	v_mfma_f32_16x16x32_bf16 v[4:7], v[170:173], v[216:219], v[4:7]
	v_mfma_f32_16x16x32_bf16 v[4:7], v[174:177], v[220:223], v[4:7]
	v_mfma_f32_16x16x32_bf16 v[20:23], v[174:177], v[212:215], v[20:23]
	v_mfma_f32_16x16x32_bf16 v[20:23], v[170:173], v[208:211], v[20:23]
	v_mfma_f32_16x16x32_bf16 v[36:39], v[170:173], v[186:189], v[36:39]
	v_mfma_f32_16x16x32_bf16 v[36:39], v[174:177], v[204:207], v[36:39]
	v_mfma_f32_16x16x32_bf16 v[52:55], v[174:177], v[182:185], v[52:55]
	v_mfma_f32_16x16x32_bf16 v[52:55], v[170:173], v[178:181], v[52:55]
	s_barrier
	s_setprio 0
	s_add_u32 s44, s44, 0x100
	s_addc_u32 s45, s45, 0
	s_add_u32 s65, s65, 0x100
	s_addc_u32 s67, s67, 0
	s_cmp_ge_i32 s72, s53
	s_mov_b32 s48, s72
	s_cbranch_scc1 .Lkloop_exit_4
.LBB0_1623:
	s_add_i32 s72, s48, 2
	s_add_u32 s73, s44, 0x80
	s_addc_u32 s49, s45, 0
	s_add_i32 s86, 0, 0x10000
	s_cmp_eq_u32 s57, s48
	s_cselect_b32 s49, s13, s49
	s_cselect_b32 s48, s12, s73
	s_cselect_b32 s77, s41, s67
	s_cselect_b32 s76, s40, s65
	s_add_i32 s73, 0, 0x14000
	v_add_u32_e32 v158, s86, v143
	v_add_u32_e32 v174, s73, v143
	ds_read_b128 v[146:149], v158
	ds_read_b128 v[150:153], v158 offset:1024
	ds_read_b128 v[154:157], v158 offset:2048
	ds_read_b128 v[158:161], v158 offset:3072
	ds_read_b128 v[162:165], v174
	ds_read_b128 v[166:169], v174 offset:1024
	ds_read_b128 v[170:173], v174 offset:2048
	ds_read_b128 v[174:177], v174 offset:3072
	v_lshl_add_u64 v[190:191], s[44:45], 0, v[138:139]
	s_add_i32 m0, s47, 0xc000
	ds_read_b128 v[178:181], v145
	ds_read_b128 v[182:185], v145 offset:1024
	ds_read_b128 v[186:189], v145 offset:2048
	ds_read_b128 v[204:207], v145 offset:3072
	ds_read_b128 v[208:211], v145 offset:4096
	ds_read_b128 v[212:215], v145 offset:5120
	ds_read_b128 v[216:219], v145 offset:6144
	ds_read_b128 v[220:223], v145 offset:7168
	global_load_lds_dwordx4 v[190:191], off
	v_lshl_add_u64 v[190:191], s[44:45], 0, v[140:141]
	s_add_i32 m0, s47, 0xe000
	s_nop 0
	global_load_lds_dwordx4 v[190:191], off
	s_waitcnt vmcnt(8)
	s_waitcnt lgkmcnt(7)
	s_setprio 1
	s_barrier
	v_mfma_f32_16x16x32_bf16 v[124:127], v[146:149], v[178:181], v[124:127]
	s_waitcnt lgkmcnt(6)
	v_mfma_f32_16x16x32_bf16 v[124:127], v[150:153], v[182:185], v[124:127]
	s_waitcnt lgkmcnt(4)
	v_mfma_f32_16x16x32_bf16 v[112:115], v[150:153], v[204:207], v[112:115]
	v_mfma_f32_16x16x32_bf16 v[112:115], v[146:149], v[186:189], v[112:115]
	s_waitcnt lgkmcnt(3)
	v_mfma_f32_16x16x32_bf16 v[96:99], v[146:149], v[208:211], v[96:99]
	s_waitcnt lgkmcnt(2)
	v_mfma_f32_16x16x32_bf16 v[96:99], v[150:153], v[212:215], v[96:99]
	s_waitcnt lgkmcnt(0)
	v_mfma_f32_16x16x32_bf16 v[80:83], v[150:153], v[220:223], v[80:83]
	v_mfma_f32_16x16x32_bf16 v[80:83], v[146:149], v[216:219], v[80:83]
	v_mfma_f32_16x16x32_bf16 v[76:79], v[154:157], v[216:219], v[76:79]
	v_mfma_f32_16x16x32_bf16 v[76:79], v[158:161], v[220:223], v[76:79]
	v_mfma_f32_16x16x32_bf16 v[92:95], v[158:161], v[212:215], v[92:95]
	v_mfma_f32_16x16x32_bf16 v[92:95], v[154:157], v[208:211], v[92:95]
	v_mfma_f32_16x16x32_bf16 v[108:111], v[154:157], v[186:189], v[108:111]
	v_mfma_f32_16x16x32_bf16 v[108:111], v[158:161], v[204:207], v[108:111]
	v_mfma_f32_16x16x32_bf16 v[128:131], v[158:161], v[182:185], v[128:131]
	v_mfma_f32_16x16x32_bf16 v[128:131], v[154:157], v[178:181], v[128:131]
	v_mfma_f32_16x16x32_bf16 v[120:123], v[162:165], v[178:181], v[120:123]
	v_mfma_f32_16x16x32_bf16 v[120:123], v[166:169], v[182:185], v[120:123]
	v_mfma_f32_16x16x32_bf16 v[104:107], v[166:169], v[204:207], v[104:107]
	v_mfma_f32_16x16x32_bf16 v[104:107], v[162:165], v[186:189], v[104:107]
	v_mfma_f32_16x16x32_bf16 v[88:91], v[162:165], v[208:211], v[88:91]
	v_mfma_f32_16x16x32_bf16 v[88:91], v[166:169], v[212:215], v[88:91]
	v_mfma_f32_16x16x32_bf16 v[72:75], v[166:169], v[220:223], v[72:75]
	v_mfma_f32_16x16x32_bf16 v[72:75], v[162:165], v[216:219], v[72:75]
	v_mfma_f32_16x16x32_bf16 v[68:71], v[170:173], v[216:219], v[68:71]
	v_mfma_f32_16x16x32_bf16 v[68:71], v[174:177], v[220:223], v[68:71]
	v_mfma_f32_16x16x32_bf16 v[84:87], v[174:177], v[212:215], v[84:87]
	v_mfma_f32_16x16x32_bf16 v[84:87], v[170:173], v[208:211], v[84:87]
	v_mfma_f32_16x16x32_bf16 v[100:103], v[170:173], v[186:189], v[100:103]
	v_mfma_f32_16x16x32_bf16 v[100:103], v[174:177], v[204:207], v[100:103]
	v_mfma_f32_16x16x32_bf16 v[116:119], v[174:177], v[182:185], v[116:119]
	v_mfma_f32_16x16x32_bf16 v[116:119], v[170:173], v[178:181], v[116:119]
	s_barrier
; #define PG8_STAGE(bufoff, gbase, voff) do { _Pragma("unroll") for (int _i = 0; _i < 2; ++_i) \
;         __builtin_amdgcn_global_load_lds((const unsigned*)((const char*)(gbase) + (voff)[_i]), (PG8_LAS unsigned*)(lds + (bufoff) + ldsw + _i * 8192), 16, 0, 0); } while (0)
; #define PG8_LDA(dst, b, h) do { _Pragma("unroll") for (int m = 0; m < 4; ++m) _Pragma("unroll") for (int k = 0; k < 2; ++k) dst[m][k] = *(const PG8_LAS bf16x8*)(lds + PG8_SA(b, h) + aoff + m * 2048 + k * 1024); } while (0)
; #define PG8_LDB(dst, b, h) do { _Pragma("unroll") for (int n = 0; n < 2; ++n) _Pragma("unroll") for (int k = 0; k < 2; ++k) dst[n][k] = *(const PG8_LAS bf16x8*)(lds + PG8_SB(b, h) + boff + n * 2048 + k * 1024); } while (0)
; #define PG8_WAIT_V(n) asm volatile("s_waitcnt vmcnt(" #n ")" ::: "memory")
; #define PG8_WAIT_L(n) asm volatile("s_waitcnt lgkmcnt(" #n ")" ::: "memory")
; #define PG8_BAR __builtin_amdgcn_s_barrier()
; #define PG8_SCHED __builtin_amdgcn_sched_barrier(0)
; template <class Epi, class Sched, bool ALIGN_EPI = false, bool SP2 = false, bool I8 = false>
; __device__ __forceinline__ void gemm_phase(PG8_LAS unsigned char* lds, const Gemm g, const Sched& S, const Epi& E) {
;     ...
;             PG8_LDA(At, 0, 1); PG8_STAGE(PG8_SB(0, 0), b2, voffB); PG8_STAGE(PG8_SB(0, 1), b2 + hstep, voffB); PG8_STAGE(PG8_SA(0, 0), a2, voffA);
;             PG8_WAIT_V(8); PG8_WAIT_L(0); PG8_BAR; PG8_MMA(1, 0, At, B0); PG8_MMA(1, 1, At, B1); PG8_BAR; PG8_SCHED;
;             PG8_LDB(B0, 1, 0); PG8_LDB(B1, 1, 1); PG8_SCHED; PG8_LDA(At, 1, 0); PG8_STAGE(PG8_SA(0, 1), a2 + hstep, voffA);
;             PG8_WAIT_V(8); PG8_WAIT_L(0); PG8_BAR; PG8_MMA(0, 0, At, B0); PG8_MMA(0, 1, At, B1); PG8_BAR; PG8_SCHED;
;             PG8_LDA(At, 1, 1); PG8_STAGE(PG8_SB(1, 0), b3, voffB); PG8_STAGE(PG8_SB(1, 1), b3 + hstep, voffB); PG8_STAGE(PG8_SA(1, 0), a3, voffA);
	s_setprio 0
	s_add_i32 s86, s86, s28
	v_lshl_add_u64 v[190:191], s[76:77], 0, v[2:3]
	s_mov_b32 m0, s86
	ds_read_b128 v[178:181], v145 offset:16384
	ds_read_b128 v[182:185], v145 offset:17408
	ds_read_b128 v[186:189], v145 offset:18432
	ds_read_b128 v[204:207], v145 offset:19456
	ds_read_b128 v[208:211], v145 offset:20480
	ds_read_b128 v[212:215], v145 offset:21504
	ds_read_b128 v[216:219], v145 offset:22528
	ds_read_b128 v[220:223], v145 offset:23552
	global_load_lds_dwordx4 v[190:191], off
	s_add_i32 m0, s86, 0x2000
	v_lshl_add_u64 v[224:225], s[76:77], 0, v[136:137]
	s_add_u32 s76, s76, s18
	s_addc_u32 s77, s77, s19
	s_add_i32 s73, s73, s28
	global_load_lds_dwordx4 v[224:225], off
	v_lshl_add_u64 v[226:227], s[76:77], 0, v[2:3]
	s_mov_b32 m0, s73
	v_lshl_add_u64 v[228:229], s[76:77], 0, v[136:137]
	global_load_lds_dwordx4 v[226:227], off
	s_add_i32 m0, s73, 0x2000
	v_lshl_add_u64 v[240:241], s[48:49], 0, v[132:133]
	global_load_lds_dwordx4 v[228:229], off
	v_lshl_add_u64 v[242:243], s[48:49], 0, v[134:135]
	s_waitcnt vmcnt(6)
	s_waitcnt lgkmcnt(7)
	s_setprio 1
	s_barrier
	v_mfma_f32_16x16x32_bf16 v[64:67], v[146:149], v[178:181], v[64:67]
	s_waitcnt lgkmcnt(6)
	v_mfma_f32_16x16x32_bf16 v[64:67], v[150:153], v[182:185], v[64:67]
	s_waitcnt lgkmcnt(4)
	v_mfma_f32_16x16x32_bf16 v[48:51], v[150:153], v[204:207], v[48:51]
	v_mfma_f32_16x16x32_bf16 v[48:51], v[146:149], v[186:189], v[48:51]
	s_waitcnt lgkmcnt(3)
	v_mfma_f32_16x16x32_bf16 v[32:35], v[146:149], v[208:211], v[32:35]
	s_waitcnt lgkmcnt(2)
	v_mfma_f32_16x16x32_bf16 v[32:35], v[150:153], v[212:215], v[32:35]
	s_waitcnt lgkmcnt(0)
	v_mfma_f32_16x16x32_bf16 v[16:19], v[150:153], v[220:223], v[16:19]
	v_mfma_f32_16x16x32_bf16 v[16:19], v[146:149], v[216:219], v[16:19]
	v_mfma_f32_16x16x32_bf16 v[12:15], v[154:157], v[216:219], v[12:15]
	v_mfma_f32_16x16x32_bf16 v[12:15], v[158:161], v[220:223], v[12:15]
	v_mfma_f32_16x16x32_bf16 v[28:31], v[158:161], v[212:215], v[28:31]
	v_mfma_f32_16x16x32_bf16 v[28:31], v[154:157], v[208:211], v[28:31]
	v_mfma_f32_16x16x32_bf16 v[44:47], v[154:157], v[186:189], v[44:47]
	v_mfma_f32_16x16x32_bf16 v[44:47], v[158:161], v[204:207], v[44:47]
	v_mfma_f32_16x16x32_bf16 v[60:63], v[158:161], v[182:185], v[60:63]
	v_mfma_f32_16x16x32_bf16 v[60:63], v[154:157], v[178:181], v[60:63]
	v_mfma_f32_16x16x32_bf16 v[56:59], v[162:165], v[178:181], v[56:59]
	v_mfma_f32_16x16x32_bf16 v[56:59], v[166:169], v[182:185], v[56:59]
	v_mfma_f32_16x16x32_bf16 v[40:43], v[166:169], v[204:207], v[40:43]
	v_mfma_f32_16x16x32_bf16 v[40:43], v[162:165], v[186:189], v[40:43]
	v_mfma_f32_16x16x32_bf16 v[24:27], v[162:165], v[208:211], v[24:27]
	v_mfma_f32_16x16x32_bf16 v[24:27], v[166:169], v[212:215], v[24:27]
	v_mfma_f32_16x16x32_bf16 v[8:11], v[166:169], v[220:223], v[8:11]
	v_mfma_f32_16x16x32_bf16 v[8:11], v[162:165], v[216:219], v[8:11]
	v_mfma_f32_16x16x32_bf16 v[4:7], v[170:173], v[216:219], v[4:7]
	v_mfma_f32_16x16x32_bf16 v[4:7], v[174:177], v[220:223], v[4:7]
	v_mfma_f32_16x16x32_bf16 v[20:23], v[174:177], v[212:215], v[20:23]
	v_mfma_f32_16x16x32_bf16 v[20:23], v[170:173], v[208:211], v[20:23]
	v_mfma_f32_16x16x32_bf16 v[36:39], v[170:173], v[186:189], v[36:39]
	v_mfma_f32_16x16x32_bf16 v[36:39], v[174:177], v[204:207], v[36:39]
	v_mfma_f32_16x16x32_bf16 v[52:55], v[174:177], v[182:185], v[52:55]
	v_mfma_f32_16x16x32_bf16 v[52:55], v[170:173], v[178:181], v[52:55]
	s_barrier
	s_setprio 0
	s_mov_b32 m0, s47
	s_nop 0
	global_load_lds_dwordx4 v[240:241], off
	s_mov_b32 m0, s50
	s_nop 0
	global_load_lds_dwordx4 v[242:243], off
	s_add_i32 s73, 0, 0x18000
	s_add_i32 s76, 0, 0x1c000
	v_add_u32_e32 v158, s73, v143
	v_add_u32_e32 v174, s76, v143
	ds_read_b128 v[146:149], v158
	ds_read_b128 v[150:153], v158 offset:1024
	ds_read_b128 v[154:157], v158 offset:2048
	ds_read_b128 v[158:161], v158 offset:3072
	ds_read_b128 v[162:165], v174
	ds_read_b128 v[166:169], v174 offset:1024
	ds_read_b128 v[170:173], v174 offset:2048
	ds_read_b128 v[174:177], v174 offset:3072
	s_add_u32 s48, s48, s18
	s_addc_u32 s49, s49, s19
	s_mov_b32 m0, s51
	ds_read_b128 v[178:181], v145 offset:32768
	ds_read_b128 v[182:185], v145 offset:33792
	ds_read_b128 v[186:189], v145 offset:34816
	ds_read_b128 v[204:207], v145 offset:35840
	ds_read_b128 v[208:211], v145 offset:36864
	ds_read_b128 v[212:215], v145 offset:37888
	ds_read_b128 v[216:219], v145 offset:38912
	ds_read_b128 v[220:223], v145 offset:39936
	global_load_lds_dwordx4 v132, s[48:49]
	s_mov_b32 m0, s52
	s_nop 0
	global_load_lds_dwordx4 v134, s[48:49]
	s_waitcnt vmcnt(8)
	s_waitcnt lgkmcnt(7)
	s_setprio 1
	s_barrier
; #define PG8_STAGE(bufoff, gbase, voff) do { _Pragma("unroll") for (int _i = 0; _i < 2; ++_i) \
;         __builtin_amdgcn_global_load_lds((const unsigned*)((const char*)(gbase) + (voff)[_i]), (PG8_LAS unsigned*)(lds + (bufoff) + ldsw + _i * 8192), 16, 0, 0); } while (0)
; #define PG8_LDA(dst, b, h) do { _Pragma("unroll") for (int m = 0; m < 4; ++m) _Pragma("unroll") for (int k = 0; k < 2; ++k) dst[m][k] = *(const PG8_LAS bf16x8*)(lds + PG8_SA(b, h) + aoff + m * 2048 + k * 1024); } while (0)
; #define PG8_LDB(dst, b, h) do { _Pragma("unroll") for (int n = 0; n < 2; ++n) _Pragma("unroll") for (int k = 0; k < 2; ++k) dst[n][k] = *(const PG8_LAS bf16x8*)(lds + PG8_SB(b, h) + boff + n * 2048 + k * 1024); } while (0)
; #define PG8_WAIT_V(n) asm volatile("s_waitcnt vmcnt(" #n ")" ::: "memory")
; #define PG8_WAIT_L(n) asm volatile("s_waitcnt lgkmcnt(" #n ")" ::: "memory")
; #define PG8_BAR __builtin_amdgcn_s_barrier()
; #define PG8_SCHED __builtin_amdgcn_sched_barrier(0)
; template <class Epi, class Sched, bool ALIGN_EPI = false, bool SP2 = false, bool I8 = false>
; __device__ __forceinline__ void gemm_phase(PG8_LAS unsigned char* lds, const Gemm g, const Sched& S, const Epi& E) {
;     ...
;             PG8_LDB(B0, 1, 0); PG8_LDB(B1, 1, 1); PG8_SCHED; PG8_LDA(At, 1, 0); PG8_STAGE(PG8_SA(0, 1), a2 + hstep, voffA);
;             PG8_WAIT_V(8); PG8_WAIT_L(0); PG8_BAR; PG8_MMA(0, 0, At, B0); PG8_MMA(0, 1, At, B1); PG8_BAR; PG8_SCHED;
;             PG8_LDA(At, 1, 1); PG8_STAGE(PG8_SB(1, 0), b3, voffB); PG8_STAGE(PG8_SB(1, 1), b3 + hstep, voffB); PG8_STAGE(PG8_SA(1, 0), a3, voffA);
;             PG8_WAIT_V(8); PG8_WAIT_L(0); PG8_BAR; PG8_MMA(1, 0, At, B0); PG8_MMA(1, 1, At, B1); PG8_BAR; PG8_SCHED;
	v_mfma_f32_16x16x32_bf16 v[124:127], v[146:149], v[178:181], v[124:127]
	s_waitcnt lgkmcnt(6)
	v_mfma_f32_16x16x32_bf16 v[124:127], v[150:153], v[182:185], v[124:127]
	s_waitcnt lgkmcnt(4)
	v_mfma_f32_16x16x32_bf16 v[112:115], v[150:153], v[204:207], v[112:115]
	v_mfma_f32_16x16x32_bf16 v[112:115], v[146:149], v[186:189], v[112:115]
	s_waitcnt lgkmcnt(3)
	v_mfma_f32_16x16x32_bf16 v[96:99], v[146:149], v[208:211], v[96:99]
	s_waitcnt lgkmcnt(2)
	v_mfma_f32_16x16x32_bf16 v[96:99], v[150:153], v[212:215], v[96:99]
	s_waitcnt lgkmcnt(0)
	v_mfma_f32_16x16x32_bf16 v[80:83], v[150:153], v[220:223], v[80:83]
	v_mfma_f32_16x16x32_bf16 v[80:83], v[146:149], v[216:219], v[80:83]
	v_mfma_f32_16x16x32_bf16 v[76:79], v[154:157], v[216:219], v[76:79]
	v_mfma_f32_16x16x32_bf16 v[76:79], v[158:161], v[220:223], v[76:79]
	v_mfma_f32_16x16x32_bf16 v[92:95], v[158:161], v[212:215], v[92:95]
	v_mfma_f32_16x16x32_bf16 v[92:95], v[154:157], v[208:211], v[92:95]
	v_mfma_f32_16x16x32_bf16 v[108:111], v[154:157], v[186:189], v[108:111]
	v_mfma_f32_16x16x32_bf16 v[108:111], v[158:161], v[204:207], v[108:111]
	v_mfma_f32_16x16x32_bf16 v[128:131], v[158:161], v[182:185], v[128:131]
	v_mfma_f32_16x16x32_bf16 v[128:131], v[154:157], v[178:181], v[128:131]
	v_mfma_f32_16x16x32_bf16 v[120:123], v[162:165], v[178:181], v[120:123]
	v_mfma_f32_16x16x32_bf16 v[120:123], v[166:169], v[182:185], v[120:123]
	v_mfma_f32_16x16x32_bf16 v[104:107], v[166:169], v[204:207], v[104:107]
	v_mfma_f32_16x16x32_bf16 v[104:107], v[162:165], v[186:189], v[104:107]
	v_mfma_f32_16x16x32_bf16 v[88:91], v[162:165], v[208:211], v[88:91]
	v_mfma_f32_16x16x32_bf16 v[88:91], v[166:169], v[212:215], v[88:91]
	v_mfma_f32_16x16x32_bf16 v[72:75], v[166:169], v[220:223], v[72:75]
	v_mfma_f32_16x16x32_bf16 v[72:75], v[162:165], v[216:219], v[72:75]
	v_mfma_f32_16x16x32_bf16 v[68:71], v[170:173], v[216:219], v[68:71]
	v_mfma_f32_16x16x32_bf16 v[68:71], v[174:177], v[220:223], v[68:71]
	v_mfma_f32_16x16x32_bf16 v[84:87], v[174:177], v[212:215], v[84:87]
	v_mfma_f32_16x16x32_bf16 v[84:87], v[170:173], v[208:211], v[84:87]
	v_mfma_f32_16x16x32_bf16 v[100:103], v[170:173], v[186:189], v[100:103]
	v_mfma_f32_16x16x32_bf16 v[100:103], v[174:177], v[204:207], v[100:103]
	v_mfma_f32_16x16x32_bf16 v[116:119], v[174:177], v[182:185], v[116:119]
	v_mfma_f32_16x16x32_bf16 v[116:119], v[170:173], v[178:181], v[116:119]
	s_barrier
	s_setprio 0
	s_add_i32 s48, s73, s28
	v_lshl_add_u64 v[190:191], v[190:191], 0, s[84:85]
	s_mov_b32 m0, s48
	ds_read_b128 v[178:181], v145 offset:49152
	ds_read_b128 v[182:185], v145 offset:50176
	ds_read_b128 v[186:189], v145 offset:51200
	ds_read_b128 v[204:207], v145 offset:52224
	ds_read_b128 v[208:211], v145 offset:53248
	ds_read_b128 v[212:215], v145 offset:54272
	ds_read_b128 v[216:219], v145 offset:55296
	ds_read_b128 v[220:223], v145 offset:56320
	global_load_lds_dwordx4 v[190:191], off
	v_lshl_add_u64 v[190:191], v[224:225], 0, s[84:85]
	s_add_i32 m0, s48, 0x2000
	s_add_i32 s48, s76, s28
	global_load_lds_dwordx4 v[190:191], off
	v_lshl_add_u64 v[190:191], v[226:227], 0, s[84:85]
	s_mov_b32 m0, s48
	s_nop 0
	global_load_lds_dwordx4 v[190:191], off
	v_lshl_add_u64 v[190:191], v[228:229], 0, s[84:85]
	s_add_i32 m0, s48, 0x2000
	s_nop 0
	global_load_lds_dwordx4 v[190:191], off
	v_lshl_add_u64 v[190:191], v[240:241], 0, s[84:85]
	s_mov_b32 m0, s55
	s_nop 0
	global_load_lds_dwordx4 v[190:191], off
	v_lshl_add_u64 v[190:191], v[242:243], 0, s[84:85]
	s_mov_b32 m0, s56
	s_nop 0
	global_load_lds_dwordx4 v[190:191], off
	s_waitcnt vmcnt(8)
	s_waitcnt lgkmcnt(7)
	s_setprio 1
	s_barrier
	v_mfma_f32_16x16x32_bf16 v[64:67], v[146:149], v[178:181], v[64:67]
	s_waitcnt lgkmcnt(6)
	v_mfma_f32_16x16x32_bf16 v[64:67], v[150:153], v[182:185], v[64:67]
	s_waitcnt lgkmcnt(4)
	v_mfma_f32_16x16x32_bf16 v[48:51], v[150:153], v[204:207], v[48:51]
	v_mfma_f32_16x16x32_bf16 v[48:51], v[146:149], v[186:189], v[48:51]
	s_waitcnt lgkmcnt(3)
	v_mfma_f32_16x16x32_bf16 v[32:35], v[146:149], v[208:211], v[32:35]
	s_waitcnt lgkmcnt(2)
	v_mfma_f32_16x16x32_bf16 v[32:35], v[150:153], v[212:215], v[32:35]
	s_waitcnt lgkmcnt(0)
	v_mfma_f32_16x16x32_bf16 v[16:19], v[150:153], v[220:223], v[16:19]
	v_mfma_f32_16x16x32_bf16 v[16:19], v[146:149], v[216:219], v[16:19]
	v_mfma_f32_16x16x32_bf16 v[12:15], v[154:157], v[216:219], v[12:15]
	v_mfma_f32_16x16x32_bf16 v[12:15], v[158:161], v[220:223], v[12:15]
	v_mfma_f32_16x16x32_bf16 v[28:31], v[158:161], v[212:215], v[28:31]
	v_mfma_f32_16x16x32_bf16 v[28:31], v[154:157], v[208:211], v[28:31]
	v_mfma_f32_16x16x32_bf16 v[44:47], v[154:157], v[186:189], v[44:47]
	v_mfma_f32_16x16x32_bf16 v[44:47], v[158:161], v[204:207], v[44:47]
	v_mfma_f32_16x16x32_bf16 v[60:63], v[158:161], v[182:185], v[60:63]
	v_mfma_f32_16x16x32_bf16 v[60:63], v[154:157], v[178:181], v[60:63]
	v_mfma_f32_16x16x32_bf16 v[56:59], v[162:165], v[178:181], v[56:59]
	v_mfma_f32_16x16x32_bf16 v[56:59], v[166:169], v[182:185], v[56:59]
	v_mfma_f32_16x16x32_bf16 v[40:43], v[166:169], v[204:207], v[40:43]
	v_mfma_f32_16x16x32_bf16 v[40:43], v[162:165], v[186:189], v[40:43]
	v_mfma_f32_16x16x32_bf16 v[24:27], v[162:165], v[208:211], v[24:27]
	v_mfma_f32_16x16x32_bf16 v[24:27], v[166:169], v[212:215], v[24:27]
	v_mfma_f32_16x16x32_bf16 v[8:11], v[166:169], v[220:223], v[8:11]
	v_mfma_f32_16x16x32_bf16 v[8:11], v[162:165], v[216:219], v[8:11]
	v_mfma_f32_16x16x32_bf16 v[4:7], v[170:173], v[216:219], v[4:7]
	v_mfma_f32_16x16x32_bf16 v[4:7], v[174:177], v[220:223], v[4:7]
	v_mfma_f32_16x16x32_bf16 v[20:23], v[174:177], v[212:215], v[20:23]
	v_mfma_f32_16x16x32_bf16 v[20:23], v[170:173], v[208:211], v[20:23]
	v_mfma_f32_16x16x32_bf16 v[36:39], v[170:173], v[186:189], v[36:39]
	v_mfma_f32_16x16x32_bf16 v[36:39], v[174:177], v[204:207], v[36:39]
	v_mfma_f32_16x16x32_bf16 v[52:55], v[174:177], v[182:185], v[52:55]
	v_mfma_f32_16x16x32_bf16 v[52:55], v[170:173], v[178:181], v[52:55]
	s_barrier
	s_setprio 0
	s_add_u32 s44, s44, 0x100
	s_addc_u32 s45, s45, 0
	s_add_u32 s65, s65, 0x100
	s_addc_u32 s67, s67, 0
	s_cmp_ge_i32 s72, s53
	s_mov_b32 s48, s72
	s_cbranch_scc0 .LBB0_1623

; #define PG8_STAGE(bufoff, gbase, voff) do { _Pragma("unroll") for (int _i = 0; _i < 2; ++_i) \
;         __builtin_amdgcn_global_load_lds((const unsigned*)((const char*)(gbase) + (voff)[_i]), (PG8_LAS unsigned*)(lds + (bufoff) + ldsw + _i * 8192), 16, 0, 0); } while (0)
; #define PG8_LDA(dst, b, h) do { _Pragma("unroll") for (int m = 0; m < 4; ++m) _Pragma("unroll") for (int k = 0; k < 2; ++k) dst[m][k] = *(const PG8_LAS bf16x8*)(lds + PG8_SA(b, h) + aoff + m * 2048 + k * 1024); } while (0)
; #define PG8_LDB(dst, b, h) do { _Pragma("unroll") for (int n = 0; n < 2; ++n) _Pragma("unroll") for (int k = 0; k < 2; ++k) dst[n][k] = *(const PG8_LAS bf16x8*)(lds + PG8_SB(b, h) + boff + n * 2048 + k * 1024); } while (0)
; #define PG8_WAIT_V(n) asm volatile("s_waitcnt vmcnt(" #n ")" ::: "memory")
; #define PG8_WAIT_L(n) asm volatile("s_waitcnt lgkmcnt(" #n ")" ::: "memory")
; #define PG8_BAR __builtin_amdgcn_s_barrier()
; #define PG8_SCHED __builtin_amdgcn_sched_barrier(0)
; template <class Epi, class Sched, bool ALIGN_EPI = false, bool SP2 = false, bool I8 = false>
; __device__ __forceinline__ void gemm_phase(PG8_LAS unsigned char* lds, const Gemm g, const Sched& S, const Epi& E) {
;     ...
;             const char* a1 = cA + (size_t)(t + 1) * kstep;
;             const char* a2 = last ? nA : cA + (size_t)(t + 2) * kstep; const char* b2 = last ? nB : cB + (size_t)(t + 2) * kstep;
;             const char* a3 = a2 + kstep; const char* b3 = b2 + kstep;
;             if (last && has_next) S.a_ready(nxt);
;             if constexpr (SP2) {
;             PG8_LDB(B0, 0, 0); PG8_LDB(B1, 0, 1); PG8_SCHED; PG8_LDA(At, 0, 0); PG8_STAGE(PG8_SA(1, 1), a1 + hstep, voffA);
;             PG8_WAIT_V(8); PG8_WAIT_L(0); PG8_BAR; PG8_MMA(0, 0, At, B0); PG8_MMA(0, 1, At, B1); PG8_BAR; PG8_SCHED;
;             PG8_LDA(At, 0, 1); PG8_STAGE(PG8_SB(0, 0), b2, voffB); PG8_STAGE(PG8_SB(0, 1), b2 + hstep, voffB); PG8_STAGE(PG8_SA(0, 0), a2, voffA);
;             PG8_WAIT_V(8); PG8_WAIT_L(0); PG8_BAR; PG8_MMA(1, 0, At, B0); PG8_MMA(1, 1, At, B1); PG8_BAR; PG8_SCHED;
.LBB0_1699:
	s_add_u32 s53, s24, 0x100
	s_addc_u32 s54, s25, 0
	s_mov_b32 s55, -2
	s_add_u32 s24, s22, 0x100
	s_addc_u32 s25, s23, 0
	s_add_i32 s56, 0, 0x10000
	s_cmpk_eq_i32 s55, 0xa8
	s_cselect_b32 s37, s13, s25
	s_cselect_b32 s36, s12, s24
	s_cselect_b32 s27, s21, s54
	s_cselect_b32 s26, s20, s53
	s_add_i32 s57, 0, 0x14000
	v_add_u32_e32 v144, s56, v240
	v_add_u32_e32 v160, s57, v240
	ds_read_b128 v[124:127], v144
	ds_read_b128 v[128:131], v144 offset:1024
	ds_read_b128 v[132:135], v144 offset:2048
	ds_read_b128 v[144:147], v144 offset:3072
	ds_read_b128 v[148:151], v160
	ds_read_b128 v[152:155], v160 offset:1024
	ds_read_b128 v[156:159], v160 offset:2048
	ds_read_b128 v[160:163], v160 offset:3072
	v_lshl_add_u64 v[218:219], s[22:23], 0, v[210:211]
	s_add_i32 m0, s42, 0xc000
	ds_read_b128 v[164:167], v242
	ds_read_b128 v[168:171], v242 offset:1024
	ds_read_b128 v[172:175], v242 offset:2048
	ds_read_b128 v[176:179], v242 offset:3072
	ds_read_b128 v[180:183], v242 offset:4096
	ds_read_b128 v[184:187], v242 offset:5120
	ds_read_b128 v[188:191], v242 offset:6144
	ds_read_b128 v[214:217], v242 offset:7168
	global_load_lds_dwordx4 v[218:219], off
	v_lshl_add_u64 v[218:219], s[22:23], 0, v[212:213]
	s_add_i32 m0, s42, 0xe000
	s_nop 0
	global_load_lds_dwordx4 v[218:219], off
	s_waitcnt vmcnt(8)
	s_waitcnt lgkmcnt(7)
	s_setprio 1
	s_barrier
	v_mfma_f32_16x16x32_bf16 v[140:143], v[124:127], v[164:167], 0
	s_waitcnt lgkmcnt(6)
	v_mfma_f32_16x16x32_bf16 v[140:143], v[128:131], v[168:171], v[140:143]
	s_waitcnt lgkmcnt(4)
	v_mfma_f32_16x16x32_bf16 v[112:115], v[128:131], v[176:179], 0
	v_mfma_f32_16x16x32_bf16 v[112:115], v[124:127], v[172:175], v[112:115]
	s_waitcnt lgkmcnt(3)
	v_mfma_f32_16x16x32_bf16 v[96:99], v[124:127], v[180:183], 0
	s_waitcnt lgkmcnt(2)
	v_mfma_f32_16x16x32_bf16 v[96:99], v[128:131], v[184:187], v[96:99]
	s_waitcnt lgkmcnt(0)
	v_mfma_f32_16x16x32_bf16 v[80:83], v[128:131], v[214:217], 0
	v_mfma_f32_16x16x32_bf16 v[80:83], v[124:127], v[188:191], v[80:83]
	v_mfma_f32_16x16x32_bf16 v[76:79], v[132:135], v[188:191], 0
	v_mfma_f32_16x16x32_bf16 v[76:79], v[144:147], v[214:217], v[76:79]
	v_mfma_f32_16x16x32_bf16 v[92:95], v[144:147], v[184:187], 0
	v_mfma_f32_16x16x32_bf16 v[92:95], v[132:135], v[180:183], v[92:95]
	v_mfma_f32_16x16x32_bf16 v[108:111], v[132:135], v[172:175], 0
	v_mfma_f32_16x16x32_bf16 v[108:111], v[144:147], v[176:179], v[108:111]
	v_mfma_f32_16x16x32_bf16 v[136:139], v[144:147], v[168:171], 0
	v_mfma_f32_16x16x32_bf16 v[136:139], v[132:135], v[164:167], v[136:139]
	v_mfma_f32_16x16x32_bf16 v[120:123], v[148:151], v[164:167], 0
	v_mfma_f32_16x16x32_bf16 v[120:123], v[152:155], v[168:171], v[120:123]
	v_mfma_f32_16x16x32_bf16 v[104:107], v[152:155], v[176:179], 0
	v_mfma_f32_16x16x32_bf16 v[104:107], v[148:151], v[172:175], v[104:107]
	v_mfma_f32_16x16x32_bf16 v[88:91], v[148:151], v[180:183], 0
	v_mfma_f32_16x16x32_bf16 v[88:91], v[152:155], v[184:187], v[88:91]
	v_mfma_f32_16x16x32_bf16 v[72:75], v[152:155], v[214:217], 0
	v_mfma_f32_16x16x32_bf16 v[72:75], v[148:151], v[188:191], v[72:75]
	v_mfma_f32_16x16x32_bf16 v[68:71], v[156:159], v[188:191], 0
	v_mfma_f32_16x16x32_bf16 v[68:71], v[160:163], v[214:217], v[68:71]
	v_mfma_f32_16x16x32_bf16 v[84:87], v[160:163], v[184:187], 0
	v_mfma_f32_16x16x32_bf16 v[84:87], v[156:159], v[180:183], v[84:87]
	v_mfma_f32_16x16x32_bf16 v[100:103], v[156:159], v[172:175], 0
	v_mfma_f32_16x16x32_bf16 v[100:103], v[160:163], v[176:179], v[100:103]
	v_mfma_f32_16x16x32_bf16 v[116:119], v[160:163], v[168:171], 0
	v_mfma_f32_16x16x32_bf16 v[116:119], v[156:159], v[164:167], v[116:119]
	s_barrier
	s_setprio 0
	s_add_i32 s22, s56, s41
	v_lshl_add_u64 v[218:219], s[26:27], 0, v[2:3]
	s_mov_b32 m0, s22
	ds_read_b128 v[164:167], v242 offset:16384
	ds_read_b128 v[168:171], v242 offset:17408
	ds_read_b128 v[172:175], v242 offset:18432
	ds_read_b128 v[176:179], v242 offset:19456
	ds_read_b128 v[180:183], v242 offset:20480
	ds_read_b128 v[184:187], v242 offset:21504
	ds_read_b128 v[188:191], v242 offset:22528
	ds_read_b128 v[214:217], v242 offset:23552
	global_load_lds_dwordx4 v[218:219], off
	s_add_i32 m0, s22, 0x2000
	s_add_u32 s22, s26, 0x2b0000
	v_lshl_add_u64 v[220:221], s[26:27], 0, v[204:205]
	s_addc_u32 s23, s27, 0
	s_add_i32 s56, s57, s41
	global_load_lds_dwordx4 v[220:221], off
	s_mov_b32 m0, s56
	v_lshl_add_u64 v[224:225], s[36:37], 0, v[206:207]
	global_load_lds_dwordx4 v2, s[22:23]
	s_add_i32 m0, s56, 0x2000
	s_nop 0
	global_load_lds_dwordx4 v204, s[22:23]
	v_lshl_add_u64 v[222:223], s[36:37], 0, v[208:209]
	s_waitcnt vmcnt(6)
	s_waitcnt lgkmcnt(7)
	s_setprio 1
	s_barrier
; #define PG8_STAGE(bufoff, gbase, voff) do { _Pragma("unroll") for (int _i = 0; _i < 2; ++_i) \
;         __builtin_amdgcn_global_load_lds((const unsigned*)((const char*)(gbase) + (voff)[_i]), (PG8_LAS unsigned*)(lds + (bufoff) + ldsw + _i * 8192), 16, 0, 0); } while (0)
; #define PG8_LDA(dst, b, h) do { _Pragma("unroll") for (int m = 0; m < 4; ++m) _Pragma("unroll") for (int k = 0; k < 2; ++k) dst[m][k] = *(const PG8_LAS bf16x8*)(lds + PG8_SA(b, h) + aoff + m * 2048 + k * 1024); } while (0)
; #define PG8_LDB(dst, b, h) do { _Pragma("unroll") for (int n = 0; n < 2; ++n) _Pragma("unroll") for (int k = 0; k < 2; ++k) dst[n][k] = *(const PG8_LAS bf16x8*)(lds + PG8_SB(b, h) + boff + n * 2048 + k * 1024); } while (0)
; #define PG8_WAIT_V(n) asm volatile("s_waitcnt vmcnt(" #n ")" ::: "memory")
; #define PG8_WAIT_L(n) asm volatile("s_waitcnt lgkmcnt(" #n ")" ::: "memory")
; #define PG8_BAR __builtin_amdgcn_s_barrier()
; #define PG8_SCHED __builtin_amdgcn_sched_barrier(0)
; template <class Epi, class Sched, bool ALIGN_EPI = false, bool SP2 = false, bool I8 = false>
; __device__ __forceinline__ void gemm_phase(PG8_LAS unsigned char* lds, const Gemm g, const Sched& S, const Epi& E) {
;     ...
;             PG8_WAIT_V(8); PG8_WAIT_L(0); PG8_BAR; PG8_MMA(1, 0, At, B0); PG8_MMA(1, 1, At, B1); PG8_BAR; PG8_SCHED;
;             PG8_LDB(B0, 1, 0); PG8_LDB(B1, 1, 1); PG8_SCHED; PG8_LDA(At, 1, 0); PG8_STAGE(PG8_SA(0, 1), a2 + hstep, voffA);
;             PG8_WAIT_V(8); PG8_WAIT_L(0); PG8_BAR; PG8_MMA(0, 0, At, B0); PG8_MMA(0, 1, At, B1); PG8_BAR; PG8_SCHED;
;             PG8_LDA(At, 1, 1); PG8_STAGE(PG8_SB(1, 0), b3, voffB); PG8_STAGE(PG8_SB(1, 1), b3 + hstep, voffB); PG8_STAGE(PG8_SA(1, 0), a3, voffA);
	v_mfma_f32_16x16x32_bf16 v[64:67], v[124:127], v[164:167], 0
	s_waitcnt lgkmcnt(6)
	v_mfma_f32_16x16x32_bf16 v[64:67], v[128:131], v[168:171], v[64:67]
	s_waitcnt lgkmcnt(4)
	v_mfma_f32_16x16x32_bf16 v[48:51], v[128:131], v[176:179], 0
	v_mfma_f32_16x16x32_bf16 v[48:51], v[124:127], v[172:175], v[48:51]
	s_waitcnt lgkmcnt(3)
	v_mfma_f32_16x16x32_bf16 v[32:35], v[124:127], v[180:183], 0
	s_waitcnt lgkmcnt(2)
	v_mfma_f32_16x16x32_bf16 v[32:35], v[128:131], v[184:187], v[32:35]
	s_waitcnt lgkmcnt(0)
	v_mfma_f32_16x16x32_bf16 v[16:19], v[128:131], v[214:217], 0
	v_mfma_f32_16x16x32_bf16 v[16:19], v[124:127], v[188:191], v[16:19]
	v_mfma_f32_16x16x32_bf16 v[12:15], v[132:135], v[188:191], 0
	v_mfma_f32_16x16x32_bf16 v[12:15], v[144:147], v[214:217], v[12:15]
	v_mfma_f32_16x16x32_bf16 v[28:31], v[144:147], v[184:187], 0
	v_mfma_f32_16x16x32_bf16 v[28:31], v[132:135], v[180:183], v[28:31]
	v_mfma_f32_16x16x32_bf16 v[44:47], v[132:135], v[172:175], 0
	v_mfma_f32_16x16x32_bf16 v[44:47], v[144:147], v[176:179], v[44:47]
	v_mfma_f32_16x16x32_bf16 v[60:63], v[144:147], v[168:171], 0
	v_mfma_f32_16x16x32_bf16 v[60:63], v[132:135], v[164:167], v[60:63]
	v_mfma_f32_16x16x32_bf16 v[56:59], v[148:151], v[164:167], 0
	v_mfma_f32_16x16x32_bf16 v[56:59], v[152:155], v[168:171], v[56:59]
	v_mfma_f32_16x16x32_bf16 v[40:43], v[152:155], v[176:179], 0
	v_mfma_f32_16x16x32_bf16 v[40:43], v[148:151], v[172:175], v[40:43]
	v_mfma_f32_16x16x32_bf16 v[24:27], v[148:151], v[180:183], 0
	v_mfma_f32_16x16x32_bf16 v[24:27], v[152:155], v[184:187], v[24:27]
	v_mfma_f32_16x16x32_bf16 v[8:11], v[152:155], v[214:217], 0
	v_mfma_f32_16x16x32_bf16 v[8:11], v[148:151], v[188:191], v[8:11]
	v_mfma_f32_16x16x32_bf16 v[4:7], v[156:159], v[188:191], 0
	v_mfma_f32_16x16x32_bf16 v[4:7], v[160:163], v[214:217], v[4:7]
	v_mfma_f32_16x16x32_bf16 v[20:23], v[160:163], v[184:187], 0
	v_mfma_f32_16x16x32_bf16 v[20:23], v[156:159], v[180:183], v[20:23]
	v_mfma_f32_16x16x32_bf16 v[36:39], v[156:159], v[172:175], 0
	v_mfma_f32_16x16x32_bf16 v[36:39], v[160:163], v[176:179], v[36:39]
	v_mfma_f32_16x16x32_bf16 v[52:55], v[160:163], v[168:171], 0
	v_mfma_f32_16x16x32_bf16 v[52:55], v[156:159], v[164:167], v[52:55]
	s_barrier
	s_setprio 0
	s_mov_b32 m0, s42
	s_nop 0
	global_load_lds_dwordx4 v[222:223], off
	s_mov_b32 m0, s43
	s_nop 0
	global_load_lds_dwordx4 v[224:225], off
	s_add_i32 s56, 0, 0x18000
	s_add_i32 s57, 0, 0x1c000
	v_add_u32_e32 v144, s56, v240
	v_add_u32_e32 v160, s57, v240
	ds_read_b128 v[124:127], v144
	ds_read_b128 v[128:131], v144 offset:1024
	ds_read_b128 v[132:135], v144 offset:2048
	ds_read_b128 v[144:147], v144 offset:3072
	ds_read_b128 v[148:151], v160
	ds_read_b128 v[152:155], v160 offset:1024
	ds_read_b128 v[156:159], v160 offset:2048
	ds_read_b128 v[160:163], v160 offset:3072
	s_add_u32 s22, s36, 0x2b0000
	s_addc_u32 s23, s37, 0
	s_mov_b32 m0, s44
	ds_read_b128 v[164:167], v242 offset:32768
	ds_read_b128 v[168:171], v242 offset:33792
	ds_read_b128 v[172:175], v242 offset:34816
	ds_read_b128 v[176:179], v242 offset:35840
	ds_read_b128 v[180:183], v242 offset:36864
	ds_read_b128 v[184:187], v242 offset:37888
	ds_read_b128 v[188:191], v242 offset:38912
	ds_read_b128 v[214:217], v242 offset:39936
	global_load_lds_dwordx4 v208, s[22:23]
	s_mov_b32 m0, s45
	s_nop 0
	global_load_lds_dwordx4 v206, s[22:23]
	s_waitcnt vmcnt(8)
	s_waitcnt lgkmcnt(7)
	s_setprio 1
	s_barrier
	v_mfma_f32_16x16x32_bf16 v[140:143], v[124:127], v[164:167], v[140:143]
	s_waitcnt lgkmcnt(6)
	v_mfma_f32_16x16x32_bf16 v[140:143], v[128:131], v[168:171], v[140:143]
	s_waitcnt lgkmcnt(4)
	v_mfma_f32_16x16x32_bf16 v[112:115], v[128:131], v[176:179], v[112:115]
	v_mfma_f32_16x16x32_bf16 v[112:115], v[124:127], v[172:175], v[112:115]
	s_waitcnt lgkmcnt(3)
	v_mfma_f32_16x16x32_bf16 v[96:99], v[124:127], v[180:183], v[96:99]
	s_waitcnt lgkmcnt(2)
	v_mfma_f32_16x16x32_bf16 v[96:99], v[128:131], v[184:187], v[96:99]
	s_waitcnt lgkmcnt(0)
	v_mfma_f32_16x16x32_bf16 v[80:83], v[128:131], v[214:217], v[80:83]
	v_mfma_f32_16x16x32_bf16 v[80:83], v[124:127], v[188:191], v[80:83]
	v_mfma_f32_16x16x32_bf16 v[76:79], v[132:135], v[188:191], v[76:79]
	v_mfma_f32_16x16x32_bf16 v[76:79], v[144:147], v[214:217], v[76:79]
	v_mfma_f32_16x16x32_bf16 v[92:95], v[144:147], v[184:187], v[92:95]
	v_mfma_f32_16x16x32_bf16 v[92:95], v[132:135], v[180:183], v[92:95]
	v_mfma_f32_16x16x32_bf16 v[108:111], v[132:135], v[172:175], v[108:111]
	v_mfma_f32_16x16x32_bf16 v[108:111], v[144:147], v[176:179], v[108:111]
	v_mfma_f32_16x16x32_bf16 v[136:139], v[144:147], v[168:171], v[136:139]
	v_mfma_f32_16x16x32_bf16 v[136:139], v[132:135], v[164:167], v[136:139]
	v_mfma_f32_16x16x32_bf16 v[120:123], v[148:151], v[164:167], v[120:123]
	v_mfma_f32_16x16x32_bf16 v[120:123], v[152:155], v[168:171], v[120:123]
	v_mfma_f32_16x16x32_bf16 v[104:107], v[152:155], v[176:179], v[104:107]
	v_mfma_f32_16x16x32_bf16 v[104:107], v[148:151], v[172:175], v[104:107]
	v_mfma_f32_16x16x32_bf16 v[88:91], v[148:151], v[180:183], v[88:91]
	v_mfma_f32_16x16x32_bf16 v[88:91], v[152:155], v[184:187], v[88:91]
	v_mfma_f32_16x16x32_bf16 v[72:75], v[152:155], v[214:217], v[72:75]
	v_mfma_f32_16x16x32_bf16 v[72:75], v[148:151], v[188:191], v[72:75]
	v_mfma_f32_16x16x32_bf16 v[68:71], v[156:159], v[188:191], v[68:71]
	v_mfma_f32_16x16x32_bf16 v[68:71], v[160:163], v[214:217], v[68:71]
	v_mfma_f32_16x16x32_bf16 v[84:87], v[160:163], v[184:187], v[84:87]
	v_mfma_f32_16x16x32_bf16 v[84:87], v[156:159], v[180:183], v[84:87]
	v_mfma_f32_16x16x32_bf16 v[100:103], v[156:159], v[172:175], v[100:103]
	v_mfma_f32_16x16x32_bf16 v[100:103], v[160:163], v[176:179], v[100:103]
	v_mfma_f32_16x16x32_bf16 v[116:119], v[160:163], v[168:171], v[116:119]
	v_mfma_f32_16x16x32_bf16 v[116:119], v[156:159], v[164:167], v[116:119]
	s_barrier
	s_setprio 0
	s_add_i32 s22, s56, s41
	v_lshl_add_u64 v[218:219], v[218:219], 0, s[84:85]
	s_mov_b32 m0, s22
	ds_read_b128 v[164:167], v242 offset:49152
	ds_read_b128 v[168:171], v242 offset:50176
	ds_read_b128 v[172:175], v242 offset:51200
	ds_read_b128 v[176:179], v242 offset:52224
	ds_read_b128 v[180:183], v242 offset:53248
	ds_read_b128 v[184:187], v242 offset:54272
	ds_read_b128 v[188:191], v242 offset:55296
	ds_read_b128 v[214:217], v242 offset:56320
	global_load_lds_dwordx4 v[218:219], off
	s_add_i32 m0, s22, 0x2000
	s_add_u32 s22, s26, 0x2b0080
	v_lshl_add_u64 v[218:219], v[220:221], 0, s[84:85]
	s_addc_u32 s23, s27, 0
	s_add_i32 s26, s57, s41
	global_load_lds_dwordx4 v[218:219], off
	s_mov_b32 m0, s26
	s_nop 0
	global_load_lds_dwordx4 v2, s[22:23]
	s_add_i32 m0, s26, 0x2000
	s_nop 0
	global_load_lds_dwordx4 v204, s[22:23]
	s_cmpk_eq_i32 s55, 0xa8
	s_cbranch_scc0 .Ldefer_1700_peel
	v_lshl_add_u64 v[218:219], v[222:223], 0, s[84:85]
	s_mov_b32 m0, s46
	s_nop 0
	global_load_lds_dwordx4 v[218:219], off
	v_lshl_add_u64 v[218:219], v[224:225], 0, s[84:85]
	s_mov_b32 m0, s47
	s_nop 0
	global_load_lds_dwordx4 v[218:219], off
; #define PG8_STAGE(bufoff, gbase, voff) do { _Pragma("unroll") for (int _i = 0; _i < 2; ++_i) \
;         __builtin_amdgcn_global_load_lds((const unsigned*)((const char*)(gbase) + (voff)[_i]), (PG8_LAS unsigned*)(lds + (bufoff) + ldsw + _i * 8192), 16, 0, 0); } while (0)
; #define PG8_LDA(dst, b, h) do { _Pragma("unroll") for (int m = 0; m < 4; ++m) _Pragma("unroll") for (int k = 0; k < 2; ++k) dst[m][k] = *(const PG8_LAS bf16x8*)(lds + PG8_SA(b, h) + aoff + m * 2048 + k * 1024); } while (0)
; #define PG8_LDB(dst, b, h) do { _Pragma("unroll") for (int n = 0; n < 2; ++n) _Pragma("unroll") for (int k = 0; k < 2; ++k) dst[n][k] = *(const PG8_LAS bf16x8*)(lds + PG8_SB(b, h) + boff + n * 2048 + k * 1024); } while (0)
; #define PG8_WAIT_V(n) asm volatile("s_waitcnt vmcnt(" #n ")" ::: "memory")
; #define PG8_WAIT_L(n) asm volatile("s_waitcnt lgkmcnt(" #n ")" ::: "memory")
; #define PG8_BAR __builtin_amdgcn_s_barrier()
; #define PG8_SCHED __builtin_amdgcn_sched_barrier(0)
; template <class Epi, class Sched, bool ALIGN_EPI = false, bool SP2 = false, bool I8 = false>
; __device__ __forceinline__ void gemm_phase(PG8_LAS unsigned char* lds, const Gemm g, const Sched& S, const Epi& E) {
;     ...
;             const char* a1 = cA + (size_t)(t + 1) * kstep;
;             const char* a2 = last ? nA : cA + (size_t)(t + 2) * kstep; const char* b2 = last ? nB : cB + (size_t)(t + 2) * kstep;
;             const char* a3 = a2 + kstep; const char* b3 = b2 + kstep;
;             if (last && has_next) S.a_ready(nxt);
;             if constexpr (SP2) {
;             PG8_LDB(B0, 0, 0); PG8_LDB(B1, 0, 1); PG8_SCHED; PG8_LDA(At, 0, 0); PG8_STAGE(PG8_SA(1, 1), a1 + hstep, voffA);
;             PG8_WAIT_V(8); PG8_WAIT_L(0); PG8_BAR; PG8_MMA(0, 0, At, B0); PG8_MMA(0, 1, At, B1); PG8_BAR; PG8_SCHED;
;     ...
;             PG8_LDA(At, 1, 1); PG8_STAGE(PG8_SB(1, 0), b3, voffB); PG8_STAGE(PG8_SB(1, 1), b3 + hstep, voffB); PG8_STAGE(PG8_SA(1, 0), a3, voffA);
;             PG8_WAIT_V(8); PG8_WAIT_L(0); PG8_BAR; PG8_MMA(1, 0, At, B0); PG8_MMA(1, 1, At, B1); PG8_BAR; PG8_SCHED;
.Ldefer_1700_peel:
	s_waitcnt vmcnt(6)
	s_waitcnt lgkmcnt(7)
	s_setprio 1
	s_barrier
	v_mfma_f32_16x16x32_bf16 v[64:67], v[124:127], v[164:167], v[64:67]
	s_waitcnt lgkmcnt(6)
	v_mfma_f32_16x16x32_bf16 v[64:67], v[128:131], v[168:171], v[64:67]
	s_waitcnt lgkmcnt(4)
	v_mfma_f32_16x16x32_bf16 v[48:51], v[128:131], v[176:179], v[48:51]
	v_mfma_f32_16x16x32_bf16 v[48:51], v[124:127], v[172:175], v[48:51]
	s_waitcnt lgkmcnt(3)
	v_mfma_f32_16x16x32_bf16 v[32:35], v[124:127], v[180:183], v[32:35]
	s_waitcnt lgkmcnt(2)
	v_mfma_f32_16x16x32_bf16 v[32:35], v[128:131], v[184:187], v[32:35]
	s_waitcnt lgkmcnt(0)
	v_mfma_f32_16x16x32_bf16 v[16:19], v[128:131], v[214:217], v[16:19]
	v_mfma_f32_16x16x32_bf16 v[16:19], v[124:127], v[188:191], v[16:19]
	v_mfma_f32_16x16x32_bf16 v[12:15], v[132:135], v[188:191], v[12:15]
	v_mfma_f32_16x16x32_bf16 v[12:15], v[144:147], v[214:217], v[12:15]
	v_mfma_f32_16x16x32_bf16 v[28:31], v[144:147], v[184:187], v[28:31]
	v_mfma_f32_16x16x32_bf16 v[28:31], v[132:135], v[180:183], v[28:31]
	v_mfma_f32_16x16x32_bf16 v[44:47], v[132:135], v[172:175], v[44:47]
	v_mfma_f32_16x16x32_bf16 v[44:47], v[144:147], v[176:179], v[44:47]
	v_mfma_f32_16x16x32_bf16 v[60:63], v[144:147], v[168:171], v[60:63]
	v_mfma_f32_16x16x32_bf16 v[60:63], v[132:135], v[164:167], v[60:63]
	v_mfma_f32_16x16x32_bf16 v[56:59], v[148:151], v[164:167], v[56:59]
	v_mfma_f32_16x16x32_bf16 v[56:59], v[152:155], v[168:171], v[56:59]
	v_mfma_f32_16x16x32_bf16 v[40:43], v[152:155], v[176:179], v[40:43]
	v_mfma_f32_16x16x32_bf16 v[40:43], v[148:151], v[172:175], v[40:43]
	v_mfma_f32_16x16x32_bf16 v[24:27], v[148:151], v[180:183], v[24:27]
	v_mfma_f32_16x16x32_bf16 v[24:27], v[152:155], v[184:187], v[24:27]
	v_mfma_f32_16x16x32_bf16 v[8:11], v[152:155], v[214:217], v[8:11]
	v_mfma_f32_16x16x32_bf16 v[8:11], v[148:151], v[188:191], v[8:11]
	v_mfma_f32_16x16x32_bf16 v[4:7], v[156:159], v[188:191], v[4:7]
	v_mfma_f32_16x16x32_bf16 v[4:7], v[160:163], v[214:217], v[4:7]
	v_mfma_f32_16x16x32_bf16 v[20:23], v[160:163], v[184:187], v[20:23]
	v_mfma_f32_16x16x32_bf16 v[20:23], v[156:159], v[180:183], v[20:23]
	v_mfma_f32_16x16x32_bf16 v[36:39], v[156:159], v[172:175], v[36:39]
	v_mfma_f32_16x16x32_bf16 v[36:39], v[160:163], v[176:179], v[36:39]
	v_mfma_f32_16x16x32_bf16 v[52:55], v[160:163], v[168:171], v[52:55]
	v_mfma_f32_16x16x32_bf16 v[52:55], v[156:159], v[164:167], v[52:55]
	s_barrier
	s_setprio 0
	s_add_i32 s55, s55, 2
	s_add_u32 s53, s53, 0x100
	s_addc_u32 s54, s54, 0
	s_cmpk_gt_u32 s55, 0xa9
	s_mov_b64 s[22:23], s[24:25]
	s_cbranch_scc1 .Lkloop_exit_5
.LBB0_1700:
	s_add_u32 s24, s22, 0x100
	s_addc_u32 s25, s23, 0
	s_add_i32 s56, 0, 0x10000
	s_cmpk_eq_i32 s55, 0xa8
	s_cselect_b32 s37, s13, s25
	s_cselect_b32 s36, s12, s24
	s_cselect_b32 s27, s21, s54
	s_cselect_b32 s26, s20, s53
	s_add_i32 s57, 0, 0x14000
	v_add_u32_e32 v144, s56, v240
	v_add_u32_e32 v160, s57, v240
	ds_read_b128 v[124:127], v144
	ds_read_b128 v[128:131], v144 offset:1024
	ds_read_b128 v[132:135], v144 offset:2048
	ds_read_b128 v[144:147], v144 offset:3072
	ds_read_b128 v[148:151], v160
	ds_read_b128 v[152:155], v160 offset:1024
	ds_read_b128 v[156:159], v160 offset:2048
	ds_read_b128 v[160:163], v160 offset:3072
	v_lshl_add_u64 v[218:219], v[222:223], 0, s[84:85]
	s_mov_b32 m0, s46
	s_nop 0
	global_load_lds_dwordx4 v[218:219], off
	v_lshl_add_u64 v[218:219], v[224:225], 0, s[84:85]
	s_mov_b32 m0, s47
	s_nop 0
	global_load_lds_dwordx4 v[218:219], off
	v_lshl_add_u64 v[218:219], s[22:23], 0, v[210:211]
	s_add_i32 m0, s42, 0xc000
	ds_read_b128 v[164:167], v242
	ds_read_b128 v[168:171], v242 offset:1024
	ds_read_b128 v[172:175], v242 offset:2048
	ds_read_b128 v[176:179], v242 offset:3072
	ds_read_b128 v[180:183], v242 offset:4096
	ds_read_b128 v[184:187], v242 offset:5120
	ds_read_b128 v[188:191], v242 offset:6144
	ds_read_b128 v[214:217], v242 offset:7168
	global_load_lds_dwordx4 v[218:219], off
	v_lshl_add_u64 v[218:219], s[22:23], 0, v[212:213]
	s_add_i32 m0, s42, 0xe000
	s_nop 0
	global_load_lds_dwordx4 v[218:219], off
	s_waitcnt vmcnt(8)
	s_waitcnt lgkmcnt(7)
	s_setprio 1
	s_barrier
	v_mfma_f32_16x16x32_bf16 v[140:143], v[124:127], v[164:167], v[140:143]
	s_waitcnt lgkmcnt(6)
	v_mfma_f32_16x16x32_bf16 v[140:143], v[128:131], v[168:171], v[140:143]
	s_waitcnt lgkmcnt(4)
	v_mfma_f32_16x16x32_bf16 v[112:115], v[128:131], v[176:179], v[112:115]
	v_mfma_f32_16x16x32_bf16 v[112:115], v[124:127], v[172:175], v[112:115]
	s_waitcnt lgkmcnt(3)
	v_mfma_f32_16x16x32_bf16 v[96:99], v[124:127], v[180:183], v[96:99]
	s_waitcnt lgkmcnt(2)
	v_mfma_f32_16x16x32_bf16 v[96:99], v[128:131], v[184:187], v[96:99]
	s_waitcnt lgkmcnt(0)
	v_mfma_f32_16x16x32_bf16 v[80:83], v[128:131], v[214:217], v[80:83]
	v_mfma_f32_16x16x32_bf16 v[80:83], v[124:127], v[188:191], v[80:83]
	v_mfma_f32_16x16x32_bf16 v[76:79], v[132:135], v[188:191], v[76:79]
	v_mfma_f32_16x16x32_bf16 v[76:79], v[144:147], v[214:217], v[76:79]
	v_mfma_f32_16x16x32_bf16 v[92:95], v[144:147], v[184:187], v[92:95]
	v_mfma_f32_16x16x32_bf16 v[92:95], v[132:135], v[180:183], v[92:95]
	v_mfma_f32_16x16x32_bf16 v[108:111], v[132:135], v[172:175], v[108:111]
	v_mfma_f32_16x16x32_bf16 v[108:111], v[144:147], v[176:179], v[108:111]
	v_mfma_f32_16x16x32_bf16 v[136:139], v[144:147], v[168:171], v[136:139]
	v_mfma_f32_16x16x32_bf16 v[136:139], v[132:135], v[164:167], v[136:139]
	v_mfma_f32_16x16x32_bf16 v[120:123], v[148:151], v[164:167], v[120:123]
	v_mfma_f32_16x16x32_bf16 v[120:123], v[152:155], v[168:171], v[120:123]
	v_mfma_f32_16x16x32_bf16 v[104:107], v[152:155], v[176:179], v[104:107]
	v_mfma_f32_16x16x32_bf16 v[104:107], v[148:151], v[172:175], v[104:107]
	v_mfma_f32_16x16x32_bf16 v[88:91], v[148:151], v[180:183], v[88:91]
	v_mfma_f32_16x16x32_bf16 v[88:91], v[152:155], v[184:187], v[88:91]
	v_mfma_f32_16x16x32_bf16 v[72:75], v[152:155], v[214:217], v[72:75]
	v_mfma_f32_16x16x32_bf16 v[72:75], v[148:151], v[188:191], v[72:75]
	v_mfma_f32_16x16x32_bf16 v[68:71], v[156:159], v[188:191], v[68:71]
	v_mfma_f32_16x16x32_bf16 v[68:71], v[160:163], v[214:217], v[68:71]
	v_mfma_f32_16x16x32_bf16 v[84:87], v[160:163], v[184:187], v[84:87]
	v_mfma_f32_16x16x32_bf16 v[84:87], v[156:159], v[180:183], v[84:87]
	v_mfma_f32_16x16x32_bf16 v[100:103], v[156:159], v[172:175], v[100:103]
	v_mfma_f32_16x16x32_bf16 v[100:103], v[160:163], v[176:179], v[100:103]
	v_mfma_f32_16x16x32_bf16 v[116:119], v[160:163], v[168:171], v[116:119]
	v_mfma_f32_16x16x32_bf16 v[116:119], v[156:159], v[164:167], v[116:119]
	s_barrier
; #define PG8_STAGE(bufoff, gbase, voff) do { _Pragma("unroll") for (int _i = 0; _i < 2; ++_i) \
;         __builtin_amdgcn_global_load_lds((const unsigned*)((const char*)(gbase) + (voff)[_i]), (PG8_LAS unsigned*)(lds + (bufoff) + ldsw + _i * 8192), 16, 0, 0); } while (0)
; #define PG8_LDA(dst, b, h) do { _Pragma("unroll") for (int m = 0; m < 4; ++m) _Pragma("unroll") for (int k = 0; k < 2; ++k) dst[m][k] = *(const PG8_LAS bf16x8*)(lds + PG8_SA(b, h) + aoff + m * 2048 + k * 1024); } while (0)
; #define PG8_LDB(dst, b, h) do { _Pragma("unroll") for (int n = 0; n < 2; ++n) _Pragma("unroll") for (int k = 0; k < 2; ++k) dst[n][k] = *(const PG8_LAS bf16x8*)(lds + PG8_SB(b, h) + boff + n * 2048 + k * 1024); } while (0)
; #define PG8_WAIT_V(n) asm volatile("s_waitcnt vmcnt(" #n ")" ::: "memory")
; #define PG8_WAIT_L(n) asm volatile("s_waitcnt lgkmcnt(" #n ")" ::: "memory")
; #define PG8_BAR __builtin_amdgcn_s_barrier()
; #define PG8_SCHED __builtin_amdgcn_sched_barrier(0)
; template <class Epi, class Sched, bool ALIGN_EPI = false, bool SP2 = false, bool I8 = false>
; __device__ __forceinline__ void gemm_phase(PG8_LAS unsigned char* lds, const Gemm g, const Sched& S, const Epi& E) {
;     ...
;             PG8_WAIT_V(8); PG8_WAIT_L(0); PG8_BAR; PG8_MMA(0, 0, At, B0); PG8_MMA(0, 1, At, B1); PG8_BAR; PG8_SCHED;
;             PG8_LDA(At, 0, 1); PG8_STAGE(PG8_SB(0, 0), b2, voffB); PG8_STAGE(PG8_SB(0, 1), b2 + hstep, voffB); PG8_STAGE(PG8_SA(0, 0), a2, voffA);
;             PG8_WAIT_V(8); PG8_WAIT_L(0); PG8_BAR; PG8_MMA(1, 0, At, B0); PG8_MMA(1, 1, At, B1); PG8_BAR; PG8_SCHED;
;             PG8_LDB(B0, 1, 0); PG8_LDB(B1, 1, 1); PG8_SCHED; PG8_LDA(At, 1, 0); PG8_STAGE(PG8_SA(0, 1), a2 + hstep, voffA);
	s_setprio 0
	s_add_i32 s22, s56, s41
	v_lshl_add_u64 v[218:219], s[26:27], 0, v[2:3]
	s_mov_b32 m0, s22
	ds_read_b128 v[164:167], v242 offset:16384
	ds_read_b128 v[168:171], v242 offset:17408
	ds_read_b128 v[172:175], v242 offset:18432
	ds_read_b128 v[176:179], v242 offset:19456
	ds_read_b128 v[180:183], v242 offset:20480
	ds_read_b128 v[184:187], v242 offset:21504
	ds_read_b128 v[188:191], v242 offset:22528
	ds_read_b128 v[214:217], v242 offset:23552
	global_load_lds_dwordx4 v[218:219], off
	s_add_i32 m0, s22, 0x2000
	s_add_u32 s22, s26, 0x2b0000
	v_lshl_add_u64 v[220:221], s[26:27], 0, v[204:205]
	s_addc_u32 s23, s27, 0
	s_add_i32 s56, s57, s41
	global_load_lds_dwordx4 v[220:221], off
	s_mov_b32 m0, s56
	v_lshl_add_u64 v[224:225], s[36:37], 0, v[206:207]
	global_load_lds_dwordx4 v2, s[22:23]
	s_add_i32 m0, s56, 0x2000
	s_nop 0
	global_load_lds_dwordx4 v204, s[22:23]
	v_lshl_add_u64 v[222:223], s[36:37], 0, v[208:209]
	s_waitcnt vmcnt(6)
	s_waitcnt lgkmcnt(7)
	s_setprio 1
	s_barrier
	v_mfma_f32_16x16x32_bf16 v[64:67], v[124:127], v[164:167], v[64:67]
	s_waitcnt lgkmcnt(6)
	v_mfma_f32_16x16x32_bf16 v[64:67], v[128:131], v[168:171], v[64:67]
	s_waitcnt lgkmcnt(4)
	v_mfma_f32_16x16x32_bf16 v[48:51], v[128:131], v[176:179], v[48:51]
	v_mfma_f32_16x16x32_bf16 v[48:51], v[124:127], v[172:175], v[48:51]
	s_waitcnt lgkmcnt(3)
	v_mfma_f32_16x16x32_bf16 v[32:35], v[124:127], v[180:183], v[32:35]
	s_waitcnt lgkmcnt(2)
	v_mfma_f32_16x16x32_bf16 v[32:35], v[128:131], v[184:187], v[32:35]
	s_waitcnt lgkmcnt(0)
	v_mfma_f32_16x16x32_bf16 v[16:19], v[128:131], v[214:217], v[16:19]
	v_mfma_f32_16x16x32_bf16 v[16:19], v[124:127], v[188:191], v[16:19]
	v_mfma_f32_16x16x32_bf16 v[12:15], v[132:135], v[188:191], v[12:15]
	v_mfma_f32_16x16x32_bf16 v[12:15], v[144:147], v[214:217], v[12:15]
	v_mfma_f32_16x16x32_bf16 v[28:31], v[144:147], v[184:187], v[28:31]
	v_mfma_f32_16x16x32_bf16 v[28:31], v[132:135], v[180:183], v[28:31]
	v_mfma_f32_16x16x32_bf16 v[44:47], v[132:135], v[172:175], v[44:47]
	v_mfma_f32_16x16x32_bf16 v[44:47], v[144:147], v[176:179], v[44:47]
	v_mfma_f32_16x16x32_bf16 v[60:63], v[144:147], v[168:171], v[60:63]
	v_mfma_f32_16x16x32_bf16 v[60:63], v[132:135], v[164:167], v[60:63]
	v_mfma_f32_16x16x32_bf16 v[56:59], v[148:151], v[164:167], v[56:59]
	v_mfma_f32_16x16x32_bf16 v[56:59], v[152:155], v[168:171], v[56:59]
	v_mfma_f32_16x16x32_bf16 v[40:43], v[152:155], v[176:179], v[40:43]
	v_mfma_f32_16x16x32_bf16 v[40:43], v[148:151], v[172:175], v[40:43]
	v_mfma_f32_16x16x32_bf16 v[24:27], v[148:151], v[180:183], v[24:27]
	v_mfma_f32_16x16x32_bf16 v[24:27], v[152:155], v[184:187], v[24:27]
	v_mfma_f32_16x16x32_bf16 v[8:11], v[152:155], v[214:217], v[8:11]
	v_mfma_f32_16x16x32_bf16 v[8:11], v[148:151], v[188:191], v[8:11]
	v_mfma_f32_16x16x32_bf16 v[4:7], v[156:159], v[188:191], v[4:7]
	v_mfma_f32_16x16x32_bf16 v[4:7], v[160:163], v[214:217], v[4:7]
	v_mfma_f32_16x16x32_bf16 v[20:23], v[160:163], v[184:187], v[20:23]
	v_mfma_f32_16x16x32_bf16 v[20:23], v[156:159], v[180:183], v[20:23]
	v_mfma_f32_16x16x32_bf16 v[36:39], v[156:159], v[172:175], v[36:39]
	v_mfma_f32_16x16x32_bf16 v[36:39], v[160:163], v[176:179], v[36:39]
	v_mfma_f32_16x16x32_bf16 v[52:55], v[160:163], v[168:171], v[52:55]
	v_mfma_f32_16x16x32_bf16 v[52:55], v[156:159], v[164:167], v[52:55]
	s_barrier
	s_setprio 0
	s_mov_b32 m0, s42
	s_nop 0
	global_load_lds_dwordx4 v[222:223], off
	s_mov_b32 m0, s43
	s_nop 0
	global_load_lds_dwordx4 v[224:225], off
	s_add_i32 s56, 0, 0x18000
	s_add_i32 s57, 0, 0x1c000
	v_add_u32_e32 v144, s56, v240
	v_add_u32_e32 v160, s57, v240
	ds_read_b128 v[124:127], v144
	ds_read_b128 v[128:131], v144 offset:1024
	ds_read_b128 v[132:135], v144 offset:2048
	ds_read_b128 v[144:147], v144 offset:3072
	ds_read_b128 v[148:151], v160
	ds_read_b128 v[152:155], v160 offset:1024
	ds_read_b128 v[156:159], v160 offset:2048
	ds_read_b128 v[160:163], v160 offset:3072
	s_add_u32 s22, s36, 0x2b0000
	s_addc_u32 s23, s37, 0
	s_mov_b32 m0, s44
	ds_read_b128 v[164:167], v242 offset:32768
	ds_read_b128 v[168:171], v242 offset:33792
	ds_read_b128 v[172:175], v242 offset:34816
	ds_read_b128 v[176:179], v242 offset:35840
	ds_read_b128 v[180:183], v242 offset:36864
	ds_read_b128 v[184:187], v242 offset:37888
	ds_read_b128 v[188:191], v242 offset:38912
	ds_read_b128 v[214:217], v242 offset:39936
	global_load_lds_dwordx4 v208, s[22:23]
	s_mov_b32 m0, s45
	s_nop 0
	global_load_lds_dwordx4 v206, s[22:23]
	s_waitcnt vmcnt(8)
	s_waitcnt lgkmcnt(7)
	s_setprio 1
	s_barrier
; #define PG8_STAGE(bufoff, gbase, voff) do { _Pragma("unroll") for (int _i = 0; _i < 2; ++_i) \
;         __builtin_amdgcn_global_load_lds((const unsigned*)((const char*)(gbase) + (voff)[_i]), (PG8_LAS unsigned*)(lds + (bufoff) + ldsw + _i * 8192), 16, 0, 0); } while (0)
; #define PG8_LDA(dst, b, h) do { _Pragma("unroll") for (int m = 0; m < 4; ++m) _Pragma("unroll") for (int k = 0; k < 2; ++k) dst[m][k] = *(const PG8_LAS bf16x8*)(lds + PG8_SA(b, h) + aoff + m * 2048 + k * 1024); } while (0)
; #define PG8_WAIT_V(n) asm volatile("s_waitcnt vmcnt(" #n ")" ::: "memory")
; #define PG8_WAIT_L(n) asm volatile("s_waitcnt lgkmcnt(" #n ")" ::: "memory")
; #define PG8_BAR __builtin_amdgcn_s_barrier()
; #define PG8_SCHED __builtin_amdgcn_sched_barrier(0)
; template <class Epi, class Sched, bool ALIGN_EPI = false, bool SP2 = false, bool I8 = false>
; __device__ __forceinline__ void gemm_phase(PG8_LAS unsigned char* lds, const Gemm g, const Sched& S, const Epi& E) {
;     ...
;             PG8_WAIT_V(8); PG8_WAIT_L(0); PG8_BAR; PG8_MMA(0, 0, At, B0); PG8_MMA(0, 1, At, B1); PG8_BAR; PG8_SCHED;
;             PG8_LDA(At, 1, 1); PG8_STAGE(PG8_SB(1, 0), b3, voffB); PG8_STAGE(PG8_SB(1, 1), b3 + hstep, voffB); PG8_STAGE(PG8_SA(1, 0), a3, voffA);
;             PG8_WAIT_V(8); PG8_WAIT_L(0); PG8_BAR; PG8_MMA(1, 0, At, B0); PG8_MMA(1, 1, At, B1); PG8_BAR; PG8_SCHED;
	v_mfma_f32_16x16x32_bf16 v[140:143], v[124:127], v[164:167], v[140:143]
	s_waitcnt lgkmcnt(6)
	v_mfma_f32_16x16x32_bf16 v[140:143], v[128:131], v[168:171], v[140:143]
	s_waitcnt lgkmcnt(4)
	v_mfma_f32_16x16x32_bf16 v[112:115], v[128:131], v[176:179], v[112:115]
	v_mfma_f32_16x16x32_bf16 v[112:115], v[124:127], v[172:175], v[112:115]
	s_waitcnt lgkmcnt(3)
	v_mfma_f32_16x16x32_bf16 v[96:99], v[124:127], v[180:183], v[96:99]
	s_waitcnt lgkmcnt(2)
	v_mfma_f32_16x16x32_bf16 v[96:99], v[128:131], v[184:187], v[96:99]
	s_waitcnt lgkmcnt(0)
	v_mfma_f32_16x16x32_bf16 v[80:83], v[128:131], v[214:217], v[80:83]
	v_mfma_f32_16x16x32_bf16 v[80:83], v[124:127], v[188:191], v[80:83]
	v_mfma_f32_16x16x32_bf16 v[76:79], v[132:135], v[188:191], v[76:79]
	v_mfma_f32_16x16x32_bf16 v[76:79], v[144:147], v[214:217], v[76:79]
	v_mfma_f32_16x16x32_bf16 v[92:95], v[144:147], v[184:187], v[92:95]
	v_mfma_f32_16x16x32_bf16 v[92:95], v[132:135], v[180:183], v[92:95]
	v_mfma_f32_16x16x32_bf16 v[108:111], v[132:135], v[172:175], v[108:111]
	v_mfma_f32_16x16x32_bf16 v[108:111], v[144:147], v[176:179], v[108:111]
	v_mfma_f32_16x16x32_bf16 v[136:139], v[144:147], v[168:171], v[136:139]
	v_mfma_f32_16x16x32_bf16 v[136:139], v[132:135], v[164:167], v[136:139]
	v_mfma_f32_16x16x32_bf16 v[120:123], v[148:151], v[164:167], v[120:123]
	v_mfma_f32_16x16x32_bf16 v[120:123], v[152:155], v[168:171], v[120:123]
	v_mfma_f32_16x16x32_bf16 v[104:107], v[152:155], v[176:179], v[104:107]
	v_mfma_f32_16x16x32_bf16 v[104:107], v[148:151], v[172:175], v[104:107]
	v_mfma_f32_16x16x32_bf16 v[88:91], v[148:151], v[180:183], v[88:91]
	v_mfma_f32_16x16x32_bf16 v[88:91], v[152:155], v[184:187], v[88:91]
	v_mfma_f32_16x16x32_bf16 v[72:75], v[152:155], v[214:217], v[72:75]
	v_mfma_f32_16x16x32_bf16 v[72:75], v[148:151], v[188:191], v[72:75]
	v_mfma_f32_16x16x32_bf16 v[68:71], v[156:159], v[188:191], v[68:71]
	v_mfma_f32_16x16x32_bf16 v[68:71], v[160:163], v[214:217], v[68:71]
	v_mfma_f32_16x16x32_bf16 v[84:87], v[160:163], v[184:187], v[84:87]
	v_mfma_f32_16x16x32_bf16 v[84:87], v[156:159], v[180:183], v[84:87]
	v_mfma_f32_16x16x32_bf16 v[100:103], v[156:159], v[172:175], v[100:103]
	v_mfma_f32_16x16x32_bf16 v[100:103], v[160:163], v[176:179], v[100:103]
	v_mfma_f32_16x16x32_bf16 v[116:119], v[160:163], v[168:171], v[116:119]
	v_mfma_f32_16x16x32_bf16 v[116:119], v[156:159], v[164:167], v[116:119]
	s_barrier
	s_setprio 0
	s_add_i32 s22, s56, s41
	v_lshl_add_u64 v[218:219], v[218:219], 0, s[84:85]
	s_mov_b32 m0, s22
	ds_read_b128 v[164:167], v242 offset:49152
	ds_read_b128 v[168:171], v242 offset:50176
	ds_read_b128 v[172:175], v242 offset:51200
	ds_read_b128 v[176:179], v242 offset:52224
	ds_read_b128 v[180:183], v242 offset:53248
	ds_read_b128 v[184:187], v242 offset:54272
	ds_read_b128 v[188:191], v242 offset:55296
	ds_read_b128 v[214:217], v242 offset:56320
	global_load_lds_dwordx4 v[218:219], off
	s_add_i32 m0, s22, 0x2000
	s_add_u32 s22, s26, 0x2b0080
	v_lshl_add_u64 v[218:219], v[220:221], 0, s[84:85]
	s_addc_u32 s23, s27, 0
	s_add_i32 s26, s57, s41
	global_load_lds_dwordx4 v[218:219], off
	s_mov_b32 m0, s26
	s_nop 0
	global_load_lds_dwordx4 v2, s[22:23]
	s_add_i32 m0, s26, 0x2000
	s_nop 0
	global_load_lds_dwordx4 v204, s[22:23]
	s_cmpk_eq_i32 s55, 0xa8
	s_cbranch_scc0 .Ldefer_1700_body
	v_lshl_add_u64 v[218:219], v[222:223], 0, s[84:85]
	s_mov_b32 m0, s46
	s_nop 0
	global_load_lds_dwordx4 v[218:219], off
	v_lshl_add_u64 v[218:219], v[224:225], 0, s[84:85]
	s_mov_b32 m0, s47
	s_nop 0
	global_load_lds_dwordx4 v[218:219], off
.Ldefer_1700_body:
	s_waitcnt vmcnt(6)
	s_waitcnt lgkmcnt(7)
	s_setprio 1
	s_barrier
	v_mfma_f32_16x16x32_bf16 v[64:67], v[124:127], v[164:167], v[64:67]
	s_waitcnt lgkmcnt(6)
	v_mfma_f32_16x16x32_bf16 v[64:67], v[128:131], v[168:171], v[64:67]
	s_waitcnt lgkmcnt(4)
	v_mfma_f32_16x16x32_bf16 v[48:51], v[128:131], v[176:179], v[48:51]
	v_mfma_f32_16x16x32_bf16 v[48:51], v[124:127], v[172:175], v[48:51]
	s_waitcnt lgkmcnt(3)
	v_mfma_f32_16x16x32_bf16 v[32:35], v[124:127], v[180:183], v[32:35]
	s_waitcnt lgkmcnt(2)
	v_mfma_f32_16x16x32_bf16 v[32:35], v[128:131], v[184:187], v[32:35]
	s_waitcnt lgkmcnt(0)
	v_mfma_f32_16x16x32_bf16 v[16:19], v[128:131], v[214:217], v[16:19]
	v_mfma_f32_16x16x32_bf16 v[16:19], v[124:127], v[188:191], v[16:19]
	v_mfma_f32_16x16x32_bf16 v[12:15], v[132:135], v[188:191], v[12:15]
	v_mfma_f32_16x16x32_bf16 v[12:15], v[144:147], v[214:217], v[12:15]
	v_mfma_f32_16x16x32_bf16 v[28:31], v[144:147], v[184:187], v[28:31]
	v_mfma_f32_16x16x32_bf16 v[28:31], v[132:135], v[180:183], v[28:31]
	v_mfma_f32_16x16x32_bf16 v[44:47], v[132:135], v[172:175], v[44:47]
	v_mfma_f32_16x16x32_bf16 v[44:47], v[144:147], v[176:179], v[44:47]
	v_mfma_f32_16x16x32_bf16 v[60:63], v[144:147], v[168:171], v[60:63]
	v_mfma_f32_16x16x32_bf16 v[60:63], v[132:135], v[164:167], v[60:63]
	v_mfma_f32_16x16x32_bf16 v[56:59], v[148:151], v[164:167], v[56:59]
	v_mfma_f32_16x16x32_bf16 v[56:59], v[152:155], v[168:171], v[56:59]
	v_mfma_f32_16x16x32_bf16 v[40:43], v[152:155], v[176:179], v[40:43]
	v_mfma_f32_16x16x32_bf16 v[40:43], v[148:151], v[172:175], v[40:43]
	v_mfma_f32_16x16x32_bf16 v[24:27], v[148:151], v[180:183], v[24:27]
	v_mfma_f32_16x16x32_bf16 v[24:27], v[152:155], v[184:187], v[24:27]
	v_mfma_f32_16x16x32_bf16 v[8:11], v[152:155], v[214:217], v[8:11]
	v_mfma_f32_16x16x32_bf16 v[8:11], v[148:151], v[188:191], v[8:11]
	v_mfma_f32_16x16x32_bf16 v[4:7], v[156:159], v[188:191], v[4:7]
	v_mfma_f32_16x16x32_bf16 v[4:7], v[160:163], v[214:217], v[4:7]
	v_mfma_f32_16x16x32_bf16 v[20:23], v[160:163], v[184:187], v[20:23]
	v_mfma_f32_16x16x32_bf16 v[20:23], v[156:159], v[180:183], v[20:23]
	v_mfma_f32_16x16x32_bf16 v[36:39], v[156:159], v[172:175], v[36:39]
	v_mfma_f32_16x16x32_bf16 v[36:39], v[160:163], v[176:179], v[36:39]
	v_mfma_f32_16x16x32_bf16 v[52:55], v[160:163], v[168:171], v[52:55]
	v_mfma_f32_16x16x32_bf16 v[52:55], v[156:159], v[164:167], v[52:55]
	s_barrier
	s_setprio 0
	s_add_i32 s55, s55, 2
	s_add_u32 s53, s53, 0x100
	s_addc_u32 s54, s54, 0
	s_cmpk_gt_u32 s55, 0xa9
	s_mov_b64 s[22:23], s[24:25]
	s_cbranch_scc0 .LBB0_1700

; #define PG8_STAGE(bufoff, gbase, voff) do { _Pragma("unroll") for (int _i = 0; _i < 2; ++_i) \
;         __builtin_amdgcn_global_load_lds((const unsigned*)((const char*)(gbase) + (voff)[_i]), (PG8_LAS unsigned*)(lds + (bufoff) + ldsw + _i * 8192), 16, 0, 0); } while (0)
; #define PG8_LDA(dst, b, h) do { _Pragma("unroll") for (int m = 0; m < 4; ++m) _Pragma("unroll") for (int k = 0; k < 2; ++k) dst[m][k] = *(const PG8_LAS bf16x8*)(lds + PG8_SA(b, h) + aoff + m * 2048 + k * 1024); } while (0)
; #define PG8_LDB(dst, b, h) do { _Pragma("unroll") for (int n = 0; n < 2; ++n) _Pragma("unroll") for (int k = 0; k < 2; ++k) dst[n][k] = *(const PG8_LAS bf16x8*)(lds + PG8_SB(b, h) + boff + n * 2048 + k * 1024); } while (0)
; #define PG8_WAIT_V(n) asm volatile("s_waitcnt vmcnt(" #n ")" ::: "memory")
; #define PG8_WAIT_L(n) asm volatile("s_waitcnt lgkmcnt(" #n ")" ::: "memory")
; #define PG8_BAR __builtin_amdgcn_s_barrier()
; #define PG8_SCHED __builtin_amdgcn_sched_barrier(0)
; template <class Epi, class Sched, bool ALIGN_EPI = false, bool SP2 = false, bool I8 = false>
; __device__ __forceinline__ void gemm_phase(PG8_LAS unsigned char* lds, const Gemm g, const Sched& S, const Epi& E) {
;     ...
;         const bool has_next = S.next(ui + 1, nxt);
;         const char* nA = has_next ? (const char*)g.A + (size_t)nxt.pm * tstep : cA; const char* nB = has_next ? (const char*)g.Bt + (size_t)nxt.pn * tstep : cB;
;         for (int t = 0; t < nt; t += 2) {
;             const bool last = (t == nt - 2);
;             const char* a1 = cA + (size_t)(t + 1) * kstep;
;             const char* a2 = last ? nA : cA + (size_t)(t + 2) * kstep; const char* b2 = last ? nB : cB + (size_t)(t + 2) * kstep;
;             const char* a3 = a2 + kstep; const char* b3 = b2 + kstep;
;             if (last && has_next) S.a_ready(nxt);
;             if constexpr (SP2) {
;             PG8_LDB(B0, 0, 0); PG8_LDB(B1, 0, 1); PG8_SCHED; PG8_LDA(At, 0, 0); PG8_STAGE(PG8_SA(1, 1), a1 + hstep, voffA);
;             PG8_WAIT_V(8); PG8_WAIT_L(0); PG8_BAR; PG8_MMA(0, 0, At, B0); PG8_MMA(0, 1, At, B1); PG8_BAR; PG8_SCHED;
;             PG8_LDA(At, 0, 1); PG8_STAGE(PG8_SB(0, 0), b2, voffB); PG8_STAGE(PG8_SB(0, 1), b2 + hstep, voffB); PG8_STAGE(PG8_SA(0, 0), a2, voffA);
;             PG8_WAIT_V(8); PG8_WAIT_L(0); PG8_BAR; PG8_MMA(1, 0, At, B0); PG8_MMA(1, 1, At, B1); PG8_BAR; PG8_SCHED;
.LBB0_1842:
	s_ashr_i32 s45, s44, 31
	s_lshl_b64 s[34:35], s[44:45], 20
	s_add_u32 s50, s47, s34
	s_addc_u32 s51, s52, s35
	s_and_b64 s[34:35], s[8:9], exec
	s_cselect_b32 s11, s51, s55
	s_cselect_b32 s13, s50, s54
	s_ashr_i32 s49, s48, 31
	s_lshl_b64 s[34:35], s[48:49], 20
	s_add_u32 s56, s53, s34
	s_addc_u32 s57, s64, s35
	s_and_b64 s[34:35], s[8:9], exec
	s_cselect_b32 s34, s57, s59
	s_cselect_b32 s35, s56, s58
	s_add_u32 s54, s54, 0x80080
	s_addc_u32 s55, s55, 0
	s_add_u32 s45, s58, 0x100
	s_addc_u32 s49, s59, 0
	s_mov_b32 s86, -2
	s_waitcnt lgkmcnt(0)
	s_add_u32 s58, s54, 0xfff80080
	s_addc_u32 s59, s55, -1
	s_add_i32 s87, 0, 0x10000
	s_cmp_eq_u32 s86, 28
	s_cselect_b32 s61, s11, s59
	s_cselect_b32 s60, s13, s58
	s_cselect_b32 s59, s34, s49
	s_cselect_b32 s58, s35, s45
	s_add_i32 vcc_lo, 0, 0x14000
	v_add_u32_e32 v40, s87, v217
	v_add_u32_e32 v160, vcc_lo, v217
	ds_read_b128 v[28:31], v40
	ds_read_b128 v[32:35], v40 offset:1024
	ds_read_b128 v[36:39], v40 offset:2048
	ds_read_b128 v[40:43], v40 offset:3072
	ds_read_b128 v[140:143], v160
	ds_read_b128 v[144:147], v160 offset:1024
	ds_read_b128 v[156:159], v160 offset:2048
	ds_read_b128 v[160:163], v160 offset:3072
	s_add_i32 m0, s65, 0xc000
	ds_read_b128 v[164:167], v219
	ds_read_b128 v[168:171], v219 offset:1024
	ds_read_b128 v[172:175], v219 offset:2048
	ds_read_b128 v[176:179], v219 offset:3072
	ds_read_b128 v[204:207], v219 offset:4096
	ds_read_b128 v[208:211], v219 offset:5120
	ds_read_b128 v[212:215], v219 offset:6144
	ds_read_b128 v[220:223], v219 offset:7168
	global_load_lds_dwordx4 v186, s[54:55]
	s_add_i32 m0, s65, 0xe000
	s_nop 0
	global_load_lds_dwordx4 v188, s[54:55]
	s_waitcnt vmcnt(8)
	s_waitcnt lgkmcnt(7)
	s_setprio 1
	s_barrier
	v_mfma_i32_16x16x64_i8 v[152:155], v[28:31], v[164:167], 0
	s_waitcnt lgkmcnt(6)
	v_mfma_i32_16x16x64_i8 v[152:155], v[32:35], v[168:171], v[152:155]
	s_waitcnt lgkmcnt(4)
	v_mfma_i32_16x16x64_i8 v[128:131], v[32:35], v[176:179], 0
	v_mfma_i32_16x16x64_i8 v[128:131], v[28:31], v[172:175], v[128:131]
	s_waitcnt lgkmcnt(3)
	v_mfma_i32_16x16x64_i8 v[112:115], v[28:31], v[204:207], 0
	s_waitcnt lgkmcnt(2)
	v_mfma_i32_16x16x64_i8 v[112:115], v[32:35], v[208:211], v[112:115]
	s_waitcnt lgkmcnt(0)
	v_mfma_i32_16x16x64_i8 v[96:99], v[32:35], v[220:223], 0
	v_mfma_i32_16x16x64_i8 v[96:99], v[28:31], v[212:215], v[96:99]
	v_mfma_i32_16x16x64_i8 v[92:95], v[36:39], v[212:215], 0
	v_mfma_i32_16x16x64_i8 v[92:95], v[40:43], v[220:223], v[92:95]
	v_mfma_i32_16x16x64_i8 v[108:111], v[40:43], v[208:211], 0
	v_mfma_i32_16x16x64_i8 v[108:111], v[36:39], v[204:207], v[108:111]
	v_mfma_i32_16x16x64_i8 v[124:127], v[36:39], v[172:175], 0
	v_mfma_i32_16x16x64_i8 v[124:127], v[40:43], v[176:179], v[124:127]
	v_mfma_i32_16x16x64_i8 v[148:151], v[40:43], v[168:171], 0
	v_mfma_i32_16x16x64_i8 v[148:151], v[36:39], v[164:167], v[148:151]
	v_mfma_i32_16x16x64_i8 v[136:139], v[140:143], v[164:167], 0
	v_mfma_i32_16x16x64_i8 v[136:139], v[144:147], v[168:171], v[136:139]
	v_mfma_i32_16x16x64_i8 v[120:123], v[144:147], v[176:179], 0
	v_mfma_i32_16x16x64_i8 v[120:123], v[140:143], v[172:175], v[120:123]
	v_mfma_i32_16x16x64_i8 v[104:107], v[140:143], v[204:207], 0
	v_mfma_i32_16x16x64_i8 v[104:107], v[144:147], v[208:211], v[104:107]
	v_mfma_i32_16x16x64_i8 v[88:91], v[144:147], v[220:223], 0
	v_mfma_i32_16x16x64_i8 v[88:91], v[140:143], v[212:215], v[88:91]
	v_mfma_i32_16x16x64_i8 v[84:87], v[156:159], v[212:215], 0
	v_mfma_i32_16x16x64_i8 v[84:87], v[160:163], v[220:223], v[84:87]
	v_mfma_i32_16x16x64_i8 v[100:103], v[160:163], v[208:211], 0
	v_mfma_i32_16x16x64_i8 v[100:103], v[156:159], v[204:207], v[100:103]
	v_mfma_i32_16x16x64_i8 v[116:119], v[156:159], v[172:175], 0
	v_mfma_i32_16x16x64_i8 v[116:119], v[160:163], v[176:179], v[116:119]
	v_mfma_i32_16x16x64_i8 v[132:135], v[160:163], v[168:171], 0
	v_mfma_i32_16x16x64_i8 v[132:135], v[156:159], v[164:167], v[132:135]
	s_barrier
	s_setprio 0
	s_add_i32 s87, s87, s46
	v_lshl_add_u64 v[190:191], s[58:59], 0, v[2:3]
	s_mov_b32 m0, s87
	ds_read_b128 v[164:167], v219 offset:16384
	ds_read_b128 v[168:171], v219 offset:17408
	ds_read_b128 v[172:175], v219 offset:18432
	ds_read_b128 v[176:179], v219 offset:19456
	ds_read_b128 v[204:207], v219 offset:20480
	ds_read_b128 v[208:211], v219 offset:21504
	ds_read_b128 v[212:215], v219 offset:22528
	ds_read_b128 v[220:223], v219 offset:23552
	global_load_lds_dwordx4 v[190:191], off
	s_add_i32 m0, s87, 0x2000
	s_add_u32 s96, s58, 0x80000
	v_lshl_add_u64 v[224:225], s[58:59], 0, v[184:185]
	s_addc_u32 s97, s59, 0
	s_add_i32 s87, vcc_lo, s46
	global_load_lds_dwordx4 v[224:225], off
	s_mov_b32 m0, s87
	v_lshl_add_u64 v[228:229], s[60:61], 0, v[182:183]
	global_load_lds_dwordx4 v2, s[96:97]
	s_add_i32 m0, s87, 0x2000
	s_nop 0
	global_load_lds_dwordx4 v184, s[96:97]
	v_lshl_add_u64 v[226:227], s[60:61], 0, v[180:181]
	s_waitcnt vmcnt(6)
	s_waitcnt lgkmcnt(7)
	s_setprio 1
	s_barrier
; #define PG8_STAGE(bufoff, gbase, voff) do { _Pragma("unroll") for (int _i = 0; _i < 2; ++_i) \
;         __builtin_amdgcn_global_load_lds((const unsigned*)((const char*)(gbase) + (voff)[_i]), (PG8_LAS unsigned*)(lds + (bufoff) + ldsw + _i * 8192), 16, 0, 0); } while (0)
; #define PG8_LDA(dst, b, h) do { _Pragma("unroll") for (int m = 0; m < 4; ++m) _Pragma("unroll") for (int k = 0; k < 2; ++k) dst[m][k] = *(const PG8_LAS bf16x8*)(lds + PG8_SA(b, h) + aoff + m * 2048 + k * 1024); } while (0)
; #define PG8_LDB(dst, b, h) do { _Pragma("unroll") for (int n = 0; n < 2; ++n) _Pragma("unroll") for (int k = 0; k < 2; ++k) dst[n][k] = *(const PG8_LAS bf16x8*)(lds + PG8_SB(b, h) + boff + n * 2048 + k * 1024); } while (0)
; #define PG8_WAIT_V(n) asm volatile("s_waitcnt vmcnt(" #n ")" ::: "memory")
; #define PG8_WAIT_L(n) asm volatile("s_waitcnt lgkmcnt(" #n ")" ::: "memory")
; #define PG8_BAR __builtin_amdgcn_s_barrier()
; #define PG8_SCHED __builtin_amdgcn_sched_barrier(0)
; template <class Epi, class Sched, bool ALIGN_EPI = false, bool SP2 = false, bool I8 = false>
; __device__ __forceinline__ void gemm_phase(PG8_LAS unsigned char* lds, const Gemm g, const Sched& S, const Epi& E) {
;     ...
;             PG8_WAIT_V(8); PG8_WAIT_L(0); PG8_BAR; PG8_MMA(1, 0, At, B0); PG8_MMA(1, 1, At, B1); PG8_BAR; PG8_SCHED;
;             PG8_LDB(B0, 1, 0); PG8_LDB(B1, 1, 1); PG8_SCHED; PG8_LDA(At, 1, 0); PG8_STAGE(PG8_SA(0, 1), a2 + hstep, voffA);
;             PG8_WAIT_V(8); PG8_WAIT_L(0); PG8_BAR; PG8_MMA(0, 0, At, B0); PG8_MMA(0, 1, At, B1); PG8_BAR; PG8_SCHED;
;             PG8_LDA(At, 1, 1); PG8_STAGE(PG8_SB(1, 0), b3, voffB); PG8_STAGE(PG8_SB(1, 1), b3 + hstep, voffB); PG8_STAGE(PG8_SA(1, 0), a3, voffA);
	v_mfma_i32_16x16x64_i8 v[80:83], v[28:31], v[164:167], 0
	s_waitcnt lgkmcnt(6)
	v_mfma_i32_16x16x64_i8 v[80:83], v[32:35], v[168:171], v[80:83]
	s_waitcnt lgkmcnt(4)
	v_mfma_i32_16x16x64_i8 v[64:67], v[32:35], v[176:179], 0
	v_mfma_i32_16x16x64_i8 v[64:67], v[28:31], v[172:175], v[64:67]
	s_waitcnt lgkmcnt(3)
	v_mfma_i32_16x16x64_i8 v[48:51], v[28:31], v[204:207], 0
	s_waitcnt lgkmcnt(2)
	v_mfma_i32_16x16x64_i8 v[48:51], v[32:35], v[208:211], v[48:51]
	s_waitcnt lgkmcnt(0)
	v_mfma_i32_16x16x64_i8 v[16:19], v[32:35], v[220:223], 0
	v_mfma_i32_16x16x64_i8 v[16:19], v[28:31], v[212:215], v[16:19]
	v_mfma_i32_16x16x64_i8 v[12:15], v[36:39], v[212:215], 0
	v_mfma_i32_16x16x64_i8 v[12:15], v[40:43], v[220:223], v[12:15]
	v_mfma_i32_16x16x64_i8 v[44:47], v[40:43], v[208:211], 0
	v_mfma_i32_16x16x64_i8 v[44:47], v[36:39], v[204:207], v[44:47]
	v_mfma_i32_16x16x64_i8 v[60:63], v[36:39], v[172:175], 0
	v_mfma_i32_16x16x64_i8 v[60:63], v[40:43], v[176:179], v[60:63]
	v_mfma_i32_16x16x64_i8 v[76:79], v[40:43], v[168:171], 0
	v_mfma_i32_16x16x64_i8 v[76:79], v[36:39], v[164:167], v[76:79]
	v_mfma_i32_16x16x64_i8 v[28:31], v[140:143], v[164:167], 0
	v_mfma_i32_16x16x64_i8 v[28:31], v[144:147], v[168:171], v[28:31]
	v_mfma_i32_16x16x64_i8 v[36:39], v[144:147], v[176:179], 0
	v_mfma_i32_16x16x64_i8 v[36:39], v[140:143], v[172:175], v[36:39]
	v_mfma_i32_16x16x64_i8 v[24:27], v[140:143], v[204:207], 0
	v_mfma_i32_16x16x64_i8 v[24:27], v[144:147], v[208:211], v[24:27]
	v_mfma_i32_16x16x64_i8 v[8:11], v[144:147], v[220:223], 0
	v_mfma_i32_16x16x64_i8 v[8:11], v[140:143], v[212:215], v[8:11]
	v_mfma_i32_16x16x64_i8 v[4:7], v[156:159], v[212:215], 0
	v_mfma_i32_16x16x64_i8 v[4:7], v[160:163], v[220:223], v[4:7]
	v_mfma_i32_16x16x64_i8 v[20:23], v[160:163], v[208:211], 0
	v_mfma_i32_16x16x64_i8 v[20:23], v[156:159], v[204:207], v[20:23]
	v_mfma_i32_16x16x64_i8 v[40:43], v[156:159], v[172:175], 0
	v_mfma_i32_16x16x64_i8 v[40:43], v[160:163], v[176:179], v[40:43]
	v_mfma_i32_16x16x64_i8 v[32:35], v[160:163], v[168:171], 0
	v_mfma_i32_16x16x64_i8 v[32:35], v[156:159], v[164:167], v[32:35]
	s_barrier
	s_setprio 0
	s_mov_b32 m0, s65
	s_nop 0
	global_load_lds_dwordx4 v[226:227], off
	s_mov_b32 m0, s67
	s_nop 0
	global_load_lds_dwordx4 v[228:229], off
	s_add_i32 s87, 0, 0x18000
	s_add_i32 s96, 0, 0x1c000
	v_add_u32_e32 v72, s87, v217
	v_add_u32_e32 v160, s96, v217
	ds_read_b128 v[52:55], v72
	ds_read_b128 v[56:59], v72 offset:1024
	ds_read_b128 v[68:71], v72 offset:2048
	ds_read_b128 v[72:75], v72 offset:3072
	ds_read_b128 v[140:143], v160
	ds_read_b128 v[144:147], v160 offset:1024
	ds_read_b128 v[156:159], v160 offset:2048
	ds_read_b128 v[160:163], v160 offset:3072
	s_add_u32 s60, s60, 0x80000
	s_addc_u32 s61, s61, 0
	s_mov_b32 m0, s72
	ds_read_b128 v[164:167], v219 offset:32768
	ds_read_b128 v[168:171], v219 offset:33792
	ds_read_b128 v[172:175], v219 offset:34816
	ds_read_b128 v[176:179], v219 offset:35840
	ds_read_b128 v[204:207], v219 offset:36864
	ds_read_b128 v[208:211], v219 offset:37888
	ds_read_b128 v[212:215], v219 offset:38912
	ds_read_b128 v[220:223], v219 offset:39936
	global_load_lds_dwordx4 v180, s[60:61]
	s_mov_b32 m0, s73
	s_nop 0
	global_load_lds_dwordx4 v182, s[60:61]
	s_waitcnt vmcnt(8)
	s_waitcnt lgkmcnt(7)
	s_setprio 1
	s_barrier
	v_mfma_i32_16x16x64_i8 v[152:155], v[52:55], v[164:167], v[152:155]
	s_waitcnt lgkmcnt(6)
	v_mfma_i32_16x16x64_i8 v[152:155], v[56:59], v[168:171], v[152:155]
	s_waitcnt lgkmcnt(4)
	v_mfma_i32_16x16x64_i8 v[128:131], v[56:59], v[176:179], v[128:131]
	v_mfma_i32_16x16x64_i8 v[128:131], v[52:55], v[172:175], v[128:131]
	s_waitcnt lgkmcnt(3)
	v_mfma_i32_16x16x64_i8 v[112:115], v[52:55], v[204:207], v[112:115]
	s_waitcnt lgkmcnt(2)
	v_mfma_i32_16x16x64_i8 v[112:115], v[56:59], v[208:211], v[112:115]
	s_waitcnt lgkmcnt(0)
	v_mfma_i32_16x16x64_i8 v[96:99], v[56:59], v[220:223], v[96:99]
	v_mfma_i32_16x16x64_i8 v[96:99], v[52:55], v[212:215], v[96:99]
	v_mfma_i32_16x16x64_i8 v[92:95], v[68:71], v[212:215], v[92:95]
	v_mfma_i32_16x16x64_i8 v[92:95], v[72:75], v[220:223], v[92:95]
	v_mfma_i32_16x16x64_i8 v[108:111], v[72:75], v[208:211], v[108:111]
	v_mfma_i32_16x16x64_i8 v[108:111], v[68:71], v[204:207], v[108:111]
	v_mfma_i32_16x16x64_i8 v[124:127], v[68:71], v[172:175], v[124:127]
	v_mfma_i32_16x16x64_i8 v[124:127], v[72:75], v[176:179], v[124:127]
	v_mfma_i32_16x16x64_i8 v[148:151], v[72:75], v[168:171], v[148:151]
	v_mfma_i32_16x16x64_i8 v[148:151], v[68:71], v[164:167], v[148:151]
	v_mfma_i32_16x16x64_i8 v[136:139], v[140:143], v[164:167], v[136:139]
	v_mfma_i32_16x16x64_i8 v[136:139], v[144:147], v[168:171], v[136:139]
	v_mfma_i32_16x16x64_i8 v[120:123], v[144:147], v[176:179], v[120:123]
	v_mfma_i32_16x16x64_i8 v[120:123], v[140:143], v[172:175], v[120:123]
	v_mfma_i32_16x16x64_i8 v[104:107], v[140:143], v[204:207], v[104:107]
	v_mfma_i32_16x16x64_i8 v[104:107], v[144:147], v[208:211], v[104:107]
	v_mfma_i32_16x16x64_i8 v[88:91], v[144:147], v[220:223], v[88:91]
	v_mfma_i32_16x16x64_i8 v[88:91], v[140:143], v[212:215], v[88:91]
	v_mfma_i32_16x16x64_i8 v[84:87], v[156:159], v[212:215], v[84:87]
	v_mfma_i32_16x16x64_i8 v[84:87], v[160:163], v[220:223], v[84:87]
	v_mfma_i32_16x16x64_i8 v[100:103], v[160:163], v[208:211], v[100:103]
	v_mfma_i32_16x16x64_i8 v[100:103], v[156:159], v[204:207], v[100:103]
	v_mfma_i32_16x16x64_i8 v[116:119], v[156:159], v[172:175], v[116:119]
	v_mfma_i32_16x16x64_i8 v[116:119], v[160:163], v[176:179], v[116:119]
	v_mfma_i32_16x16x64_i8 v[132:135], v[160:163], v[168:171], v[132:135]
	v_mfma_i32_16x16x64_i8 v[132:135], v[156:159], v[164:167], v[132:135]
	s_barrier
	s_setprio 0
	s_add_i32 s60, s87, s46
	v_lshl_add_u64 v[190:191], v[190:191], 0, s[84:85]
	s_mov_b32 m0, s60
	ds_read_b128 v[164:167], v219 offset:49152
	ds_read_b128 v[168:171], v219 offset:50176
	ds_read_b128 v[172:175], v219 offset:51200
	ds_read_b128 v[176:179], v219 offset:52224
	ds_read_b128 v[204:207], v219 offset:53248
	ds_read_b128 v[208:211], v219 offset:54272
	ds_read_b128 v[212:215], v219 offset:55296
	ds_read_b128 v[220:223], v219 offset:56320
	global_load_lds_dwordx4 v[190:191], off
	s_add_i32 m0, s60, 0x2000
	s_add_u32 s58, s58, 0x80080
	v_lshl_add_u64 v[190:191], v[224:225], 0, s[84:85]
	s_addc_u32 s59, s59, 0
	s_add_i32 s60, s96, s46
	global_load_lds_dwordx4 v[190:191], off
	s_mov_b32 m0, s60
	s_nop 0
	global_load_lds_dwordx4 v2, s[58:59]
	s_add_i32 m0, s60, 0x2000
	s_nop 0
	global_load_lds_dwordx4 v184, s[58:59]
	s_cmp_eq_u32 s86, 28
	s_cbranch_scc0 .Ldefer_1843_peel
	v_lshl_add_u64 v[190:191], v[226:227], 0, s[84:85]
	s_mov_b32 m0, s28
	s_nop 0
	global_load_lds_dwordx4 v[190:191], off
	v_lshl_add_u64 v[190:191], v[228:229], 0, s[84:85]
	s_mov_b32 m0, s77
	s_nop 0
	global_load_lds_dwordx4 v[190:191], off
; #define PG8_STAGE(bufoff, gbase, voff) do { _Pragma("unroll") for (int _i = 0; _i < 2; ++_i) \
;         __builtin_amdgcn_global_load_lds((const unsigned*)((const char*)(gbase) + (voff)[_i]), (PG8_LAS unsigned*)(lds + (bufoff) + ldsw + _i * 8192), 16, 0, 0); } while (0)
; #define PG8_LDA(dst, b, h) do { _Pragma("unroll") for (int m = 0; m < 4; ++m) _Pragma("unroll") for (int k = 0; k < 2; ++k) dst[m][k] = *(const PG8_LAS bf16x8*)(lds + PG8_SA(b, h) + aoff + m * 2048 + k * 1024); } while (0)
; #define PG8_LDB(dst, b, h) do { _Pragma("unroll") for (int n = 0; n < 2; ++n) _Pragma("unroll") for (int k = 0; k < 2; ++k) dst[n][k] = *(const PG8_LAS bf16x8*)(lds + PG8_SB(b, h) + boff + n * 2048 + k * 1024); } while (0)
; #define PG8_WAIT_V(n) asm volatile("s_waitcnt vmcnt(" #n ")" ::: "memory")
; #define PG8_WAIT_L(n) asm volatile("s_waitcnt lgkmcnt(" #n ")" ::: "memory")
; #define PG8_BAR __builtin_amdgcn_s_barrier()
; #define PG8_SCHED __builtin_amdgcn_sched_barrier(0)
; template <class Epi, class Sched, bool ALIGN_EPI = false, bool SP2 = false, bool I8 = false>
; __device__ __forceinline__ void gemm_phase(PG8_LAS unsigned char* lds, const Gemm g, const Sched& S, const Epi& E) {
;     ...
;         for (int t = 0; t < nt; t += 2) {
;             const bool last = (t == nt - 2);
;             const char* a1 = cA + (size_t)(t + 1) * kstep;
;             const char* a2 = last ? nA : cA + (size_t)(t + 2) * kstep; const char* b2 = last ? nB : cB + (size_t)(t + 2) * kstep;
;             const char* a3 = a2 + kstep; const char* b3 = b2 + kstep;
;             if (last && has_next) S.a_ready(nxt);
;             if constexpr (SP2) {
;             PG8_LDB(B0, 0, 0); PG8_LDB(B1, 0, 1); PG8_SCHED; PG8_LDA(At, 0, 0); PG8_STAGE(PG8_SA(1, 1), a1 + hstep, voffA);
;             PG8_WAIT_V(8); PG8_WAIT_L(0); PG8_BAR; PG8_MMA(0, 0, At, B0); PG8_MMA(0, 1, At, B1); PG8_BAR; PG8_SCHED;
;     ...
;             PG8_LDA(At, 1, 1); PG8_STAGE(PG8_SB(1, 0), b3, voffB); PG8_STAGE(PG8_SB(1, 1), b3 + hstep, voffB); PG8_STAGE(PG8_SA(1, 0), a3, voffA);
;             PG8_WAIT_V(8); PG8_WAIT_L(0); PG8_BAR; PG8_MMA(1, 0, At, B0); PG8_MMA(1, 1, At, B1); PG8_BAR; PG8_SCHED;
.Ldefer_1843_peel:
	s_waitcnt vmcnt(6)
	s_waitcnt lgkmcnt(7)
	s_setprio 1
	s_barrier
	v_mfma_i32_16x16x64_i8 v[80:83], v[52:55], v[164:167], v[80:83]
	s_waitcnt lgkmcnt(6)
	v_mfma_i32_16x16x64_i8 v[80:83], v[56:59], v[168:171], v[80:83]
	s_waitcnt lgkmcnt(4)
	v_mfma_i32_16x16x64_i8 v[64:67], v[56:59], v[176:179], v[64:67]
	v_mfma_i32_16x16x64_i8 v[64:67], v[52:55], v[172:175], v[64:67]
	s_waitcnt lgkmcnt(3)
	v_mfma_i32_16x16x64_i8 v[48:51], v[52:55], v[204:207], v[48:51]
	s_waitcnt lgkmcnt(2)
	v_mfma_i32_16x16x64_i8 v[48:51], v[56:59], v[208:211], v[48:51]
	s_waitcnt lgkmcnt(0)
	v_mfma_i32_16x16x64_i8 v[16:19], v[56:59], v[220:223], v[16:19]
	v_mfma_i32_16x16x64_i8 v[16:19], v[52:55], v[212:215], v[16:19]
	v_mfma_i32_16x16x64_i8 v[12:15], v[68:71], v[212:215], v[12:15]
	v_mfma_i32_16x16x64_i8 v[12:15], v[72:75], v[220:223], v[12:15]
	v_mfma_i32_16x16x64_i8 v[44:47], v[72:75], v[208:211], v[44:47]
	v_mfma_i32_16x16x64_i8 v[44:47], v[68:71], v[204:207], v[44:47]
	v_mfma_i32_16x16x64_i8 v[60:63], v[68:71], v[172:175], v[60:63]
	v_mfma_i32_16x16x64_i8 v[60:63], v[72:75], v[176:179], v[60:63]
	v_mfma_i32_16x16x64_i8 v[76:79], v[72:75], v[168:171], v[76:79]
	v_mfma_i32_16x16x64_i8 v[76:79], v[68:71], v[164:167], v[76:79]
	v_mfma_i32_16x16x64_i8 v[28:31], v[140:143], v[164:167], v[28:31]
	v_mfma_i32_16x16x64_i8 v[72:75], v[144:147], v[168:171], v[28:31]
	v_mfma_i32_16x16x64_i8 v[28:31], v[144:147], v[176:179], v[36:39]
	v_mfma_i32_16x16x64_i8 v[56:59], v[140:143], v[172:175], v[28:31]
	v_mfma_i32_16x16x64_i8 v[24:27], v[140:143], v[204:207], v[24:27]
	v_mfma_i32_16x16x64_i8 v[24:27], v[144:147], v[208:211], v[24:27]
	v_mfma_i32_16x16x64_i8 v[8:11], v[144:147], v[220:223], v[8:11]
	v_mfma_i32_16x16x64_i8 v[8:11], v[140:143], v[212:215], v[8:11]
	v_mfma_i32_16x16x64_i8 v[4:7], v[156:159], v[212:215], v[4:7]
	v_mfma_i32_16x16x64_i8 v[4:7], v[160:163], v[220:223], v[4:7]
	v_mfma_i32_16x16x64_i8 v[20:23], v[160:163], v[208:211], v[20:23]
	v_mfma_i32_16x16x64_i8 v[20:23], v[156:159], v[204:207], v[20:23]
	v_mfma_i32_16x16x64_i8 v[28:31], v[156:159], v[172:175], v[40:43]
	v_mfma_i32_16x16x64_i8 v[52:55], v[160:163], v[176:179], v[28:31]
	v_mfma_i32_16x16x64_i8 v[28:31], v[160:163], v[168:171], v[32:35]
	v_mfma_i32_16x16x64_i8 v[68:71], v[156:159], v[164:167], v[28:31]
	s_barrier
	s_setprio 0
	s_add_i32 s86, s86, 2
	s_add_u32 s54, s54, 0x100
	s_addc_u32 s55, s55, 0
	s_add_u32 s45, s45, 0x100
	s_addc_u32 s49, s49, 0
	s_cmp_gt_u32 s86, 29
	s_cbranch_scc1 .Lkloop_exit_6
.LBB0_1843:
	s_add_u32 s58, s54, 0xfff80080
	s_addc_u32 s59, s55, -1
	s_add_i32 s87, 0, 0x10000
	s_cmp_eq_u32 s86, 28
	s_cselect_b32 s61, s11, s59
	s_cselect_b32 s60, s13, s58
	s_cselect_b32 s59, s34, s49
	s_cselect_b32 s58, s35, s45
	s_add_i32 vcc_lo, 0, 0x14000
	v_add_u32_e32 v40, s87, v217
	v_add_u32_e32 v160, vcc_lo, v217
	ds_read_b128 v[28:31], v40
	ds_read_b128 v[32:35], v40 offset:1024
	ds_read_b128 v[36:39], v40 offset:2048
	ds_read_b128 v[40:43], v40 offset:3072
	ds_read_b128 v[140:143], v160
	ds_read_b128 v[144:147], v160 offset:1024
	ds_read_b128 v[156:159], v160 offset:2048
	ds_read_b128 v[160:163], v160 offset:3072
	v_lshl_add_u64 v[190:191], v[226:227], 0, s[84:85]
	s_mov_b32 m0, s28
	s_nop 0
	global_load_lds_dwordx4 v[190:191], off
	v_lshl_add_u64 v[190:191], v[228:229], 0, s[84:85]
	s_mov_b32 m0, s77
	s_nop 0
	global_load_lds_dwordx4 v[190:191], off
	s_add_i32 m0, s65, 0xc000
	ds_read_b128 v[164:167], v219
	ds_read_b128 v[168:171], v219 offset:1024
	ds_read_b128 v[172:175], v219 offset:2048
	ds_read_b128 v[176:179], v219 offset:3072
	ds_read_b128 v[204:207], v219 offset:4096
	ds_read_b128 v[208:211], v219 offset:5120
	ds_read_b128 v[212:215], v219 offset:6144
	ds_read_b128 v[220:223], v219 offset:7168
	global_load_lds_dwordx4 v186, s[54:55]
	s_add_i32 m0, s65, 0xe000
	s_nop 0
	global_load_lds_dwordx4 v188, s[54:55]
	s_waitcnt vmcnt(8)
	s_waitcnt lgkmcnt(7)
	s_setprio 1
	s_barrier
	v_mfma_i32_16x16x64_i8 v[152:155], v[28:31], v[164:167], v[152:155]
	s_waitcnt lgkmcnt(6)
	v_mfma_i32_16x16x64_i8 v[152:155], v[32:35], v[168:171], v[152:155]
	s_waitcnt lgkmcnt(4)
	v_mfma_i32_16x16x64_i8 v[128:131], v[32:35], v[176:179], v[128:131]
	v_mfma_i32_16x16x64_i8 v[128:131], v[28:31], v[172:175], v[128:131]
	s_waitcnt lgkmcnt(3)
	v_mfma_i32_16x16x64_i8 v[112:115], v[28:31], v[204:207], v[112:115]
	s_waitcnt lgkmcnt(2)
	v_mfma_i32_16x16x64_i8 v[112:115], v[32:35], v[208:211], v[112:115]
	s_waitcnt lgkmcnt(0)
	v_mfma_i32_16x16x64_i8 v[96:99], v[32:35], v[220:223], v[96:99]
	v_mfma_i32_16x16x64_i8 v[96:99], v[28:31], v[212:215], v[96:99]
	v_mfma_i32_16x16x64_i8 v[92:95], v[36:39], v[212:215], v[92:95]
	v_mfma_i32_16x16x64_i8 v[92:95], v[40:43], v[220:223], v[92:95]
	v_mfma_i32_16x16x64_i8 v[108:111], v[40:43], v[208:211], v[108:111]
	v_mfma_i32_16x16x64_i8 v[108:111], v[36:39], v[204:207], v[108:111]
	v_mfma_i32_16x16x64_i8 v[124:127], v[36:39], v[172:175], v[124:127]
	v_mfma_i32_16x16x64_i8 v[124:127], v[40:43], v[176:179], v[124:127]
	v_mfma_i32_16x16x64_i8 v[148:151], v[40:43], v[168:171], v[148:151]
	v_mfma_i32_16x16x64_i8 v[148:151], v[36:39], v[164:167], v[148:151]
	v_mfma_i32_16x16x64_i8 v[136:139], v[140:143], v[164:167], v[136:139]
	v_mfma_i32_16x16x64_i8 v[136:139], v[144:147], v[168:171], v[136:139]
	v_mfma_i32_16x16x64_i8 v[120:123], v[144:147], v[176:179], v[120:123]
	v_mfma_i32_16x16x64_i8 v[120:123], v[140:143], v[172:175], v[120:123]
	v_mfma_i32_16x16x64_i8 v[104:107], v[140:143], v[204:207], v[104:107]
	v_mfma_i32_16x16x64_i8 v[104:107], v[144:147], v[208:211], v[104:107]
	v_mfma_i32_16x16x64_i8 v[88:91], v[144:147], v[220:223], v[88:91]
	v_mfma_i32_16x16x64_i8 v[88:91], v[140:143], v[212:215], v[88:91]
	v_mfma_i32_16x16x64_i8 v[84:87], v[156:159], v[212:215], v[84:87]
	v_mfma_i32_16x16x64_i8 v[84:87], v[160:163], v[220:223], v[84:87]
	v_mfma_i32_16x16x64_i8 v[100:103], v[160:163], v[208:211], v[100:103]
	v_mfma_i32_16x16x64_i8 v[100:103], v[156:159], v[204:207], v[100:103]
	v_mfma_i32_16x16x64_i8 v[116:119], v[156:159], v[172:175], v[116:119]
	v_mfma_i32_16x16x64_i8 v[116:119], v[160:163], v[176:179], v[116:119]
	v_mfma_i32_16x16x64_i8 v[132:135], v[160:163], v[168:171], v[132:135]
	v_mfma_i32_16x16x64_i8 v[132:135], v[156:159], v[164:167], v[132:135]
	s_barrier
; #define PG8_STAGE(bufoff, gbase, voff) do { _Pragma("unroll") for (int _i = 0; _i < 2; ++_i) \
;         __builtin_amdgcn_global_load_lds((const unsigned*)((const char*)(gbase) + (voff)[_i]), (PG8_LAS unsigned*)(lds + (bufoff) + ldsw + _i * 8192), 16, 0, 0); } while (0)
; #define PG8_LDA(dst, b, h) do { _Pragma("unroll") for (int m = 0; m < 4; ++m) _Pragma("unroll") for (int k = 0; k < 2; ++k) dst[m][k] = *(const PG8_LAS bf16x8*)(lds + PG8_SA(b, h) + aoff + m * 2048 + k * 1024); } while (0)
; #define PG8_LDB(dst, b, h) do { _Pragma("unroll") for (int n = 0; n < 2; ++n) _Pragma("unroll") for (int k = 0; k < 2; ++k) dst[n][k] = *(const PG8_LAS bf16x8*)(lds + PG8_SB(b, h) + boff + n * 2048 + k * 1024); } while (0)
; #define PG8_WAIT_V(n) asm volatile("s_waitcnt vmcnt(" #n ")" ::: "memory")
; #define PG8_WAIT_L(n) asm volatile("s_waitcnt lgkmcnt(" #n ")" ::: "memory")
; #define PG8_BAR __builtin_amdgcn_s_barrier()
; #define PG8_SCHED __builtin_amdgcn_sched_barrier(0)
; template <class Epi, class Sched, bool ALIGN_EPI = false, bool SP2 = false, bool I8 = false>
; __device__ __forceinline__ void gemm_phase(PG8_LAS unsigned char* lds, const Gemm g, const Sched& S, const Epi& E) {
;     ...
;             PG8_WAIT_V(8); PG8_WAIT_L(0); PG8_BAR; PG8_MMA(0, 0, At, B0); PG8_MMA(0, 1, At, B1); PG8_BAR; PG8_SCHED;
;             PG8_LDA(At, 0, 1); PG8_STAGE(PG8_SB(0, 0), b2, voffB); PG8_STAGE(PG8_SB(0, 1), b2 + hstep, voffB); PG8_STAGE(PG8_SA(0, 0), a2, voffA);
;             PG8_WAIT_V(8); PG8_WAIT_L(0); PG8_BAR; PG8_MMA(1, 0, At, B0); PG8_MMA(1, 1, At, B1); PG8_BAR; PG8_SCHED;
;             PG8_LDB(B0, 1, 0); PG8_LDB(B1, 1, 1); PG8_SCHED; PG8_LDA(At, 1, 0); PG8_STAGE(PG8_SA(0, 1), a2 + hstep, voffA);
	s_setprio 0
	s_add_i32 s87, s87, s46
	v_lshl_add_u64 v[190:191], s[58:59], 0, v[2:3]
	s_mov_b32 m0, s87
	ds_read_b128 v[164:167], v219 offset:16384
	ds_read_b128 v[168:171], v219 offset:17408
	ds_read_b128 v[172:175], v219 offset:18432
	ds_read_b128 v[176:179], v219 offset:19456
	ds_read_b128 v[204:207], v219 offset:20480
	ds_read_b128 v[208:211], v219 offset:21504
	ds_read_b128 v[212:215], v219 offset:22528
	ds_read_b128 v[220:223], v219 offset:23552
	global_load_lds_dwordx4 v[190:191], off
	s_add_i32 m0, s87, 0x2000
	s_add_u32 s96, s58, 0x80000
	v_lshl_add_u64 v[224:225], s[58:59], 0, v[184:185]
	s_addc_u32 s97, s59, 0
	s_add_i32 s87, vcc_lo, s46
	global_load_lds_dwordx4 v[224:225], off
	s_mov_b32 m0, s87
	v_lshl_add_u64 v[228:229], s[60:61], 0, v[182:183]
	global_load_lds_dwordx4 v2, s[96:97]
	s_add_i32 m0, s87, 0x2000
	s_nop 0
	global_load_lds_dwordx4 v184, s[96:97]
	v_lshl_add_u64 v[226:227], s[60:61], 0, v[180:181]
	s_waitcnt vmcnt(6)
	s_waitcnt lgkmcnt(7)
	s_setprio 1
	s_barrier
	v_mfma_i32_16x16x64_i8 v[80:83], v[28:31], v[164:167], v[80:83]
	s_waitcnt lgkmcnt(6)
	v_mfma_i32_16x16x64_i8 v[80:83], v[32:35], v[168:171], v[80:83]
	s_waitcnt lgkmcnt(4)
	v_mfma_i32_16x16x64_i8 v[64:67], v[32:35], v[176:179], v[64:67]
	v_mfma_i32_16x16x64_i8 v[64:67], v[28:31], v[172:175], v[64:67]
	s_waitcnt lgkmcnt(3)
	v_mfma_i32_16x16x64_i8 v[48:51], v[28:31], v[204:207], v[48:51]
	s_waitcnt lgkmcnt(2)
	v_mfma_i32_16x16x64_i8 v[48:51], v[32:35], v[208:211], v[48:51]
	s_waitcnt lgkmcnt(0)
	v_mfma_i32_16x16x64_i8 v[16:19], v[32:35], v[220:223], v[16:19]
	v_mfma_i32_16x16x64_i8 v[16:19], v[28:31], v[212:215], v[16:19]
	v_mfma_i32_16x16x64_i8 v[12:15], v[36:39], v[212:215], v[12:15]
	v_mfma_i32_16x16x64_i8 v[12:15], v[40:43], v[220:223], v[12:15]
	v_mfma_i32_16x16x64_i8 v[44:47], v[40:43], v[208:211], v[44:47]
	v_mfma_i32_16x16x64_i8 v[44:47], v[36:39], v[204:207], v[44:47]
	v_mfma_i32_16x16x64_i8 v[60:63], v[36:39], v[172:175], v[60:63]
	v_mfma_i32_16x16x64_i8 v[60:63], v[40:43], v[176:179], v[60:63]
	v_mfma_i32_16x16x64_i8 v[76:79], v[40:43], v[168:171], v[76:79]
	v_mfma_i32_16x16x64_i8 v[76:79], v[36:39], v[164:167], v[76:79]
	v_mfma_i32_16x16x64_i8 v[28:31], v[140:143], v[164:167], v[72:75]
	v_mfma_i32_16x16x64_i8 v[28:31], v[144:147], v[168:171], v[28:31]
	v_mfma_i32_16x16x64_i8 v[36:39], v[144:147], v[176:179], v[56:59]
	v_mfma_i32_16x16x64_i8 v[36:39], v[140:143], v[172:175], v[36:39]
	v_mfma_i32_16x16x64_i8 v[24:27], v[140:143], v[204:207], v[24:27]
	v_mfma_i32_16x16x64_i8 v[24:27], v[144:147], v[208:211], v[24:27]
	v_mfma_i32_16x16x64_i8 v[8:11], v[144:147], v[220:223], v[8:11]
	v_mfma_i32_16x16x64_i8 v[8:11], v[140:143], v[212:215], v[8:11]
	v_mfma_i32_16x16x64_i8 v[4:7], v[156:159], v[212:215], v[4:7]
	v_mfma_i32_16x16x64_i8 v[4:7], v[160:163], v[220:223], v[4:7]
	v_mfma_i32_16x16x64_i8 v[20:23], v[160:163], v[208:211], v[20:23]
	v_mfma_i32_16x16x64_i8 v[20:23], v[156:159], v[204:207], v[20:23]
	v_mfma_i32_16x16x64_i8 v[40:43], v[156:159], v[172:175], v[52:55]
	v_mfma_i32_16x16x64_i8 v[40:43], v[160:163], v[176:179], v[40:43]
	v_mfma_i32_16x16x64_i8 v[32:35], v[160:163], v[168:171], v[68:71]
	v_mfma_i32_16x16x64_i8 v[32:35], v[156:159], v[164:167], v[32:35]
	s_barrier
	s_setprio 0
	s_mov_b32 m0, s65
	s_nop 0
	global_load_lds_dwordx4 v[226:227], off
	s_mov_b32 m0, s67
	s_nop 0
	global_load_lds_dwordx4 v[228:229], off
	s_add_i32 s87, 0, 0x18000
	s_add_i32 s96, 0, 0x1c000
	v_add_u32_e32 v72, s87, v217
	v_add_u32_e32 v160, s96, v217
	ds_read_b128 v[52:55], v72
	ds_read_b128 v[56:59], v72 offset:1024
	ds_read_b128 v[68:71], v72 offset:2048
	ds_read_b128 v[72:75], v72 offset:3072
	ds_read_b128 v[140:143], v160
	ds_read_b128 v[144:147], v160 offset:1024
	ds_read_b128 v[156:159], v160 offset:2048
	ds_read_b128 v[160:163], v160 offset:3072
	s_add_u32 s60, s60, 0x80000
	s_addc_u32 s61, s61, 0
	s_mov_b32 m0, s72
	ds_read_b128 v[164:167], v219 offset:32768
	ds_read_b128 v[168:171], v219 offset:33792
	ds_read_b128 v[172:175], v219 offset:34816
	ds_read_b128 v[176:179], v219 offset:35840
	ds_read_b128 v[204:207], v219 offset:36864
	ds_read_b128 v[208:211], v219 offset:37888
	ds_read_b128 v[212:215], v219 offset:38912
	ds_read_b128 v[220:223], v219 offset:39936
	global_load_lds_dwordx4 v180, s[60:61]
	s_mov_b32 m0, s73
	s_nop 0
	global_load_lds_dwordx4 v182, s[60:61]
	s_waitcnt vmcnt(8)
	s_waitcnt lgkmcnt(7)
	s_setprio 1
	s_barrier
; #define PG8_STAGE(bufoff, gbase, voff) do { _Pragma("unroll") for (int _i = 0; _i < 2; ++_i) \
;         __builtin_amdgcn_global_load_lds((const unsigned*)((const char*)(gbase) + (voff)[_i]), (PG8_LAS unsigned*)(lds + (bufoff) + ldsw + _i * 8192), 16, 0, 0); } while (0)
; #define PG8_LDA(dst, b, h) do { _Pragma("unroll") for (int m = 0; m < 4; ++m) _Pragma("unroll") for (int k = 0; k < 2; ++k) dst[m][k] = *(const PG8_LAS bf16x8*)(lds + PG8_SA(b, h) + aoff + m * 2048 + k * 1024); } while (0)
; #define PG8_WAIT_V(n) asm volatile("s_waitcnt vmcnt(" #n ")" ::: "memory")
; #define PG8_WAIT_L(n) asm volatile("s_waitcnt lgkmcnt(" #n ")" ::: "memory")
; #define PG8_BAR __builtin_amdgcn_s_barrier()
; #define PG8_SCHED __builtin_amdgcn_sched_barrier(0)
; template <class Epi, class Sched, bool ALIGN_EPI = false, bool SP2 = false, bool I8 = false>
; __device__ __forceinline__ void gemm_phase(PG8_LAS unsigned char* lds, const Gemm g, const Sched& S, const Epi& E) {
;     ...
;             PG8_WAIT_V(8); PG8_WAIT_L(0); PG8_BAR; PG8_MMA(0, 0, At, B0); PG8_MMA(0, 1, At, B1); PG8_BAR; PG8_SCHED;
;             PG8_LDA(At, 1, 1); PG8_STAGE(PG8_SB(1, 0), b3, voffB); PG8_STAGE(PG8_SB(1, 1), b3 + hstep, voffB); PG8_STAGE(PG8_SA(1, 0), a3, voffA);
;             PG8_WAIT_V(8); PG8_WAIT_L(0); PG8_BAR; PG8_MMA(1, 0, At, B0); PG8_MMA(1, 1, At, B1); PG8_BAR; PG8_SCHED;
	v_mfma_i32_16x16x64_i8 v[152:155], v[52:55], v[164:167], v[152:155]
	s_waitcnt lgkmcnt(6)
	v_mfma_i32_16x16x64_i8 v[152:155], v[56:59], v[168:171], v[152:155]
	s_waitcnt lgkmcnt(4)
	v_mfma_i32_16x16x64_i8 v[128:131], v[56:59], v[176:179], v[128:131]
	v_mfma_i32_16x16x64_i8 v[128:131], v[52:55], v[172:175], v[128:131]
	s_waitcnt lgkmcnt(3)
	v_mfma_i32_16x16x64_i8 v[112:115], v[52:55], v[204:207], v[112:115]
	s_waitcnt lgkmcnt(2)
	v_mfma_i32_16x16x64_i8 v[112:115], v[56:59], v[208:211], v[112:115]
	s_waitcnt lgkmcnt(0)
	v_mfma_i32_16x16x64_i8 v[96:99], v[56:59], v[220:223], v[96:99]
	v_mfma_i32_16x16x64_i8 v[96:99], v[52:55], v[212:215], v[96:99]
	v_mfma_i32_16x16x64_i8 v[92:95], v[68:71], v[212:215], v[92:95]
	v_mfma_i32_16x16x64_i8 v[92:95], v[72:75], v[220:223], v[92:95]
	v_mfma_i32_16x16x64_i8 v[108:111], v[72:75], v[208:211], v[108:111]
	v_mfma_i32_16x16x64_i8 v[108:111], v[68:71], v[204:207], v[108:111]
	v_mfma_i32_16x16x64_i8 v[124:127], v[68:71], v[172:175], v[124:127]
	v_mfma_i32_16x16x64_i8 v[124:127], v[72:75], v[176:179], v[124:127]
	v_mfma_i32_16x16x64_i8 v[148:151], v[72:75], v[168:171], v[148:151]
	v_mfma_i32_16x16x64_i8 v[148:151], v[68:71], v[164:167], v[148:151]
	v_mfma_i32_16x16x64_i8 v[136:139], v[140:143], v[164:167], v[136:139]
	v_mfma_i32_16x16x64_i8 v[136:139], v[144:147], v[168:171], v[136:139]
	v_mfma_i32_16x16x64_i8 v[120:123], v[144:147], v[176:179], v[120:123]
	v_mfma_i32_16x16x64_i8 v[120:123], v[140:143], v[172:175], v[120:123]
	v_mfma_i32_16x16x64_i8 v[104:107], v[140:143], v[204:207], v[104:107]
	v_mfma_i32_16x16x64_i8 v[104:107], v[144:147], v[208:211], v[104:107]
	v_mfma_i32_16x16x64_i8 v[88:91], v[144:147], v[220:223], v[88:91]
	v_mfma_i32_16x16x64_i8 v[88:91], v[140:143], v[212:215], v[88:91]
	v_mfma_i32_16x16x64_i8 v[84:87], v[156:159], v[212:215], v[84:87]
	v_mfma_i32_16x16x64_i8 v[84:87], v[160:163], v[220:223], v[84:87]
	v_mfma_i32_16x16x64_i8 v[100:103], v[160:163], v[208:211], v[100:103]
	v_mfma_i32_16x16x64_i8 v[100:103], v[156:159], v[204:207], v[100:103]
	v_mfma_i32_16x16x64_i8 v[116:119], v[156:159], v[172:175], v[116:119]
	v_mfma_i32_16x16x64_i8 v[116:119], v[160:163], v[176:179], v[116:119]
	v_mfma_i32_16x16x64_i8 v[132:135], v[160:163], v[168:171], v[132:135]
	v_mfma_i32_16x16x64_i8 v[132:135], v[156:159], v[164:167], v[132:135]
	s_barrier
	s_setprio 0
	s_add_i32 s60, s87, s46
	v_lshl_add_u64 v[190:191], v[190:191], 0, s[84:85]
	s_mov_b32 m0, s60
	ds_read_b128 v[164:167], v219 offset:49152
	ds_read_b128 v[168:171], v219 offset:50176
	ds_read_b128 v[172:175], v219 offset:51200
	ds_read_b128 v[176:179], v219 offset:52224
	ds_read_b128 v[204:207], v219 offset:53248
	ds_read_b128 v[208:211], v219 offset:54272
	ds_read_b128 v[212:215], v219 offset:55296
	ds_read_b128 v[220:223], v219 offset:56320
	global_load_lds_dwordx4 v[190:191], off
	s_add_i32 m0, s60, 0x2000
	s_add_u32 s58, s58, 0x80080
	v_lshl_add_u64 v[190:191], v[224:225], 0, s[84:85]
	s_addc_u32 s59, s59, 0
	s_add_i32 s60, s96, s46
	global_load_lds_dwordx4 v[190:191], off
	s_mov_b32 m0, s60
	s_nop 0
	global_load_lds_dwordx4 v2, s[58:59]
	s_add_i32 m0, s60, 0x2000
	s_nop 0
	global_load_lds_dwordx4 v184, s[58:59]
	s_cmp_eq_u32 s86, 28
	s_cbranch_scc0 .Ldefer_1843_body
	v_lshl_add_u64 v[190:191], v[226:227], 0, s[84:85]
	s_mov_b32 m0, s28
	s_nop 0
	global_load_lds_dwordx4 v[190:191], off
	v_lshl_add_u64 v[190:191], v[228:229], 0, s[84:85]
	s_mov_b32 m0, s77
	s_nop 0
	global_load_lds_dwordx4 v[190:191], off
.Ldefer_1843_body:
	s_waitcnt vmcnt(6)
	s_waitcnt lgkmcnt(7)
	s_setprio 1
	s_barrier
	v_mfma_i32_16x16x64_i8 v[80:83], v[52:55], v[164:167], v[80:83]
	s_waitcnt lgkmcnt(6)
	v_mfma_i32_16x16x64_i8 v[80:83], v[56:59], v[168:171], v[80:83]
	s_waitcnt lgkmcnt(4)
	v_mfma_i32_16x16x64_i8 v[64:67], v[56:59], v[176:179], v[64:67]
	v_mfma_i32_16x16x64_i8 v[64:67], v[52:55], v[172:175], v[64:67]
	s_waitcnt lgkmcnt(3)
	v_mfma_i32_16x16x64_i8 v[48:51], v[52:55], v[204:207], v[48:51]
	s_waitcnt lgkmcnt(2)
	v_mfma_i32_16x16x64_i8 v[48:51], v[56:59], v[208:211], v[48:51]
	s_waitcnt lgkmcnt(0)
	v_mfma_i32_16x16x64_i8 v[16:19], v[56:59], v[220:223], v[16:19]
	v_mfma_i32_16x16x64_i8 v[16:19], v[52:55], v[212:215], v[16:19]
	v_mfma_i32_16x16x64_i8 v[12:15], v[68:71], v[212:215], v[12:15]
	v_mfma_i32_16x16x64_i8 v[12:15], v[72:75], v[220:223], v[12:15]
	v_mfma_i32_16x16x64_i8 v[44:47], v[72:75], v[208:211], v[44:47]
	v_mfma_i32_16x16x64_i8 v[44:47], v[68:71], v[204:207], v[44:47]
	v_mfma_i32_16x16x64_i8 v[60:63], v[68:71], v[172:175], v[60:63]
	v_mfma_i32_16x16x64_i8 v[60:63], v[72:75], v[176:179], v[60:63]
	v_mfma_i32_16x16x64_i8 v[76:79], v[72:75], v[168:171], v[76:79]
	v_mfma_i32_16x16x64_i8 v[76:79], v[68:71], v[164:167], v[76:79]
	v_mfma_i32_16x16x64_i8 v[28:31], v[140:143], v[164:167], v[28:31]
	v_mfma_i32_16x16x64_i8 v[72:75], v[144:147], v[168:171], v[28:31]
	v_mfma_i32_16x16x64_i8 v[28:31], v[144:147], v[176:179], v[36:39]
	v_mfma_i32_16x16x64_i8 v[56:59], v[140:143], v[172:175], v[28:31]
	v_mfma_i32_16x16x64_i8 v[24:27], v[140:143], v[204:207], v[24:27]
	v_mfma_i32_16x16x64_i8 v[24:27], v[144:147], v[208:211], v[24:27]
	v_mfma_i32_16x16x64_i8 v[8:11], v[144:147], v[220:223], v[8:11]
	v_mfma_i32_16x16x64_i8 v[8:11], v[140:143], v[212:215], v[8:11]
	v_mfma_i32_16x16x64_i8 v[4:7], v[156:159], v[212:215], v[4:7]
	v_mfma_i32_16x16x64_i8 v[4:7], v[160:163], v[220:223], v[4:7]
	v_mfma_i32_16x16x64_i8 v[20:23], v[160:163], v[208:211], v[20:23]
	v_mfma_i32_16x16x64_i8 v[20:23], v[156:159], v[204:207], v[20:23]
	v_mfma_i32_16x16x64_i8 v[28:31], v[156:159], v[172:175], v[40:43]
	v_mfma_i32_16x16x64_i8 v[52:55], v[160:163], v[176:179], v[28:31]
	v_mfma_i32_16x16x64_i8 v[28:31], v[160:163], v[168:171], v[32:35]
	v_mfma_i32_16x16x64_i8 v[68:71], v[156:159], v[164:167], v[28:31]
	s_barrier
	s_setprio 0
	s_add_i32 s86, s86, 2
	s_add_u32 s54, s54, 0x100
	s_addc_u32 s55, s55, 0
	s_add_u32 s45, s45, 0x100
	s_addc_u32 s49, s49, 0
	s_cmp_gt_u32 s86, 29
	s_cbranch_scc0 .LBB0_1843
